# GEMM loops: LDS read base precomputed per tile (-4 VALU/iter); attention: bias-region change detected in SALU (negm rebuild only on change), sum chains start without +0
# speedup vs baseline: 1.0187x; 1.0020x over previous
.LBB0_136:
	s_ashr_i32 s13, s12, 31
	s_lshl_b64 s[22:23], s[12:13], 20
	s_add_u32 s22, s2, s22
	s_addc_u32 s23, s3, s23
	s_and_b64 s[24:25], s[18:19], exec
	s_cselect_b32 s13, s23, s29
	s_cselect_b32 s43, s22, s28
	s_ashr_i32 s15, s14, 31
	s_lshl_b64 s[24:25], s[14:15], 20
	s_add_u32 s24, s20, s24
	s_addc_u32 s25, s21, s25
	s_and_b64 s[34:35], s[18:19], exec
	s_cselect_b32 s15, s25, s31
	s_cselect_b32 s44, s24, s30
	s_add_u32 s28, s28, 0x80080
	s_addc_u32 s29, s29, 0
	s_add_u32 s45, s30, 0x100
	s_addc_u32 s46, s31, 0
	s_mov_b32 s47, -2
	v_add_u32_e32 v253, 0x10000, v143
	s_add_u32 s30, s28, 0xfff80080
	s_addc_u32 s31, s29, -1
	s_add_i32 s48, 0, 0x10000
	s_cmp_eq_u32 s47, 28
	s_cselect_b32 s35, s13, s31
	s_cselect_b32 s34, s43, s30
	s_cselect_b32 s31, s15, s46
	s_cselect_b32 s30, s44, s45
	s_add_i32 s50, 0, 0x14000
	ds_read_b128 v[146:149], v253
	ds_read_b128 v[150:153], v253 offset:1024
	ds_read_b128 v[154:157], v253 offset:2048
	ds_read_b128 v[158:161], v253 offset:3072
	ds_read_b128 v[162:165], v253 offset:16384
	ds_read_b128 v[166:169], v253 offset:17408
	ds_read_b128 v[170:173], v253 offset:18432
	ds_read_b128 v[178:181], v253 offset:19456
	s_add_i32 m0, s27, 0xc000
	ds_read_b128 v[182:185], v144
	ds_read_b128 v[186:189], v144 offset:1024
	ds_read_b128 v[190:193], v144 offset:2048
	ds_read_b128 v[194:197], v144 offset:3072
	ds_read_b128 v[198:201], v144 offset:4096
	ds_read_b128 v[202:205], v144 offset:5120
	ds_read_b128 v[206:209], v144 offset:6144
	ds_read_b128 v[220:223], v144 offset:7168
	global_load_lds_dwordx4 v136, s[28:29]
	s_add_i32 m0, s27, 0xe000
	s_nop 0
	global_load_lds_dwordx4 v138, s[28:29]
	s_waitcnt vmcnt(8)
	s_waitcnt lgkmcnt(0)
	s_barrier
	s_setprio 1
	s_waitcnt lgkmcnt(0)
	v_mfma_f32_16x16x32_bf16 v[124:127], v[146:149], v[182:185], 0
	v_mfma_f32_16x16x32_bf16 v[120:123], v[154:157], v[182:185], 0
	v_mfma_f32_16x16x32_bf16 v[108:111], v[146:149], v[190:193], 0
	v_mfma_f32_16x16x32_bf16 v[104:107], v[154:157], v[190:193], 0
	v_mfma_f32_16x16x32_bf16 v[92:95], v[146:149], v[198:201], 0
	v_mfma_f32_16x16x32_bf16 v[88:91], v[154:157], v[198:201], 0
	v_mfma_f32_16x16x32_bf16 v[76:79], v[146:149], v[206:209], 0
	v_mfma_f32_16x16x32_bf16 v[72:75], v[154:157], v[206:209], 0
	v_mfma_f32_16x16x32_bf16 v[124:127], v[150:153], v[186:189], v[124:127]
	v_mfma_f32_16x16x32_bf16 v[120:123], v[158:161], v[186:189], v[120:123]
	v_mfma_f32_16x16x32_bf16 v[108:111], v[150:153], v[194:197], v[108:111]
	v_mfma_f32_16x16x32_bf16 v[104:107], v[158:161], v[194:197], v[104:107]
	v_mfma_f32_16x16x32_bf16 v[92:95], v[150:153], v[202:205], v[92:95]
	v_mfma_f32_16x16x32_bf16 v[88:91], v[158:161], v[202:205], v[88:91]
	v_mfma_f32_16x16x32_bf16 v[76:79], v[150:153], v[220:223], v[76:79]
	v_mfma_f32_16x16x32_bf16 v[72:75], v[158:161], v[220:223], v[72:75]
	s_setprio 0
	s_setprio 1
	v_mfma_f32_16x16x32_bf16 v[116:119], v[162:165], v[182:185], 0
	v_mfma_f32_16x16x32_bf16 v[112:115], v[170:173], v[182:185], 0
	v_mfma_f32_16x16x32_bf16 v[100:103], v[162:165], v[190:193], 0
	v_mfma_f32_16x16x32_bf16 v[96:99], v[170:173], v[190:193], 0
	v_mfma_f32_16x16x32_bf16 v[84:87], v[162:165], v[198:201], 0
	v_mfma_f32_16x16x32_bf16 v[80:83], v[170:173], v[198:201], 0
	v_mfma_f32_16x16x32_bf16 v[68:71], v[162:165], v[206:209], 0
	v_mfma_f32_16x16x32_bf16 v[64:67], v[170:173], v[206:209], 0
	v_mfma_f32_16x16x32_bf16 v[116:119], v[166:169], v[186:189], v[116:119]
	v_mfma_f32_16x16x32_bf16 v[112:115], v[178:181], v[186:189], v[112:115]
	v_mfma_f32_16x16x32_bf16 v[100:103], v[166:169], v[194:197], v[100:103]
	v_mfma_f32_16x16x32_bf16 v[96:99], v[178:181], v[194:197], v[96:99]
	v_mfma_f32_16x16x32_bf16 v[84:87], v[166:169], v[202:205], v[84:87]
	v_mfma_f32_16x16x32_bf16 v[80:83], v[178:181], v[202:205], v[80:83]
	v_mfma_f32_16x16x32_bf16 v[68:71], v[166:169], v[220:223], v[68:71]
	v_mfma_f32_16x16x32_bf16 v[64:67], v[178:181], v[220:223], v[64:67]
	s_setprio 0
	s_barrier
	s_add_i32 s48, s48, s26
	s_mov_b32 m0, s48
	ds_read_b128 v[182:185], v144 offset:16384
	ds_read_b128 v[186:189], v144 offset:17408
	ds_read_b128 v[190:193], v144 offset:18432
	ds_read_b128 v[194:197], v144 offset:19456
	ds_read_b128 v[198:201], v144 offset:20480
	ds_read_b128 v[202:205], v144 offset:21504
	ds_read_b128 v[206:209], v144 offset:22528
	ds_read_b128 v[220:223], v144 offset:23552
	global_load_lds_dwordx4 v132, s[30:31]
	s_add_i32 m0, s48, 0x2000
	s_add_u32 s48, s30, 0x80000
	s_addc_u32 s49, s31, 0
	s_add_i32 s50, s50, s26
	global_load_lds_dwordx4 v128, s[30:31]
	s_mov_b32 m0, s50
	s_nop 0
	global_load_lds_dwordx4 v132, s[48:49]
	s_add_i32 m0, s50, 0x2000
	s_nop 0
	global_load_lds_dwordx4 v128, s[48:49]
	s_add_u32 s60, s34, 0x80
	s_addc_u32 s61, s35, 0
	s_mov_b32 m0, s27
	s_nop 0
	global_load_lds_dwordx4 v134, s[34:35]
	s_mov_b32 m0, s33
	s_nop 0
	global_load_lds_dwordx4 v130, s[34:35]
	s_waitcnt vmcnt(8)
	s_waitcnt lgkmcnt(0)
	s_barrier
	s_setprio 1
	s_waitcnt lgkmcnt(0)
	v_mfma_f32_16x16x32_bf16 v[60:63], v[146:149], v[182:185], 0
	v_mfma_f32_16x16x32_bf16 v[56:59], v[154:157], v[182:185], 0
	v_mfma_f32_16x16x32_bf16 v[44:47], v[146:149], v[190:193], 0
	v_mfma_f32_16x16x32_bf16 v[40:43], v[154:157], v[190:193], 0
	v_mfma_f32_16x16x32_bf16 v[28:31], v[146:149], v[198:201], 0
	v_mfma_f32_16x16x32_bf16 v[24:27], v[154:157], v[198:201], 0
	v_mfma_f32_16x16x32_bf16 v[12:15], v[146:149], v[206:209], 0
	v_mfma_f32_16x16x32_bf16 v[8:11], v[154:157], v[206:209], 0
	v_mfma_f32_16x16x32_bf16 v[60:63], v[150:153], v[186:189], v[60:63]
	v_mfma_f32_16x16x32_bf16 v[56:59], v[158:161], v[186:189], v[56:59]
	v_mfma_f32_16x16x32_bf16 v[44:47], v[150:153], v[194:197], v[44:47]
	v_mfma_f32_16x16x32_bf16 v[40:43], v[158:161], v[194:197], v[40:43]
	v_mfma_f32_16x16x32_bf16 v[28:31], v[150:153], v[202:205], v[28:31]
	v_mfma_f32_16x16x32_bf16 v[24:27], v[158:161], v[202:205], v[24:27]
	v_mfma_f32_16x16x32_bf16 v[12:15], v[150:153], v[220:223], v[12:15]
	v_mfma_f32_16x16x32_bf16 v[8:11], v[158:161], v[220:223], v[8:11]
	s_setprio 0
	s_setprio 1
	v_mfma_f32_16x16x32_bf16 v[52:55], v[162:165], v[182:185], 0
	v_mfma_f32_16x16x32_bf16 v[48:51], v[170:173], v[182:185], 0
	v_mfma_f32_16x16x32_bf16 v[36:39], v[162:165], v[190:193], 0
	v_mfma_f32_16x16x32_bf16 v[32:35], v[170:173], v[190:193], 0
	v_mfma_f32_16x16x32_bf16 v[20:23], v[162:165], v[198:201], 0
	v_mfma_f32_16x16x32_bf16 v[16:19], v[170:173], v[198:201], 0
	v_mfma_f32_16x16x32_bf16 v[4:7], v[162:165], v[206:209], 0
	v_mfma_f32_16x16x32_bf16 v[0:3], v[170:173], v[206:209], 0
	v_mfma_f32_16x16x32_bf16 v[52:55], v[166:169], v[186:189], v[52:55]
	v_mfma_f32_16x16x32_bf16 v[48:51], v[178:181], v[186:189], v[48:51]
	v_mfma_f32_16x16x32_bf16 v[36:39], v[166:169], v[194:197], v[36:39]
	v_mfma_f32_16x16x32_bf16 v[32:35], v[178:181], v[194:197], v[32:35]
	v_mfma_f32_16x16x32_bf16 v[20:23], v[166:169], v[202:205], v[20:23]
	v_mfma_f32_16x16x32_bf16 v[16:19], v[178:181], v[202:205], v[16:19]
	v_mfma_f32_16x16x32_bf16 v[4:7], v[166:169], v[220:223], v[4:7]
	v_mfma_f32_16x16x32_bf16 v[0:3], v[178:181], v[220:223], v[0:3]
	s_setprio 0
	s_barrier
	s_add_i32 s48, 0, 0x18000
	s_add_i32 s49, 0, 0x1c000
	ds_read_b128 v[146:149], v253 offset:32768
	ds_read_b128 v[150:153], v253 offset:33792
	ds_read_b128 v[154:157], v253 offset:34816
	ds_read_b128 v[158:161], v253 offset:35840
	ds_read_b128 v[162:165], v253 offset:49152
	ds_read_b128 v[166:169], v253 offset:50176
	ds_read_b128 v[170:173], v253 offset:51200
	ds_read_b128 v[178:181], v253 offset:52224
	s_add_u32 s34, s34, 0x80000
	s_addc_u32 s35, s35, 0
	s_mov_b32 m0, s36
	ds_read_b128 v[182:185], v144 offset:32768
	ds_read_b128 v[186:189], v144 offset:33792
	ds_read_b128 v[190:193], v144 offset:34816
	ds_read_b128 v[194:197], v144 offset:35840
	ds_read_b128 v[198:201], v144 offset:36864
	ds_read_b128 v[202:205], v144 offset:37888
	ds_read_b128 v[206:209], v144 offset:38912
	ds_read_b128 v[220:223], v144 offset:39936
	global_load_lds_dwordx4 v134, s[34:35]
	s_mov_b32 m0, s37
	s_nop 0
	global_load_lds_dwordx4 v130, s[34:35]
	s_waitcnt vmcnt(8)
	s_waitcnt lgkmcnt(0)
	s_barrier
	s_setprio 1
	s_waitcnt lgkmcnt(0)
	v_mfma_f32_16x16x32_bf16 v[124:127], v[146:149], v[182:185], v[124:127]
	v_mfma_f32_16x16x32_bf16 v[120:123], v[154:157], v[182:185], v[120:123]
	v_mfma_f32_16x16x32_bf16 v[108:111], v[146:149], v[190:193], v[108:111]
	v_mfma_f32_16x16x32_bf16 v[104:107], v[154:157], v[190:193], v[104:107]
	v_mfma_f32_16x16x32_bf16 v[92:95], v[146:149], v[198:201], v[92:95]
	v_mfma_f32_16x16x32_bf16 v[88:91], v[154:157], v[198:201], v[88:91]
	v_mfma_f32_16x16x32_bf16 v[76:79], v[146:149], v[206:209], v[76:79]
	v_mfma_f32_16x16x32_bf16 v[72:75], v[154:157], v[206:209], v[72:75]
	v_mfma_f32_16x16x32_bf16 v[124:127], v[150:153], v[186:189], v[124:127]
	v_mfma_f32_16x16x32_bf16 v[120:123], v[158:161], v[186:189], v[120:123]
	v_mfma_f32_16x16x32_bf16 v[108:111], v[150:153], v[194:197], v[108:111]
	v_mfma_f32_16x16x32_bf16 v[104:107], v[158:161], v[194:197], v[104:107]
	v_mfma_f32_16x16x32_bf16 v[92:95], v[150:153], v[202:205], v[92:95]
	v_mfma_f32_16x16x32_bf16 v[88:91], v[158:161], v[202:205], v[88:91]
	v_mfma_f32_16x16x32_bf16 v[76:79], v[150:153], v[220:223], v[76:79]
	v_mfma_f32_16x16x32_bf16 v[72:75], v[158:161], v[220:223], v[72:75]
	s_setprio 0
	s_setprio 1
	v_mfma_f32_16x16x32_bf16 v[116:119], v[162:165], v[182:185], v[116:119]
	v_mfma_f32_16x16x32_bf16 v[112:115], v[170:173], v[182:185], v[112:115]
	v_mfma_f32_16x16x32_bf16 v[100:103], v[162:165], v[190:193], v[100:103]
	v_mfma_f32_16x16x32_bf16 v[96:99], v[170:173], v[190:193], v[96:99]
	v_mfma_f32_16x16x32_bf16 v[84:87], v[162:165], v[198:201], v[84:87]
	v_mfma_f32_16x16x32_bf16 v[80:83], v[170:173], v[198:201], v[80:83]
	v_mfma_f32_16x16x32_bf16 v[68:71], v[162:165], v[206:209], v[68:71]
	v_mfma_f32_16x16x32_bf16 v[64:67], v[170:173], v[206:209], v[64:67]
	v_mfma_f32_16x16x32_bf16 v[116:119], v[166:169], v[186:189], v[116:119]
	v_mfma_f32_16x16x32_bf16 v[112:115], v[178:181], v[186:189], v[112:115]
	v_mfma_f32_16x16x32_bf16 v[100:103], v[166:169], v[194:197], v[100:103]
	v_mfma_f32_16x16x32_bf16 v[96:99], v[178:181], v[194:197], v[96:99]
	v_mfma_f32_16x16x32_bf16 v[84:87], v[166:169], v[202:205], v[84:87]
	v_mfma_f32_16x16x32_bf16 v[80:83], v[178:181], v[202:205], v[80:83]
	v_mfma_f32_16x16x32_bf16 v[68:71], v[166:169], v[220:223], v[68:71]
	v_mfma_f32_16x16x32_bf16 v[64:67], v[178:181], v[220:223], v[64:67]
	s_setprio 0
	s_barrier
	s_add_i32 s34, s48, s26
	s_mov_b32 m0, s34
	ds_read_b128 v[182:185], v144 offset:49152
	ds_read_b128 v[186:189], v144 offset:50176
	ds_read_b128 v[190:193], v144 offset:51200
	ds_read_b128 v[194:197], v144 offset:52224
	ds_read_b128 v[198:201], v144 offset:53248
	ds_read_b128 v[202:205], v144 offset:54272
	ds_read_b128 v[206:209], v144 offset:55296
	ds_read_b128 v[220:223], v144 offset:56320
	s_add_u32 s98, s30, 0x80
	s_addc_u32 s99, s31, 0
	global_load_lds_dwordx4 v132, s[98:99]
	s_add_i32 m0, s34, 0x2000
	s_add_u32 s30, s30, 0x80080
	s_addc_u32 s31, s31, 0
	s_add_i32 s34, s49, s26
	s_add_u32 s98, s30, 0xfff80000
	s_addc_u32 s99, s31, -1
	global_load_lds_dwordx4 v128, s[98:99]
	s_mov_b32 m0, s34
	s_nop 0
	global_load_lds_dwordx4 v132, s[30:31]
	s_add_i32 m0, s34, 0x2000
	s_nop 0
	global_load_lds_dwordx4 v128, s[30:31]
	s_mov_b32 m0, s38
	s_nop 0
	global_load_lds_dwordx4 v134, s[60:61]
	s_mov_b32 m0, s39
	s_nop 0
	global_load_lds_dwordx4 v130, s[60:61]
	s_waitcnt vmcnt(8)
	s_waitcnt lgkmcnt(0)
	s_barrier
	s_setprio 1
	s_waitcnt lgkmcnt(0)
	v_mfma_f32_16x16x32_bf16 v[60:63], v[146:149], v[182:185], v[60:63]
	v_mfma_f32_16x16x32_bf16 v[56:59], v[154:157], v[182:185], v[56:59]
	v_mfma_f32_16x16x32_bf16 v[44:47], v[146:149], v[190:193], v[44:47]
	v_mfma_f32_16x16x32_bf16 v[40:43], v[154:157], v[190:193], v[40:43]
	v_mfma_f32_16x16x32_bf16 v[28:31], v[146:149], v[198:201], v[28:31]
	v_mfma_f32_16x16x32_bf16 v[24:27], v[154:157], v[198:201], v[24:27]
	v_mfma_f32_16x16x32_bf16 v[12:15], v[146:149], v[206:209], v[12:15]
	v_mfma_f32_16x16x32_bf16 v[8:11], v[154:157], v[206:209], v[8:11]
	v_mfma_f32_16x16x32_bf16 v[60:63], v[150:153], v[186:189], v[60:63]
	v_mfma_f32_16x16x32_bf16 v[56:59], v[158:161], v[186:189], v[56:59]
	v_mfma_f32_16x16x32_bf16 v[44:47], v[150:153], v[194:197], v[44:47]
	v_mfma_f32_16x16x32_bf16 v[40:43], v[158:161], v[194:197], v[40:43]
	v_mfma_f32_16x16x32_bf16 v[28:31], v[150:153], v[202:205], v[28:31]
	v_mfma_f32_16x16x32_bf16 v[24:27], v[158:161], v[202:205], v[24:27]
	v_mfma_f32_16x16x32_bf16 v[12:15], v[150:153], v[220:223], v[12:15]
	v_mfma_f32_16x16x32_bf16 v[8:11], v[158:161], v[220:223], v[8:11]
	s_setprio 0
	s_setprio 1
	v_mfma_f32_16x16x32_bf16 v[52:55], v[162:165], v[182:185], v[52:55]
	v_mfma_f32_16x16x32_bf16 v[48:51], v[170:173], v[182:185], v[48:51]
	v_mfma_f32_16x16x32_bf16 v[36:39], v[162:165], v[190:193], v[36:39]
	v_mfma_f32_16x16x32_bf16 v[32:35], v[170:173], v[190:193], v[32:35]
	v_mfma_f32_16x16x32_bf16 v[20:23], v[162:165], v[198:201], v[20:23]
	v_mfma_f32_16x16x32_bf16 v[16:19], v[170:173], v[198:201], v[16:19]
	v_mfma_f32_16x16x32_bf16 v[4:7], v[162:165], v[206:209], v[4:7]
	v_mfma_f32_16x16x32_bf16 v[0:3], v[170:173], v[206:209], v[0:3]
	v_mfma_f32_16x16x32_bf16 v[52:55], v[166:169], v[186:189], v[52:55]
	v_mfma_f32_16x16x32_bf16 v[48:51], v[178:181], v[186:189], v[48:51]
	v_mfma_f32_16x16x32_bf16 v[36:39], v[166:169], v[194:197], v[36:39]
	v_mfma_f32_16x16x32_bf16 v[32:35], v[178:181], v[194:197], v[32:35]
	v_mfma_f32_16x16x32_bf16 v[20:23], v[166:169], v[202:205], v[20:23]
	v_mfma_f32_16x16x32_bf16 v[16:19], v[178:181], v[202:205], v[16:19]
	v_mfma_f32_16x16x32_bf16 v[4:7], v[166:169], v[220:223], v[4:7]
	v_mfma_f32_16x16x32_bf16 v[0:3], v[178:181], v[220:223], v[0:3]
	s_setprio 0
	s_barrier
	s_add_i32 s47, s47, 2
	s_add_u32 s28, s28, 0x100
	s_addc_u32 s29, s29, 0
	s_add_u32 s45, s45, 0x100
	s_addc_u32 s46, s46, 0
	s_cmp_gt_u32 s47, 29
.LBB0_137:
	s_add_u32 s30, s28, 0xfff80080
	s_addc_u32 s31, s29, -1
	s_add_i32 s48, 0, 0x10000
	s_cmp_eq_u32 s47, 28
	s_cselect_b32 s35, s13, s31
	s_cselect_b32 s34, s43, s30
	s_cselect_b32 s31, s15, s46
	s_cselect_b32 s30, s44, s45
	s_add_i32 s50, 0, 0x14000
	ds_read_b128 v[146:149], v253
	ds_read_b128 v[150:153], v253 offset:1024
	ds_read_b128 v[154:157], v253 offset:2048
	ds_read_b128 v[158:161], v253 offset:3072
	ds_read_b128 v[162:165], v253 offset:16384
	ds_read_b128 v[166:169], v253 offset:17408
	ds_read_b128 v[170:173], v253 offset:18432
	ds_read_b128 v[178:181], v253 offset:19456
	s_add_i32 m0, s27, 0xc000
	ds_read_b128 v[182:185], v144
	ds_read_b128 v[186:189], v144 offset:1024
	ds_read_b128 v[190:193], v144 offset:2048
	ds_read_b128 v[194:197], v144 offset:3072
	ds_read_b128 v[198:201], v144 offset:4096
	ds_read_b128 v[202:205], v144 offset:5120
	ds_read_b128 v[206:209], v144 offset:6144
	ds_read_b128 v[220:223], v144 offset:7168
	global_load_lds_dwordx4 v136, s[28:29]
	s_add_i32 m0, s27, 0xe000
	s_nop 0
	global_load_lds_dwordx4 v138, s[28:29]
	s_waitcnt vmcnt(8)
	s_waitcnt lgkmcnt(0)
	s_barrier
	s_setprio 1
	s_waitcnt lgkmcnt(0)
	v_mfma_f32_16x16x32_bf16 v[124:127], v[146:149], v[182:185], v[124:127]
	v_mfma_f32_16x16x32_bf16 v[120:123], v[154:157], v[182:185], v[120:123]
	v_mfma_f32_16x16x32_bf16 v[108:111], v[146:149], v[190:193], v[108:111]
	v_mfma_f32_16x16x32_bf16 v[104:107], v[154:157], v[190:193], v[104:107]
	v_mfma_f32_16x16x32_bf16 v[92:95], v[146:149], v[198:201], v[92:95]
	v_mfma_f32_16x16x32_bf16 v[88:91], v[154:157], v[198:201], v[88:91]
	v_mfma_f32_16x16x32_bf16 v[76:79], v[146:149], v[206:209], v[76:79]
	v_mfma_f32_16x16x32_bf16 v[72:75], v[154:157], v[206:209], v[72:75]
	v_mfma_f32_16x16x32_bf16 v[124:127], v[150:153], v[186:189], v[124:127]
	v_mfma_f32_16x16x32_bf16 v[120:123], v[158:161], v[186:189], v[120:123]
	v_mfma_f32_16x16x32_bf16 v[108:111], v[150:153], v[194:197], v[108:111]
	v_mfma_f32_16x16x32_bf16 v[104:107], v[158:161], v[194:197], v[104:107]
	v_mfma_f32_16x16x32_bf16 v[92:95], v[150:153], v[202:205], v[92:95]
	v_mfma_f32_16x16x32_bf16 v[88:91], v[158:161], v[202:205], v[88:91]
	v_mfma_f32_16x16x32_bf16 v[76:79], v[150:153], v[220:223], v[76:79]
	v_mfma_f32_16x16x32_bf16 v[72:75], v[158:161], v[220:223], v[72:75]
	s_setprio 0
	s_setprio 1
	v_mfma_f32_16x16x32_bf16 v[116:119], v[162:165], v[182:185], v[116:119]
	v_mfma_f32_16x16x32_bf16 v[112:115], v[170:173], v[182:185], v[112:115]
	v_mfma_f32_16x16x32_bf16 v[100:103], v[162:165], v[190:193], v[100:103]
	v_mfma_f32_16x16x32_bf16 v[96:99], v[170:173], v[190:193], v[96:99]
	v_mfma_f32_16x16x32_bf16 v[84:87], v[162:165], v[198:201], v[84:87]
	v_mfma_f32_16x16x32_bf16 v[80:83], v[170:173], v[198:201], v[80:83]
	v_mfma_f32_16x16x32_bf16 v[68:71], v[162:165], v[206:209], v[68:71]
	v_mfma_f32_16x16x32_bf16 v[64:67], v[170:173], v[206:209], v[64:67]
	v_mfma_f32_16x16x32_bf16 v[116:119], v[166:169], v[186:189], v[116:119]
	v_mfma_f32_16x16x32_bf16 v[112:115], v[178:181], v[186:189], v[112:115]
	v_mfma_f32_16x16x32_bf16 v[100:103], v[166:169], v[194:197], v[100:103]
	v_mfma_f32_16x16x32_bf16 v[96:99], v[178:181], v[194:197], v[96:99]
	v_mfma_f32_16x16x32_bf16 v[84:87], v[166:169], v[202:205], v[84:87]
	v_mfma_f32_16x16x32_bf16 v[80:83], v[178:181], v[202:205], v[80:83]
	v_mfma_f32_16x16x32_bf16 v[68:71], v[166:169], v[220:223], v[68:71]
	v_mfma_f32_16x16x32_bf16 v[64:67], v[178:181], v[220:223], v[64:67]
	s_setprio 0
	s_barrier
	s_add_i32 s48, s48, s26
	s_mov_b32 m0, s48
	ds_read_b128 v[182:185], v144 offset:16384
	ds_read_b128 v[186:189], v144 offset:17408
	ds_read_b128 v[190:193], v144 offset:18432
	ds_read_b128 v[194:197], v144 offset:19456
	ds_read_b128 v[198:201], v144 offset:20480
	ds_read_b128 v[202:205], v144 offset:21504
	ds_read_b128 v[206:209], v144 offset:22528
	ds_read_b128 v[220:223], v144 offset:23552
	global_load_lds_dwordx4 v132, s[30:31]
	s_add_i32 m0, s48, 0x2000
	s_add_u32 s48, s30, 0x80000
	s_addc_u32 s49, s31, 0
	s_add_i32 s50, s50, s26
	global_load_lds_dwordx4 v128, s[30:31]
	s_mov_b32 m0, s50
	s_nop 0
	global_load_lds_dwordx4 v132, s[48:49]
	s_add_i32 m0, s50, 0x2000
	s_nop 0
	global_load_lds_dwordx4 v128, s[48:49]
	s_add_u32 s60, s34, 0x80
	s_addc_u32 s61, s35, 0
	s_mov_b32 m0, s27
	s_nop 0
	global_load_lds_dwordx4 v134, s[34:35]
	s_mov_b32 m0, s33
	s_nop 0
	global_load_lds_dwordx4 v130, s[34:35]
	s_waitcnt vmcnt(8)
	s_waitcnt lgkmcnt(0)
	s_barrier
	s_setprio 1
	s_waitcnt lgkmcnt(0)
	v_mfma_f32_16x16x32_bf16 v[60:63], v[146:149], v[182:185], v[60:63]
	v_mfma_f32_16x16x32_bf16 v[56:59], v[154:157], v[182:185], v[56:59]
	v_mfma_f32_16x16x32_bf16 v[44:47], v[146:149], v[190:193], v[44:47]
	v_mfma_f32_16x16x32_bf16 v[40:43], v[154:157], v[190:193], v[40:43]
	v_mfma_f32_16x16x32_bf16 v[28:31], v[146:149], v[198:201], v[28:31]
	v_mfma_f32_16x16x32_bf16 v[24:27], v[154:157], v[198:201], v[24:27]
	v_mfma_f32_16x16x32_bf16 v[12:15], v[146:149], v[206:209], v[12:15]
	v_mfma_f32_16x16x32_bf16 v[8:11], v[154:157], v[206:209], v[8:11]
	v_mfma_f32_16x16x32_bf16 v[60:63], v[150:153], v[186:189], v[60:63]
	v_mfma_f32_16x16x32_bf16 v[56:59], v[158:161], v[186:189], v[56:59]
	v_mfma_f32_16x16x32_bf16 v[44:47], v[150:153], v[194:197], v[44:47]
	v_mfma_f32_16x16x32_bf16 v[40:43], v[158:161], v[194:197], v[40:43]
	v_mfma_f32_16x16x32_bf16 v[28:31], v[150:153], v[202:205], v[28:31]
	v_mfma_f32_16x16x32_bf16 v[24:27], v[158:161], v[202:205], v[24:27]
	v_mfma_f32_16x16x32_bf16 v[12:15], v[150:153], v[220:223], v[12:15]
	v_mfma_f32_16x16x32_bf16 v[8:11], v[158:161], v[220:223], v[8:11]
	s_setprio 0
	s_setprio 1
	v_mfma_f32_16x16x32_bf16 v[52:55], v[162:165], v[182:185], v[52:55]
	v_mfma_f32_16x16x32_bf16 v[48:51], v[170:173], v[182:185], v[48:51]
	v_mfma_f32_16x16x32_bf16 v[36:39], v[162:165], v[190:193], v[36:39]
	v_mfma_f32_16x16x32_bf16 v[32:35], v[170:173], v[190:193], v[32:35]
	v_mfma_f32_16x16x32_bf16 v[20:23], v[162:165], v[198:201], v[20:23]
	v_mfma_f32_16x16x32_bf16 v[16:19], v[170:173], v[198:201], v[16:19]
	v_mfma_f32_16x16x32_bf16 v[4:7], v[162:165], v[206:209], v[4:7]
	v_mfma_f32_16x16x32_bf16 v[0:3], v[170:173], v[206:209], v[0:3]
	v_mfma_f32_16x16x32_bf16 v[52:55], v[166:169], v[186:189], v[52:55]
	v_mfma_f32_16x16x32_bf16 v[48:51], v[178:181], v[186:189], v[48:51]
	v_mfma_f32_16x16x32_bf16 v[36:39], v[166:169], v[194:197], v[36:39]
	v_mfma_f32_16x16x32_bf16 v[32:35], v[178:181], v[194:197], v[32:35]
	v_mfma_f32_16x16x32_bf16 v[20:23], v[166:169], v[202:205], v[20:23]
	v_mfma_f32_16x16x32_bf16 v[16:19], v[178:181], v[202:205], v[16:19]
	v_mfma_f32_16x16x32_bf16 v[4:7], v[166:169], v[220:223], v[4:7]
	v_mfma_f32_16x16x32_bf16 v[0:3], v[178:181], v[220:223], v[0:3]
	s_setprio 0
	s_barrier
	s_add_i32 s48, 0, 0x18000
	s_add_i32 s49, 0, 0x1c000
	ds_read_b128 v[146:149], v253 offset:32768
	ds_read_b128 v[150:153], v253 offset:33792
	ds_read_b128 v[154:157], v253 offset:34816
	ds_read_b128 v[158:161], v253 offset:35840
	ds_read_b128 v[162:165], v253 offset:49152
	ds_read_b128 v[166:169], v253 offset:50176
	ds_read_b128 v[170:173], v253 offset:51200
	ds_read_b128 v[178:181], v253 offset:52224
	s_add_u32 s34, s34, 0x80000
	s_addc_u32 s35, s35, 0
	s_mov_b32 m0, s36
	ds_read_b128 v[182:185], v144 offset:32768
	ds_read_b128 v[186:189], v144 offset:33792
	ds_read_b128 v[190:193], v144 offset:34816
	ds_read_b128 v[194:197], v144 offset:35840
	ds_read_b128 v[198:201], v144 offset:36864
	ds_read_b128 v[202:205], v144 offset:37888
	ds_read_b128 v[206:209], v144 offset:38912
	ds_read_b128 v[220:223], v144 offset:39936
	global_load_lds_dwordx4 v134, s[34:35]
	s_mov_b32 m0, s37
	s_nop 0
	global_load_lds_dwordx4 v130, s[34:35]
	s_waitcnt vmcnt(8)
	s_waitcnt lgkmcnt(0)
	s_barrier
	s_setprio 1
	s_waitcnt lgkmcnt(0)
	v_mfma_f32_16x16x32_bf16 v[124:127], v[146:149], v[182:185], v[124:127]
	v_mfma_f32_16x16x32_bf16 v[120:123], v[154:157], v[182:185], v[120:123]
	v_mfma_f32_16x16x32_bf16 v[108:111], v[146:149], v[190:193], v[108:111]
	v_mfma_f32_16x16x32_bf16 v[104:107], v[154:157], v[190:193], v[104:107]
	v_mfma_f32_16x16x32_bf16 v[92:95], v[146:149], v[198:201], v[92:95]
	v_mfma_f32_16x16x32_bf16 v[88:91], v[154:157], v[198:201], v[88:91]
	v_mfma_f32_16x16x32_bf16 v[76:79], v[146:149], v[206:209], v[76:79]
	v_mfma_f32_16x16x32_bf16 v[72:75], v[154:157], v[206:209], v[72:75]
	v_mfma_f32_16x16x32_bf16 v[124:127], v[150:153], v[186:189], v[124:127]
	v_mfma_f32_16x16x32_bf16 v[120:123], v[158:161], v[186:189], v[120:123]
	v_mfma_f32_16x16x32_bf16 v[108:111], v[150:153], v[194:197], v[108:111]
	v_mfma_f32_16x16x32_bf16 v[104:107], v[158:161], v[194:197], v[104:107]
	v_mfma_f32_16x16x32_bf16 v[92:95], v[150:153], v[202:205], v[92:95]
	v_mfma_f32_16x16x32_bf16 v[88:91], v[158:161], v[202:205], v[88:91]
	v_mfma_f32_16x16x32_bf16 v[76:79], v[150:153], v[220:223], v[76:79]
	v_mfma_f32_16x16x32_bf16 v[72:75], v[158:161], v[220:223], v[72:75]
	s_setprio 0
	s_setprio 1
	v_mfma_f32_16x16x32_bf16 v[116:119], v[162:165], v[182:185], v[116:119]
	v_mfma_f32_16x16x32_bf16 v[112:115], v[170:173], v[182:185], v[112:115]
	v_mfma_f32_16x16x32_bf16 v[100:103], v[162:165], v[190:193], v[100:103]
	v_mfma_f32_16x16x32_bf16 v[96:99], v[170:173], v[190:193], v[96:99]
	v_mfma_f32_16x16x32_bf16 v[84:87], v[162:165], v[198:201], v[84:87]
	v_mfma_f32_16x16x32_bf16 v[80:83], v[170:173], v[198:201], v[80:83]
	v_mfma_f32_16x16x32_bf16 v[68:71], v[162:165], v[206:209], v[68:71]
	v_mfma_f32_16x16x32_bf16 v[64:67], v[170:173], v[206:209], v[64:67]
	v_mfma_f32_16x16x32_bf16 v[116:119], v[166:169], v[186:189], v[116:119]
	v_mfma_f32_16x16x32_bf16 v[112:115], v[178:181], v[186:189], v[112:115]
	v_mfma_f32_16x16x32_bf16 v[100:103], v[166:169], v[194:197], v[100:103]
	v_mfma_f32_16x16x32_bf16 v[96:99], v[178:181], v[194:197], v[96:99]
	v_mfma_f32_16x16x32_bf16 v[84:87], v[166:169], v[202:205], v[84:87]
	v_mfma_f32_16x16x32_bf16 v[80:83], v[178:181], v[202:205], v[80:83]
	v_mfma_f32_16x16x32_bf16 v[68:71], v[166:169], v[220:223], v[68:71]
	v_mfma_f32_16x16x32_bf16 v[64:67], v[178:181], v[220:223], v[64:67]
	s_setprio 0
	s_barrier
	s_add_i32 s34, s48, s26
	s_mov_b32 m0, s34
	ds_read_b128 v[182:185], v144 offset:49152
	ds_read_b128 v[186:189], v144 offset:50176
	ds_read_b128 v[190:193], v144 offset:51200
	ds_read_b128 v[194:197], v144 offset:52224
	ds_read_b128 v[198:201], v144 offset:53248
	ds_read_b128 v[202:205], v144 offset:54272
	ds_read_b128 v[206:209], v144 offset:55296
	ds_read_b128 v[220:223], v144 offset:56320
	s_add_u32 s98, s30, 0x80
	s_addc_u32 s99, s31, 0
	global_load_lds_dwordx4 v132, s[98:99]
	s_add_i32 m0, s34, 0x2000
	s_add_u32 s30, s30, 0x80080
	s_addc_u32 s31, s31, 0
	s_add_i32 s34, s49, s26
	s_add_u32 s98, s30, 0xfff80000
	s_addc_u32 s99, s31, -1
	global_load_lds_dwordx4 v128, s[98:99]
	s_mov_b32 m0, s34
	s_nop 0
	global_load_lds_dwordx4 v132, s[30:31]
	s_add_i32 m0, s34, 0x2000
	s_nop 0
	global_load_lds_dwordx4 v128, s[30:31]
	s_mov_b32 m0, s38
	s_nop 0
	global_load_lds_dwordx4 v134, s[60:61]
	s_mov_b32 m0, s39
	s_nop 0
	global_load_lds_dwordx4 v130, s[60:61]
	s_waitcnt vmcnt(8)
	s_waitcnt lgkmcnt(0)
	s_barrier
	s_setprio 1
	s_waitcnt lgkmcnt(0)
	v_mfma_f32_16x16x32_bf16 v[60:63], v[146:149], v[182:185], v[60:63]
	v_mfma_f32_16x16x32_bf16 v[56:59], v[154:157], v[182:185], v[56:59]
	v_mfma_f32_16x16x32_bf16 v[44:47], v[146:149], v[190:193], v[44:47]
	v_mfma_f32_16x16x32_bf16 v[40:43], v[154:157], v[190:193], v[40:43]
	v_mfma_f32_16x16x32_bf16 v[28:31], v[146:149], v[198:201], v[28:31]
	v_mfma_f32_16x16x32_bf16 v[24:27], v[154:157], v[198:201], v[24:27]
	v_mfma_f32_16x16x32_bf16 v[12:15], v[146:149], v[206:209], v[12:15]
	v_mfma_f32_16x16x32_bf16 v[8:11], v[154:157], v[206:209], v[8:11]
	v_mfma_f32_16x16x32_bf16 v[60:63], v[150:153], v[186:189], v[60:63]
	v_mfma_f32_16x16x32_bf16 v[56:59], v[158:161], v[186:189], v[56:59]
	v_mfma_f32_16x16x32_bf16 v[44:47], v[150:153], v[194:197], v[44:47]
	v_mfma_f32_16x16x32_bf16 v[40:43], v[158:161], v[194:197], v[40:43]
	v_mfma_f32_16x16x32_bf16 v[28:31], v[150:153], v[202:205], v[28:31]
	v_mfma_f32_16x16x32_bf16 v[24:27], v[158:161], v[202:205], v[24:27]
	v_mfma_f32_16x16x32_bf16 v[12:15], v[150:153], v[220:223], v[12:15]
	v_mfma_f32_16x16x32_bf16 v[8:11], v[158:161], v[220:223], v[8:11]
	s_setprio 0
	s_setprio 1
	v_mfma_f32_16x16x32_bf16 v[52:55], v[162:165], v[182:185], v[52:55]
	v_mfma_f32_16x16x32_bf16 v[48:51], v[170:173], v[182:185], v[48:51]
	v_mfma_f32_16x16x32_bf16 v[36:39], v[162:165], v[190:193], v[36:39]
	v_mfma_f32_16x16x32_bf16 v[32:35], v[170:173], v[190:193], v[32:35]
	v_mfma_f32_16x16x32_bf16 v[20:23], v[162:165], v[198:201], v[20:23]
	v_mfma_f32_16x16x32_bf16 v[16:19], v[170:173], v[198:201], v[16:19]
	v_mfma_f32_16x16x32_bf16 v[4:7], v[162:165], v[206:209], v[4:7]
	v_mfma_f32_16x16x32_bf16 v[0:3], v[170:173], v[206:209], v[0:3]
	v_mfma_f32_16x16x32_bf16 v[52:55], v[166:169], v[186:189], v[52:55]
	v_mfma_f32_16x16x32_bf16 v[48:51], v[178:181], v[186:189], v[48:51]
	v_mfma_f32_16x16x32_bf16 v[36:39], v[166:169], v[194:197], v[36:39]
	v_mfma_f32_16x16x32_bf16 v[32:35], v[178:181], v[194:197], v[32:35]
	v_mfma_f32_16x16x32_bf16 v[20:23], v[166:169], v[202:205], v[20:23]
	v_mfma_f32_16x16x32_bf16 v[16:19], v[178:181], v[202:205], v[16:19]
	v_mfma_f32_16x16x32_bf16 v[4:7], v[166:169], v[220:223], v[4:7]
	v_mfma_f32_16x16x32_bf16 v[0:3], v[178:181], v[220:223], v[0:3]
	s_setprio 0
	s_barrier
	s_add_i32 s47, s47, 2
	s_add_u32 s28, s28, 0x100
	s_addc_u32 s29, s29, 0
	s_add_u32 s45, s45, 0x100
	s_addc_u32 s46, s46, 0
	s_cmp_gt_u32 s47, 29
	s_cbranch_scc0 .LBB0_137
	s_and_b64 vcc, exec, s[10:11]
	s_cbranch_vccz .LBB0_140
	s_barrier

.LBB0_207:
	s_ashr_i32 s53, s52, 31
	s_lshl_b64 s[14:15], s[52:53], 20
	s_add_u32 s68, s3, s14
	s_addc_u32 s69, s20, s15
	s_and_b64 s[14:15], s[56:57], exec
	s_cselect_b32 s23, s69, s1
	s_cselect_b32 s26, s68, s0
	s_ashr_i32 s55, s54, 31
	s_lshl_b64 s[14:15], s[54:55], 20
	s_add_u32 s70, s21, s14
	s_addc_u32 s71, s24, s15
	s_and_b64 s[14:15], s[56:57], exec
	s_cselect_b32 s33, s71, s13
	s_cselect_b32 s45, s70, s12
	s_add_u32 s0, s0, 0x80080
	s_addc_u32 s1, s1, 0
	s_add_u32 s50, s12, 0x100
	s_addc_u32 s51, s13, 0
	s_mov_b32 s53, -2
	v_add_u32_e32 v253, 0x10000, v197
	s_add_u32 s12, s0, 0xfff80080
	s_addc_u32 s13, s1, -1
	s_add_i32 s55, 0, 0x10000
	s_cmp_eq_u32 s53, 28
	s_cselect_b32 s15, s23, s13
	s_cselect_b32 s14, s26, s12
	s_cselect_b32 s13, s33, s51
	s_cselect_b32 s12, s45, s50
	s_add_i32 s60, 0, 0x14000
	ds_read_b128 v[120:123], v253
	ds_read_b128 v[124:127], v253 offset:1024
	ds_read_b128 v[132:135], v253 offset:2048
	ds_read_b128 v[136:139], v253 offset:3072
	ds_read_b128 v[140:143], v253 offset:16384
	ds_read_b128 v[144:147], v253 offset:17408
	ds_read_b128 v[152:155], v253 offset:18432
	ds_read_b128 v[156:159], v253 offset:19456
	s_add_i32 m0, s27, 0xc000
	ds_read_b128 v[160:163], v199
	ds_read_b128 v[178:181], v199 offset:1024
	ds_read_b128 v[182:185], v199 offset:2048
	ds_read_b128 v[186:189], v199 offset:3072
	ds_read_b128 v[190:193], v199 offset:4096
	ds_read_b128 v[200:203], v199 offset:5120
	ds_read_b128 v[204:207], v199 offset:6144
	ds_read_b128 v[220:223], v199 offset:7168
	global_load_lds_dwordx4 v170, s[0:1]
	s_add_i32 m0, s27, 0xe000
	s_nop 0
	global_load_lds_dwordx4 v172, s[0:1]
	s_waitcnt vmcnt(8)
	s_waitcnt lgkmcnt(0)
	s_barrier
	s_setprio 1
	s_waitcnt lgkmcnt(0)
	v_mfma_f32_16x16x32_bf16 v[148:151], v[120:123], v[160:163], 0
	v_mfma_f32_16x16x32_bf16 v[128:131], v[132:135], v[160:163], 0
	v_mfma_f32_16x16x32_bf16 v[116:119], v[120:123], v[182:185], 0
	v_mfma_f32_16x16x32_bf16 v[112:115], v[132:135], v[182:185], 0
	v_mfma_f32_16x16x32_bf16 v[108:111], v[120:123], v[190:193], 0
	v_mfma_f32_16x16x32_bf16 v[104:107], v[132:135], v[190:193], 0
	v_mfma_f32_16x16x32_bf16 v[100:103], v[120:123], v[204:207], 0
	v_mfma_f32_16x16x32_bf16 v[96:99], v[132:135], v[204:207], 0
	v_mfma_f32_16x16x32_bf16 v[148:151], v[124:127], v[178:181], v[148:151]
	v_mfma_f32_16x16x32_bf16 v[128:131], v[136:139], v[178:181], v[128:131]
	v_mfma_f32_16x16x32_bf16 v[116:119], v[124:127], v[186:189], v[116:119]
	v_mfma_f32_16x16x32_bf16 v[112:115], v[136:139], v[186:189], v[112:115]
	v_mfma_f32_16x16x32_bf16 v[108:111], v[124:127], v[200:203], v[108:111]
	v_mfma_f32_16x16x32_bf16 v[104:107], v[136:139], v[200:203], v[104:107]
	v_mfma_f32_16x16x32_bf16 v[100:103], v[124:127], v[220:223], v[100:103]
	v_mfma_f32_16x16x32_bf16 v[96:99], v[136:139], v[220:223], v[96:99]
	s_setprio 0
	s_setprio 1
	v_mfma_f32_16x16x32_bf16 v[60:63], v[140:143], v[160:163], 0
	v_mfma_f32_16x16x32_bf16 v[56:59], v[152:155], v[160:163], 0
	v_mfma_f32_16x16x32_bf16 v[52:55], v[140:143], v[182:185], 0
	v_mfma_f32_16x16x32_bf16 v[48:51], v[152:155], v[182:185], 0
	v_mfma_f32_16x16x32_bf16 v[44:47], v[140:143], v[190:193], 0
	v_mfma_f32_16x16x32_bf16 v[40:43], v[152:155], v[190:193], 0
	v_mfma_f32_16x16x32_bf16 v[36:39], v[140:143], v[204:207], 0
	v_mfma_f32_16x16x32_bf16 v[32:35], v[152:155], v[204:207], 0
	v_mfma_f32_16x16x32_bf16 v[60:63], v[144:147], v[178:181], v[60:63]
	v_mfma_f32_16x16x32_bf16 v[56:59], v[156:159], v[178:181], v[56:59]
	v_mfma_f32_16x16x32_bf16 v[52:55], v[144:147], v[186:189], v[52:55]
	v_mfma_f32_16x16x32_bf16 v[48:51], v[156:159], v[186:189], v[48:51]
	v_mfma_f32_16x16x32_bf16 v[44:47], v[144:147], v[200:203], v[44:47]
	v_mfma_f32_16x16x32_bf16 v[40:43], v[156:159], v[200:203], v[40:43]
	v_mfma_f32_16x16x32_bf16 v[36:39], v[144:147], v[220:223], v[36:39]
	v_mfma_f32_16x16x32_bf16 v[32:35], v[156:159], v[220:223], v[32:35]
	s_setprio 0
	s_barrier
	s_add_i32 s55, s55, s25
	s_mov_b32 m0, s55
	ds_read_b128 v[160:163], v199 offset:16384
	ds_read_b128 v[178:181], v199 offset:17408
	ds_read_b128 v[182:185], v199 offset:18432
	ds_read_b128 v[186:189], v199 offset:19456
	ds_read_b128 v[190:193], v199 offset:20480
	ds_read_b128 v[200:203], v199 offset:21504
	ds_read_b128 v[204:207], v199 offset:22528
	ds_read_b128 v[220:223], v199 offset:23552
	global_load_lds_dwordx4 v176, s[12:13]
	s_add_i32 m0, s55, 0x2000
	s_add_u32 s58, s12, 0x80000
	s_addc_u32 s59, s13, 0
	s_add_i32 s55, s60, s25
	global_load_lds_dwordx4 v164, s[12:13]
	s_mov_b32 m0, s55
	v_lshl_add_u64 v[224:225], s[14:15], 0, v[166:167]
	global_load_lds_dwordx4 v176, s[58:59]
	s_add_i32 m0, s55, 0x2000
	s_nop 0
	global_load_lds_dwordx4 v164, s[58:59]
	v_lshl_add_u64 v[208:209], s[14:15], 0, v[168:169]
	s_mov_b32 m0, s27
	s_nop 0
	global_load_lds_dwordx4 v168, s[14:15]
	s_mov_b32 m0, s28
	s_nop 0
	global_load_lds_dwordx4 v166, s[14:15]
	s_waitcnt vmcnt(8)
	s_waitcnt lgkmcnt(0)
	s_barrier
	s_setprio 1
	s_waitcnt lgkmcnt(0)
	v_mfma_f32_16x16x32_bf16 v[92:95], v[120:123], v[160:163], 0
	v_mfma_f32_16x16x32_bf16 v[88:91], v[132:135], v[160:163], 0
	v_mfma_f32_16x16x32_bf16 v[84:87], v[120:123], v[182:185], 0
	v_mfma_f32_16x16x32_bf16 v[80:83], v[132:135], v[182:185], 0
	v_mfma_f32_16x16x32_bf16 v[76:79], v[120:123], v[190:193], 0
	v_mfma_f32_16x16x32_bf16 v[72:75], v[132:135], v[190:193], 0
	v_mfma_f32_16x16x32_bf16 v[68:71], v[120:123], v[204:207], 0
	v_mfma_f32_16x16x32_bf16 v[64:67], v[132:135], v[204:207], 0
	v_mfma_f32_16x16x32_bf16 v[92:95], v[124:127], v[178:181], v[92:95]
	v_mfma_f32_16x16x32_bf16 v[88:91], v[136:139], v[178:181], v[88:91]
	v_mfma_f32_16x16x32_bf16 v[84:87], v[124:127], v[186:189], v[84:87]
	v_mfma_f32_16x16x32_bf16 v[80:83], v[136:139], v[186:189], v[80:83]
	v_mfma_f32_16x16x32_bf16 v[76:79], v[124:127], v[200:203], v[76:79]
	v_mfma_f32_16x16x32_bf16 v[72:75], v[136:139], v[200:203], v[72:75]
	v_mfma_f32_16x16x32_bf16 v[68:71], v[124:127], v[220:223], v[68:71]
	v_mfma_f32_16x16x32_bf16 v[64:67], v[136:139], v[220:223], v[64:67]
	s_setprio 0
	s_setprio 1
	v_mfma_f32_16x16x32_bf16 v[28:31], v[140:143], v[160:163], 0
	v_mfma_f32_16x16x32_bf16 v[24:27], v[152:155], v[160:163], 0
	v_mfma_f32_16x16x32_bf16 v[20:23], v[140:143], v[182:185], 0
	v_mfma_f32_16x16x32_bf16 v[16:19], v[152:155], v[182:185], 0
	v_mfma_f32_16x16x32_bf16 v[12:15], v[140:143], v[190:193], 0
	v_mfma_f32_16x16x32_bf16 v[8:11], v[152:155], v[190:193], 0
	v_mfma_f32_16x16x32_bf16 v[4:7], v[140:143], v[204:207], 0
	v_mfma_f32_16x16x32_bf16 v[0:3], v[152:155], v[204:207], 0
	v_mfma_f32_16x16x32_bf16 v[28:31], v[144:147], v[178:181], v[28:31]
	v_mfma_f32_16x16x32_bf16 v[24:27], v[156:159], v[178:181], v[24:27]
	v_mfma_f32_16x16x32_bf16 v[20:23], v[144:147], v[186:189], v[20:23]
	v_mfma_f32_16x16x32_bf16 v[16:19], v[156:159], v[186:189], v[16:19]
	v_mfma_f32_16x16x32_bf16 v[12:15], v[144:147], v[200:203], v[12:15]
	v_mfma_f32_16x16x32_bf16 v[8:11], v[156:159], v[200:203], v[8:11]
	v_mfma_f32_16x16x32_bf16 v[4:7], v[144:147], v[220:223], v[4:7]
	v_mfma_f32_16x16x32_bf16 v[0:3], v[156:159], v[220:223], v[0:3]
	s_setprio 0
	s_barrier
	s_add_i32 s55, 0, 0x18000
	s_add_i32 s58, 0, 0x1c000
	ds_read_b128 v[120:123], v253 offset:32768
	ds_read_b128 v[124:127], v253 offset:33792
	ds_read_b128 v[132:135], v253 offset:34816
	ds_read_b128 v[136:139], v253 offset:35840
	ds_read_b128 v[140:143], v253 offset:49152
	ds_read_b128 v[144:147], v253 offset:50176
	ds_read_b128 v[152:155], v253 offset:51200
	ds_read_b128 v[156:159], v253 offset:52224
	s_add_u32 s14, s14, 0x80000
	s_addc_u32 s15, s15, 0
	s_mov_b32 m0, s29
	ds_read_b128 v[160:163], v199 offset:32768
	ds_read_b128 v[178:181], v199 offset:33792
	ds_read_b128 v[182:185], v199 offset:34816
	ds_read_b128 v[186:189], v199 offset:35840
	ds_read_b128 v[190:193], v199 offset:36864
	ds_read_b128 v[200:203], v199 offset:37888
	ds_read_b128 v[204:207], v199 offset:38912
	ds_read_b128 v[220:223], v199 offset:39936
	global_load_lds_dwordx4 v168, s[14:15]
	s_mov_b32 m0, s38
	s_nop 0
	global_load_lds_dwordx4 v166, s[14:15]
	s_waitcnt vmcnt(8)
	s_waitcnt lgkmcnt(0)
	s_barrier
	s_setprio 1
	s_waitcnt lgkmcnt(0)
	v_mfma_f32_16x16x32_bf16 v[148:151], v[120:123], v[160:163], v[148:151]
	v_mfma_f32_16x16x32_bf16 v[128:131], v[132:135], v[160:163], v[128:131]
	v_mfma_f32_16x16x32_bf16 v[116:119], v[120:123], v[182:185], v[116:119]
	v_mfma_f32_16x16x32_bf16 v[112:115], v[132:135], v[182:185], v[112:115]
	v_mfma_f32_16x16x32_bf16 v[108:111], v[120:123], v[190:193], v[108:111]
	v_mfma_f32_16x16x32_bf16 v[104:107], v[132:135], v[190:193], v[104:107]
	v_mfma_f32_16x16x32_bf16 v[100:103], v[120:123], v[204:207], v[100:103]
	v_mfma_f32_16x16x32_bf16 v[96:99], v[132:135], v[204:207], v[96:99]
	v_mfma_f32_16x16x32_bf16 v[148:151], v[124:127], v[178:181], v[148:151]
	v_mfma_f32_16x16x32_bf16 v[128:131], v[136:139], v[178:181], v[128:131]
	v_mfma_f32_16x16x32_bf16 v[116:119], v[124:127], v[186:189], v[116:119]
	v_mfma_f32_16x16x32_bf16 v[112:115], v[136:139], v[186:189], v[112:115]
	v_mfma_f32_16x16x32_bf16 v[108:111], v[124:127], v[200:203], v[108:111]
	v_mfma_f32_16x16x32_bf16 v[104:107], v[136:139], v[200:203], v[104:107]
	v_mfma_f32_16x16x32_bf16 v[100:103], v[124:127], v[220:223], v[100:103]
	v_mfma_f32_16x16x32_bf16 v[96:99], v[136:139], v[220:223], v[96:99]
	s_setprio 0
	s_setprio 1
	v_mfma_f32_16x16x32_bf16 v[60:63], v[140:143], v[160:163], v[60:63]
	v_mfma_f32_16x16x32_bf16 v[56:59], v[152:155], v[160:163], v[56:59]
	v_mfma_f32_16x16x32_bf16 v[52:55], v[140:143], v[182:185], v[52:55]
	v_mfma_f32_16x16x32_bf16 v[48:51], v[152:155], v[182:185], v[48:51]
	v_mfma_f32_16x16x32_bf16 v[44:47], v[140:143], v[190:193], v[44:47]
	v_mfma_f32_16x16x32_bf16 v[40:43], v[152:155], v[190:193], v[40:43]
	v_mfma_f32_16x16x32_bf16 v[36:39], v[140:143], v[204:207], v[36:39]
	v_mfma_f32_16x16x32_bf16 v[32:35], v[152:155], v[204:207], v[32:35]
	v_mfma_f32_16x16x32_bf16 v[60:63], v[144:147], v[178:181], v[60:63]
	v_mfma_f32_16x16x32_bf16 v[56:59], v[156:159], v[178:181], v[56:59]
	v_mfma_f32_16x16x32_bf16 v[52:55], v[144:147], v[186:189], v[52:55]
	v_mfma_f32_16x16x32_bf16 v[48:51], v[156:159], v[186:189], v[48:51]
	v_mfma_f32_16x16x32_bf16 v[44:47], v[144:147], v[200:203], v[44:47]
	v_mfma_f32_16x16x32_bf16 v[40:43], v[156:159], v[200:203], v[40:43]
	v_mfma_f32_16x16x32_bf16 v[36:39], v[144:147], v[220:223], v[36:39]
	v_mfma_f32_16x16x32_bf16 v[32:35], v[156:159], v[220:223], v[32:35]
	s_setprio 0
	s_barrier
	s_add_i32 s14, s55, s25
	s_mov_b32 m0, s14
	ds_read_b128 v[160:163], v199 offset:49152
	ds_read_b128 v[178:181], v199 offset:50176
	ds_read_b128 v[182:185], v199 offset:51200
	ds_read_b128 v[186:189], v199 offset:52224
	ds_read_b128 v[190:193], v199 offset:53248
	ds_read_b128 v[200:203], v199 offset:54272
	ds_read_b128 v[204:207], v199 offset:55296
	ds_read_b128 v[220:223], v199 offset:56320
	s_add_u32 s98, s12, 0x80
	s_addc_u32 s99, s13, 0
	global_load_lds_dwordx4 v176, s[98:99]
	s_add_i32 m0, s14, 0x2000
	s_add_u32 s12, s12, 0x80080
	s_addc_u32 s13, s13, 0
	s_add_i32 s14, s58, s25
	s_add_u32 s98, s12, 0xfff80000
	s_addc_u32 s99, s13, -1
	global_load_lds_dwordx4 v164, s[98:99]
	s_mov_b32 m0, s14
	s_nop 0
	global_load_lds_dwordx4 v176, s[12:13]
	s_add_i32 m0, s14, 0x2000
	s_nop 0
	global_load_lds_dwordx4 v164, s[12:13]
	v_lshl_add_u64 v[174:175], v[208:209], 0, s[74:75]
	s_mov_b32 m0, s42
	s_nop 0
	global_load_lds_dwordx4 v[174:175], off
	v_lshl_add_u64 v[174:175], v[224:225], 0, s[74:75]
	s_mov_b32 m0, s43
	s_nop 0
	global_load_lds_dwordx4 v[174:175], off
	s_waitcnt vmcnt(8)
	s_waitcnt lgkmcnt(0)
	s_barrier
	s_setprio 1
	s_waitcnt lgkmcnt(0)
	v_mfma_f32_16x16x32_bf16 v[92:95], v[120:123], v[160:163], v[92:95]
	v_mfma_f32_16x16x32_bf16 v[88:91], v[132:135], v[160:163], v[88:91]
	v_mfma_f32_16x16x32_bf16 v[84:87], v[120:123], v[182:185], v[84:87]
	v_mfma_f32_16x16x32_bf16 v[80:83], v[132:135], v[182:185], v[80:83]
	v_mfma_f32_16x16x32_bf16 v[76:79], v[120:123], v[190:193], v[76:79]
	v_mfma_f32_16x16x32_bf16 v[72:75], v[132:135], v[190:193], v[72:75]
	v_mfma_f32_16x16x32_bf16 v[68:71], v[120:123], v[204:207], v[68:71]
	v_mfma_f32_16x16x32_bf16 v[64:67], v[132:135], v[204:207], v[64:67]
	v_mfma_f32_16x16x32_bf16 v[92:95], v[124:127], v[178:181], v[92:95]
	v_mfma_f32_16x16x32_bf16 v[88:91], v[136:139], v[178:181], v[88:91]
	v_mfma_f32_16x16x32_bf16 v[84:87], v[124:127], v[186:189], v[84:87]
	v_mfma_f32_16x16x32_bf16 v[80:83], v[136:139], v[186:189], v[80:83]
	v_mfma_f32_16x16x32_bf16 v[76:79], v[124:127], v[200:203], v[76:79]
	v_mfma_f32_16x16x32_bf16 v[72:75], v[136:139], v[200:203], v[72:75]
	v_mfma_f32_16x16x32_bf16 v[68:71], v[124:127], v[220:223], v[68:71]
	v_mfma_f32_16x16x32_bf16 v[64:67], v[136:139], v[220:223], v[64:67]
	s_setprio 0
	s_setprio 1
	v_mfma_f32_16x16x32_bf16 v[28:31], v[140:143], v[160:163], v[28:31]
	v_mfma_f32_16x16x32_bf16 v[24:27], v[152:155], v[160:163], v[24:27]
	v_mfma_f32_16x16x32_bf16 v[20:23], v[140:143], v[182:185], v[20:23]
	v_mfma_f32_16x16x32_bf16 v[16:19], v[152:155], v[182:185], v[16:19]
	v_mfma_f32_16x16x32_bf16 v[12:15], v[140:143], v[190:193], v[12:15]
	v_mfma_f32_16x16x32_bf16 v[8:11], v[152:155], v[190:193], v[8:11]
	v_mfma_f32_16x16x32_bf16 v[4:7], v[140:143], v[204:207], v[4:7]
	v_mfma_f32_16x16x32_bf16 v[0:3], v[152:155], v[204:207], v[0:3]
	v_mfma_f32_16x16x32_bf16 v[28:31], v[144:147], v[178:181], v[28:31]
	v_mfma_f32_16x16x32_bf16 v[24:27], v[156:159], v[178:181], v[24:27]
	v_mfma_f32_16x16x32_bf16 v[20:23], v[144:147], v[186:189], v[20:23]
	v_mfma_f32_16x16x32_bf16 v[16:19], v[156:159], v[186:189], v[16:19]
	v_mfma_f32_16x16x32_bf16 v[12:15], v[144:147], v[200:203], v[12:15]
	v_mfma_f32_16x16x32_bf16 v[8:11], v[156:159], v[200:203], v[8:11]
	v_mfma_f32_16x16x32_bf16 v[4:7], v[144:147], v[220:223], v[4:7]
	v_mfma_f32_16x16x32_bf16 v[0:3], v[156:159], v[220:223], v[0:3]
	s_setprio 0
	s_barrier
	s_add_i32 s53, s53, 2
	s_add_u32 s0, s0, 0x100
	s_addc_u32 s1, s1, 0
	s_add_u32 s50, s50, 0x100
	s_addc_u32 s51, s51, 0
	s_cmp_gt_u32 s53, 29
.LBB0_208:
	s_add_u32 s12, s0, 0xfff80080
	s_addc_u32 s13, s1, -1
	s_add_i32 s55, 0, 0x10000
	s_cmp_eq_u32 s53, 28
	s_cselect_b32 s15, s23, s13
	s_cselect_b32 s14, s26, s12
	s_cselect_b32 s13, s33, s51
	s_cselect_b32 s12, s45, s50
	s_add_i32 s60, 0, 0x14000
	ds_read_b128 v[120:123], v253
	ds_read_b128 v[124:127], v253 offset:1024
	ds_read_b128 v[132:135], v253 offset:2048
	ds_read_b128 v[136:139], v253 offset:3072
	ds_read_b128 v[140:143], v253 offset:16384
	ds_read_b128 v[144:147], v253 offset:17408
	ds_read_b128 v[152:155], v253 offset:18432
	ds_read_b128 v[156:159], v253 offset:19456
	s_add_i32 m0, s27, 0xc000
	ds_read_b128 v[160:163], v199
	ds_read_b128 v[178:181], v199 offset:1024
	ds_read_b128 v[182:185], v199 offset:2048
	ds_read_b128 v[186:189], v199 offset:3072
	ds_read_b128 v[190:193], v199 offset:4096
	ds_read_b128 v[200:203], v199 offset:5120
	ds_read_b128 v[204:207], v199 offset:6144
	ds_read_b128 v[220:223], v199 offset:7168
	global_load_lds_dwordx4 v170, s[0:1]
	s_add_i32 m0, s27, 0xe000
	s_nop 0
	global_load_lds_dwordx4 v172, s[0:1]
	s_waitcnt vmcnt(8)
	s_waitcnt lgkmcnt(0)
	s_barrier
	s_setprio 1
	s_waitcnt lgkmcnt(0)
	v_mfma_f32_16x16x32_bf16 v[148:151], v[120:123], v[160:163], v[148:151]
	v_mfma_f32_16x16x32_bf16 v[128:131], v[132:135], v[160:163], v[128:131]
	v_mfma_f32_16x16x32_bf16 v[116:119], v[120:123], v[182:185], v[116:119]
	v_mfma_f32_16x16x32_bf16 v[112:115], v[132:135], v[182:185], v[112:115]
	v_mfma_f32_16x16x32_bf16 v[108:111], v[120:123], v[190:193], v[108:111]
	v_mfma_f32_16x16x32_bf16 v[104:107], v[132:135], v[190:193], v[104:107]
	v_mfma_f32_16x16x32_bf16 v[100:103], v[120:123], v[204:207], v[100:103]
	v_mfma_f32_16x16x32_bf16 v[96:99], v[132:135], v[204:207], v[96:99]
	v_mfma_f32_16x16x32_bf16 v[148:151], v[124:127], v[178:181], v[148:151]
	v_mfma_f32_16x16x32_bf16 v[128:131], v[136:139], v[178:181], v[128:131]
	v_mfma_f32_16x16x32_bf16 v[116:119], v[124:127], v[186:189], v[116:119]
	v_mfma_f32_16x16x32_bf16 v[112:115], v[136:139], v[186:189], v[112:115]
	v_mfma_f32_16x16x32_bf16 v[108:111], v[124:127], v[200:203], v[108:111]
	v_mfma_f32_16x16x32_bf16 v[104:107], v[136:139], v[200:203], v[104:107]
	v_mfma_f32_16x16x32_bf16 v[100:103], v[124:127], v[220:223], v[100:103]
	v_mfma_f32_16x16x32_bf16 v[96:99], v[136:139], v[220:223], v[96:99]
	s_setprio 0
	s_setprio 1
	v_mfma_f32_16x16x32_bf16 v[60:63], v[140:143], v[160:163], v[60:63]
	v_mfma_f32_16x16x32_bf16 v[56:59], v[152:155], v[160:163], v[56:59]
	v_mfma_f32_16x16x32_bf16 v[52:55], v[140:143], v[182:185], v[52:55]
	v_mfma_f32_16x16x32_bf16 v[48:51], v[152:155], v[182:185], v[48:51]
	v_mfma_f32_16x16x32_bf16 v[44:47], v[140:143], v[190:193], v[44:47]
	v_mfma_f32_16x16x32_bf16 v[40:43], v[152:155], v[190:193], v[40:43]
	v_mfma_f32_16x16x32_bf16 v[36:39], v[140:143], v[204:207], v[36:39]
	v_mfma_f32_16x16x32_bf16 v[32:35], v[152:155], v[204:207], v[32:35]
	v_mfma_f32_16x16x32_bf16 v[60:63], v[144:147], v[178:181], v[60:63]
	v_mfma_f32_16x16x32_bf16 v[56:59], v[156:159], v[178:181], v[56:59]
	v_mfma_f32_16x16x32_bf16 v[52:55], v[144:147], v[186:189], v[52:55]
	v_mfma_f32_16x16x32_bf16 v[48:51], v[156:159], v[186:189], v[48:51]
	v_mfma_f32_16x16x32_bf16 v[44:47], v[144:147], v[200:203], v[44:47]
	v_mfma_f32_16x16x32_bf16 v[40:43], v[156:159], v[200:203], v[40:43]
	v_mfma_f32_16x16x32_bf16 v[36:39], v[144:147], v[220:223], v[36:39]
	v_mfma_f32_16x16x32_bf16 v[32:35], v[156:159], v[220:223], v[32:35]
	s_setprio 0
	s_barrier
	s_add_i32 s55, s55, s25
	s_mov_b32 m0, s55
	ds_read_b128 v[160:163], v199 offset:16384
	ds_read_b128 v[178:181], v199 offset:17408
	ds_read_b128 v[182:185], v199 offset:18432
	ds_read_b128 v[186:189], v199 offset:19456
	ds_read_b128 v[190:193], v199 offset:20480
	ds_read_b128 v[200:203], v199 offset:21504
	ds_read_b128 v[204:207], v199 offset:22528
	ds_read_b128 v[220:223], v199 offset:23552
	global_load_lds_dwordx4 v176, s[12:13]
	s_add_i32 m0, s55, 0x2000
	s_add_u32 s58, s12, 0x80000
	s_addc_u32 s59, s13, 0
	s_add_i32 s55, s60, s25
	global_load_lds_dwordx4 v164, s[12:13]
	s_mov_b32 m0, s55
	v_lshl_add_u64 v[224:225], s[14:15], 0, v[166:167]
	global_load_lds_dwordx4 v176, s[58:59]
	s_add_i32 m0, s55, 0x2000
	s_nop 0
	global_load_lds_dwordx4 v164, s[58:59]
	v_lshl_add_u64 v[208:209], s[14:15], 0, v[168:169]
	s_mov_b32 m0, s27
	s_nop 0
	global_load_lds_dwordx4 v168, s[14:15]
	s_mov_b32 m0, s28
	s_nop 0
	global_load_lds_dwordx4 v166, s[14:15]
	s_waitcnt vmcnt(8)
	s_waitcnt lgkmcnt(0)
	s_barrier
	s_setprio 1
	s_waitcnt lgkmcnt(0)
	v_mfma_f32_16x16x32_bf16 v[92:95], v[120:123], v[160:163], v[92:95]
	v_mfma_f32_16x16x32_bf16 v[88:91], v[132:135], v[160:163], v[88:91]
	v_mfma_f32_16x16x32_bf16 v[84:87], v[120:123], v[182:185], v[84:87]
	v_mfma_f32_16x16x32_bf16 v[80:83], v[132:135], v[182:185], v[80:83]
	v_mfma_f32_16x16x32_bf16 v[76:79], v[120:123], v[190:193], v[76:79]
	v_mfma_f32_16x16x32_bf16 v[72:75], v[132:135], v[190:193], v[72:75]
	v_mfma_f32_16x16x32_bf16 v[68:71], v[120:123], v[204:207], v[68:71]
	v_mfma_f32_16x16x32_bf16 v[64:67], v[132:135], v[204:207], v[64:67]
	v_mfma_f32_16x16x32_bf16 v[92:95], v[124:127], v[178:181], v[92:95]
	v_mfma_f32_16x16x32_bf16 v[88:91], v[136:139], v[178:181], v[88:91]
	v_mfma_f32_16x16x32_bf16 v[84:87], v[124:127], v[186:189], v[84:87]
	v_mfma_f32_16x16x32_bf16 v[80:83], v[136:139], v[186:189], v[80:83]
	v_mfma_f32_16x16x32_bf16 v[76:79], v[124:127], v[200:203], v[76:79]
	v_mfma_f32_16x16x32_bf16 v[72:75], v[136:139], v[200:203], v[72:75]
	v_mfma_f32_16x16x32_bf16 v[68:71], v[124:127], v[220:223], v[68:71]
	v_mfma_f32_16x16x32_bf16 v[64:67], v[136:139], v[220:223], v[64:67]
	s_setprio 0
	s_setprio 1
	v_mfma_f32_16x16x32_bf16 v[28:31], v[140:143], v[160:163], v[28:31]
	v_mfma_f32_16x16x32_bf16 v[24:27], v[152:155], v[160:163], v[24:27]
	v_mfma_f32_16x16x32_bf16 v[20:23], v[140:143], v[182:185], v[20:23]
	v_mfma_f32_16x16x32_bf16 v[16:19], v[152:155], v[182:185], v[16:19]
	v_mfma_f32_16x16x32_bf16 v[12:15], v[140:143], v[190:193], v[12:15]
	v_mfma_f32_16x16x32_bf16 v[8:11], v[152:155], v[190:193], v[8:11]
	v_mfma_f32_16x16x32_bf16 v[4:7], v[140:143], v[204:207], v[4:7]
	v_mfma_f32_16x16x32_bf16 v[0:3], v[152:155], v[204:207], v[0:3]
	v_mfma_f32_16x16x32_bf16 v[28:31], v[144:147], v[178:181], v[28:31]
	v_mfma_f32_16x16x32_bf16 v[24:27], v[156:159], v[178:181], v[24:27]
	v_mfma_f32_16x16x32_bf16 v[20:23], v[144:147], v[186:189], v[20:23]
	v_mfma_f32_16x16x32_bf16 v[16:19], v[156:159], v[186:189], v[16:19]
	v_mfma_f32_16x16x32_bf16 v[12:15], v[144:147], v[200:203], v[12:15]
	v_mfma_f32_16x16x32_bf16 v[8:11], v[156:159], v[200:203], v[8:11]
	v_mfma_f32_16x16x32_bf16 v[4:7], v[144:147], v[220:223], v[4:7]
	v_mfma_f32_16x16x32_bf16 v[0:3], v[156:159], v[220:223], v[0:3]
	s_setprio 0
	s_barrier
	s_add_i32 s55, 0, 0x18000
	s_add_i32 s58, 0, 0x1c000
	ds_read_b128 v[120:123], v253 offset:32768
	ds_read_b128 v[124:127], v253 offset:33792
	ds_read_b128 v[132:135], v253 offset:34816
	ds_read_b128 v[136:139], v253 offset:35840
	ds_read_b128 v[140:143], v253 offset:49152
	ds_read_b128 v[144:147], v253 offset:50176
	ds_read_b128 v[152:155], v253 offset:51200
	ds_read_b128 v[156:159], v253 offset:52224
	s_add_u32 s14, s14, 0x80000
	s_addc_u32 s15, s15, 0
	s_mov_b32 m0, s29
	ds_read_b128 v[160:163], v199 offset:32768
	ds_read_b128 v[178:181], v199 offset:33792
	ds_read_b128 v[182:185], v199 offset:34816
	ds_read_b128 v[186:189], v199 offset:35840
	ds_read_b128 v[190:193], v199 offset:36864
	ds_read_b128 v[200:203], v199 offset:37888
	ds_read_b128 v[204:207], v199 offset:38912
	ds_read_b128 v[220:223], v199 offset:39936
	global_load_lds_dwordx4 v168, s[14:15]
	s_mov_b32 m0, s38
	s_nop 0
	global_load_lds_dwordx4 v166, s[14:15]
	s_waitcnt vmcnt(8)
	s_waitcnt lgkmcnt(0)
	s_barrier
	s_setprio 1
	s_waitcnt lgkmcnt(0)
	v_mfma_f32_16x16x32_bf16 v[148:151], v[120:123], v[160:163], v[148:151]
	v_mfma_f32_16x16x32_bf16 v[128:131], v[132:135], v[160:163], v[128:131]
	v_mfma_f32_16x16x32_bf16 v[116:119], v[120:123], v[182:185], v[116:119]
	v_mfma_f32_16x16x32_bf16 v[112:115], v[132:135], v[182:185], v[112:115]
	v_mfma_f32_16x16x32_bf16 v[108:111], v[120:123], v[190:193], v[108:111]
	v_mfma_f32_16x16x32_bf16 v[104:107], v[132:135], v[190:193], v[104:107]
	v_mfma_f32_16x16x32_bf16 v[100:103], v[120:123], v[204:207], v[100:103]
	v_mfma_f32_16x16x32_bf16 v[96:99], v[132:135], v[204:207], v[96:99]
	v_mfma_f32_16x16x32_bf16 v[148:151], v[124:127], v[178:181], v[148:151]
	v_mfma_f32_16x16x32_bf16 v[128:131], v[136:139], v[178:181], v[128:131]
	v_mfma_f32_16x16x32_bf16 v[116:119], v[124:127], v[186:189], v[116:119]
	v_mfma_f32_16x16x32_bf16 v[112:115], v[136:139], v[186:189], v[112:115]
	v_mfma_f32_16x16x32_bf16 v[108:111], v[124:127], v[200:203], v[108:111]
	v_mfma_f32_16x16x32_bf16 v[104:107], v[136:139], v[200:203], v[104:107]
	v_mfma_f32_16x16x32_bf16 v[100:103], v[124:127], v[220:223], v[100:103]
	v_mfma_f32_16x16x32_bf16 v[96:99], v[136:139], v[220:223], v[96:99]
	s_setprio 0
	s_setprio 1
	v_mfma_f32_16x16x32_bf16 v[60:63], v[140:143], v[160:163], v[60:63]
	v_mfma_f32_16x16x32_bf16 v[56:59], v[152:155], v[160:163], v[56:59]
	v_mfma_f32_16x16x32_bf16 v[52:55], v[140:143], v[182:185], v[52:55]
	v_mfma_f32_16x16x32_bf16 v[48:51], v[152:155], v[182:185], v[48:51]
	v_mfma_f32_16x16x32_bf16 v[44:47], v[140:143], v[190:193], v[44:47]
	v_mfma_f32_16x16x32_bf16 v[40:43], v[152:155], v[190:193], v[40:43]
	v_mfma_f32_16x16x32_bf16 v[36:39], v[140:143], v[204:207], v[36:39]
	v_mfma_f32_16x16x32_bf16 v[32:35], v[152:155], v[204:207], v[32:35]
	v_mfma_f32_16x16x32_bf16 v[60:63], v[144:147], v[178:181], v[60:63]
	v_mfma_f32_16x16x32_bf16 v[56:59], v[156:159], v[178:181], v[56:59]
	v_mfma_f32_16x16x32_bf16 v[52:55], v[144:147], v[186:189], v[52:55]
	v_mfma_f32_16x16x32_bf16 v[48:51], v[156:159], v[186:189], v[48:51]
	v_mfma_f32_16x16x32_bf16 v[44:47], v[144:147], v[200:203], v[44:47]
	v_mfma_f32_16x16x32_bf16 v[40:43], v[156:159], v[200:203], v[40:43]
	v_mfma_f32_16x16x32_bf16 v[36:39], v[144:147], v[220:223], v[36:39]
	v_mfma_f32_16x16x32_bf16 v[32:35], v[156:159], v[220:223], v[32:35]
	s_setprio 0
	s_barrier
	s_add_i32 s14, s55, s25
	s_mov_b32 m0, s14
	ds_read_b128 v[160:163], v199 offset:49152
	ds_read_b128 v[178:181], v199 offset:50176
	ds_read_b128 v[182:185], v199 offset:51200
	ds_read_b128 v[186:189], v199 offset:52224
	ds_read_b128 v[190:193], v199 offset:53248
	ds_read_b128 v[200:203], v199 offset:54272
	ds_read_b128 v[204:207], v199 offset:55296
	ds_read_b128 v[220:223], v199 offset:56320
	s_add_u32 s98, s12, 0x80
	s_addc_u32 s99, s13, 0
	global_load_lds_dwordx4 v176, s[98:99]
	s_add_i32 m0, s14, 0x2000
	s_add_u32 s12, s12, 0x80080
	s_addc_u32 s13, s13, 0
	s_add_i32 s14, s58, s25
	s_add_u32 s98, s12, 0xfff80000
	s_addc_u32 s99, s13, -1
	global_load_lds_dwordx4 v164, s[98:99]
	s_mov_b32 m0, s14
	s_nop 0
	global_load_lds_dwordx4 v176, s[12:13]
	s_add_i32 m0, s14, 0x2000
	s_nop 0
	global_load_lds_dwordx4 v164, s[12:13]
	v_lshl_add_u64 v[174:175], v[208:209], 0, s[74:75]
	s_mov_b32 m0, s42
	s_nop 0
	global_load_lds_dwordx4 v[174:175], off
	v_lshl_add_u64 v[174:175], v[224:225], 0, s[74:75]
	s_mov_b32 m0, s43
	s_nop 0
	global_load_lds_dwordx4 v[174:175], off
	s_waitcnt vmcnt(8)
	s_waitcnt lgkmcnt(0)
	s_barrier
	s_setprio 1
	s_waitcnt lgkmcnt(0)
	v_mfma_f32_16x16x32_bf16 v[92:95], v[120:123], v[160:163], v[92:95]
	v_mfma_f32_16x16x32_bf16 v[88:91], v[132:135], v[160:163], v[88:91]
	v_mfma_f32_16x16x32_bf16 v[84:87], v[120:123], v[182:185], v[84:87]
	v_mfma_f32_16x16x32_bf16 v[80:83], v[132:135], v[182:185], v[80:83]
	v_mfma_f32_16x16x32_bf16 v[76:79], v[120:123], v[190:193], v[76:79]
	v_mfma_f32_16x16x32_bf16 v[72:75], v[132:135], v[190:193], v[72:75]
	v_mfma_f32_16x16x32_bf16 v[68:71], v[120:123], v[204:207], v[68:71]
	v_mfma_f32_16x16x32_bf16 v[64:67], v[132:135], v[204:207], v[64:67]
	v_mfma_f32_16x16x32_bf16 v[92:95], v[124:127], v[178:181], v[92:95]
	v_mfma_f32_16x16x32_bf16 v[88:91], v[136:139], v[178:181], v[88:91]
	v_mfma_f32_16x16x32_bf16 v[84:87], v[124:127], v[186:189], v[84:87]
	v_mfma_f32_16x16x32_bf16 v[80:83], v[136:139], v[186:189], v[80:83]
	v_mfma_f32_16x16x32_bf16 v[76:79], v[124:127], v[200:203], v[76:79]
	v_mfma_f32_16x16x32_bf16 v[72:75], v[136:139], v[200:203], v[72:75]
	v_mfma_f32_16x16x32_bf16 v[68:71], v[124:127], v[220:223], v[68:71]
	v_mfma_f32_16x16x32_bf16 v[64:67], v[136:139], v[220:223], v[64:67]
	s_setprio 0
	s_setprio 1
	v_mfma_f32_16x16x32_bf16 v[28:31], v[140:143], v[160:163], v[28:31]
	v_mfma_f32_16x16x32_bf16 v[24:27], v[152:155], v[160:163], v[24:27]
	v_mfma_f32_16x16x32_bf16 v[20:23], v[140:143], v[182:185], v[20:23]
	v_mfma_f32_16x16x32_bf16 v[16:19], v[152:155], v[182:185], v[16:19]
	v_mfma_f32_16x16x32_bf16 v[12:15], v[140:143], v[190:193], v[12:15]
	v_mfma_f32_16x16x32_bf16 v[8:11], v[152:155], v[190:193], v[8:11]
	v_mfma_f32_16x16x32_bf16 v[4:7], v[140:143], v[204:207], v[4:7]
	v_mfma_f32_16x16x32_bf16 v[0:3], v[152:155], v[204:207], v[0:3]
	v_mfma_f32_16x16x32_bf16 v[28:31], v[144:147], v[178:181], v[28:31]
	v_mfma_f32_16x16x32_bf16 v[24:27], v[156:159], v[178:181], v[24:27]
	v_mfma_f32_16x16x32_bf16 v[20:23], v[144:147], v[186:189], v[20:23]
	v_mfma_f32_16x16x32_bf16 v[16:19], v[156:159], v[186:189], v[16:19]
	v_mfma_f32_16x16x32_bf16 v[12:15], v[144:147], v[200:203], v[12:15]
	v_mfma_f32_16x16x32_bf16 v[8:11], v[156:159], v[200:203], v[8:11]
	v_mfma_f32_16x16x32_bf16 v[4:7], v[144:147], v[220:223], v[4:7]
	v_mfma_f32_16x16x32_bf16 v[0:3], v[156:159], v[220:223], v[0:3]
	s_setprio 0
	s_barrier
	s_add_i32 s53, s53, 2
	s_add_u32 s0, s0, 0x100
	s_addc_u32 s1, s1, 0
	s_add_u32 s50, s50, 0x100
	s_addc_u32 s51, s51, 0
	s_cmp_gt_u32 s53, 29
	s_cbranch_scc0 .LBB0_208
	s_and_b64 vcc, exec, s[40:41]
	s_cbranch_vccz .LBB0_211
	s_barrier

.LBB0_289:
	s_mov_b32 s61, s60
	s_add_i32 s60, s60, 1
	s_cmp_lt_u32 s61, 2
	s_cselect_b64 s[12:13], -1, 0
	s_lshl_b32 s1, s60, 5
	s_add_i32 s1, s90, s1
	s_and_b64 s[14:15], s[12:13], exec
	s_mov_b32 s2, s70
	s_cselect_b32 s70, s1, s70
	s_mov_b32 s0, s68
	s_cselect_b32 s68, s94, s68
	s_ashr_i32 s71, s70, 31
	s_lshl_b64 s[14:15], s[70:71], 20
	s_add_u32 s1, s24, s14
	s_addc_u32 s3, s25, s15
	s_mov_b64 s[8:9], s[34:35]
	s_and_b64 s[14:15], s[12:13], exec
	s_cselect_b32 s35, s3, s9
	s_cselect_b32 s34, s1, s8
	s_ashr_i32 s69, s68, 31
	s_lshl_b64 s[14:15], s[68:69], 20
	s_add_u32 s1, s27, s14
	s_addc_u32 s3, s28, s15
	s_mov_b64 s[10:11], s[30:31]
	s_and_b64 s[12:13], s[12:13], exec
	s_cselect_b32 s31, s3, s11
	s_cselect_b32 s30, s1, s10
	s_add_u32 s8, s8, 0x80080
	s_addc_u32 s9, s9, 0
	s_add_u32 s1, s10, 0x100
	s_addc_u32 s3, s11, 0
	s_mov_b32 s14, -2
	s_waitcnt lgkmcnt(0)
	v_add_u32_e32 v253, 0x10000, v209
	s_add_u32 s10, s8, 0xfff80080
	s_addc_u32 s11, s9, -1
	s_add_i32 s15, 0, 0x10000
	s_cmp_eq_u32 s14, 28
	s_cselect_b32 s13, s35, s11
	s_cselect_b32 s12, s34, s10
	s_cselect_b32 s11, s31, s3
	s_cselect_b32 s10, s30, s1
	s_add_i32 s22, 0, 0x14000
	ds_read_b128 v[112:115], v253
	ds_read_b128 v[116:119], v253 offset:1024
	ds_read_b128 v[120:123], v253 offset:2048
	ds_read_b128 v[124:127], v253 offset:3072
	ds_read_b128 v[136:139], v253 offset:16384
	ds_read_b128 v[140:143], v253 offset:17408
	ds_read_b128 v[152:155], v253 offset:18432
	ds_read_b128 v[156:159], v253 offset:19456
	s_add_i32 m0, s38, 0xc000
	ds_read_b128 v[160:163], v228
	ds_read_b128 v[164:167], v228 offset:1024
	ds_read_b128 v[168:171], v228 offset:2048
	ds_read_b128 v[172:175], v228 offset:3072
	ds_read_b128 v[230:233], v228 offset:4096
	ds_read_b128 v[234:237], v228 offset:5120
	ds_read_b128 v[238:241], v228 offset:6144
	ds_read_b128 v[242:245], v228 offset:7168
	global_load_lds_dwordx4 v202, s[8:9]
	s_add_i32 m0, s38, 0xe000
	s_nop 0
	global_load_lds_dwordx4 v204, s[8:9]
	s_waitcnt vmcnt(8)
	s_waitcnt lgkmcnt(0)
	s_barrier
	s_setprio 1
	s_waitcnt lgkmcnt(0)
	v_mfma_f32_16x16x32_bf16 v[148:151], v[112:115], v[160:163], 0
	v_mfma_f32_16x16x32_bf16 v[144:147], v[120:123], v[160:163], 0
	v_mfma_f32_16x16x32_bf16 v[108:111], v[112:115], v[168:171], 0
	v_mfma_f32_16x16x32_bf16 v[104:107], v[120:123], v[168:171], 0
	v_mfma_f32_16x16x32_bf16 v[92:95], v[112:115], v[230:233], 0
	v_mfma_f32_16x16x32_bf16 v[88:91], v[120:123], v[230:233], 0
	v_mfma_f32_16x16x32_bf16 v[76:79], v[112:115], v[238:241], 0
	v_mfma_f32_16x16x32_bf16 v[72:75], v[120:123], v[238:241], 0
	v_mfma_f32_16x16x32_bf16 v[148:151], v[116:119], v[164:167], v[148:151]
	v_mfma_f32_16x16x32_bf16 v[144:147], v[124:127], v[164:167], v[144:147]
	v_mfma_f32_16x16x32_bf16 v[108:111], v[116:119], v[172:175], v[108:111]
	v_mfma_f32_16x16x32_bf16 v[104:107], v[124:127], v[172:175], v[104:107]
	v_mfma_f32_16x16x32_bf16 v[92:95], v[116:119], v[234:237], v[92:95]
	v_mfma_f32_16x16x32_bf16 v[88:91], v[124:127], v[234:237], v[88:91]
	v_mfma_f32_16x16x32_bf16 v[76:79], v[116:119], v[242:245], v[76:79]
	v_mfma_f32_16x16x32_bf16 v[72:75], v[124:127], v[242:245], v[72:75]
	s_setprio 0
	s_setprio 1
	v_mfma_f32_16x16x32_bf16 v[132:135], v[136:139], v[160:163], 0
	v_mfma_f32_16x16x32_bf16 v[128:131], v[152:155], v[160:163], 0
	v_mfma_f32_16x16x32_bf16 v[100:103], v[136:139], v[168:171], 0
	v_mfma_f32_16x16x32_bf16 v[96:99], v[152:155], v[168:171], 0
	v_mfma_f32_16x16x32_bf16 v[84:87], v[136:139], v[230:233], 0
	v_mfma_f32_16x16x32_bf16 v[80:83], v[152:155], v[230:233], 0
	v_mfma_f32_16x16x32_bf16 v[68:71], v[136:139], v[238:241], 0
	v_mfma_f32_16x16x32_bf16 v[64:67], v[152:155], v[238:241], 0
	v_mfma_f32_16x16x32_bf16 v[132:135], v[140:143], v[164:167], v[132:135]
	v_mfma_f32_16x16x32_bf16 v[128:131], v[156:159], v[164:167], v[128:131]
	v_mfma_f32_16x16x32_bf16 v[100:103], v[140:143], v[172:175], v[100:103]
	v_mfma_f32_16x16x32_bf16 v[96:99], v[156:159], v[172:175], v[96:99]
	v_mfma_f32_16x16x32_bf16 v[84:87], v[140:143], v[234:237], v[84:87]
	v_mfma_f32_16x16x32_bf16 v[80:83], v[156:159], v[234:237], v[80:83]
	v_mfma_f32_16x16x32_bf16 v[68:71], v[140:143], v[242:245], v[68:71]
	v_mfma_f32_16x16x32_bf16 v[64:67], v[156:159], v[242:245], v[64:67]
	s_setprio 0
	s_barrier
	s_add_i32 s15, s15, s29
	s_mov_b32 m0, s15
	ds_read_b128 v[160:163], v228 offset:16384
	ds_read_b128 v[164:167], v228 offset:17408
	ds_read_b128 v[168:171], v228 offset:18432
	ds_read_b128 v[172:175], v228 offset:19456
	ds_read_b128 v[230:233], v228 offset:20480
	ds_read_b128 v[234:237], v228 offset:21504
	ds_read_b128 v[238:241], v228 offset:22528
	ds_read_b128 v[242:245], v228 offset:23552
	global_load_lds_dwordx4 v176, s[10:11]
	s_add_i32 m0, s15, 0x2000
	s_add_u32 s20, s10, 0x80000
	s_addc_u32 s21, s11, 0
	s_add_i32 s15, s22, s29
	global_load_lds_dwordx4 v182, s[10:11]
	s_mov_b32 m0, s15
	s_nop 0
	global_load_lds_dwordx4 v176, s[20:21]
	s_add_i32 m0, s15, 0x2000
	s_nop 0
	global_load_lds_dwordx4 v182, s[20:21]
	s_add_u32 s50, s12, 0x80
	s_addc_u32 s51, s13, 0
	s_mov_b32 m0, s38
	s_nop 0
	global_load_lds_dwordx4 v178, s[12:13]
	s_mov_b32 m0, s39
	s_nop 0
	global_load_lds_dwordx4 v180, s[12:13]
	s_waitcnt vmcnt(8)
	s_waitcnt lgkmcnt(0)
	s_barrier
	s_setprio 1
	s_waitcnt lgkmcnt(0)
	v_mfma_f32_16x16x32_bf16 v[60:63], v[112:115], v[160:163], 0
	v_mfma_f32_16x16x32_bf16 v[56:59], v[120:123], v[160:163], 0
	v_mfma_f32_16x16x32_bf16 v[44:47], v[112:115], v[168:171], 0
	v_mfma_f32_16x16x32_bf16 v[40:43], v[120:123], v[168:171], 0
	v_mfma_f32_16x16x32_bf16 v[28:31], v[112:115], v[230:233], 0
	v_mfma_f32_16x16x32_bf16 v[24:27], v[120:123], v[230:233], 0
	v_mfma_f32_16x16x32_bf16 v[12:15], v[112:115], v[238:241], 0
	v_mfma_f32_16x16x32_bf16 v[8:11], v[120:123], v[238:241], 0
	v_mfma_f32_16x16x32_bf16 v[60:63], v[116:119], v[164:167], v[60:63]
	v_mfma_f32_16x16x32_bf16 v[56:59], v[124:127], v[164:167], v[56:59]
	v_mfma_f32_16x16x32_bf16 v[44:47], v[116:119], v[172:175], v[44:47]
	v_mfma_f32_16x16x32_bf16 v[40:43], v[124:127], v[172:175], v[40:43]
	v_mfma_f32_16x16x32_bf16 v[28:31], v[116:119], v[234:237], v[28:31]
	v_mfma_f32_16x16x32_bf16 v[24:27], v[124:127], v[234:237], v[24:27]
	v_mfma_f32_16x16x32_bf16 v[12:15], v[116:119], v[242:245], v[12:15]
	v_mfma_f32_16x16x32_bf16 v[8:11], v[124:127], v[242:245], v[8:11]
	s_setprio 0
	s_setprio 1
	v_mfma_f32_16x16x32_bf16 v[52:55], v[136:139], v[160:163], 0
	v_mfma_f32_16x16x32_bf16 v[48:51], v[152:155], v[160:163], 0
	v_mfma_f32_16x16x32_bf16 v[36:39], v[136:139], v[168:171], 0
	v_mfma_f32_16x16x32_bf16 v[32:35], v[152:155], v[168:171], 0
	v_mfma_f32_16x16x32_bf16 v[20:23], v[136:139], v[230:233], 0
	v_mfma_f32_16x16x32_bf16 v[16:19], v[152:155], v[230:233], 0
	v_mfma_f32_16x16x32_bf16 v[4:7], v[136:139], v[238:241], 0
	v_mfma_f32_16x16x32_bf16 v[0:3], v[152:155], v[238:241], 0
	v_mfma_f32_16x16x32_bf16 v[52:55], v[140:143], v[164:167], v[52:55]
	v_mfma_f32_16x16x32_bf16 v[48:51], v[156:159], v[164:167], v[48:51]
	v_mfma_f32_16x16x32_bf16 v[36:39], v[140:143], v[172:175], v[36:39]
	v_mfma_f32_16x16x32_bf16 v[32:35], v[156:159], v[172:175], v[32:35]
	v_mfma_f32_16x16x32_bf16 v[20:23], v[140:143], v[234:237], v[20:23]
	v_mfma_f32_16x16x32_bf16 v[16:19], v[156:159], v[234:237], v[16:19]
	v_mfma_f32_16x16x32_bf16 v[4:7], v[140:143], v[242:245], v[4:7]
	v_mfma_f32_16x16x32_bf16 v[0:3], v[156:159], v[242:245], v[0:3]
	s_setprio 0
	s_barrier
	s_add_i32 s15, 0, 0x18000
	s_add_i32 s20, 0, 0x1c000
	ds_read_b128 v[112:115], v253 offset:32768
	ds_read_b128 v[116:119], v253 offset:33792
	ds_read_b128 v[120:123], v253 offset:34816
	ds_read_b128 v[124:127], v253 offset:35840
	ds_read_b128 v[136:139], v253 offset:49152
	ds_read_b128 v[140:143], v253 offset:50176
	ds_read_b128 v[152:155], v253 offset:51200
	ds_read_b128 v[156:159], v253 offset:52224
	s_add_u32 s12, s12, 0x80000
	s_addc_u32 s13, s13, 0
	s_mov_b32 m0, s42
	ds_read_b128 v[160:163], v228 offset:32768
	ds_read_b128 v[164:167], v228 offset:33792
	ds_read_b128 v[168:171], v228 offset:34816
	ds_read_b128 v[172:175], v228 offset:35840
	ds_read_b128 v[230:233], v228 offset:36864
	ds_read_b128 v[234:237], v228 offset:37888
	ds_read_b128 v[238:241], v228 offset:38912
	ds_read_b128 v[242:245], v228 offset:39936
	global_load_lds_dwordx4 v178, s[12:13]
	s_mov_b32 m0, s43
	s_nop 0
	global_load_lds_dwordx4 v180, s[12:13]
	s_waitcnt vmcnt(8)
	s_waitcnt lgkmcnt(0)
	s_barrier
	s_setprio 1
	s_waitcnt lgkmcnt(0)
	v_mfma_f32_16x16x32_bf16 v[148:151], v[112:115], v[160:163], v[148:151]
	v_mfma_f32_16x16x32_bf16 v[144:147], v[120:123], v[160:163], v[144:147]
	v_mfma_f32_16x16x32_bf16 v[108:111], v[112:115], v[168:171], v[108:111]
	v_mfma_f32_16x16x32_bf16 v[104:107], v[120:123], v[168:171], v[104:107]
	v_mfma_f32_16x16x32_bf16 v[92:95], v[112:115], v[230:233], v[92:95]
	v_mfma_f32_16x16x32_bf16 v[88:91], v[120:123], v[230:233], v[88:91]
	v_mfma_f32_16x16x32_bf16 v[76:79], v[112:115], v[238:241], v[76:79]
	v_mfma_f32_16x16x32_bf16 v[72:75], v[120:123], v[238:241], v[72:75]
	v_mfma_f32_16x16x32_bf16 v[148:151], v[116:119], v[164:167], v[148:151]
	v_mfma_f32_16x16x32_bf16 v[144:147], v[124:127], v[164:167], v[144:147]
	v_mfma_f32_16x16x32_bf16 v[108:111], v[116:119], v[172:175], v[108:111]
	v_mfma_f32_16x16x32_bf16 v[104:107], v[124:127], v[172:175], v[104:107]
	v_mfma_f32_16x16x32_bf16 v[92:95], v[116:119], v[234:237], v[92:95]
	v_mfma_f32_16x16x32_bf16 v[88:91], v[124:127], v[234:237], v[88:91]
	v_mfma_f32_16x16x32_bf16 v[76:79], v[116:119], v[242:245], v[76:79]
	v_mfma_f32_16x16x32_bf16 v[72:75], v[124:127], v[242:245], v[72:75]
	s_setprio 0
	s_setprio 1
	v_mfma_f32_16x16x32_bf16 v[132:135], v[136:139], v[160:163], v[132:135]
	v_mfma_f32_16x16x32_bf16 v[128:131], v[152:155], v[160:163], v[128:131]
	v_mfma_f32_16x16x32_bf16 v[100:103], v[136:139], v[168:171], v[100:103]
	v_mfma_f32_16x16x32_bf16 v[96:99], v[152:155], v[168:171], v[96:99]
	v_mfma_f32_16x16x32_bf16 v[84:87], v[136:139], v[230:233], v[84:87]
	v_mfma_f32_16x16x32_bf16 v[80:83], v[152:155], v[230:233], v[80:83]
	v_mfma_f32_16x16x32_bf16 v[68:71], v[136:139], v[238:241], v[68:71]
	v_mfma_f32_16x16x32_bf16 v[64:67], v[152:155], v[238:241], v[64:67]
	v_mfma_f32_16x16x32_bf16 v[132:135], v[140:143], v[164:167], v[132:135]
	v_mfma_f32_16x16x32_bf16 v[128:131], v[156:159], v[164:167], v[128:131]
	v_mfma_f32_16x16x32_bf16 v[100:103], v[140:143], v[172:175], v[100:103]
	v_mfma_f32_16x16x32_bf16 v[96:99], v[156:159], v[172:175], v[96:99]
	v_mfma_f32_16x16x32_bf16 v[84:87], v[140:143], v[234:237], v[84:87]
	v_mfma_f32_16x16x32_bf16 v[80:83], v[156:159], v[234:237], v[80:83]
	v_mfma_f32_16x16x32_bf16 v[68:71], v[140:143], v[242:245], v[68:71]
	v_mfma_f32_16x16x32_bf16 v[64:67], v[156:159], v[242:245], v[64:67]
	s_setprio 0
	s_barrier
	s_add_i32 s12, s15, s29
	s_mov_b32 m0, s12
	ds_read_b128 v[160:163], v228 offset:49152
	ds_read_b128 v[164:167], v228 offset:50176
	ds_read_b128 v[168:171], v228 offset:51200
	ds_read_b128 v[172:175], v228 offset:52224
	ds_read_b128 v[230:233], v228 offset:53248
	ds_read_b128 v[234:237], v228 offset:54272
	ds_read_b128 v[238:241], v228 offset:55296
	ds_read_b128 v[242:245], v228 offset:56320
	s_add_u32 s98, s10, 0x80
	s_addc_u32 s99, s11, 0
	global_load_lds_dwordx4 v176, s[98:99]
	s_add_i32 m0, s12, 0x2000
	s_add_u32 s10, s10, 0x80080
	s_addc_u32 s11, s11, 0
	s_add_i32 s12, s20, s29
	s_add_u32 s98, s10, 0xfff80000
	s_addc_u32 s99, s11, -1
	global_load_lds_dwordx4 v182, s[98:99]
	s_mov_b32 m0, s12
	s_nop 0
	global_load_lds_dwordx4 v176, s[10:11]
	s_add_i32 m0, s12, 0x2000
	s_nop 0
	global_load_lds_dwordx4 v182, s[10:11]
	s_mov_b32 m0, s58
	s_nop 0
	global_load_lds_dwordx4 v178, s[50:51]
	s_mov_b32 m0, s59
	s_nop 0
	global_load_lds_dwordx4 v180, s[50:51]
	s_waitcnt vmcnt(8)
	s_waitcnt lgkmcnt(0)
	s_barrier
	s_setprio 1
	s_waitcnt lgkmcnt(0)
	v_mfma_f32_16x16x32_bf16 v[60:63], v[112:115], v[160:163], v[60:63]
	v_mfma_f32_16x16x32_bf16 v[56:59], v[120:123], v[160:163], v[56:59]
	v_mfma_f32_16x16x32_bf16 v[44:47], v[112:115], v[168:171], v[44:47]
	v_mfma_f32_16x16x32_bf16 v[40:43], v[120:123], v[168:171], v[40:43]
	v_mfma_f32_16x16x32_bf16 v[28:31], v[112:115], v[230:233], v[28:31]
	v_mfma_f32_16x16x32_bf16 v[24:27], v[120:123], v[230:233], v[24:27]
	v_mfma_f32_16x16x32_bf16 v[12:15], v[112:115], v[238:241], v[12:15]
	v_mfma_f32_16x16x32_bf16 v[8:11], v[120:123], v[238:241], v[8:11]
	v_mfma_f32_16x16x32_bf16 v[60:63], v[116:119], v[164:167], v[60:63]
	v_mfma_f32_16x16x32_bf16 v[56:59], v[124:127], v[164:167], v[56:59]
	v_mfma_f32_16x16x32_bf16 v[44:47], v[116:119], v[172:175], v[44:47]
	v_mfma_f32_16x16x32_bf16 v[40:43], v[124:127], v[172:175], v[40:43]
	v_mfma_f32_16x16x32_bf16 v[28:31], v[116:119], v[234:237], v[28:31]
	v_mfma_f32_16x16x32_bf16 v[24:27], v[124:127], v[234:237], v[24:27]
	v_mfma_f32_16x16x32_bf16 v[12:15], v[116:119], v[242:245], v[12:15]
	v_mfma_f32_16x16x32_bf16 v[8:11], v[124:127], v[242:245], v[8:11]
	s_setprio 0
	s_setprio 1
	v_mfma_f32_16x16x32_bf16 v[52:55], v[136:139], v[160:163], v[52:55]
	v_mfma_f32_16x16x32_bf16 v[48:51], v[152:155], v[160:163], v[48:51]
	v_mfma_f32_16x16x32_bf16 v[36:39], v[136:139], v[168:171], v[36:39]
	v_mfma_f32_16x16x32_bf16 v[32:35], v[152:155], v[168:171], v[32:35]
	v_mfma_f32_16x16x32_bf16 v[20:23], v[136:139], v[230:233], v[20:23]
	v_mfma_f32_16x16x32_bf16 v[16:19], v[152:155], v[230:233], v[16:19]
	v_mfma_f32_16x16x32_bf16 v[4:7], v[136:139], v[238:241], v[4:7]
	v_mfma_f32_16x16x32_bf16 v[0:3], v[152:155], v[238:241], v[0:3]
	v_mfma_f32_16x16x32_bf16 v[52:55], v[140:143], v[164:167], v[52:55]
	v_mfma_f32_16x16x32_bf16 v[48:51], v[156:159], v[164:167], v[48:51]
	v_mfma_f32_16x16x32_bf16 v[36:39], v[140:143], v[172:175], v[36:39]
	v_mfma_f32_16x16x32_bf16 v[32:35], v[156:159], v[172:175], v[32:35]
	v_mfma_f32_16x16x32_bf16 v[20:23], v[140:143], v[234:237], v[20:23]
	v_mfma_f32_16x16x32_bf16 v[16:19], v[156:159], v[234:237], v[16:19]
	v_mfma_f32_16x16x32_bf16 v[4:7], v[140:143], v[242:245], v[4:7]
	v_mfma_f32_16x16x32_bf16 v[0:3], v[156:159], v[242:245], v[0:3]
	s_setprio 0
	s_barrier
	s_add_i32 s14, s14, 2
	s_add_u32 s8, s8, 0x100
	s_addc_u32 s9, s9, 0
	s_add_u32 s1, s1, 0x100
	s_addc_u32 s3, s3, 0
	s_cmp_gt_u32 s14, 29
.LBB0_290:
	s_add_u32 s10, s8, 0xfff80080
	s_addc_u32 s11, s9, -1
	s_add_i32 s15, 0, 0x10000
	s_cmp_eq_u32 s14, 28
	s_cselect_b32 s13, s35, s11
	s_cselect_b32 s12, s34, s10
	s_cselect_b32 s11, s31, s3
	s_cselect_b32 s10, s30, s1
	s_add_i32 s22, 0, 0x14000
	ds_read_b128 v[112:115], v253
	ds_read_b128 v[116:119], v253 offset:1024
	ds_read_b128 v[120:123], v253 offset:2048
	ds_read_b128 v[124:127], v253 offset:3072
	ds_read_b128 v[136:139], v253 offset:16384
	ds_read_b128 v[140:143], v253 offset:17408
	ds_read_b128 v[152:155], v253 offset:18432
	ds_read_b128 v[156:159], v253 offset:19456
	s_add_i32 m0, s38, 0xc000
	ds_read_b128 v[160:163], v228
	ds_read_b128 v[164:167], v228 offset:1024
	ds_read_b128 v[168:171], v228 offset:2048
	ds_read_b128 v[172:175], v228 offset:3072
	ds_read_b128 v[230:233], v228 offset:4096
	ds_read_b128 v[234:237], v228 offset:5120
	ds_read_b128 v[238:241], v228 offset:6144
	ds_read_b128 v[242:245], v228 offset:7168
	global_load_lds_dwordx4 v202, s[8:9]
	s_add_i32 m0, s38, 0xe000
	s_nop 0
	global_load_lds_dwordx4 v204, s[8:9]
	s_waitcnt vmcnt(8)
	s_waitcnt lgkmcnt(0)
	s_barrier
	s_setprio 1
	s_waitcnt lgkmcnt(0)
	v_mfma_f32_16x16x32_bf16 v[148:151], v[112:115], v[160:163], v[148:151]
	v_mfma_f32_16x16x32_bf16 v[144:147], v[120:123], v[160:163], v[144:147]
	v_mfma_f32_16x16x32_bf16 v[108:111], v[112:115], v[168:171], v[108:111]
	v_mfma_f32_16x16x32_bf16 v[104:107], v[120:123], v[168:171], v[104:107]
	v_mfma_f32_16x16x32_bf16 v[92:95], v[112:115], v[230:233], v[92:95]
	v_mfma_f32_16x16x32_bf16 v[88:91], v[120:123], v[230:233], v[88:91]
	v_mfma_f32_16x16x32_bf16 v[76:79], v[112:115], v[238:241], v[76:79]
	v_mfma_f32_16x16x32_bf16 v[72:75], v[120:123], v[238:241], v[72:75]
	v_mfma_f32_16x16x32_bf16 v[148:151], v[116:119], v[164:167], v[148:151]
	v_mfma_f32_16x16x32_bf16 v[144:147], v[124:127], v[164:167], v[144:147]
	v_mfma_f32_16x16x32_bf16 v[108:111], v[116:119], v[172:175], v[108:111]
	v_mfma_f32_16x16x32_bf16 v[104:107], v[124:127], v[172:175], v[104:107]
	v_mfma_f32_16x16x32_bf16 v[92:95], v[116:119], v[234:237], v[92:95]
	v_mfma_f32_16x16x32_bf16 v[88:91], v[124:127], v[234:237], v[88:91]
	v_mfma_f32_16x16x32_bf16 v[76:79], v[116:119], v[242:245], v[76:79]
	v_mfma_f32_16x16x32_bf16 v[72:75], v[124:127], v[242:245], v[72:75]
	s_setprio 0
	s_setprio 1
	v_mfma_f32_16x16x32_bf16 v[132:135], v[136:139], v[160:163], v[132:135]
	v_mfma_f32_16x16x32_bf16 v[128:131], v[152:155], v[160:163], v[128:131]
	v_mfma_f32_16x16x32_bf16 v[100:103], v[136:139], v[168:171], v[100:103]
	v_mfma_f32_16x16x32_bf16 v[96:99], v[152:155], v[168:171], v[96:99]
	v_mfma_f32_16x16x32_bf16 v[84:87], v[136:139], v[230:233], v[84:87]
	v_mfma_f32_16x16x32_bf16 v[80:83], v[152:155], v[230:233], v[80:83]
	v_mfma_f32_16x16x32_bf16 v[68:71], v[136:139], v[238:241], v[68:71]
	v_mfma_f32_16x16x32_bf16 v[64:67], v[152:155], v[238:241], v[64:67]
	v_mfma_f32_16x16x32_bf16 v[132:135], v[140:143], v[164:167], v[132:135]
	v_mfma_f32_16x16x32_bf16 v[128:131], v[156:159], v[164:167], v[128:131]
	v_mfma_f32_16x16x32_bf16 v[100:103], v[140:143], v[172:175], v[100:103]
	v_mfma_f32_16x16x32_bf16 v[96:99], v[156:159], v[172:175], v[96:99]
	v_mfma_f32_16x16x32_bf16 v[84:87], v[140:143], v[234:237], v[84:87]
	v_mfma_f32_16x16x32_bf16 v[80:83], v[156:159], v[234:237], v[80:83]
	v_mfma_f32_16x16x32_bf16 v[68:71], v[140:143], v[242:245], v[68:71]
	v_mfma_f32_16x16x32_bf16 v[64:67], v[156:159], v[242:245], v[64:67]
	s_setprio 0
	s_barrier
	s_add_i32 s15, s15, s29
	s_mov_b32 m0, s15
	ds_read_b128 v[160:163], v228 offset:16384
	ds_read_b128 v[164:167], v228 offset:17408
	ds_read_b128 v[168:171], v228 offset:18432
	ds_read_b128 v[172:175], v228 offset:19456
	ds_read_b128 v[230:233], v228 offset:20480
	ds_read_b128 v[234:237], v228 offset:21504
	ds_read_b128 v[238:241], v228 offset:22528
	ds_read_b128 v[242:245], v228 offset:23552
	global_load_lds_dwordx4 v176, s[10:11]
	s_add_i32 m0, s15, 0x2000
	s_add_u32 s20, s10, 0x80000
	s_addc_u32 s21, s11, 0
	s_add_i32 s15, s22, s29
	global_load_lds_dwordx4 v182, s[10:11]
	s_mov_b32 m0, s15
	s_nop 0
	global_load_lds_dwordx4 v176, s[20:21]
	s_add_i32 m0, s15, 0x2000
	s_nop 0
	global_load_lds_dwordx4 v182, s[20:21]
	s_add_u32 s50, s12, 0x80
	s_addc_u32 s51, s13, 0
	s_mov_b32 m0, s38
	s_nop 0
	global_load_lds_dwordx4 v178, s[12:13]
	s_mov_b32 m0, s39
	s_nop 0
	global_load_lds_dwordx4 v180, s[12:13]
	s_waitcnt vmcnt(8)
	s_waitcnt lgkmcnt(0)
	s_barrier
	s_setprio 1
	s_waitcnt lgkmcnt(0)
	v_mfma_f32_16x16x32_bf16 v[60:63], v[112:115], v[160:163], v[60:63]
	v_mfma_f32_16x16x32_bf16 v[56:59], v[120:123], v[160:163], v[56:59]
	v_mfma_f32_16x16x32_bf16 v[44:47], v[112:115], v[168:171], v[44:47]
	v_mfma_f32_16x16x32_bf16 v[40:43], v[120:123], v[168:171], v[40:43]
	v_mfma_f32_16x16x32_bf16 v[28:31], v[112:115], v[230:233], v[28:31]
	v_mfma_f32_16x16x32_bf16 v[24:27], v[120:123], v[230:233], v[24:27]
	v_mfma_f32_16x16x32_bf16 v[12:15], v[112:115], v[238:241], v[12:15]
	v_mfma_f32_16x16x32_bf16 v[8:11], v[120:123], v[238:241], v[8:11]
	v_mfma_f32_16x16x32_bf16 v[60:63], v[116:119], v[164:167], v[60:63]
	v_mfma_f32_16x16x32_bf16 v[56:59], v[124:127], v[164:167], v[56:59]
	v_mfma_f32_16x16x32_bf16 v[44:47], v[116:119], v[172:175], v[44:47]
	v_mfma_f32_16x16x32_bf16 v[40:43], v[124:127], v[172:175], v[40:43]
	v_mfma_f32_16x16x32_bf16 v[28:31], v[116:119], v[234:237], v[28:31]
	v_mfma_f32_16x16x32_bf16 v[24:27], v[124:127], v[234:237], v[24:27]
	v_mfma_f32_16x16x32_bf16 v[12:15], v[116:119], v[242:245], v[12:15]
	v_mfma_f32_16x16x32_bf16 v[8:11], v[124:127], v[242:245], v[8:11]
	s_setprio 0
	s_setprio 1
	v_mfma_f32_16x16x32_bf16 v[52:55], v[136:139], v[160:163], v[52:55]
	v_mfma_f32_16x16x32_bf16 v[48:51], v[152:155], v[160:163], v[48:51]
	v_mfma_f32_16x16x32_bf16 v[36:39], v[136:139], v[168:171], v[36:39]
	v_mfma_f32_16x16x32_bf16 v[32:35], v[152:155], v[168:171], v[32:35]
	v_mfma_f32_16x16x32_bf16 v[20:23], v[136:139], v[230:233], v[20:23]
	v_mfma_f32_16x16x32_bf16 v[16:19], v[152:155], v[230:233], v[16:19]
	v_mfma_f32_16x16x32_bf16 v[4:7], v[136:139], v[238:241], v[4:7]
	v_mfma_f32_16x16x32_bf16 v[0:3], v[152:155], v[238:241], v[0:3]
	v_mfma_f32_16x16x32_bf16 v[52:55], v[140:143], v[164:167], v[52:55]
	v_mfma_f32_16x16x32_bf16 v[48:51], v[156:159], v[164:167], v[48:51]
	v_mfma_f32_16x16x32_bf16 v[36:39], v[140:143], v[172:175], v[36:39]
	v_mfma_f32_16x16x32_bf16 v[32:35], v[156:159], v[172:175], v[32:35]
	v_mfma_f32_16x16x32_bf16 v[20:23], v[140:143], v[234:237], v[20:23]
	v_mfma_f32_16x16x32_bf16 v[16:19], v[156:159], v[234:237], v[16:19]
	v_mfma_f32_16x16x32_bf16 v[4:7], v[140:143], v[242:245], v[4:7]
	v_mfma_f32_16x16x32_bf16 v[0:3], v[156:159], v[242:245], v[0:3]
	s_setprio 0
	s_barrier
	s_add_i32 s15, 0, 0x18000
	s_add_i32 s20, 0, 0x1c000
	ds_read_b128 v[112:115], v253 offset:32768
	ds_read_b128 v[116:119], v253 offset:33792
	ds_read_b128 v[120:123], v253 offset:34816
	ds_read_b128 v[124:127], v253 offset:35840
	ds_read_b128 v[136:139], v253 offset:49152
	ds_read_b128 v[140:143], v253 offset:50176
	ds_read_b128 v[152:155], v253 offset:51200
	ds_read_b128 v[156:159], v253 offset:52224
	s_add_u32 s12, s12, 0x80000
	s_addc_u32 s13, s13, 0
	s_mov_b32 m0, s42
	ds_read_b128 v[160:163], v228 offset:32768
	ds_read_b128 v[164:167], v228 offset:33792
	ds_read_b128 v[168:171], v228 offset:34816
	ds_read_b128 v[172:175], v228 offset:35840
	ds_read_b128 v[230:233], v228 offset:36864
	ds_read_b128 v[234:237], v228 offset:37888
	ds_read_b128 v[238:241], v228 offset:38912
	ds_read_b128 v[242:245], v228 offset:39936
	global_load_lds_dwordx4 v178, s[12:13]
	s_mov_b32 m0, s43
	s_nop 0
	global_load_lds_dwordx4 v180, s[12:13]
	s_waitcnt vmcnt(8)
	s_waitcnt lgkmcnt(0)
	s_barrier
	s_setprio 1
	s_waitcnt lgkmcnt(0)
	v_mfma_f32_16x16x32_bf16 v[148:151], v[112:115], v[160:163], v[148:151]
	v_mfma_f32_16x16x32_bf16 v[144:147], v[120:123], v[160:163], v[144:147]
	v_mfma_f32_16x16x32_bf16 v[108:111], v[112:115], v[168:171], v[108:111]
	v_mfma_f32_16x16x32_bf16 v[104:107], v[120:123], v[168:171], v[104:107]
	v_mfma_f32_16x16x32_bf16 v[92:95], v[112:115], v[230:233], v[92:95]
	v_mfma_f32_16x16x32_bf16 v[88:91], v[120:123], v[230:233], v[88:91]
	v_mfma_f32_16x16x32_bf16 v[76:79], v[112:115], v[238:241], v[76:79]
	v_mfma_f32_16x16x32_bf16 v[72:75], v[120:123], v[238:241], v[72:75]
	v_mfma_f32_16x16x32_bf16 v[148:151], v[116:119], v[164:167], v[148:151]
	v_mfma_f32_16x16x32_bf16 v[144:147], v[124:127], v[164:167], v[144:147]
	v_mfma_f32_16x16x32_bf16 v[108:111], v[116:119], v[172:175], v[108:111]
	v_mfma_f32_16x16x32_bf16 v[104:107], v[124:127], v[172:175], v[104:107]
	v_mfma_f32_16x16x32_bf16 v[92:95], v[116:119], v[234:237], v[92:95]
	v_mfma_f32_16x16x32_bf16 v[88:91], v[124:127], v[234:237], v[88:91]
	v_mfma_f32_16x16x32_bf16 v[76:79], v[116:119], v[242:245], v[76:79]
	v_mfma_f32_16x16x32_bf16 v[72:75], v[124:127], v[242:245], v[72:75]
	s_setprio 0
	s_setprio 1
	v_mfma_f32_16x16x32_bf16 v[132:135], v[136:139], v[160:163], v[132:135]
	v_mfma_f32_16x16x32_bf16 v[128:131], v[152:155], v[160:163], v[128:131]
	v_mfma_f32_16x16x32_bf16 v[100:103], v[136:139], v[168:171], v[100:103]
	v_mfma_f32_16x16x32_bf16 v[96:99], v[152:155], v[168:171], v[96:99]
	v_mfma_f32_16x16x32_bf16 v[84:87], v[136:139], v[230:233], v[84:87]
	v_mfma_f32_16x16x32_bf16 v[80:83], v[152:155], v[230:233], v[80:83]
	v_mfma_f32_16x16x32_bf16 v[68:71], v[136:139], v[238:241], v[68:71]
	v_mfma_f32_16x16x32_bf16 v[64:67], v[152:155], v[238:241], v[64:67]
	v_mfma_f32_16x16x32_bf16 v[132:135], v[140:143], v[164:167], v[132:135]
	v_mfma_f32_16x16x32_bf16 v[128:131], v[156:159], v[164:167], v[128:131]
	v_mfma_f32_16x16x32_bf16 v[100:103], v[140:143], v[172:175], v[100:103]
	v_mfma_f32_16x16x32_bf16 v[96:99], v[156:159], v[172:175], v[96:99]
	v_mfma_f32_16x16x32_bf16 v[84:87], v[140:143], v[234:237], v[84:87]
	v_mfma_f32_16x16x32_bf16 v[80:83], v[156:159], v[234:237], v[80:83]
	v_mfma_f32_16x16x32_bf16 v[68:71], v[140:143], v[242:245], v[68:71]
	v_mfma_f32_16x16x32_bf16 v[64:67], v[156:159], v[242:245], v[64:67]
	s_setprio 0
	s_barrier
	s_add_i32 s12, s15, s29
	s_mov_b32 m0, s12
	ds_read_b128 v[160:163], v228 offset:49152
	ds_read_b128 v[164:167], v228 offset:50176
	ds_read_b128 v[168:171], v228 offset:51200
	ds_read_b128 v[172:175], v228 offset:52224
	ds_read_b128 v[230:233], v228 offset:53248
	ds_read_b128 v[234:237], v228 offset:54272
	ds_read_b128 v[238:241], v228 offset:55296
	ds_read_b128 v[242:245], v228 offset:56320
	s_add_u32 s98, s10, 0x80
	s_addc_u32 s99, s11, 0
	global_load_lds_dwordx4 v176, s[98:99]
	s_add_i32 m0, s12, 0x2000
	s_add_u32 s10, s10, 0x80080
	s_addc_u32 s11, s11, 0
	s_add_i32 s12, s20, s29
	s_add_u32 s98, s10, 0xfff80000
	s_addc_u32 s99, s11, -1
	global_load_lds_dwordx4 v182, s[98:99]
	s_mov_b32 m0, s12
	s_nop 0
	global_load_lds_dwordx4 v176, s[10:11]
	s_add_i32 m0, s12, 0x2000
	s_nop 0
	global_load_lds_dwordx4 v182, s[10:11]
	s_mov_b32 m0, s58
	s_nop 0
	global_load_lds_dwordx4 v178, s[50:51]
	s_mov_b32 m0, s59
	s_nop 0
	global_load_lds_dwordx4 v180, s[50:51]
	s_waitcnt vmcnt(8)
	s_waitcnt lgkmcnt(0)
	s_barrier
	s_setprio 1
	s_waitcnt lgkmcnt(0)
	v_mfma_f32_16x16x32_bf16 v[60:63], v[112:115], v[160:163], v[60:63]
	v_mfma_f32_16x16x32_bf16 v[56:59], v[120:123], v[160:163], v[56:59]
	v_mfma_f32_16x16x32_bf16 v[44:47], v[112:115], v[168:171], v[44:47]
	v_mfma_f32_16x16x32_bf16 v[40:43], v[120:123], v[168:171], v[40:43]
	v_mfma_f32_16x16x32_bf16 v[28:31], v[112:115], v[230:233], v[28:31]
	v_mfma_f32_16x16x32_bf16 v[24:27], v[120:123], v[230:233], v[24:27]
	v_mfma_f32_16x16x32_bf16 v[12:15], v[112:115], v[238:241], v[12:15]
	v_mfma_f32_16x16x32_bf16 v[8:11], v[120:123], v[238:241], v[8:11]
	v_mfma_f32_16x16x32_bf16 v[60:63], v[116:119], v[164:167], v[60:63]
	v_mfma_f32_16x16x32_bf16 v[56:59], v[124:127], v[164:167], v[56:59]
	v_mfma_f32_16x16x32_bf16 v[44:47], v[116:119], v[172:175], v[44:47]
	v_mfma_f32_16x16x32_bf16 v[40:43], v[124:127], v[172:175], v[40:43]
	v_mfma_f32_16x16x32_bf16 v[28:31], v[116:119], v[234:237], v[28:31]
	v_mfma_f32_16x16x32_bf16 v[24:27], v[124:127], v[234:237], v[24:27]
	v_mfma_f32_16x16x32_bf16 v[12:15], v[116:119], v[242:245], v[12:15]
	v_mfma_f32_16x16x32_bf16 v[8:11], v[124:127], v[242:245], v[8:11]
	s_setprio 0
	s_setprio 1
	v_mfma_f32_16x16x32_bf16 v[52:55], v[136:139], v[160:163], v[52:55]
	v_mfma_f32_16x16x32_bf16 v[48:51], v[152:155], v[160:163], v[48:51]
	v_mfma_f32_16x16x32_bf16 v[36:39], v[136:139], v[168:171], v[36:39]
	v_mfma_f32_16x16x32_bf16 v[32:35], v[152:155], v[168:171], v[32:35]
	v_mfma_f32_16x16x32_bf16 v[20:23], v[136:139], v[230:233], v[20:23]
	v_mfma_f32_16x16x32_bf16 v[16:19], v[152:155], v[230:233], v[16:19]
	v_mfma_f32_16x16x32_bf16 v[4:7], v[136:139], v[238:241], v[4:7]
	v_mfma_f32_16x16x32_bf16 v[0:3], v[152:155], v[238:241], v[0:3]
	v_mfma_f32_16x16x32_bf16 v[52:55], v[140:143], v[164:167], v[52:55]
	v_mfma_f32_16x16x32_bf16 v[48:51], v[156:159], v[164:167], v[48:51]
	v_mfma_f32_16x16x32_bf16 v[36:39], v[140:143], v[172:175], v[36:39]
	v_mfma_f32_16x16x32_bf16 v[32:35], v[156:159], v[172:175], v[32:35]
	v_mfma_f32_16x16x32_bf16 v[20:23], v[140:143], v[234:237], v[20:23]
	v_mfma_f32_16x16x32_bf16 v[16:19], v[156:159], v[234:237], v[16:19]
	v_mfma_f32_16x16x32_bf16 v[4:7], v[140:143], v[242:245], v[4:7]
	v_mfma_f32_16x16x32_bf16 v[0:3], v[156:159], v[242:245], v[0:3]
	s_setprio 0
	s_barrier
	s_add_i32 s14, s14, 2
	s_add_u32 s8, s8, 0x100
	s_addc_u32 s9, s9, 0
	s_add_u32 s1, s1, 0x100
	s_addc_u32 s3, s3, 0
	s_cmp_gt_u32 s14, 29
	s_cbranch_scc0 .LBB0_290
	s_and_b64 vcc, exec, s[56:57]
	s_cbranch_vccz .LBB0_293
	s_barrier

.LBB0_419:
	s_ashr_i32 s15, s14, 31
	s_lshl_b64 s[8:9], s[14:15], 20
	s_cmp_eq_u32 s53, 0
	s_cselect_b32 s19, s2, s26
	s_cselect_b32 s15, s3, s27
	s_cselect_b32 s29, s21, s3
	s_cselect_b32 s28, s20, s2
	s_add_u32 s24, s19, s8
	s_addc_u32 s25, s15, s9
	s_and_b64 s[8:9], s[22:23], exec
	s_cselect_b32 s15, s25, s5
	s_cselect_b32 s30, s24, s4
	s_ashr_i32 s19, s18, 31
	s_lshl_b64 s[8:9], s[18:19], 20
	s_add_u32 s28, s28, s8
	s_addc_u32 s29, s29, s9
	s_and_b64 s[8:9], s[22:23], exec
	s_cselect_b32 s19, s29, s7
	s_cselect_b32 s31, s28, s6
	s_add_u32 s4, s4, 0x80080
	s_addc_u32 s5, s5, 0
	s_add_u32 s34, s6, 0x100
	s_addc_u32 s35, s7, 0
	s_mov_b32 s36, -2
	v_add_u32_e32 v253, 0x10000, v149
	s_add_u32 s6, s4, 0xfff80080
	s_addc_u32 s7, s5, -1
	s_add_i32 s37, 0, 0x10000
	s_cmp_eq_u32 s36, 28
	s_cselect_b32 s9, s15, s7
	s_cselect_b32 s8, s30, s6
	s_cselect_b32 s7, s19, s35
	s_cselect_b32 s6, s31, s34
	s_add_i32 s56, 0, 0x14000
	ds_read_b128 v[130:133], v253
	ds_read_b128 v[134:137], v253 offset:1024
	ds_read_b128 v[154:157], v253 offset:2048
	ds_read_b128 v[162:165], v253 offset:3072
	ds_read_b128 v[166:169], v253 offset:16384
	ds_read_b128 v[170:173], v253 offset:17408
	ds_read_b128 v[178:181], v253 offset:18432
	ds_read_b128 v[182:185], v253 offset:19456
	s_add_i32 m0, s38, 0xc000
	ds_read_b128 v[186:189], v161
	ds_read_b128 v[190:193], v161 offset:1024
	ds_read_b128 v[194:197], v161 offset:2048
	ds_read_b128 v[198:201], v161 offset:3072
	ds_read_b128 v[202:205], v161 offset:4096
	ds_read_b128 v[206:209], v161 offset:5120
	ds_read_b128 v[220:223], v161 offset:6144
	ds_read_b128 v[224:227], v161 offset:7168
	global_load_lds_dwordx4 v150, s[4:5]
	s_add_i32 m0, s38, 0xe000
	s_nop 0
	global_load_lds_dwordx4 v152, s[4:5]
	s_waitcnt vmcnt(8)
	s_waitcnt lgkmcnt(0)
	s_barrier
	s_setprio 1
	s_waitcnt lgkmcnt(0)
	v_mfma_f32_16x16x32_bf16 v[124:127], v[130:133], v[186:189], 0
	v_mfma_f32_16x16x32_bf16 v[120:123], v[154:157], v[186:189], 0
	v_mfma_f32_16x16x32_bf16 v[108:111], v[130:133], v[194:197], 0
	v_mfma_f32_16x16x32_bf16 v[104:107], v[154:157], v[194:197], 0
	v_mfma_f32_16x16x32_bf16 v[92:95], v[130:133], v[202:205], 0
	v_mfma_f32_16x16x32_bf16 v[88:91], v[154:157], v[202:205], 0
	v_mfma_f32_16x16x32_bf16 v[76:79], v[130:133], v[220:223], 0
	v_mfma_f32_16x16x32_bf16 v[72:75], v[154:157], v[220:223], 0
	v_mfma_f32_16x16x32_bf16 v[124:127], v[134:137], v[190:193], v[124:127]
	v_mfma_f32_16x16x32_bf16 v[120:123], v[162:165], v[190:193], v[120:123]
	v_mfma_f32_16x16x32_bf16 v[108:111], v[134:137], v[198:201], v[108:111]
	v_mfma_f32_16x16x32_bf16 v[104:107], v[162:165], v[198:201], v[104:107]
	v_mfma_f32_16x16x32_bf16 v[92:95], v[134:137], v[206:209], v[92:95]
	v_mfma_f32_16x16x32_bf16 v[88:91], v[162:165], v[206:209], v[88:91]
	v_mfma_f32_16x16x32_bf16 v[76:79], v[134:137], v[224:227], v[76:79]
	v_mfma_f32_16x16x32_bf16 v[72:75], v[162:165], v[224:227], v[72:75]
	s_setprio 0
	s_setprio 1
	v_mfma_f32_16x16x32_bf16 v[116:119], v[166:169], v[186:189], 0
	v_mfma_f32_16x16x32_bf16 v[112:115], v[178:181], v[186:189], 0
	v_mfma_f32_16x16x32_bf16 v[100:103], v[166:169], v[194:197], 0
	v_mfma_f32_16x16x32_bf16 v[96:99], v[178:181], v[194:197], 0
	v_mfma_f32_16x16x32_bf16 v[84:87], v[166:169], v[202:205], 0
	v_mfma_f32_16x16x32_bf16 v[80:83], v[178:181], v[202:205], 0
	v_mfma_f32_16x16x32_bf16 v[68:71], v[166:169], v[220:223], 0
	v_mfma_f32_16x16x32_bf16 v[64:67], v[178:181], v[220:223], 0
	v_mfma_f32_16x16x32_bf16 v[116:119], v[170:173], v[190:193], v[116:119]
	v_mfma_f32_16x16x32_bf16 v[112:115], v[182:185], v[190:193], v[112:115]
	v_mfma_f32_16x16x32_bf16 v[100:103], v[170:173], v[198:201], v[100:103]
	v_mfma_f32_16x16x32_bf16 v[96:99], v[182:185], v[198:201], v[96:99]
	v_mfma_f32_16x16x32_bf16 v[84:87], v[170:173], v[206:209], v[84:87]
	v_mfma_f32_16x16x32_bf16 v[80:83], v[182:185], v[206:209], v[80:83]
	v_mfma_f32_16x16x32_bf16 v[68:71], v[170:173], v[224:227], v[68:71]
	v_mfma_f32_16x16x32_bf16 v[64:67], v[182:185], v[224:227], v[64:67]
	s_setprio 0
	s_barrier
	s_add_i32 s37, s37, s33
	s_mov_b32 m0, s37
	ds_read_b128 v[186:189], v161 offset:16384
	ds_read_b128 v[190:193], v161 offset:17408
	ds_read_b128 v[194:197], v161 offset:18432
	ds_read_b128 v[198:201], v161 offset:19456
	ds_read_b128 v[202:205], v161 offset:20480
	ds_read_b128 v[206:209], v161 offset:21504
	ds_read_b128 v[220:223], v161 offset:22528
	ds_read_b128 v[224:227], v161 offset:23552
	global_load_lds_dwordx4 v142, s[6:7]
	s_add_i32 m0, s37, 0x2000
	s_add_u32 s54, s6, 0x80000
	s_addc_u32 s55, s7, 0
	s_add_i32 s37, s56, s33
	global_load_lds_dwordx4 v138, s[6:7]
	s_mov_b32 m0, s37
	s_nop 0
	global_load_lds_dwordx4 v142, s[54:55]
	s_add_i32 m0, s37, 0x2000
	s_nop 0
	global_load_lds_dwordx4 v138, s[54:55]
	s_add_u32 s60, s8, 0x80
	s_addc_u32 s61, s9, 0
	s_mov_b32 m0, s38
	s_nop 0
	global_load_lds_dwordx4 v144, s[8:9]
	s_mov_b32 m0, s39
	s_nop 0
	global_load_lds_dwordx4 v140, s[8:9]
	s_waitcnt vmcnt(8)
	s_waitcnt lgkmcnt(0)
	s_barrier
	s_setprio 1
	s_waitcnt lgkmcnt(0)
	v_mfma_f32_16x16x32_bf16 v[60:63], v[130:133], v[186:189], 0
	v_mfma_f32_16x16x32_bf16 v[56:59], v[154:157], v[186:189], 0
	v_mfma_f32_16x16x32_bf16 v[44:47], v[130:133], v[194:197], 0
	v_mfma_f32_16x16x32_bf16 v[40:43], v[154:157], v[194:197], 0
	v_mfma_f32_16x16x32_bf16 v[28:31], v[130:133], v[202:205], 0
	v_mfma_f32_16x16x32_bf16 v[24:27], v[154:157], v[202:205], 0
	v_mfma_f32_16x16x32_bf16 v[12:15], v[130:133], v[220:223], 0
	v_mfma_f32_16x16x32_bf16 v[8:11], v[154:157], v[220:223], 0
	v_mfma_f32_16x16x32_bf16 v[60:63], v[134:137], v[190:193], v[60:63]
	v_mfma_f32_16x16x32_bf16 v[56:59], v[162:165], v[190:193], v[56:59]
	v_mfma_f32_16x16x32_bf16 v[44:47], v[134:137], v[198:201], v[44:47]
	v_mfma_f32_16x16x32_bf16 v[40:43], v[162:165], v[198:201], v[40:43]
	v_mfma_f32_16x16x32_bf16 v[28:31], v[134:137], v[206:209], v[28:31]
	v_mfma_f32_16x16x32_bf16 v[24:27], v[162:165], v[206:209], v[24:27]
	v_mfma_f32_16x16x32_bf16 v[12:15], v[134:137], v[224:227], v[12:15]
	v_mfma_f32_16x16x32_bf16 v[8:11], v[162:165], v[224:227], v[8:11]
	s_setprio 0
	s_setprio 1
	v_mfma_f32_16x16x32_bf16 v[52:55], v[166:169], v[186:189], 0
	v_mfma_f32_16x16x32_bf16 v[48:51], v[178:181], v[186:189], 0
	v_mfma_f32_16x16x32_bf16 v[36:39], v[166:169], v[194:197], 0
	v_mfma_f32_16x16x32_bf16 v[32:35], v[178:181], v[194:197], 0
	v_mfma_f32_16x16x32_bf16 v[20:23], v[166:169], v[202:205], 0
	v_mfma_f32_16x16x32_bf16 v[16:19], v[178:181], v[202:205], 0
	v_mfma_f32_16x16x32_bf16 v[4:7], v[166:169], v[220:223], 0
	v_mfma_f32_16x16x32_bf16 v[0:3], v[178:181], v[220:223], 0
	v_mfma_f32_16x16x32_bf16 v[52:55], v[170:173], v[190:193], v[52:55]
	v_mfma_f32_16x16x32_bf16 v[48:51], v[182:185], v[190:193], v[48:51]
	v_mfma_f32_16x16x32_bf16 v[36:39], v[170:173], v[198:201], v[36:39]
	v_mfma_f32_16x16x32_bf16 v[32:35], v[182:185], v[198:201], v[32:35]
	v_mfma_f32_16x16x32_bf16 v[20:23], v[170:173], v[206:209], v[20:23]
	v_mfma_f32_16x16x32_bf16 v[16:19], v[182:185], v[206:209], v[16:19]
	v_mfma_f32_16x16x32_bf16 v[4:7], v[170:173], v[224:227], v[4:7]
	v_mfma_f32_16x16x32_bf16 v[0:3], v[182:185], v[224:227], v[0:3]
	s_setprio 0
	s_barrier
	s_add_i32 s37, 0, 0x18000
	s_add_i32 s54, 0, 0x1c000
	ds_read_b128 v[130:133], v253 offset:32768
	ds_read_b128 v[134:137], v253 offset:33792
	ds_read_b128 v[154:157], v253 offset:34816
	ds_read_b128 v[162:165], v253 offset:35840
	ds_read_b128 v[166:169], v253 offset:49152
	ds_read_b128 v[170:173], v253 offset:50176
	ds_read_b128 v[178:181], v253 offset:51200
	ds_read_b128 v[182:185], v253 offset:52224
	s_add_u32 s8, s8, 0x80000
	s_addc_u32 s9, s9, 0
	s_mov_b32 m0, s40
	ds_read_b128 v[186:189], v161 offset:32768
	ds_read_b128 v[190:193], v161 offset:33792
	ds_read_b128 v[194:197], v161 offset:34816
	ds_read_b128 v[198:201], v161 offset:35840
	ds_read_b128 v[202:205], v161 offset:36864
	ds_read_b128 v[206:209], v161 offset:37888
	ds_read_b128 v[220:223], v161 offset:38912
	ds_read_b128 v[224:227], v161 offset:39936
	global_load_lds_dwordx4 v144, s[8:9]
	s_mov_b32 m0, s41
	s_nop 0
	global_load_lds_dwordx4 v140, s[8:9]
	s_waitcnt vmcnt(8)
	s_waitcnt lgkmcnt(0)
	s_barrier
	s_setprio 1
	s_waitcnt lgkmcnt(0)
	v_mfma_f32_16x16x32_bf16 v[124:127], v[130:133], v[186:189], v[124:127]
	v_mfma_f32_16x16x32_bf16 v[120:123], v[154:157], v[186:189], v[120:123]
	v_mfma_f32_16x16x32_bf16 v[108:111], v[130:133], v[194:197], v[108:111]
	v_mfma_f32_16x16x32_bf16 v[104:107], v[154:157], v[194:197], v[104:107]
	v_mfma_f32_16x16x32_bf16 v[92:95], v[130:133], v[202:205], v[92:95]
	v_mfma_f32_16x16x32_bf16 v[88:91], v[154:157], v[202:205], v[88:91]
	v_mfma_f32_16x16x32_bf16 v[76:79], v[130:133], v[220:223], v[76:79]
	v_mfma_f32_16x16x32_bf16 v[72:75], v[154:157], v[220:223], v[72:75]
	v_mfma_f32_16x16x32_bf16 v[124:127], v[134:137], v[190:193], v[124:127]
	v_mfma_f32_16x16x32_bf16 v[120:123], v[162:165], v[190:193], v[120:123]
	v_mfma_f32_16x16x32_bf16 v[108:111], v[134:137], v[198:201], v[108:111]
	v_mfma_f32_16x16x32_bf16 v[104:107], v[162:165], v[198:201], v[104:107]
	v_mfma_f32_16x16x32_bf16 v[92:95], v[134:137], v[206:209], v[92:95]
	v_mfma_f32_16x16x32_bf16 v[88:91], v[162:165], v[206:209], v[88:91]
	v_mfma_f32_16x16x32_bf16 v[76:79], v[134:137], v[224:227], v[76:79]
	v_mfma_f32_16x16x32_bf16 v[72:75], v[162:165], v[224:227], v[72:75]
	s_setprio 0
	s_setprio 1
	v_mfma_f32_16x16x32_bf16 v[116:119], v[166:169], v[186:189], v[116:119]
	v_mfma_f32_16x16x32_bf16 v[112:115], v[178:181], v[186:189], v[112:115]
	v_mfma_f32_16x16x32_bf16 v[100:103], v[166:169], v[194:197], v[100:103]
	v_mfma_f32_16x16x32_bf16 v[96:99], v[178:181], v[194:197], v[96:99]
	v_mfma_f32_16x16x32_bf16 v[84:87], v[166:169], v[202:205], v[84:87]
	v_mfma_f32_16x16x32_bf16 v[80:83], v[178:181], v[202:205], v[80:83]
	v_mfma_f32_16x16x32_bf16 v[68:71], v[166:169], v[220:223], v[68:71]
	v_mfma_f32_16x16x32_bf16 v[64:67], v[178:181], v[220:223], v[64:67]
	v_mfma_f32_16x16x32_bf16 v[116:119], v[170:173], v[190:193], v[116:119]
	v_mfma_f32_16x16x32_bf16 v[112:115], v[182:185], v[190:193], v[112:115]
	v_mfma_f32_16x16x32_bf16 v[100:103], v[170:173], v[198:201], v[100:103]
	v_mfma_f32_16x16x32_bf16 v[96:99], v[182:185], v[198:201], v[96:99]
	v_mfma_f32_16x16x32_bf16 v[84:87], v[170:173], v[206:209], v[84:87]
	v_mfma_f32_16x16x32_bf16 v[80:83], v[182:185], v[206:209], v[80:83]
	v_mfma_f32_16x16x32_bf16 v[68:71], v[170:173], v[224:227], v[68:71]
	v_mfma_f32_16x16x32_bf16 v[64:67], v[182:185], v[224:227], v[64:67]
	s_setprio 0
	s_barrier
	s_add_i32 s8, s37, s33
	s_mov_b32 m0, s8
	ds_read_b128 v[186:189], v161 offset:49152
	ds_read_b128 v[190:193], v161 offset:50176
	ds_read_b128 v[194:197], v161 offset:51200
	ds_read_b128 v[198:201], v161 offset:52224
	ds_read_b128 v[202:205], v161 offset:53248
	ds_read_b128 v[206:209], v161 offset:54272
	ds_read_b128 v[220:223], v161 offset:55296
	ds_read_b128 v[224:227], v161 offset:56320
	s_add_u32 s98, s6, 0x80
	s_addc_u32 s99, s7, 0
	global_load_lds_dwordx4 v142, s[98:99]
	s_add_i32 m0, s8, 0x2000
	s_add_u32 s6, s6, 0x80080
	s_addc_u32 s7, s7, 0
	s_add_i32 s8, s54, s33
	s_add_u32 s98, s6, 0xfff80000
	s_addc_u32 s99, s7, -1
	global_load_lds_dwordx4 v138, s[98:99]
	s_mov_b32 m0, s8
	s_nop 0
	global_load_lds_dwordx4 v142, s[6:7]
	s_add_i32 m0, s8, 0x2000
	s_nop 0
	global_load_lds_dwordx4 v138, s[6:7]
	s_mov_b32 m0, s49
	s_nop 0
	global_load_lds_dwordx4 v144, s[60:61]
	s_mov_b32 m0, s50
	s_nop 0
	global_load_lds_dwordx4 v140, s[60:61]
	s_waitcnt vmcnt(8)
	s_waitcnt lgkmcnt(0)
	s_barrier
	s_setprio 1
	s_waitcnt lgkmcnt(0)
	v_mfma_f32_16x16x32_bf16 v[60:63], v[130:133], v[186:189], v[60:63]
	v_mfma_f32_16x16x32_bf16 v[56:59], v[154:157], v[186:189], v[56:59]
	v_mfma_f32_16x16x32_bf16 v[44:47], v[130:133], v[194:197], v[44:47]
	v_mfma_f32_16x16x32_bf16 v[40:43], v[154:157], v[194:197], v[40:43]
	v_mfma_f32_16x16x32_bf16 v[28:31], v[130:133], v[202:205], v[28:31]
	v_mfma_f32_16x16x32_bf16 v[24:27], v[154:157], v[202:205], v[24:27]
	v_mfma_f32_16x16x32_bf16 v[12:15], v[130:133], v[220:223], v[12:15]
	v_mfma_f32_16x16x32_bf16 v[8:11], v[154:157], v[220:223], v[8:11]
	v_mfma_f32_16x16x32_bf16 v[60:63], v[134:137], v[190:193], v[60:63]
	v_mfma_f32_16x16x32_bf16 v[56:59], v[162:165], v[190:193], v[56:59]
	v_mfma_f32_16x16x32_bf16 v[44:47], v[134:137], v[198:201], v[44:47]
	v_mfma_f32_16x16x32_bf16 v[40:43], v[162:165], v[198:201], v[40:43]
	v_mfma_f32_16x16x32_bf16 v[28:31], v[134:137], v[206:209], v[28:31]
	v_mfma_f32_16x16x32_bf16 v[24:27], v[162:165], v[206:209], v[24:27]
	v_mfma_f32_16x16x32_bf16 v[12:15], v[134:137], v[224:227], v[12:15]
	v_mfma_f32_16x16x32_bf16 v[8:11], v[162:165], v[224:227], v[8:11]
	s_setprio 0
	s_setprio 1
	v_mfma_f32_16x16x32_bf16 v[52:55], v[166:169], v[186:189], v[52:55]
	v_mfma_f32_16x16x32_bf16 v[48:51], v[178:181], v[186:189], v[48:51]
	v_mfma_f32_16x16x32_bf16 v[36:39], v[166:169], v[194:197], v[36:39]
	v_mfma_f32_16x16x32_bf16 v[32:35], v[178:181], v[194:197], v[32:35]
	v_mfma_f32_16x16x32_bf16 v[20:23], v[166:169], v[202:205], v[20:23]
	v_mfma_f32_16x16x32_bf16 v[16:19], v[178:181], v[202:205], v[16:19]
	v_mfma_f32_16x16x32_bf16 v[4:7], v[166:169], v[220:223], v[4:7]
	v_mfma_f32_16x16x32_bf16 v[0:3], v[178:181], v[220:223], v[0:3]
	v_mfma_f32_16x16x32_bf16 v[52:55], v[170:173], v[190:193], v[52:55]
	v_mfma_f32_16x16x32_bf16 v[48:51], v[182:185], v[190:193], v[48:51]
	v_mfma_f32_16x16x32_bf16 v[36:39], v[170:173], v[198:201], v[36:39]
	v_mfma_f32_16x16x32_bf16 v[32:35], v[182:185], v[198:201], v[32:35]
	v_mfma_f32_16x16x32_bf16 v[20:23], v[170:173], v[206:209], v[20:23]
	v_mfma_f32_16x16x32_bf16 v[16:19], v[182:185], v[206:209], v[16:19]
	v_mfma_f32_16x16x32_bf16 v[4:7], v[170:173], v[224:227], v[4:7]
	v_mfma_f32_16x16x32_bf16 v[0:3], v[182:185], v[224:227], v[0:3]
	s_setprio 0
	s_barrier
	s_add_i32 s36, s36, 2
	s_add_u32 s4, s4, 0x100
	s_addc_u32 s5, s5, 0
	s_add_u32 s34, s34, 0x100
	s_addc_u32 s35, s35, 0
	s_cmp_gt_u32 s36, 29
.LBB0_420:
	s_add_u32 s6, s4, 0xfff80080
	s_addc_u32 s7, s5, -1
	s_add_i32 s37, 0, 0x10000
	s_cmp_eq_u32 s36, 28
	s_cselect_b32 s9, s15, s7
	s_cselect_b32 s8, s30, s6
	s_cselect_b32 s7, s19, s35
	s_cselect_b32 s6, s31, s34
	s_add_i32 s56, 0, 0x14000
	ds_read_b128 v[130:133], v253
	ds_read_b128 v[134:137], v253 offset:1024
	ds_read_b128 v[154:157], v253 offset:2048
	ds_read_b128 v[162:165], v253 offset:3072
	ds_read_b128 v[166:169], v253 offset:16384
	ds_read_b128 v[170:173], v253 offset:17408
	ds_read_b128 v[178:181], v253 offset:18432
	ds_read_b128 v[182:185], v253 offset:19456
	s_add_i32 m0, s38, 0xc000
	ds_read_b128 v[186:189], v161
	ds_read_b128 v[190:193], v161 offset:1024
	ds_read_b128 v[194:197], v161 offset:2048
	ds_read_b128 v[198:201], v161 offset:3072
	ds_read_b128 v[202:205], v161 offset:4096
	ds_read_b128 v[206:209], v161 offset:5120
	ds_read_b128 v[220:223], v161 offset:6144
	ds_read_b128 v[224:227], v161 offset:7168
	global_load_lds_dwordx4 v150, s[4:5]
	s_add_i32 m0, s38, 0xe000
	s_nop 0
	global_load_lds_dwordx4 v152, s[4:5]
	s_waitcnt vmcnt(8)
	s_waitcnt lgkmcnt(0)
	s_barrier
	s_setprio 1
	s_waitcnt lgkmcnt(0)
	v_mfma_f32_16x16x32_bf16 v[124:127], v[130:133], v[186:189], v[124:127]
	v_mfma_f32_16x16x32_bf16 v[120:123], v[154:157], v[186:189], v[120:123]
	v_mfma_f32_16x16x32_bf16 v[108:111], v[130:133], v[194:197], v[108:111]
	v_mfma_f32_16x16x32_bf16 v[104:107], v[154:157], v[194:197], v[104:107]
	v_mfma_f32_16x16x32_bf16 v[92:95], v[130:133], v[202:205], v[92:95]
	v_mfma_f32_16x16x32_bf16 v[88:91], v[154:157], v[202:205], v[88:91]
	v_mfma_f32_16x16x32_bf16 v[76:79], v[130:133], v[220:223], v[76:79]
	v_mfma_f32_16x16x32_bf16 v[72:75], v[154:157], v[220:223], v[72:75]
	v_mfma_f32_16x16x32_bf16 v[124:127], v[134:137], v[190:193], v[124:127]
	v_mfma_f32_16x16x32_bf16 v[120:123], v[162:165], v[190:193], v[120:123]
	v_mfma_f32_16x16x32_bf16 v[108:111], v[134:137], v[198:201], v[108:111]
	v_mfma_f32_16x16x32_bf16 v[104:107], v[162:165], v[198:201], v[104:107]
	v_mfma_f32_16x16x32_bf16 v[92:95], v[134:137], v[206:209], v[92:95]
	v_mfma_f32_16x16x32_bf16 v[88:91], v[162:165], v[206:209], v[88:91]
	v_mfma_f32_16x16x32_bf16 v[76:79], v[134:137], v[224:227], v[76:79]
	v_mfma_f32_16x16x32_bf16 v[72:75], v[162:165], v[224:227], v[72:75]
	s_setprio 0
	s_setprio 1
	v_mfma_f32_16x16x32_bf16 v[116:119], v[166:169], v[186:189], v[116:119]
	v_mfma_f32_16x16x32_bf16 v[112:115], v[178:181], v[186:189], v[112:115]
	v_mfma_f32_16x16x32_bf16 v[100:103], v[166:169], v[194:197], v[100:103]
	v_mfma_f32_16x16x32_bf16 v[96:99], v[178:181], v[194:197], v[96:99]
	v_mfma_f32_16x16x32_bf16 v[84:87], v[166:169], v[202:205], v[84:87]
	v_mfma_f32_16x16x32_bf16 v[80:83], v[178:181], v[202:205], v[80:83]
	v_mfma_f32_16x16x32_bf16 v[68:71], v[166:169], v[220:223], v[68:71]
	v_mfma_f32_16x16x32_bf16 v[64:67], v[178:181], v[220:223], v[64:67]
	v_mfma_f32_16x16x32_bf16 v[116:119], v[170:173], v[190:193], v[116:119]
	v_mfma_f32_16x16x32_bf16 v[112:115], v[182:185], v[190:193], v[112:115]
	v_mfma_f32_16x16x32_bf16 v[100:103], v[170:173], v[198:201], v[100:103]
	v_mfma_f32_16x16x32_bf16 v[96:99], v[182:185], v[198:201], v[96:99]
	v_mfma_f32_16x16x32_bf16 v[84:87], v[170:173], v[206:209], v[84:87]
	v_mfma_f32_16x16x32_bf16 v[80:83], v[182:185], v[206:209], v[80:83]
	v_mfma_f32_16x16x32_bf16 v[68:71], v[170:173], v[224:227], v[68:71]
	v_mfma_f32_16x16x32_bf16 v[64:67], v[182:185], v[224:227], v[64:67]
	s_setprio 0
	s_barrier
	s_add_i32 s37, s37, s33
	s_mov_b32 m0, s37
	ds_read_b128 v[186:189], v161 offset:16384
	ds_read_b128 v[190:193], v161 offset:17408
	ds_read_b128 v[194:197], v161 offset:18432
	ds_read_b128 v[198:201], v161 offset:19456
	ds_read_b128 v[202:205], v161 offset:20480
	ds_read_b128 v[206:209], v161 offset:21504
	ds_read_b128 v[220:223], v161 offset:22528
	ds_read_b128 v[224:227], v161 offset:23552
	global_load_lds_dwordx4 v142, s[6:7]
	s_add_i32 m0, s37, 0x2000
	s_add_u32 s54, s6, 0x80000
	s_addc_u32 s55, s7, 0
	s_add_i32 s37, s56, s33
	global_load_lds_dwordx4 v138, s[6:7]
	s_mov_b32 m0, s37
	s_nop 0
	global_load_lds_dwordx4 v142, s[54:55]
	s_add_i32 m0, s37, 0x2000
	s_nop 0
	global_load_lds_dwordx4 v138, s[54:55]
	s_add_u32 s60, s8, 0x80
	s_addc_u32 s61, s9, 0
	s_mov_b32 m0, s38
	s_nop 0
	global_load_lds_dwordx4 v144, s[8:9]
	s_mov_b32 m0, s39
	s_nop 0
	global_load_lds_dwordx4 v140, s[8:9]
	s_waitcnt vmcnt(8)
	s_waitcnt lgkmcnt(0)
	s_barrier
	s_setprio 1
	s_waitcnt lgkmcnt(0)
	v_mfma_f32_16x16x32_bf16 v[60:63], v[130:133], v[186:189], v[60:63]
	v_mfma_f32_16x16x32_bf16 v[56:59], v[154:157], v[186:189], v[56:59]
	v_mfma_f32_16x16x32_bf16 v[44:47], v[130:133], v[194:197], v[44:47]
	v_mfma_f32_16x16x32_bf16 v[40:43], v[154:157], v[194:197], v[40:43]
	v_mfma_f32_16x16x32_bf16 v[28:31], v[130:133], v[202:205], v[28:31]
	v_mfma_f32_16x16x32_bf16 v[24:27], v[154:157], v[202:205], v[24:27]
	v_mfma_f32_16x16x32_bf16 v[12:15], v[130:133], v[220:223], v[12:15]
	v_mfma_f32_16x16x32_bf16 v[8:11], v[154:157], v[220:223], v[8:11]
	v_mfma_f32_16x16x32_bf16 v[60:63], v[134:137], v[190:193], v[60:63]
	v_mfma_f32_16x16x32_bf16 v[56:59], v[162:165], v[190:193], v[56:59]
	v_mfma_f32_16x16x32_bf16 v[44:47], v[134:137], v[198:201], v[44:47]
	v_mfma_f32_16x16x32_bf16 v[40:43], v[162:165], v[198:201], v[40:43]
	v_mfma_f32_16x16x32_bf16 v[28:31], v[134:137], v[206:209], v[28:31]
	v_mfma_f32_16x16x32_bf16 v[24:27], v[162:165], v[206:209], v[24:27]
	v_mfma_f32_16x16x32_bf16 v[12:15], v[134:137], v[224:227], v[12:15]
	v_mfma_f32_16x16x32_bf16 v[8:11], v[162:165], v[224:227], v[8:11]
	s_setprio 0
	s_setprio 1
	v_mfma_f32_16x16x32_bf16 v[52:55], v[166:169], v[186:189], v[52:55]
	v_mfma_f32_16x16x32_bf16 v[48:51], v[178:181], v[186:189], v[48:51]
	v_mfma_f32_16x16x32_bf16 v[36:39], v[166:169], v[194:197], v[36:39]
	v_mfma_f32_16x16x32_bf16 v[32:35], v[178:181], v[194:197], v[32:35]
	v_mfma_f32_16x16x32_bf16 v[20:23], v[166:169], v[202:205], v[20:23]
	v_mfma_f32_16x16x32_bf16 v[16:19], v[178:181], v[202:205], v[16:19]
	v_mfma_f32_16x16x32_bf16 v[4:7], v[166:169], v[220:223], v[4:7]
	v_mfma_f32_16x16x32_bf16 v[0:3], v[178:181], v[220:223], v[0:3]
	v_mfma_f32_16x16x32_bf16 v[52:55], v[170:173], v[190:193], v[52:55]
	v_mfma_f32_16x16x32_bf16 v[48:51], v[182:185], v[190:193], v[48:51]
	v_mfma_f32_16x16x32_bf16 v[36:39], v[170:173], v[198:201], v[36:39]
	v_mfma_f32_16x16x32_bf16 v[32:35], v[182:185], v[198:201], v[32:35]
	v_mfma_f32_16x16x32_bf16 v[20:23], v[170:173], v[206:209], v[20:23]
	v_mfma_f32_16x16x32_bf16 v[16:19], v[182:185], v[206:209], v[16:19]
	v_mfma_f32_16x16x32_bf16 v[4:7], v[170:173], v[224:227], v[4:7]
	v_mfma_f32_16x16x32_bf16 v[0:3], v[182:185], v[224:227], v[0:3]
	s_setprio 0
	s_barrier
	s_add_i32 s37, 0, 0x18000
	s_add_i32 s54, 0, 0x1c000
	ds_read_b128 v[130:133], v253 offset:32768
	ds_read_b128 v[134:137], v253 offset:33792
	ds_read_b128 v[154:157], v253 offset:34816
	ds_read_b128 v[162:165], v253 offset:35840
	ds_read_b128 v[166:169], v253 offset:49152
	ds_read_b128 v[170:173], v253 offset:50176
	ds_read_b128 v[178:181], v253 offset:51200
	ds_read_b128 v[182:185], v253 offset:52224
	s_add_u32 s8, s8, 0x80000
	s_addc_u32 s9, s9, 0
	s_mov_b32 m0, s40
	ds_read_b128 v[186:189], v161 offset:32768
	ds_read_b128 v[190:193], v161 offset:33792
	ds_read_b128 v[194:197], v161 offset:34816
	ds_read_b128 v[198:201], v161 offset:35840
	ds_read_b128 v[202:205], v161 offset:36864
	ds_read_b128 v[206:209], v161 offset:37888
	ds_read_b128 v[220:223], v161 offset:38912
	ds_read_b128 v[224:227], v161 offset:39936
	global_load_lds_dwordx4 v144, s[8:9]
	s_mov_b32 m0, s41
	s_nop 0
	global_load_lds_dwordx4 v140, s[8:9]
	s_waitcnt vmcnt(8)
	s_waitcnt lgkmcnt(0)
	s_barrier
	s_setprio 1
	s_waitcnt lgkmcnt(0)
	v_mfma_f32_16x16x32_bf16 v[124:127], v[130:133], v[186:189], v[124:127]
	v_mfma_f32_16x16x32_bf16 v[120:123], v[154:157], v[186:189], v[120:123]
	v_mfma_f32_16x16x32_bf16 v[108:111], v[130:133], v[194:197], v[108:111]
	v_mfma_f32_16x16x32_bf16 v[104:107], v[154:157], v[194:197], v[104:107]
	v_mfma_f32_16x16x32_bf16 v[92:95], v[130:133], v[202:205], v[92:95]
	v_mfma_f32_16x16x32_bf16 v[88:91], v[154:157], v[202:205], v[88:91]
	v_mfma_f32_16x16x32_bf16 v[76:79], v[130:133], v[220:223], v[76:79]
	v_mfma_f32_16x16x32_bf16 v[72:75], v[154:157], v[220:223], v[72:75]
	v_mfma_f32_16x16x32_bf16 v[124:127], v[134:137], v[190:193], v[124:127]
	v_mfma_f32_16x16x32_bf16 v[120:123], v[162:165], v[190:193], v[120:123]
	v_mfma_f32_16x16x32_bf16 v[108:111], v[134:137], v[198:201], v[108:111]
	v_mfma_f32_16x16x32_bf16 v[104:107], v[162:165], v[198:201], v[104:107]
	v_mfma_f32_16x16x32_bf16 v[92:95], v[134:137], v[206:209], v[92:95]
	v_mfma_f32_16x16x32_bf16 v[88:91], v[162:165], v[206:209], v[88:91]
	v_mfma_f32_16x16x32_bf16 v[76:79], v[134:137], v[224:227], v[76:79]
	v_mfma_f32_16x16x32_bf16 v[72:75], v[162:165], v[224:227], v[72:75]
	s_setprio 0
	s_setprio 1
	v_mfma_f32_16x16x32_bf16 v[116:119], v[166:169], v[186:189], v[116:119]
	v_mfma_f32_16x16x32_bf16 v[112:115], v[178:181], v[186:189], v[112:115]
	v_mfma_f32_16x16x32_bf16 v[100:103], v[166:169], v[194:197], v[100:103]
	v_mfma_f32_16x16x32_bf16 v[96:99], v[178:181], v[194:197], v[96:99]
	v_mfma_f32_16x16x32_bf16 v[84:87], v[166:169], v[202:205], v[84:87]
	v_mfma_f32_16x16x32_bf16 v[80:83], v[178:181], v[202:205], v[80:83]
	v_mfma_f32_16x16x32_bf16 v[68:71], v[166:169], v[220:223], v[68:71]
	v_mfma_f32_16x16x32_bf16 v[64:67], v[178:181], v[220:223], v[64:67]
	v_mfma_f32_16x16x32_bf16 v[116:119], v[170:173], v[190:193], v[116:119]
	v_mfma_f32_16x16x32_bf16 v[112:115], v[182:185], v[190:193], v[112:115]
	v_mfma_f32_16x16x32_bf16 v[100:103], v[170:173], v[198:201], v[100:103]
	v_mfma_f32_16x16x32_bf16 v[96:99], v[182:185], v[198:201], v[96:99]
	v_mfma_f32_16x16x32_bf16 v[84:87], v[170:173], v[206:209], v[84:87]
	v_mfma_f32_16x16x32_bf16 v[80:83], v[182:185], v[206:209], v[80:83]
	v_mfma_f32_16x16x32_bf16 v[68:71], v[170:173], v[224:227], v[68:71]
	v_mfma_f32_16x16x32_bf16 v[64:67], v[182:185], v[224:227], v[64:67]
	s_setprio 0
	s_barrier
	s_add_i32 s8, s37, s33
	s_mov_b32 m0, s8
	ds_read_b128 v[186:189], v161 offset:49152
	ds_read_b128 v[190:193], v161 offset:50176
	ds_read_b128 v[194:197], v161 offset:51200
	ds_read_b128 v[198:201], v161 offset:52224
	ds_read_b128 v[202:205], v161 offset:53248
	ds_read_b128 v[206:209], v161 offset:54272
	ds_read_b128 v[220:223], v161 offset:55296
	ds_read_b128 v[224:227], v161 offset:56320
	s_add_u32 s98, s6, 0x80
	s_addc_u32 s99, s7, 0
	global_load_lds_dwordx4 v142, s[98:99]
	s_add_i32 m0, s8, 0x2000
	s_add_u32 s6, s6, 0x80080
	s_addc_u32 s7, s7, 0
	s_add_i32 s8, s54, s33
	s_add_u32 s98, s6, 0xfff80000
	s_addc_u32 s99, s7, -1
	global_load_lds_dwordx4 v138, s[98:99]
	s_mov_b32 m0, s8
	s_nop 0
	global_load_lds_dwordx4 v142, s[6:7]
	s_add_i32 m0, s8, 0x2000
	s_nop 0
	global_load_lds_dwordx4 v138, s[6:7]
	s_mov_b32 m0, s49
	s_nop 0
	global_load_lds_dwordx4 v144, s[60:61]
	s_mov_b32 m0, s50
	s_nop 0
	global_load_lds_dwordx4 v140, s[60:61]
	s_waitcnt vmcnt(8)
	s_waitcnt lgkmcnt(0)
	s_barrier
	s_setprio 1
	s_waitcnt lgkmcnt(0)
	v_mfma_f32_16x16x32_bf16 v[60:63], v[130:133], v[186:189], v[60:63]
	v_mfma_f32_16x16x32_bf16 v[56:59], v[154:157], v[186:189], v[56:59]
	v_mfma_f32_16x16x32_bf16 v[44:47], v[130:133], v[194:197], v[44:47]
	v_mfma_f32_16x16x32_bf16 v[40:43], v[154:157], v[194:197], v[40:43]
	v_mfma_f32_16x16x32_bf16 v[28:31], v[130:133], v[202:205], v[28:31]
	v_mfma_f32_16x16x32_bf16 v[24:27], v[154:157], v[202:205], v[24:27]
	v_mfma_f32_16x16x32_bf16 v[12:15], v[130:133], v[220:223], v[12:15]
	v_mfma_f32_16x16x32_bf16 v[8:11], v[154:157], v[220:223], v[8:11]
	v_mfma_f32_16x16x32_bf16 v[60:63], v[134:137], v[190:193], v[60:63]
	v_mfma_f32_16x16x32_bf16 v[56:59], v[162:165], v[190:193], v[56:59]
	v_mfma_f32_16x16x32_bf16 v[44:47], v[134:137], v[198:201], v[44:47]
	v_mfma_f32_16x16x32_bf16 v[40:43], v[162:165], v[198:201], v[40:43]
	v_mfma_f32_16x16x32_bf16 v[28:31], v[134:137], v[206:209], v[28:31]
	v_mfma_f32_16x16x32_bf16 v[24:27], v[162:165], v[206:209], v[24:27]
	v_mfma_f32_16x16x32_bf16 v[12:15], v[134:137], v[224:227], v[12:15]
	v_mfma_f32_16x16x32_bf16 v[8:11], v[162:165], v[224:227], v[8:11]
	s_setprio 0
	s_setprio 1
	v_mfma_f32_16x16x32_bf16 v[52:55], v[166:169], v[186:189], v[52:55]
	v_mfma_f32_16x16x32_bf16 v[48:51], v[178:181], v[186:189], v[48:51]
	v_mfma_f32_16x16x32_bf16 v[36:39], v[166:169], v[194:197], v[36:39]
	v_mfma_f32_16x16x32_bf16 v[32:35], v[178:181], v[194:197], v[32:35]
	v_mfma_f32_16x16x32_bf16 v[20:23], v[166:169], v[202:205], v[20:23]
	v_mfma_f32_16x16x32_bf16 v[16:19], v[178:181], v[202:205], v[16:19]
	v_mfma_f32_16x16x32_bf16 v[4:7], v[166:169], v[220:223], v[4:7]
	v_mfma_f32_16x16x32_bf16 v[0:3], v[178:181], v[220:223], v[0:3]
	v_mfma_f32_16x16x32_bf16 v[52:55], v[170:173], v[190:193], v[52:55]
	v_mfma_f32_16x16x32_bf16 v[48:51], v[182:185], v[190:193], v[48:51]
	v_mfma_f32_16x16x32_bf16 v[36:39], v[170:173], v[198:201], v[36:39]
	v_mfma_f32_16x16x32_bf16 v[32:35], v[182:185], v[198:201], v[32:35]
	v_mfma_f32_16x16x32_bf16 v[20:23], v[170:173], v[206:209], v[20:23]
	v_mfma_f32_16x16x32_bf16 v[16:19], v[182:185], v[206:209], v[16:19]
	v_mfma_f32_16x16x32_bf16 v[4:7], v[170:173], v[224:227], v[4:7]
	v_mfma_f32_16x16x32_bf16 v[0:3], v[182:185], v[224:227], v[0:3]
	s_setprio 0
	s_barrier
	s_add_i32 s36, s36, 2
	s_add_u32 s4, s4, 0x100
	s_addc_u32 s5, s5, 0
	s_add_u32 s34, s34, 0x100
	s_addc_u32 s35, s35, 0
	s_cmp_gt_u32 s36, 29
	s_cbranch_scc0 .LBB0_420
	s_and_b64 vcc, exec, s[12:13]
	s_cbranch_vccz .LBB0_423
	s_barrier

.LBB0_523:
	s_ashr_i32 s15, s14, 31
	s_lshl_b64 s[18:19], s[14:15], 17
	s_add_u32 s18, s2, s18
	s_addc_u32 s19, s3, s19
	s_and_b64 s[30:31], s[30:31], exec
	s_cselect_b32 s13, s19, s25
	s_cselect_b32 s15, s18, s24
	s_mov_b32 s36, 0
	s_mov_b64 s[30:31], -1
	s_mov_b64 s[34:35], 0
	v_add_u32_e32 v253, 0x10000, v137
	s_add_u32 s37, s24, s36
	s_addc_u32 s42, s25, 0
	s_add_u32 s40, s37, 0x100
	s_addc_u32 s41, s42, 0
	s_and_b64 s[38:39], s[34:35], exec
	s_cselect_b32 s39, s13, s41
	s_cselect_b32 s38, s15, s40
	s_add_u32 s36, s22, s36
	s_addc_u32 s40, s23, 0
	s_add_u32 s36, s36, 0x100
	s_addc_u32 s40, s40, 0
	s_add_i32 s65, 0, 0x10000
	s_and_b64 s[34:35], s[34:35], exec
	s_cselect_b32 s41, s17, s40
	s_cselect_b32 s40, s16, s36
	s_add_i32 s35, 0, 0x14000
	s_add_u32 s46, s37, 0x10080
	s_addc_u32 s47, s42, 0
	s_add_i32 s64, s65, s26
	s_add_i32 m0, s27, 0xc000
	s_add_i32 s67, s27, 0xe000
	s_add_i32 s60, s64, 0x2000
	s_add_u32 s42, s40, 0xc0000
	ds_read_b128 v[140:143], v253
	ds_read_b128 v[144:147], v253 offset:1024
	ds_read_b128 v[148:151], v253 offset:2048
	ds_read_b128 v[152:155], v253 offset:3072
	s_addc_u32 s43, s41, 0
	s_add_i32 s63, s35, s26
	ds_read_b128 v[156:159], v253 offset:16384
	ds_read_b128 v[160:163], v253 offset:17408
	ds_read_b128 v[164:167], v253 offset:18432
	ds_read_b128 v[168:171], v253 offset:19456
	s_add_i32 s61, s63, 0x2000
	s_add_i32 s59, 0, 0x18000
	s_add_i32 s58, 0, 0x1c000
	s_add_u32 s36, s38, 0x10000
	s_addc_u32 s37, s39, 0
	s_add_i32 s57, s59, s26
	s_add_i32 s56, s57, 0x2000
	s_add_u32 s34, s40, 0xc0080
	s_addc_u32 s35, s41, 0
	s_add_i32 s66, s58, s26
	s_add_i32 s65, s66, 0x2000
	ds_read_b128 v[172:175], v138
	ds_read_b128 v[178:181], v138 offset:1024
	ds_read_b128 v[182:185], v138 offset:2048
	ds_read_b128 v[186:189], v138 offset:3072
	ds_read_b128 v[190:193], v138 offset:4096
	ds_read_b128 v[194:197], v138 offset:5120
	ds_read_b128 v[198:201], v138 offset:6144
	ds_read_b128 v[202:205], v138 offset:7168
	global_load_lds_dwordx4 v134, s[46:47]
	s_mov_b32 m0, s67
	s_nop 0
	global_load_lds_dwordx4 v130, s[46:47]
	s_waitcnt vmcnt(8)
	s_waitcnt lgkmcnt(0)
	s_barrier
	s_setprio 1
	s_waitcnt lgkmcnt(0)
	v_mfma_f32_16x16x32_bf16 v[124:127], v[140:143], v[172:175], 0
	v_mfma_f32_16x16x32_bf16 v[120:123], v[148:151], v[172:175], 0
	v_mfma_f32_16x16x32_bf16 v[116:119], v[140:143], v[182:185], 0
	v_mfma_f32_16x16x32_bf16 v[112:115], v[148:151], v[182:185], 0
	v_mfma_f32_16x16x32_bf16 v[100:103], v[140:143], v[190:193], 0
	v_mfma_f32_16x16x32_bf16 v[96:99], v[148:151], v[190:193], 0
	v_mfma_f32_16x16x32_bf16 v[84:87], v[140:143], v[198:201], 0
	v_mfma_f32_16x16x32_bf16 v[80:83], v[148:151], v[198:201], 0
	v_mfma_f32_16x16x32_bf16 v[124:127], v[144:147], v[178:181], v[124:127]
	v_mfma_f32_16x16x32_bf16 v[120:123], v[152:155], v[178:181], v[120:123]
	v_mfma_f32_16x16x32_bf16 v[116:119], v[144:147], v[186:189], v[116:119]
	v_mfma_f32_16x16x32_bf16 v[112:115], v[152:155], v[186:189], v[112:115]
	v_mfma_f32_16x16x32_bf16 v[100:103], v[144:147], v[194:197], v[100:103]
	v_mfma_f32_16x16x32_bf16 v[96:99], v[152:155], v[194:197], v[96:99]
	v_mfma_f32_16x16x32_bf16 v[84:87], v[144:147], v[202:205], v[84:87]
	v_mfma_f32_16x16x32_bf16 v[80:83], v[152:155], v[202:205], v[80:83]
	s_setprio 0
	s_setprio 1
	v_mfma_f32_16x16x32_bf16 v[108:111], v[156:159], v[172:175], 0
	v_mfma_f32_16x16x32_bf16 v[104:107], v[164:167], v[172:175], 0
	v_mfma_f32_16x16x32_bf16 v[92:95], v[156:159], v[182:185], 0
	v_mfma_f32_16x16x32_bf16 v[88:91], v[164:167], v[182:185], 0
	v_mfma_f32_16x16x32_bf16 v[76:79], v[156:159], v[190:193], 0
	v_mfma_f32_16x16x32_bf16 v[72:75], v[164:167], v[190:193], 0
	v_mfma_f32_16x16x32_bf16 v[68:71], v[156:159], v[198:201], 0
	v_mfma_f32_16x16x32_bf16 v[64:67], v[164:167], v[198:201], 0
	v_mfma_f32_16x16x32_bf16 v[108:111], v[160:163], v[178:181], v[108:111]
	v_mfma_f32_16x16x32_bf16 v[104:107], v[168:171], v[178:181], v[104:107]
	v_mfma_f32_16x16x32_bf16 v[92:95], v[160:163], v[186:189], v[92:95]
	v_mfma_f32_16x16x32_bf16 v[88:91], v[168:171], v[186:189], v[88:91]
	v_mfma_f32_16x16x32_bf16 v[76:79], v[160:163], v[194:197], v[76:79]
	v_mfma_f32_16x16x32_bf16 v[72:75], v[168:171], v[194:197], v[72:75]
	v_mfma_f32_16x16x32_bf16 v[68:71], v[160:163], v[202:205], v[68:71]
	v_mfma_f32_16x16x32_bf16 v[64:67], v[168:171], v[202:205], v[64:67]
	s_setprio 0
	s_barrier
	s_mov_b32 m0, s64
	ds_read_b128 v[172:175], v138 offset:16384
	ds_read_b128 v[178:181], v138 offset:17408
	ds_read_b128 v[182:185], v138 offset:18432
	ds_read_b128 v[186:189], v138 offset:19456
	ds_read_b128 v[190:193], v138 offset:20480
	ds_read_b128 v[194:197], v138 offset:21504
	ds_read_b128 v[198:201], v138 offset:22528
	ds_read_b128 v[202:205], v138 offset:23552
	global_load_lds_dwordx4 v132, s[40:41]
	s_mov_b32 m0, s60
	s_nop 0
	global_load_lds_dwordx4 v128, s[40:41]
	s_mov_b32 m0, s63
	s_nop 0
	global_load_lds_dwordx4 v132, s[42:43]
	s_mov_b32 m0, s61
	s_nop 0
	global_load_lds_dwordx4 v128, s[42:43]
	s_mov_b32 m0, s27
	s_nop 0
	global_load_lds_dwordx4 v134, s[38:39]
	s_mov_b32 m0, s33
	s_nop 0
	global_load_lds_dwordx4 v130, s[38:39]
	s_waitcnt vmcnt(8)
	s_waitcnt lgkmcnt(0)
	s_barrier
	s_setprio 1
	s_waitcnt lgkmcnt(0)
	v_mfma_f32_16x16x32_bf16 v[60:63], v[140:143], v[172:175], 0
	v_mfma_f32_16x16x32_bf16 v[56:59], v[148:151], v[172:175], 0
	v_mfma_f32_16x16x32_bf16 v[52:55], v[140:143], v[182:185], 0
	v_mfma_f32_16x16x32_bf16 v[48:51], v[148:151], v[182:185], 0
	v_mfma_f32_16x16x32_bf16 v[36:39], v[140:143], v[190:193], 0
	v_mfma_f32_16x16x32_bf16 v[32:35], v[148:151], v[190:193], 0
	v_mfma_f32_16x16x32_bf16 v[20:23], v[140:143], v[198:201], 0
	v_mfma_f32_16x16x32_bf16 v[16:19], v[148:151], v[198:201], 0
	v_mfma_f32_16x16x32_bf16 v[60:63], v[144:147], v[178:181], v[60:63]
	v_mfma_f32_16x16x32_bf16 v[56:59], v[152:155], v[178:181], v[56:59]
	v_mfma_f32_16x16x32_bf16 v[52:55], v[144:147], v[186:189], v[52:55]
	v_mfma_f32_16x16x32_bf16 v[48:51], v[152:155], v[186:189], v[48:51]
	v_mfma_f32_16x16x32_bf16 v[36:39], v[144:147], v[194:197], v[36:39]
	v_mfma_f32_16x16x32_bf16 v[32:35], v[152:155], v[194:197], v[32:35]
	v_mfma_f32_16x16x32_bf16 v[20:23], v[144:147], v[202:205], v[20:23]
	v_mfma_f32_16x16x32_bf16 v[16:19], v[152:155], v[202:205], v[16:19]
	s_setprio 0
	s_setprio 1
	v_mfma_f32_16x16x32_bf16 v[44:47], v[156:159], v[172:175], 0
	v_mfma_f32_16x16x32_bf16 v[40:43], v[164:167], v[172:175], 0
	v_mfma_f32_16x16x32_bf16 v[28:31], v[156:159], v[182:185], 0
	v_mfma_f32_16x16x32_bf16 v[24:27], v[164:167], v[182:185], 0
	v_mfma_f32_16x16x32_bf16 v[12:15], v[156:159], v[190:193], 0
	v_mfma_f32_16x16x32_bf16 v[8:11], v[164:167], v[190:193], 0
	v_mfma_f32_16x16x32_bf16 v[4:7], v[156:159], v[198:201], 0
	v_mfma_f32_16x16x32_bf16 v[0:3], v[164:167], v[198:201], 0
	v_mfma_f32_16x16x32_bf16 v[44:47], v[160:163], v[178:181], v[44:47]
	v_mfma_f32_16x16x32_bf16 v[40:43], v[168:171], v[178:181], v[40:43]
	v_mfma_f32_16x16x32_bf16 v[28:31], v[160:163], v[186:189], v[28:31]
	v_mfma_f32_16x16x32_bf16 v[24:27], v[168:171], v[186:189], v[24:27]
	v_mfma_f32_16x16x32_bf16 v[12:15], v[160:163], v[194:197], v[12:15]
	v_mfma_f32_16x16x32_bf16 v[8:11], v[168:171], v[194:197], v[8:11]
	v_mfma_f32_16x16x32_bf16 v[4:7], v[160:163], v[202:205], v[4:7]
	v_mfma_f32_16x16x32_bf16 v[0:3], v[168:171], v[202:205], v[0:3]
	s_setprio 0
	s_barrier
	ds_read_b128 v[140:143], v253 offset:32768
	ds_read_b128 v[144:147], v253 offset:33792
	ds_read_b128 v[148:151], v253 offset:34816
	ds_read_b128 v[152:155], v253 offset:35840
	ds_read_b128 v[156:159], v253 offset:49152
	ds_read_b128 v[160:163], v253 offset:50176
	ds_read_b128 v[164:167], v253 offset:51200
	ds_read_b128 v[168:171], v253 offset:52224
	s_mov_b32 m0, s44
	ds_read_b128 v[172:175], v138 offset:32768
	ds_read_b128 v[178:181], v138 offset:33792
	ds_read_b128 v[182:185], v138 offset:34816
	ds_read_b128 v[186:189], v138 offset:35840
	ds_read_b128 v[190:193], v138 offset:36864
	ds_read_b128 v[194:197], v138 offset:37888
	ds_read_b128 v[198:201], v138 offset:38912
	ds_read_b128 v[202:205], v138 offset:39936
	global_load_lds_dwordx4 v134, s[36:37]
	s_mov_b32 m0, s45
	s_nop 0
	global_load_lds_dwordx4 v130, s[36:37]
	s_waitcnt vmcnt(8)
	s_waitcnt lgkmcnt(0)
	s_barrier
	s_setprio 1
	s_waitcnt lgkmcnt(0)
	v_mfma_f32_16x16x32_bf16 v[124:127], v[140:143], v[172:175], v[124:127]
	v_mfma_f32_16x16x32_bf16 v[120:123], v[148:151], v[172:175], v[120:123]
	v_mfma_f32_16x16x32_bf16 v[116:119], v[140:143], v[182:185], v[116:119]
	v_mfma_f32_16x16x32_bf16 v[112:115], v[148:151], v[182:185], v[112:115]
	v_mfma_f32_16x16x32_bf16 v[100:103], v[140:143], v[190:193], v[100:103]
	v_mfma_f32_16x16x32_bf16 v[96:99], v[148:151], v[190:193], v[96:99]
	v_mfma_f32_16x16x32_bf16 v[84:87], v[140:143], v[198:201], v[84:87]
	v_mfma_f32_16x16x32_bf16 v[80:83], v[148:151], v[198:201], v[80:83]
	v_mfma_f32_16x16x32_bf16 v[124:127], v[144:147], v[178:181], v[124:127]
	v_mfma_f32_16x16x32_bf16 v[120:123], v[152:155], v[178:181], v[120:123]
	v_mfma_f32_16x16x32_bf16 v[116:119], v[144:147], v[186:189], v[116:119]
	v_mfma_f32_16x16x32_bf16 v[112:115], v[152:155], v[186:189], v[112:115]
	v_mfma_f32_16x16x32_bf16 v[100:103], v[144:147], v[194:197], v[100:103]
	v_mfma_f32_16x16x32_bf16 v[96:99], v[152:155], v[194:197], v[96:99]
	v_mfma_f32_16x16x32_bf16 v[84:87], v[144:147], v[202:205], v[84:87]
	v_mfma_f32_16x16x32_bf16 v[80:83], v[152:155], v[202:205], v[80:83]
	s_setprio 0
	s_setprio 1
	v_mfma_f32_16x16x32_bf16 v[108:111], v[156:159], v[172:175], v[108:111]
	v_mfma_f32_16x16x32_bf16 v[104:107], v[164:167], v[172:175], v[104:107]
	v_mfma_f32_16x16x32_bf16 v[92:95], v[156:159], v[182:185], v[92:95]
	v_mfma_f32_16x16x32_bf16 v[88:91], v[164:167], v[182:185], v[88:91]
	v_mfma_f32_16x16x32_bf16 v[76:79], v[156:159], v[190:193], v[76:79]
	v_mfma_f32_16x16x32_bf16 v[72:75], v[164:167], v[190:193], v[72:75]
	v_mfma_f32_16x16x32_bf16 v[68:71], v[156:159], v[198:201], v[68:71]
	v_mfma_f32_16x16x32_bf16 v[64:67], v[164:167], v[198:201], v[64:67]
	v_mfma_f32_16x16x32_bf16 v[108:111], v[160:163], v[178:181], v[108:111]
	v_mfma_f32_16x16x32_bf16 v[104:107], v[168:171], v[178:181], v[104:107]
	v_mfma_f32_16x16x32_bf16 v[92:95], v[160:163], v[186:189], v[92:95]
	v_mfma_f32_16x16x32_bf16 v[88:91], v[168:171], v[186:189], v[88:91]
	v_mfma_f32_16x16x32_bf16 v[76:79], v[160:163], v[194:197], v[76:79]
	v_mfma_f32_16x16x32_bf16 v[72:75], v[168:171], v[194:197], v[72:75]
	v_mfma_f32_16x16x32_bf16 v[68:71], v[160:163], v[202:205], v[68:71]
	v_mfma_f32_16x16x32_bf16 v[64:67], v[168:171], v[202:205], v[64:67]
	s_setprio 0
	s_barrier
	s_mov_b32 m0, s57
	ds_read_b128 v[172:175], v138 offset:49152
	ds_read_b128 v[178:181], v138 offset:50176
	ds_read_b128 v[182:185], v138 offset:51200
	ds_read_b128 v[186:189], v138 offset:52224
	ds_read_b128 v[190:193], v138 offset:53248
	ds_read_b128 v[194:197], v138 offset:54272
	ds_read_b128 v[198:201], v138 offset:55296
	ds_read_b128 v[202:205], v138 offset:56320
	s_add_u32 s98, s40, 0x80
	s_addc_u32 s99, s41, 0
	global_load_lds_dwordx4 v132, s[98:99]
	s_mov_b32 m0, s56
	s_nop 0
	s_add_u32 s98, s40, 0x80
	s_addc_u32 s99, s41, 0
	global_load_lds_dwordx4 v128, s[98:99]
	s_mov_b32 m0, s66
	s_nop 0
	global_load_lds_dwordx4 v132, s[34:35]
	s_mov_b32 m0, s65
	s_nop 0
	global_load_lds_dwordx4 v128, s[34:35]
	s_mov_b32 m0, s50
	s_nop 0
	s_add_u32 s98, s38, 0x80
	s_addc_u32 s99, s39, 0
	global_load_lds_dwordx4 v134, s[98:99]
	s_mov_b32 m0, s51
	s_nop 0
	s_add_u32 s98, s38, 0x80
	s_addc_u32 s99, s39, 0
	global_load_lds_dwordx4 v130, s[98:99]
	s_waitcnt vmcnt(8)
	s_waitcnt lgkmcnt(0)
	s_barrier
	s_setprio 1
	s_waitcnt lgkmcnt(0)
	v_mfma_f32_16x16x32_bf16 v[60:63], v[140:143], v[172:175], v[60:63]
	v_mfma_f32_16x16x32_bf16 v[56:59], v[148:151], v[172:175], v[56:59]
	v_mfma_f32_16x16x32_bf16 v[52:55], v[140:143], v[182:185], v[52:55]
	v_mfma_f32_16x16x32_bf16 v[48:51], v[148:151], v[182:185], v[48:51]
	v_mfma_f32_16x16x32_bf16 v[36:39], v[140:143], v[190:193], v[36:39]
	v_mfma_f32_16x16x32_bf16 v[32:35], v[148:151], v[190:193], v[32:35]
	v_mfma_f32_16x16x32_bf16 v[20:23], v[140:143], v[198:201], v[20:23]
	v_mfma_f32_16x16x32_bf16 v[16:19], v[148:151], v[198:201], v[16:19]
	v_mfma_f32_16x16x32_bf16 v[60:63], v[144:147], v[178:181], v[60:63]
	v_mfma_f32_16x16x32_bf16 v[56:59], v[152:155], v[178:181], v[56:59]
	v_mfma_f32_16x16x32_bf16 v[52:55], v[144:147], v[186:189], v[52:55]
	v_mfma_f32_16x16x32_bf16 v[48:51], v[152:155], v[186:189], v[48:51]
	v_mfma_f32_16x16x32_bf16 v[36:39], v[144:147], v[194:197], v[36:39]
	v_mfma_f32_16x16x32_bf16 v[32:35], v[152:155], v[194:197], v[32:35]
	v_mfma_f32_16x16x32_bf16 v[20:23], v[144:147], v[202:205], v[20:23]
	v_mfma_f32_16x16x32_bf16 v[16:19], v[152:155], v[202:205], v[16:19]
	s_setprio 0
	s_setprio 1
	v_mfma_f32_16x16x32_bf16 v[44:47], v[156:159], v[172:175], v[44:47]
	v_mfma_f32_16x16x32_bf16 v[40:43], v[164:167], v[172:175], v[40:43]
	v_mfma_f32_16x16x32_bf16 v[28:31], v[156:159], v[182:185], v[28:31]
	v_mfma_f32_16x16x32_bf16 v[24:27], v[164:167], v[182:185], v[24:27]
	v_mfma_f32_16x16x32_bf16 v[12:15], v[156:159], v[190:193], v[12:15]
	v_mfma_f32_16x16x32_bf16 v[8:11], v[164:167], v[190:193], v[8:11]
	v_mfma_f32_16x16x32_bf16 v[4:7], v[156:159], v[198:201], v[4:7]
	v_mfma_f32_16x16x32_bf16 v[0:3], v[164:167], v[198:201], v[0:3]
	v_mfma_f32_16x16x32_bf16 v[44:47], v[160:163], v[178:181], v[44:47]
	v_mfma_f32_16x16x32_bf16 v[40:43], v[168:171], v[178:181], v[40:43]
	v_mfma_f32_16x16x32_bf16 v[28:31], v[160:163], v[186:189], v[28:31]
	v_mfma_f32_16x16x32_bf16 v[24:27], v[168:171], v[186:189], v[24:27]
	v_mfma_f32_16x16x32_bf16 v[12:15], v[160:163], v[194:197], v[12:15]
	v_mfma_f32_16x16x32_bf16 v[8:11], v[168:171], v[194:197], v[8:11]
	v_mfma_f32_16x16x32_bf16 v[4:7], v[160:163], v[202:205], v[4:7]
	v_mfma_f32_16x16x32_bf16 v[0:3], v[168:171], v[202:205], v[0:3]
	s_setprio 0
	s_barrier
	s_movk_i32 s36, 0x100
	s_andn2_b64 vcc, exec, s[30:31]
	s_mov_b64 s[34:35], -1
	s_mov_b64 s[30:31], 0
.LBB0_524:
	s_add_u32 s37, s24, s36
	s_addc_u32 s42, s25, 0
	s_add_u32 s40, s37, 0x100
	s_addc_u32 s41, s42, 0
	s_and_b64 s[38:39], s[34:35], exec
	s_cselect_b32 s39, s13, s41
	s_cselect_b32 s38, s15, s40
	s_add_u32 s36, s22, s36
	s_addc_u32 s40, s23, 0
	s_add_u32 s36, s36, 0x100
	s_addc_u32 s40, s40, 0
	s_add_i32 s65, 0, 0x10000
	s_and_b64 s[34:35], s[34:35], exec
	s_cselect_b32 s41, s17, s40
	s_cselect_b32 s40, s16, s36
	s_add_i32 s35, 0, 0x14000
	s_add_u32 s46, s37, 0x10080
	s_addc_u32 s47, s42, 0
	s_add_i32 s64, s65, s26
	s_add_i32 m0, s27, 0xc000
	s_add_i32 s67, s27, 0xe000
	s_add_i32 s60, s64, 0x2000
	s_add_u32 s42, s40, 0xc0000
	ds_read_b128 v[140:143], v253
	ds_read_b128 v[144:147], v253 offset:1024
	ds_read_b128 v[148:151], v253 offset:2048
	ds_read_b128 v[152:155], v253 offset:3072
	s_addc_u32 s43, s41, 0
	s_add_i32 s63, s35, s26
	ds_read_b128 v[156:159], v253 offset:16384
	ds_read_b128 v[160:163], v253 offset:17408
	ds_read_b128 v[164:167], v253 offset:18432
	ds_read_b128 v[168:171], v253 offset:19456
	s_add_i32 s61, s63, 0x2000
	s_add_i32 s59, 0, 0x18000
	s_add_i32 s58, 0, 0x1c000
	s_add_u32 s36, s38, 0x10000
	s_addc_u32 s37, s39, 0
	s_add_i32 s57, s59, s26
	s_add_i32 s56, s57, 0x2000
	s_add_u32 s34, s40, 0xc0080
	s_addc_u32 s35, s41, 0
	s_add_i32 s66, s58, s26
	s_add_i32 s65, s66, 0x2000
	ds_read_b128 v[172:175], v138
	ds_read_b128 v[178:181], v138 offset:1024
	ds_read_b128 v[182:185], v138 offset:2048
	ds_read_b128 v[186:189], v138 offset:3072
	ds_read_b128 v[190:193], v138 offset:4096
	ds_read_b128 v[194:197], v138 offset:5120
	ds_read_b128 v[198:201], v138 offset:6144
	ds_read_b128 v[202:205], v138 offset:7168
	global_load_lds_dwordx4 v134, s[46:47]
	s_mov_b32 m0, s67
	s_nop 0
	global_load_lds_dwordx4 v130, s[46:47]
	s_waitcnt vmcnt(8)
	s_waitcnt lgkmcnt(0)
	s_barrier
	s_setprio 1
	s_waitcnt lgkmcnt(0)
	v_mfma_f32_16x16x32_bf16 v[124:127], v[140:143], v[172:175], v[124:127]
	v_mfma_f32_16x16x32_bf16 v[120:123], v[148:151], v[172:175], v[120:123]
	v_mfma_f32_16x16x32_bf16 v[116:119], v[140:143], v[182:185], v[116:119]
	v_mfma_f32_16x16x32_bf16 v[112:115], v[148:151], v[182:185], v[112:115]
	v_mfma_f32_16x16x32_bf16 v[100:103], v[140:143], v[190:193], v[100:103]
	v_mfma_f32_16x16x32_bf16 v[96:99], v[148:151], v[190:193], v[96:99]
	v_mfma_f32_16x16x32_bf16 v[84:87], v[140:143], v[198:201], v[84:87]
	v_mfma_f32_16x16x32_bf16 v[80:83], v[148:151], v[198:201], v[80:83]
	v_mfma_f32_16x16x32_bf16 v[124:127], v[144:147], v[178:181], v[124:127]
	v_mfma_f32_16x16x32_bf16 v[120:123], v[152:155], v[178:181], v[120:123]
	v_mfma_f32_16x16x32_bf16 v[116:119], v[144:147], v[186:189], v[116:119]
	v_mfma_f32_16x16x32_bf16 v[112:115], v[152:155], v[186:189], v[112:115]
	v_mfma_f32_16x16x32_bf16 v[100:103], v[144:147], v[194:197], v[100:103]
	v_mfma_f32_16x16x32_bf16 v[96:99], v[152:155], v[194:197], v[96:99]
	v_mfma_f32_16x16x32_bf16 v[84:87], v[144:147], v[202:205], v[84:87]
	v_mfma_f32_16x16x32_bf16 v[80:83], v[152:155], v[202:205], v[80:83]
	s_setprio 0
	s_setprio 1
	v_mfma_f32_16x16x32_bf16 v[108:111], v[156:159], v[172:175], v[108:111]
	v_mfma_f32_16x16x32_bf16 v[104:107], v[164:167], v[172:175], v[104:107]
	v_mfma_f32_16x16x32_bf16 v[92:95], v[156:159], v[182:185], v[92:95]
	v_mfma_f32_16x16x32_bf16 v[88:91], v[164:167], v[182:185], v[88:91]
	v_mfma_f32_16x16x32_bf16 v[76:79], v[156:159], v[190:193], v[76:79]
	v_mfma_f32_16x16x32_bf16 v[72:75], v[164:167], v[190:193], v[72:75]
	v_mfma_f32_16x16x32_bf16 v[68:71], v[156:159], v[198:201], v[68:71]
	v_mfma_f32_16x16x32_bf16 v[64:67], v[164:167], v[198:201], v[64:67]
	v_mfma_f32_16x16x32_bf16 v[108:111], v[160:163], v[178:181], v[108:111]
	v_mfma_f32_16x16x32_bf16 v[104:107], v[168:171], v[178:181], v[104:107]
	v_mfma_f32_16x16x32_bf16 v[92:95], v[160:163], v[186:189], v[92:95]
	v_mfma_f32_16x16x32_bf16 v[88:91], v[168:171], v[186:189], v[88:91]
	v_mfma_f32_16x16x32_bf16 v[76:79], v[160:163], v[194:197], v[76:79]
	v_mfma_f32_16x16x32_bf16 v[72:75], v[168:171], v[194:197], v[72:75]
	v_mfma_f32_16x16x32_bf16 v[68:71], v[160:163], v[202:205], v[68:71]
	v_mfma_f32_16x16x32_bf16 v[64:67], v[168:171], v[202:205], v[64:67]
	s_setprio 0
	s_barrier
	s_mov_b32 m0, s64
	ds_read_b128 v[172:175], v138 offset:16384
	ds_read_b128 v[178:181], v138 offset:17408
	ds_read_b128 v[182:185], v138 offset:18432
	ds_read_b128 v[186:189], v138 offset:19456
	ds_read_b128 v[190:193], v138 offset:20480
	ds_read_b128 v[194:197], v138 offset:21504
	ds_read_b128 v[198:201], v138 offset:22528
	ds_read_b128 v[202:205], v138 offset:23552
	global_load_lds_dwordx4 v132, s[40:41]
	s_mov_b32 m0, s60
	s_nop 0
	global_load_lds_dwordx4 v128, s[40:41]
	s_mov_b32 m0, s63
	s_nop 0
	global_load_lds_dwordx4 v132, s[42:43]
	s_mov_b32 m0, s61
	s_nop 0
	global_load_lds_dwordx4 v128, s[42:43]
	s_mov_b32 m0, s27
	s_nop 0
	global_load_lds_dwordx4 v134, s[38:39]
	s_mov_b32 m0, s33
	s_nop 0
	global_load_lds_dwordx4 v130, s[38:39]
	s_waitcnt vmcnt(8)
	s_waitcnt lgkmcnt(0)
	s_barrier
	s_setprio 1
	s_waitcnt lgkmcnt(0)
	v_mfma_f32_16x16x32_bf16 v[60:63], v[140:143], v[172:175], v[60:63]
	v_mfma_f32_16x16x32_bf16 v[56:59], v[148:151], v[172:175], v[56:59]
	v_mfma_f32_16x16x32_bf16 v[52:55], v[140:143], v[182:185], v[52:55]
	v_mfma_f32_16x16x32_bf16 v[48:51], v[148:151], v[182:185], v[48:51]
	v_mfma_f32_16x16x32_bf16 v[36:39], v[140:143], v[190:193], v[36:39]
	v_mfma_f32_16x16x32_bf16 v[32:35], v[148:151], v[190:193], v[32:35]
	v_mfma_f32_16x16x32_bf16 v[20:23], v[140:143], v[198:201], v[20:23]
	v_mfma_f32_16x16x32_bf16 v[16:19], v[148:151], v[198:201], v[16:19]
	v_mfma_f32_16x16x32_bf16 v[60:63], v[144:147], v[178:181], v[60:63]
	v_mfma_f32_16x16x32_bf16 v[56:59], v[152:155], v[178:181], v[56:59]
	v_mfma_f32_16x16x32_bf16 v[52:55], v[144:147], v[186:189], v[52:55]
	v_mfma_f32_16x16x32_bf16 v[48:51], v[152:155], v[186:189], v[48:51]
	v_mfma_f32_16x16x32_bf16 v[36:39], v[144:147], v[194:197], v[36:39]
	v_mfma_f32_16x16x32_bf16 v[32:35], v[152:155], v[194:197], v[32:35]
	v_mfma_f32_16x16x32_bf16 v[20:23], v[144:147], v[202:205], v[20:23]
	v_mfma_f32_16x16x32_bf16 v[16:19], v[152:155], v[202:205], v[16:19]
	s_setprio 0
	s_setprio 1
	v_mfma_f32_16x16x32_bf16 v[44:47], v[156:159], v[172:175], v[44:47]
	v_mfma_f32_16x16x32_bf16 v[40:43], v[164:167], v[172:175], v[40:43]
	v_mfma_f32_16x16x32_bf16 v[28:31], v[156:159], v[182:185], v[28:31]
	v_mfma_f32_16x16x32_bf16 v[24:27], v[164:167], v[182:185], v[24:27]
	v_mfma_f32_16x16x32_bf16 v[12:15], v[156:159], v[190:193], v[12:15]
	v_mfma_f32_16x16x32_bf16 v[8:11], v[164:167], v[190:193], v[8:11]
	v_mfma_f32_16x16x32_bf16 v[4:7], v[156:159], v[198:201], v[4:7]
	v_mfma_f32_16x16x32_bf16 v[0:3], v[164:167], v[198:201], v[0:3]
	v_mfma_f32_16x16x32_bf16 v[44:47], v[160:163], v[178:181], v[44:47]
	v_mfma_f32_16x16x32_bf16 v[40:43], v[168:171], v[178:181], v[40:43]
	v_mfma_f32_16x16x32_bf16 v[28:31], v[160:163], v[186:189], v[28:31]
	v_mfma_f32_16x16x32_bf16 v[24:27], v[168:171], v[186:189], v[24:27]
	v_mfma_f32_16x16x32_bf16 v[12:15], v[160:163], v[194:197], v[12:15]
	v_mfma_f32_16x16x32_bf16 v[8:11], v[168:171], v[194:197], v[8:11]
	v_mfma_f32_16x16x32_bf16 v[4:7], v[160:163], v[202:205], v[4:7]
	v_mfma_f32_16x16x32_bf16 v[0:3], v[168:171], v[202:205], v[0:3]
	s_setprio 0
	s_barrier
	ds_read_b128 v[140:143], v253 offset:32768
	ds_read_b128 v[144:147], v253 offset:33792
	ds_read_b128 v[148:151], v253 offset:34816
	ds_read_b128 v[152:155], v253 offset:35840
	ds_read_b128 v[156:159], v253 offset:49152
	ds_read_b128 v[160:163], v253 offset:50176
	ds_read_b128 v[164:167], v253 offset:51200
	ds_read_b128 v[168:171], v253 offset:52224
	s_mov_b32 m0, s44
	ds_read_b128 v[172:175], v138 offset:32768
	ds_read_b128 v[178:181], v138 offset:33792
	ds_read_b128 v[182:185], v138 offset:34816
	ds_read_b128 v[186:189], v138 offset:35840
	ds_read_b128 v[190:193], v138 offset:36864
	ds_read_b128 v[194:197], v138 offset:37888
	ds_read_b128 v[198:201], v138 offset:38912
	ds_read_b128 v[202:205], v138 offset:39936
	global_load_lds_dwordx4 v134, s[36:37]
	s_mov_b32 m0, s45
	s_nop 0
	global_load_lds_dwordx4 v130, s[36:37]
	s_waitcnt vmcnt(8)
	s_waitcnt lgkmcnt(0)
	s_barrier
	s_setprio 1
	s_waitcnt lgkmcnt(0)
	v_mfma_f32_16x16x32_bf16 v[124:127], v[140:143], v[172:175], v[124:127]
	v_mfma_f32_16x16x32_bf16 v[120:123], v[148:151], v[172:175], v[120:123]
	v_mfma_f32_16x16x32_bf16 v[116:119], v[140:143], v[182:185], v[116:119]
	v_mfma_f32_16x16x32_bf16 v[112:115], v[148:151], v[182:185], v[112:115]
	v_mfma_f32_16x16x32_bf16 v[100:103], v[140:143], v[190:193], v[100:103]
	v_mfma_f32_16x16x32_bf16 v[96:99], v[148:151], v[190:193], v[96:99]
	v_mfma_f32_16x16x32_bf16 v[84:87], v[140:143], v[198:201], v[84:87]
	v_mfma_f32_16x16x32_bf16 v[80:83], v[148:151], v[198:201], v[80:83]
	v_mfma_f32_16x16x32_bf16 v[124:127], v[144:147], v[178:181], v[124:127]
	v_mfma_f32_16x16x32_bf16 v[120:123], v[152:155], v[178:181], v[120:123]
	v_mfma_f32_16x16x32_bf16 v[116:119], v[144:147], v[186:189], v[116:119]
	v_mfma_f32_16x16x32_bf16 v[112:115], v[152:155], v[186:189], v[112:115]
	v_mfma_f32_16x16x32_bf16 v[100:103], v[144:147], v[194:197], v[100:103]
	v_mfma_f32_16x16x32_bf16 v[96:99], v[152:155], v[194:197], v[96:99]
	v_mfma_f32_16x16x32_bf16 v[84:87], v[144:147], v[202:205], v[84:87]
	v_mfma_f32_16x16x32_bf16 v[80:83], v[152:155], v[202:205], v[80:83]
	s_setprio 0
	s_setprio 1
	v_mfma_f32_16x16x32_bf16 v[108:111], v[156:159], v[172:175], v[108:111]
	v_mfma_f32_16x16x32_bf16 v[104:107], v[164:167], v[172:175], v[104:107]
	v_mfma_f32_16x16x32_bf16 v[92:95], v[156:159], v[182:185], v[92:95]
	v_mfma_f32_16x16x32_bf16 v[88:91], v[164:167], v[182:185], v[88:91]
	v_mfma_f32_16x16x32_bf16 v[76:79], v[156:159], v[190:193], v[76:79]
	v_mfma_f32_16x16x32_bf16 v[72:75], v[164:167], v[190:193], v[72:75]
	v_mfma_f32_16x16x32_bf16 v[68:71], v[156:159], v[198:201], v[68:71]
	v_mfma_f32_16x16x32_bf16 v[64:67], v[164:167], v[198:201], v[64:67]
	v_mfma_f32_16x16x32_bf16 v[108:111], v[160:163], v[178:181], v[108:111]
	v_mfma_f32_16x16x32_bf16 v[104:107], v[168:171], v[178:181], v[104:107]
	v_mfma_f32_16x16x32_bf16 v[92:95], v[160:163], v[186:189], v[92:95]
	v_mfma_f32_16x16x32_bf16 v[88:91], v[168:171], v[186:189], v[88:91]
	v_mfma_f32_16x16x32_bf16 v[76:79], v[160:163], v[194:197], v[76:79]
	v_mfma_f32_16x16x32_bf16 v[72:75], v[168:171], v[194:197], v[72:75]
	v_mfma_f32_16x16x32_bf16 v[68:71], v[160:163], v[202:205], v[68:71]
	v_mfma_f32_16x16x32_bf16 v[64:67], v[168:171], v[202:205], v[64:67]
	s_setprio 0
	s_barrier
	s_mov_b32 m0, s57
	ds_read_b128 v[172:175], v138 offset:49152
	ds_read_b128 v[178:181], v138 offset:50176
	ds_read_b128 v[182:185], v138 offset:51200
	ds_read_b128 v[186:189], v138 offset:52224
	ds_read_b128 v[190:193], v138 offset:53248
	ds_read_b128 v[194:197], v138 offset:54272
	ds_read_b128 v[198:201], v138 offset:55296
	ds_read_b128 v[202:205], v138 offset:56320
	s_add_u32 s98, s40, 0x80
	s_addc_u32 s99, s41, 0
	global_load_lds_dwordx4 v132, s[98:99]
	s_mov_b32 m0, s56
	s_nop 0
	s_add_u32 s98, s40, 0x80
	s_addc_u32 s99, s41, 0
	global_load_lds_dwordx4 v128, s[98:99]
	s_mov_b32 m0, s66
	s_nop 0
	global_load_lds_dwordx4 v132, s[34:35]
	s_mov_b32 m0, s65
	s_nop 0
	global_load_lds_dwordx4 v128, s[34:35]
	s_mov_b32 m0, s50
	s_nop 0
	s_add_u32 s98, s38, 0x80
	s_addc_u32 s99, s39, 0
	global_load_lds_dwordx4 v134, s[98:99]
	s_mov_b32 m0, s51
	s_nop 0
	s_add_u32 s98, s38, 0x80
	s_addc_u32 s99, s39, 0
	global_load_lds_dwordx4 v130, s[98:99]
	s_waitcnt vmcnt(8)
	s_waitcnt lgkmcnt(0)
	s_barrier
	s_setprio 1
	s_waitcnt lgkmcnt(0)
	v_mfma_f32_16x16x32_bf16 v[60:63], v[140:143], v[172:175], v[60:63]
	v_mfma_f32_16x16x32_bf16 v[56:59], v[148:151], v[172:175], v[56:59]
	v_mfma_f32_16x16x32_bf16 v[52:55], v[140:143], v[182:185], v[52:55]
	v_mfma_f32_16x16x32_bf16 v[48:51], v[148:151], v[182:185], v[48:51]
	v_mfma_f32_16x16x32_bf16 v[36:39], v[140:143], v[190:193], v[36:39]
	v_mfma_f32_16x16x32_bf16 v[32:35], v[148:151], v[190:193], v[32:35]
	v_mfma_f32_16x16x32_bf16 v[20:23], v[140:143], v[198:201], v[20:23]
	v_mfma_f32_16x16x32_bf16 v[16:19], v[148:151], v[198:201], v[16:19]
	v_mfma_f32_16x16x32_bf16 v[60:63], v[144:147], v[178:181], v[60:63]
	v_mfma_f32_16x16x32_bf16 v[56:59], v[152:155], v[178:181], v[56:59]
	v_mfma_f32_16x16x32_bf16 v[52:55], v[144:147], v[186:189], v[52:55]
	v_mfma_f32_16x16x32_bf16 v[48:51], v[152:155], v[186:189], v[48:51]
	v_mfma_f32_16x16x32_bf16 v[36:39], v[144:147], v[194:197], v[36:39]
	v_mfma_f32_16x16x32_bf16 v[32:35], v[152:155], v[194:197], v[32:35]
	v_mfma_f32_16x16x32_bf16 v[20:23], v[144:147], v[202:205], v[20:23]
	v_mfma_f32_16x16x32_bf16 v[16:19], v[152:155], v[202:205], v[16:19]
	s_setprio 0
	s_setprio 1
	v_mfma_f32_16x16x32_bf16 v[44:47], v[156:159], v[172:175], v[44:47]
	v_mfma_f32_16x16x32_bf16 v[40:43], v[164:167], v[172:175], v[40:43]
	v_mfma_f32_16x16x32_bf16 v[28:31], v[156:159], v[182:185], v[28:31]
	v_mfma_f32_16x16x32_bf16 v[24:27], v[164:167], v[182:185], v[24:27]
	v_mfma_f32_16x16x32_bf16 v[12:15], v[156:159], v[190:193], v[12:15]
	v_mfma_f32_16x16x32_bf16 v[8:11], v[164:167], v[190:193], v[8:11]
	v_mfma_f32_16x16x32_bf16 v[4:7], v[156:159], v[198:201], v[4:7]
	v_mfma_f32_16x16x32_bf16 v[0:3], v[164:167], v[198:201], v[0:3]
	v_mfma_f32_16x16x32_bf16 v[44:47], v[160:163], v[178:181], v[44:47]
	v_mfma_f32_16x16x32_bf16 v[40:43], v[168:171], v[178:181], v[40:43]
	v_mfma_f32_16x16x32_bf16 v[28:31], v[160:163], v[186:189], v[28:31]
	v_mfma_f32_16x16x32_bf16 v[24:27], v[168:171], v[186:189], v[24:27]
	v_mfma_f32_16x16x32_bf16 v[12:15], v[160:163], v[194:197], v[12:15]
	v_mfma_f32_16x16x32_bf16 v[8:11], v[168:171], v[194:197], v[8:11]
	v_mfma_f32_16x16x32_bf16 v[4:7], v[160:163], v[202:205], v[4:7]
	v_mfma_f32_16x16x32_bf16 v[0:3], v[168:171], v[202:205], v[0:3]
	s_setprio 0
	s_barrier
	s_movk_i32 s36, 0x100
	s_andn2_b64 vcc, exec, s[30:31]
	s_mov_b64 s[34:35], -1
	s_mov_b64 s[30:31], 0
	s_cbranch_vccz .LBB0_524
	s_and_b64 vcc, exec, s[8:9]
	s_cbranch_vccz .LBB0_527
	s_barrier

.LBB0_621:
	s_nop 10
	v_max_f32_e32 v32, v1, v1
	v_max_f32_e32 v33, v17, v17
	v_max_f32_e32 v32, v33, v32
	v_max_f32_e32 v33, v2, v2
	v_max_f32_e32 v34, v18, v18
	v_max_f32_e32 v33, v34, v33
	v_max_f32_e32 v34, v3, v3
	v_max_f32_e32 v35, v19, v19
	v_max3_f32 v32, v16, v0, v32
	v_max_f32_e32 v34, v35, v34
	v_max3_f32 v32, v32, v33, v34
	v_max_f32_e32 v33, v4, v4
	v_max_f32_e32 v34, v20, v20
	v_max_f32_e32 v33, v34, v33
	v_max_f32_e32 v34, v5, v5
	v_max_f32_e32 v35, v21, v21
	v_max_f32_e32 v34, v35, v34
	v_max3_f32 v32, v32, v33, v34
	v_max_f32_e32 v33, v6, v6
	v_max_f32_e32 v34, v22, v22
	v_max_f32_e32 v33, v34, v33
	v_max_f32_e32 v34, v7, v7
	v_max_f32_e32 v35, v23, v23
	v_max_f32_e32 v34, v35, v34
	v_max3_f32 v32, v32, v33, v34
	v_max_f32_e32 v33, v8, v8
	v_max_f32_e32 v34, v24, v24
	v_max_f32_e32 v33, v34, v33
	v_max_f32_e32 v34, v9, v9
	v_max_f32_e32 v35, v25, v25
	v_max_f32_e32 v34, v35, v34
	v_max3_f32 v32, v32, v33, v34
	v_max_f32_e32 v33, v10, v10
	v_max_f32_e32 v34, v26, v26
	v_max_f32_e32 v33, v34, v33
	v_max_f32_e32 v34, v11, v11
	v_max_f32_e32 v35, v27, v27
	v_max_f32_e32 v34, v35, v34
	v_max3_f32 v32, v32, v33, v34
	v_max_f32_e32 v33, v12, v12
	v_max_f32_e32 v34, v28, v28
	v_max_f32_e32 v33, v34, v33
	v_max_f32_e32 v34, v13, v13
	v_max_f32_e32 v35, v29, v29
	v_max_f32_e32 v34, v35, v34
	v_max3_f32 v32, v32, v33, v34
	v_max_f32_e32 v33, v14, v14
	v_max_f32_e32 v34, v30, v30
	v_max_f32_e32 v33, v34, v33
	v_max_f32_e32 v34, v15, v15
	v_max_f32_e32 v35, v31, v31
	v_max_f32_e32 v34, v35, v34
	v_max3_f32 v32, v32, v33, v34
	v_mov_b32_e32 v33, v32
	s_nop 1
	v_permlane32_swap_b32_e32 v32, v33
	v_max_f32_e32 v33, v33, v33
	v_max_f32_e32 v32, v32, v32
	v_max_f32_e32 v64, v32, v33
	v_sub_f32_e32 v32, v0, v64
	v_sub_f32_e32 v0, v16, v64
	v_sub_f32_e32 v33, v1, v64
	v_sub_f32_e32 v1, v17, v64
	v_exp_f32_e32 v0, v0
	v_sub_f32_e32 v34, v2, v64
	v_sub_f32_e32 v2, v18, v64
	v_exp_f32_e32 v1, v1
	v_sub_f32_e32 v35, v3, v64
	v_sub_f32_e32 v3, v19, v64
	v_exp_f32_e32 v2, v2
	v_sub_f32_e32 v36, v4, v64
	v_sub_f32_e32 v4, v20, v64
	v_exp_f32_e32 v3, v3
	v_sub_f32_e32 v37, v5, v64
	v_sub_f32_e32 v5, v21, v64
	v_add_f32_e32 v16, 0, v0
	v_exp_f32_e32 v4, v4
	v_sub_f32_e32 v38, v6, v64
	v_sub_f32_e32 v6, v22, v64
	v_add_f32_e32 v16, v1, v16
	v_exp_f32_e32 v5, v5
	v_sub_f32_e32 v39, v7, v64
	v_sub_f32_e32 v7, v23, v64
	v_add_f32_e32 v16, v2, v16
	v_exp_f32_e32 v6, v6
	v_sub_f32_e32 v65, v8, v64
	v_sub_f32_e32 v8, v24, v64
	v_add_f32_e32 v16, v3, v16
	v_exp_f32_e32 v7, v7
	v_sub_f32_e32 v98, v9, v64
	v_sub_f32_e32 v9, v25, v64
	v_add_f32_e32 v16, v4, v16
	v_exp_f32_e32 v8, v8
	v_sub_f32_e32 v99, v10, v64
	v_sub_f32_e32 v10, v26, v64
	v_add_f32_e32 v16, v5, v16
	v_exp_f32_e32 v9, v9
	v_sub_f32_e32 v100, v11, v64
	v_sub_f32_e32 v11, v27, v64
	v_add_f32_e32 v16, v6, v16
	v_exp_f32_e32 v10, v10
	v_sub_f32_e32 v101, v12, v64
	v_sub_f32_e32 v12, v28, v64
	v_add_f32_e32 v16, v7, v16
	v_exp_f32_e32 v11, v11
	v_sub_f32_e32 v102, v13, v64
	v_sub_f32_e32 v13, v29, v64
	v_add_f32_e32 v16, v8, v16
	v_exp_f32_e32 v12, v12
	v_sub_f32_e32 v103, v14, v64
	v_sub_f32_e32 v14, v30, v64
	v_add_f32_e32 v16, v9, v16
	v_exp_f32_e32 v13, v13
	v_sub_f32_e32 v104, v15, v64
	v_sub_f32_e32 v15, v31, v64
	v_add_f32_e32 v16, v10, v16
	v_exp_f32_e32 v14, v14
	v_add_f32_e32 v16, v11, v16
	v_exp_f32_e32 v15, v15
	v_add_f32_e32 v16, v12, v16
	v_add_f32_e32 v16, v13, v16
	v_mul_u32_u24_e32 v143, 0x90, v140
	v_and_b32_e32 v163, 32, v141
	v_add_f32_e32 v16, v14, v16
	v_add_f32_e32 v16, v15, v16
	s_waitcnt vmcnt(5) lgkmcnt(0)
	s_barrier
	v_add3_u32 v105, 0, v143, v163
	v_add_f32_e32 v107, 0, v16
	v_cvt_pk_bf16_f32 v16, v0, v1
	v_cvt_pk_bf16_f32 v17, v2, v3
	v_cvt_pk_bf16_f32 v18, v4, v5
	v_cvt_pk_bf16_f32 v19, v6, v7
	ds_read_b128 v[0:3], v105 offset:18432
	ds_read_b128 v[20:23], v105 offset:18448
	ds_read_b128 v[4:7], v105 offset:23040
	ds_read_b128 v[24:27], v105 offset:23056
	v_cvt_pk_bf16_f32 v66, v8, v9
	v_cvt_pk_bf16_f32 v67, v10, v11
	v_cvt_pk_bf16_f32 v68, v12, v13
	v_cvt_pk_bf16_f32 v69, v14, v15
	ds_read_b128 v[28:31], v105 offset:27648
	ds_read_b128 v[70:73], v105 offset:27664
	ds_read_b128 v[74:77], v105 offset:32256
	ds_read_b128 v[78:81], v105 offset:32272
	s_waitcnt lgkmcnt(0)
	v_mfma_f32_32x32x16_bf16 v[48:63], v[0:3], v[16:19], 0
	v_exp_f32_e32 v106, v32
	v_exp_f32_e32 v108, v33
	v_exp_f32_e32 v109, v34
	v_exp_f32_e32 v110, v35
	v_mfma_f32_32x32x16_bf16 v[0:15], v[4:7], v[16:19], 0
	v_mfma_f32_32x32x16_bf16 v[48:63], v[20:23], v[66:69], v[48:63]
	v_exp_f32_e32 v111, v36
	v_exp_f32_e32 v128, v37
	v_exp_f32_e32 v129, v38
	v_exp_f32_e32 v130, v39
	v_mfma_f32_32x32x16_bf16 v[0:15], v[24:27], v[66:69], v[0:15]
	ds_read_b128 v[82:85], v105 offset:18496
	ds_read_b128 v[86:89], v105 offset:18512
	ds_read_b128 v[90:93], v105 offset:23104
	ds_read_b128 v[94:97], v105 offset:23120
	v_mfma_f32_32x32x16_bf16 v[32:47], v[28:31], v[16:19], 0
	v_exp_f32_e32 v65, v65
	v_exp_f32_e32 v131, v98
	v_exp_f32_e32 v132, v99
	v_exp_f32_e32 v133, v100
	v_mfma_f32_32x32x16_bf16 v[16:31], v[74:77], v[16:19], 0
	v_mfma_f32_32x32x16_bf16 v[32:47], v[70:73], v[66:69], v[32:47]
	v_exp_f32_e32 v134, v101
	v_exp_f32_e32 v135, v102
	v_exp_f32_e32 v136, v103
	v_exp_f32_e32 v137, v104
	v_cvt_pk_bf16_f32 v70, v65, v131
	v_cvt_pk_bf16_f32 v71, v132, v133
	v_cvt_pk_bf16_f32 v72, v134, v135
	v_mfma_f32_32x32x16_bf16 v[16:31], v[78:81], v[66:69], v[16:31]
	v_cvt_pk_bf16_f32 v66, v106, v108
	v_cvt_pk_bf16_f32 v67, v109, v110
	v_cvt_pk_bf16_f32 v68, v111, v128
	v_cvt_pk_bf16_f32 v69, v129, v130
	v_cvt_pk_bf16_f32 v73, v136, v137
	ds_read_b128 v[74:77], v105 offset:27712
	ds_read_b128 v[78:81], v105 offset:27728
	ds_read_b128 v[98:101], v105 offset:32320
	ds_read_b128 v[102:105], v105 offset:32336
	s_waitcnt lgkmcnt(0)
	v_mfma_f32_32x32x16_bf16 v[48:63], v[82:85], v[66:69], v[48:63]
	v_mfma_f32_32x32x16_bf16 v[0:15], v[90:93], v[66:69], v[0:15]
	v_mfma_f32_32x32x16_bf16 v[48:63], v[86:89], v[70:73], v[48:63]
	v_mfma_f32_32x32x16_bf16 v[0:15], v[94:97], v[70:73], v[0:15]
	v_mfma_f32_32x32x16_bf16 v[32:47], v[74:77], v[66:69], v[32:47]
	v_mfma_f32_32x32x16_bf16 v[16:31], v[98:101], v[66:69], v[16:31]
	v_mfma_f32_32x32x16_bf16 v[32:47], v[78:81], v[70:73], v[32:47]
	v_mfma_f32_32x32x16_bf16 v[16:31], v[102:105], v[70:73], v[16:31]
	v_add_f32_e32 v66, 0, v106
	v_add_f32_e32 v66, v108, v66
	v_add_f32_e32 v66, v109, v66
	v_add_f32_e32 v66, v110, v66
	v_add_f32_e32 v66, v111, v66
	v_add_f32_e32 v66, v128, v66
	v_add_f32_e32 v66, v129, v66
	v_add_f32_e32 v66, v130, v66
	v_add_f32_e32 v65, v65, v66
	v_add_f32_e32 v65, v131, v65
	v_add_f32_e32 v65, v132, v65
	v_add_f32_e32 v65, v133, v65
	v_add_f32_e32 v65, v134, v65
	v_add_f32_e32 v65, v135, v65
	v_add_f32_e32 v65, v136, v65
	v_add_f32_e32 v65, v137, v65
	v_mov_b32_e32 v106, v177
	s_add_i32 s4, s20, s88
	s_waitcnt lgkmcnt(0)
	s_barrier
	v_pk_add_f32 v[156:157], v[64:65], v[106:107]
	v_add_u32_e32 v65, s4, v140
	v_sub_f32_e32 v64, v142, v156
	v_sub_u32_e32 v65, v146, v65
	v_add_u32_e32 v164, 64, v65
	s_mov_b32 s87, 0
	s_sub_i32 s91, 0, s4
	s_mov_b32 s8, 1
	s_mov_b32 s9, 0x9000
	s_mov_b64 s[46:47], s[10:11]
	s_mov_b64 s[40:41], s[76:77]
	s_mov_b32 s56, 0
	v_mov_b32_e32 v65, v64
	v_mov_b32_e32 v66, v64
	v_mov_b32_e32 v67, v64
	v_mov_b32_e32 v68, v64
	v_mov_b32_e32 v69, v64
	v_mov_b32_e32 v70, v64
	v_mov_b32_e32 v71, v64
	v_mov_b32_e32 v72, v64
	v_mov_b32_e32 v73, v64
	v_mov_b32_e32 v74, v64
	v_mov_b32_e32 v75, v64
	v_mov_b32_e32 v76, v64
	v_mov_b32_e32 v77, v64
	v_mov_b32_e32 v78, v64
	v_mov_b32_e32 v79, v64
	s_add_u32 vcc_lo, s46, 0xffffff80
	s_addc_u32 vcc_hi, s47, -1
	s_mov_b32 s16, 0x60000
	s_and_b64 s[4:5], s[52:53], exec
	s_cselect_b32 s17, s41, vcc_hi
	s_cselect_b32 s80, s40, vcc_lo
	s_cselect_b32 s81, 0x80, s16
	s_and_b64 s[4:5], s[48:49], exec
	s_cselect_b32 s17, s47, s17
	s_cselect_b32 s80, s46, s80
	s_cselect_b32 s81, s16, s81
	s_and_b64 s[4:5], s[36:37], exec
	s_cselect_b32 s5, vcc_hi, s17
	s_cselect_b32 s4, vcc_lo, s80
	s_cselect_b32 s81, s16, s81
	v_lshl_add_u64 v[240:241], s[4:5], 0, v[176:177]
	v_mov_b32_e32 v200, s81
	v_mov_b32_e32 v201, 0
	s_and_b64 s[4:5], s[28:29], exec
	s_cselect_b32 s17, s41, vcc_hi
	s_cselect_b32 s80, s40, vcc_lo
	s_cselect_b32 s81, 0x80, s16
	s_and_b64 s[4:5], s[66:67], exec
	s_cselect_b32 s17, s47, s17
	s_cselect_b32 s80, s46, s80
	s_cselect_b32 s81, s16, s81
	s_and_b64 s[4:5], s[50:51], exec
	s_cselect_b32 s5, vcc_hi, s17
	s_cselect_b32 s4, vcc_lo, s80
	s_cselect_b32 s81, s16, s81
	v_lshl_add_u64 v[242:243], s[4:5], 0, v[148:149]
	v_mov_b32_e32 v202, s81
	v_mov_b32_e32 v203, 0
	s_and_b64 s[4:5], s[60:61], exec
	s_cselect_b32 s17, s41, vcc_hi
	s_cselect_b32 s80, s40, vcc_lo
	s_cselect_b32 s81, 0x80, s16
	s_and_b64 s[4:5], s[38:39], exec
	s_cselect_b32 s17, s47, s17
	s_cselect_b32 s80, s46, s80
	s_cselect_b32 s81, s16, s81
	s_and_b64 s[4:5], s[62:63], exec
	s_cselect_b32 s5, vcc_hi, s17
	s_cselect_b32 s4, vcc_lo, s80
	s_cselect_b32 s81, s16, s81
	v_lshl_add_u64 v[244:245], s[4:5], 0, v[150:151]
	v_mov_b32_e32 v204, s81
	v_mov_b32_e32 v205, 0
	s_and_b64 s[4:5], s[6:7], exec
	s_cselect_b32 s17, s41, vcc_hi
	s_cselect_b32 s80, s40, vcc_lo
	s_cselect_b32 s81, 0x80, s16
	s_and_b64 s[4:5], s[12:13], exec
	s_cselect_b32 s17, s47, s17
	s_cselect_b32 s80, s46, s80
	s_cselect_b32 s81, s16, s81
	s_and_b64 s[4:5], s[22:23], exec
	s_cselect_b32 s5, vcc_hi, s17
	s_cselect_b32 s4, vcc_lo, s80
	s_cselect_b32 s81, s16, s81
	v_lshl_add_u64 v[246:247], s[4:5], 0, v[152:153]
	v_mov_b32_e32 v206, s81
	v_mov_b32_e32 v207, 0
	s_and_b64 s[4:5], s[14:15], exec
	s_cselect_b32 s17, s41, vcc_hi
	s_cselect_b32 s80, s40, vcc_lo
	s_cselect_b32 s81, 0x80, s16
	s_and_b64 s[4:5], s[0:1], exec
	s_cselect_b32 s17, s47, s17
	s_cselect_b32 s80, s46, s80
	s_cselect_b32 s81, s16, s81
	s_and_b64 s[4:5], s[68:69], exec
	s_cselect_b32 s5, vcc_hi, s17
	s_cselect_b32 s4, vcc_lo, s80
	s_cselect_b32 s81, s16, s81
	v_lshl_add_u64 v[248:249], s[4:5], 0, v[154:155]
	v_mov_b32_e32 v208, s81
	v_mov_b32_e32 v209, 0
	s_mov_b32 s32, 3
	s_branch .LBB0_623
.LBB0_622:
	v_exp_f32_e32 v96, v96
	v_exp_f32_e32 v97, v97
	v_exp_f32_e32 v98, v98
	v_exp_f32_e32 v99, v99
	v_exp_f32_e32 v100, v100
	v_add_f32_e32 v128, v97, v96
	v_exp_f32_e32 v101, v101
	v_add_f32_e32 v128, v98, v128
	v_exp_f32_e32 v102, v102
	v_add_f32_e32 v128, v99, v128
	v_exp_f32_e32 v103, v103
	v_add_f32_e32 v128, v100, v128
	v_exp_f32_e32 v104, v104
	v_add_f32_e32 v128, v101, v128
	v_exp_f32_e32 v105, v105
	v_add_f32_e32 v128, v102, v128
	v_exp_f32_e32 v106, v106
	v_add_f32_e32 v128, v103, v128
	v_exp_f32_e32 v107, v107
	v_add_f32_e32 v128, v104, v128
	v_exp_f32_e32 v108, v108
	v_add_f32_e32 v128, v105, v128
	v_exp_f32_e32 v109, v109
	v_add_f32_e32 v128, v106, v128
	v_exp_f32_e32 v110, v110
	v_add_f32_e32 v128, v107, v128
	v_exp_f32_e32 v111, v111
	v_add_f32_e32 v128, v108, v128
	v_add_f32_e32 v128, v109, v128
	v_add_f32_e32 v128, v110, v128
	v_add_f32_e32 v128, v111, v128
	v_add3_u32 v165, s57, v143, v163
	v_add_f32_e32 v157, v157, v128
	v_cvt_pk_bf16_f32 v96, v96, v97
	v_cvt_pk_bf16_f32 v97, v98, v99
	v_cvt_pk_bf16_f32 v98, v100, v101
	v_cvt_pk_bf16_f32 v99, v102, v103
	v_cvt_pk_bf16_f32 v100, v104, v105
	v_cvt_pk_bf16_f32 v101, v106, v107
	v_cvt_pk_bf16_f32 v102, v108, v109
	v_cvt_pk_bf16_f32 v103, v110, v111
	ds_read_b128 v[104:107], v165 offset:18432
	ds_read_b128 v[108:111], v165 offset:18448
	ds_read_b128 v[128:131], v165 offset:23040
	ds_read_b128 v[132:135], v165 offset:23056
	ds_read_b128 v[136:139], v165 offset:27648
	ds_read_b128 v[166:169], v165 offset:27664
	ds_read_b128 v[170:173], v165 offset:32256
	ds_read_b128 v[178:181], v165 offset:32272
	s_waitcnt lgkmcnt(0)
	v_mfma_f32_32x32x16_bf16 v[48:63], v[104:107], v[96:99], v[48:63]
	v_exp_f32_e32 v174, v80
	v_exp_f32_e32 v175, v81
	v_exp_f32_e32 v182, v82
	v_exp_f32_e32 v183, v83
	v_add_f32_e32 v80, v175, v174
	v_add_f32_e32 v80, v182, v80
	v_mfma_f32_32x32x16_bf16 v[0:15], v[128:131], v[96:99], v[0:15]
	v_add_f32_e32 v80, v183, v80
	v_mfma_f32_32x32x16_bf16 v[48:63], v[108:111], v[100:103], v[48:63]
	v_exp_f32_e32 v128, v84
	v_exp_f32_e32 v129, v85
	v_exp_f32_e32 v130, v86
	v_exp_f32_e32 v131, v87
	v_add_f32_e32 v80, v128, v80
	v_add_f32_e32 v80, v129, v80
	v_add_f32_e32 v80, v130, v80
	v_mfma_f32_32x32x16_bf16 v[0:15], v[132:135], v[100:103], v[0:15]
	v_add_f32_e32 v184, v131, v80
	ds_read_b128 v[80:83], v165 offset:18496
	ds_read_b128 v[84:87], v165 offset:18512
	ds_read_b128 v[104:107], v165 offset:23104
	ds_read_b128 v[108:111], v165 offset:23120
	v_mfma_f32_32x32x16_bf16 v[32:47], v[136:139], v[96:99], v[32:47]
	v_exp_f32_e32 v132, v88
	v_exp_f32_e32 v133, v89
	v_exp_f32_e32 v134, v90
	v_exp_f32_e32 v135, v91
	v_add_f32_e32 v88, v132, v184
	v_add_f32_e32 v88, v133, v88
	v_add_f32_e32 v88, v134, v88
	v_mfma_f32_32x32x16_bf16 v[16:31], v[170:173], v[96:99], v[16:31]
	v_add_f32_e32 v88, v135, v88
	v_exp_f32_e32 v96, v92
	v_mfma_f32_32x32x16_bf16 v[32:47], v[166:169], v[100:103], v[32:47]
	v_exp_f32_e32 v97, v93
	v_exp_f32_e32 v98, v94
	v_exp_f32_e32 v95, v95
	v_add_f32_e32 v88, v96, v88
	v_add_f32_e32 v88, v97, v88
	v_add_f32_e32 v88, v98, v88
	v_add_f32_e32 v88, v95, v88
	v_mfma_f32_32x32x16_bf16 v[16:31], v[178:181], v[100:103], v[16:31]
	v_add_f32_e32 v157, v157, v88
	v_cvt_pk_bf16_f32 v88, v174, v175
	v_cvt_pk_bf16_f32 v89, v182, v183
	v_cvt_pk_bf16_f32 v90, v128, v129
	v_cvt_pk_bf16_f32 v91, v130, v131
	v_cvt_pk_bf16_f32 v92, v132, v133
	v_cvt_pk_bf16_f32 v93, v134, v135
	v_cvt_pk_bf16_f32 v94, v96, v97
	v_cvt_pk_bf16_f32 v95, v98, v95
	ds_read_b128 v[96:99], v165 offset:27712
	ds_read_b128 v[100:103], v165 offset:27728
	ds_read_b128 v[128:131], v165 offset:32320
	ds_read_b128 v[132:135], v165 offset:32336
	s_waitcnt lgkmcnt(0)
	v_mfma_f32_32x32x16_bf16 v[48:63], v[80:83], v[88:91], v[48:63]
	v_mfma_f32_32x32x16_bf16 v[0:15], v[104:107], v[88:91], v[0:15]
	v_mfma_f32_32x32x16_bf16 v[48:63], v[84:87], v[92:95], v[48:63]
	v_mfma_f32_32x32x16_bf16 v[0:15], v[108:111], v[92:95], v[0:15]
	v_mfma_f32_32x32x16_bf16 v[32:47], v[96:99], v[88:91], v[32:47]
	v_mfma_f32_32x32x16_bf16 v[16:31], v[128:131], v[88:91], v[16:31]
	v_mfma_f32_32x32x16_bf16 v[32:47], v[100:103], v[92:95], v[32:47]
	v_mfma_f32_32x32x16_bf16 v[16:31], v[132:135], v[92:95], v[16:31]
	s_add_i32 s4, s9, 0x9000
	s_cmp_lg_u32 s9, 0x12000
	s_cselect_b32 s9, s4, 0
	s_add_i32 s4, s56, 1
	s_cmp_lg_u32 s56, 2
	s_cselect_b32 s56, s4, 0
	s_add_i32 s8, s8, 1
	s_add_u32 s40, s40, 0x80
	s_addc_u32 s41, s41, 0
	s_add_u32 s46, s46, 0x60000
	s_waitcnt lgkmcnt(0)
	s_barrier
	s_addc_u32 s47, s47, 0
	s_add_i32 s87, s87, 64
	s_cmpk_lg_i32 s87, 0xfc0
	s_cbranch_scc0 .LBB0_633

.LBB0_625:
	ds_read_b128 v[166:169], v84 offset:64
	ds_read_b128 v[170:173], v84 offset:96
	ds_read_b128 v[178:181], v84 offset:4672
	ds_read_b128 v[182:185], v84 offset:4704
	s_add_i32 s16, s91, s87
	s_add_i32 s4, s16, 64
	s_cmpk_lt_i32 s4, 0xff42
	s_cselect_b32 s5, 1, 0
	s_cmpk_gt_i32 s4, 0x9e
	s_cselect_b32 s4, 2, s5
	s_cmp_eq_u32 s4, s32
	s_cbranch_scc1 .Lattn_negm_keep_0
	s_mov_b32 s32, s4
	s_cmp_eq_u32 s4, 1
	s_cselect_b64 vcc, -1, 0
	s_cmp_eq_u32 s4, 2
	s_cselect_b64 s[4:5], -1, 0
	v_cndmask_b32_e64 v84, 0, v160, s[4:5]
	v_cndmask_b32_e32 v252, v84, v159, vcc
	v_sub_f32_e32 v84, v252, v156
	v_mov_b32_e32 v79, v84
	v_mov_b32_e32 v78, v84
	v_mov_b32_e32 v77, v84
	v_mov_b32_e32 v76, v84
	v_mov_b32_e32 v75, v84
	v_mov_b32_e32 v74, v84
	v_mov_b32_e32 v73, v84
	v_mov_b32_e32 v72, v84
	v_mov_b32_e32 v71, v84
	v_mov_b32_e32 v70, v84
	v_mov_b32_e32 v69, v84
	v_mov_b32_e32 v68, v84
	v_mov_b32_e32 v67, v84
	v_mov_b32_e32 v66, v84
	v_mov_b32_e32 v65, v84
	v_mov_b32_e32 v64, v84
.Lattn_negm_keep_0:
	s_addk_i32 s16, 0xffa1
	s_cmp_lt_u32 s16, 0xfffffea3
	s_waitcnt lgkmcnt(0)
	s_nop 0
	v_mfma_f32_32x32x16_bf16 v[96:111], v[80:83], v[112:115], v[64:79]
	v_mfma_f32_32x32x16_bf16 v[80:95], v[136:139], v[112:115], v[64:79]
	v_mfma_f32_32x32x16_bf16 v[96:111], v[128:131], v[116:119], v[96:111]
	v_mfma_f32_32x32x16_bf16 v[80:95], v[132:135], v[116:119], v[80:95]
	v_mfma_f32_32x32x16_bf16 v[96:111], v[166:169], v[120:123], v[96:111]
	v_mfma_f32_32x32x16_bf16 v[80:95], v[178:181], v[120:123], v[80:95]
	v_mfma_f32_32x32x16_bf16 v[96:111], v[170:173], v[124:127], v[96:111]
	v_mfma_f32_32x32x16_bf16 v[80:95], v[182:185], v[124:127], v[80:95]
	s_cbranch_scc1 .LBB0_627
	v_add_u32_e32 v180, s87, v164
	v_max_i32_e32 v130, 0xffffff7f, v180
	v_add_u32_e32 v130, 0x81, v130
	s_add_i32 s80, 0, 0x20000
	v_min_u32_e32 v130, 0x100, v130
	v_lshl_add_u32 v132, v130, 2, s80
	v_max_i32_e32 v130, 0xffffff7e, v180
	v_add_u32_e32 v130, 0x82, v130
	v_max_i32_e32 v138, 0xffffff7b, v180
	v_min_u32_e32 v130, 0x100, v130
	v_add_u32_e32 v138, 0x85, v138
	v_max_i32_e32 v128, 0xffffff80, v180
	v_max_i32_e32 v129, 0xffffff60, v180
	v_max_i32_e32 v131, 0xffffff5f, v180
	v_max_i32_e32 v133, 0xffffff5e, v180
	v_lshl_add_u32 v134, v130, 2, s80
	v_max_i32_e32 v130, 0xffffff7d, v180
	v_max_i32_e32 v135, 0xffffff5d, v180
	v_min_u32_e32 v138, 0x100, v138
	v_add_u32_e32 v128, 0x80, v128
	v_add_u32_e32 v129, 0xa0, v129
	v_add_u32_e32 v131, 0xa1, v131
	v_add_u32_e32 v133, 0xa2, v133
	v_add_u32_e32 v130, 0x83, v130
	v_add_u32_e32 v135, 0xa3, v135
	v_lshl_add_u32 v166, v138, 2, s80
	v_max_i32_e32 v138, 0xffffff7a, v180
	v_min_u32_e32 v128, 0x100, v128
	v_min_u32_e32 v129, 0x100, v129
	v_min_u32_e32 v131, 0x100, v131
	v_min_u32_e32 v133, 0x100, v133
	v_min_u32_e32 v130, 0x100, v130
	v_min_u32_e32 v135, 0x100, v135
	v_add_u32_e32 v138, 0x86, v138
	v_max_i32_e32 v172, 0xffffff77, v180
	v_lshl_add_u32 v128, v128, 2, s80
	v_lshl_add_u32 v129, v129, 2, s80
	v_lshl_add_u32 v131, v131, 2, s80
	v_lshl_add_u32 v133, v133, 2, s80
	v_lshl_add_u32 v136, v130, 2, s80
	v_lshl_add_u32 v135, v135, 2, s80
	v_min_u32_e32 v138, 0x100, v138
	v_add_u32_e32 v172, 0x89, v172
	ds_read_b32 v128, v128
	ds_read_b32 v130, v129
	ds_read_b32 v129, v132
	ds_read_b32 v131, v131
	ds_read_b32 v132, v134
	ds_read_b32 v134, v133
	ds_read_b32 v133, v136
	ds_read_b32 v135, v135
	v_max_i32_e32 v136, 0xffffff7c, v180
	v_max_i32_e32 v137, 0xffffff5c, v180
	v_max_i32_e32 v139, 0xffffff5b, v180
	v_max_i32_e32 v167, 0xffffff5a, v180
	v_lshl_add_u32 v168, v138, 2, s80
	v_max_i32_e32 v138, 0xffffff79, v180
	v_max_i32_e32 v169, 0xffffff59, v180
	v_min_u32_e32 v172, 0x100, v172
	v_add_u32_e32 v136, 0x84, v136
	v_add_u32_e32 v137, 0xa4, v137
	v_add_u32_e32 v139, 0xa5, v139
	v_add_u32_e32 v167, 0xa6, v167
	v_add_u32_e32 v138, 0x87, v138
	v_add_u32_e32 v169, 0xa7, v169
	v_lshl_add_u32 v174, v172, 2, s80
	v_max_i32_e32 v172, 0xffffff76, v180
	v_min_u32_e32 v136, 0x100, v136
	v_min_u32_e32 v137, 0x100, v137
	v_min_u32_e32 v139, 0x100, v139
	v_min_u32_e32 v167, 0x100, v167
	v_min_u32_e32 v138, 0x100, v138
	v_min_u32_e32 v169, 0x100, v169
	v_add_u32_e32 v172, 0x8a, v172
	v_lshl_add_u32 v136, v136, 2, s80
	v_lshl_add_u32 v137, v137, 2, s80
	v_lshl_add_u32 v139, v139, 2, s80
	v_lshl_add_u32 v167, v167, 2, s80
	v_lshl_add_u32 v170, v138, 2, s80
	v_lshl_add_u32 v169, v169, 2, s80
	v_min_u32_e32 v172, 0x100, v172
	ds_read_b32 v136, v136
	ds_read_b32 v138, v137
	ds_read_b32 v137, v166
	ds_read_b32 v139, v139
	ds_read_b32 v166, v168
	ds_read_b32 v168, v167
	ds_read_b32 v167, v170
	ds_read_b32 v169, v169
	v_max_i32_e32 v170, 0xffffff78, v180
	v_max_i32_e32 v171, 0xffffff58, v180
	v_max_i32_e32 v173, 0xffffff57, v180
	v_max_i32_e32 v175, 0xffffff56, v180
	v_lshl_add_u32 v178, v172, 2, s80
	v_max_i32_e32 v172, 0xffffff75, v180
	v_max_i32_e32 v179, 0xffffff55, v180
	v_add_u32_e32 v170, 0x88, v170
	v_add_u32_e32 v171, 0xa8, v171
	v_add_u32_e32 v173, 0xa9, v173
	v_add_u32_e32 v175, 0xaa, v175
	v_add_u32_e32 v172, 0x8b, v172
	v_add_u32_e32 v179, 0xab, v179
	v_max_i32_e32 v184, 0xffffff53, v180
	v_max_i32_e32 v185, 0xffffff52, v180
	v_min_u32_e32 v170, 0x100, v170
	v_min_u32_e32 v171, 0x100, v171
	v_min_u32_e32 v173, 0x100, v173
	v_min_u32_e32 v175, 0x100, v175
	v_min_u32_e32 v172, 0x100, v172
	v_min_u32_e32 v179, 0x100, v179
	v_add_u32_e32 v184, 0xad, v184
	v_add_u32_e32 v185, 0xae, v185
	v_lshl_add_u32 v170, v170, 2, s80
	v_lshl_add_u32 v171, v171, 2, s80
	v_lshl_add_u32 v173, v173, 2, s80
	v_lshl_add_u32 v175, v175, 2, s80
	v_lshl_add_u32 v181, v172, 2, s80
	v_lshl_add_u32 v179, v179, 2, s80
	v_min_u32_e32 v184, 0x100, v184
	v_min_u32_e32 v185, 0x100, v185
	ds_read_b32 v170, v170
	ds_read_b32 v172, v171
	ds_read_b32 v171, v174
	ds_read_b32 v173, v173
	ds_read_b32 v174, v178
	ds_read_b32 v178, v175
	ds_read_b32 v175, v181
	ds_read_b32 v179, v179
	v_max_i32_e32 v181, 0xffffff74, v180
	v_max_i32_e32 v182, 0xffffff54, v180
	v_max_i32_e32 v183, 0xffffff73, v180
	v_lshl_add_u32 v188, v184, 2, s80
	v_max_i32_e32 v184, 0xffffff72, v180
	v_lshl_add_u32 v186, v185, 2, s80
	v_max_i32_e32 v185, 0xffffff71, v180
	v_max_i32_e32 v180, 0xffffff51, v180
	v_add_u32_e32 v181, 0x8c, v181
	v_add_u32_e32 v182, 0xac, v182
	v_add_u32_e32 v183, 0x8d, v183
	v_add_u32_e32 v184, 0x8e, v184
	v_add_u32_e32 v185, 0x8f, v185
	v_add_u32_e32 v180, 0xaf, v180
	v_min_u32_e32 v181, 0x100, v181
	v_min_u32_e32 v182, 0x100, v182
	v_min_u32_e32 v183, 0x100, v183
	v_min_u32_e32 v184, 0x100, v184
	v_min_u32_e32 v185, 0x100, v185
	v_min_u32_e32 v180, 0x100, v180
	v_lshl_add_u32 v181, v181, 2, s80
	v_lshl_add_u32 v182, v182, 2, s80
	v_lshl_add_u32 v183, v183, 2, s80
	v_lshl_add_u32 v184, v184, 2, s80
	v_lshl_add_u32 v185, v185, 2, s80
	v_lshl_add_u32 v187, v180, 2, s80
	ds_read_b32 v180, v181
	ds_read_b32 v182, v182
	ds_read_b32 v184, v184
	ds_read_b32 v185, v185
	ds_read_b32 v181, v183
	ds_read_b32 v187, v187
	ds_read_b32 v186, v186
	ds_read_b32 v183, v188
	s_waitcnt lgkmcnt(0)
	v_pk_add_f32 v[110:111], v[110:111], v[184:185]
	v_pk_add_f32 v[108:109], v[108:109], v[180:181]
	v_pk_add_f32 v[106:107], v[106:107], v[174:175]
	v_pk_add_f32 v[104:105], v[104:105], v[170:171]
	v_pk_add_f32 v[102:103], v[102:103], v[166:167]
	v_pk_add_f32 v[100:101], v[100:101], v[136:137]
	v_pk_add_f32 v[98:99], v[98:99], v[132:133]
	v_pk_add_f32 v[96:97], v[96:97], v[128:129]
	v_pk_add_f32 v[94:95], v[94:95], v[186:187]
	v_pk_add_f32 v[92:93], v[92:93], v[182:183]
	v_pk_add_f32 v[90:91], v[90:91], v[178:179]
	v_pk_add_f32 v[88:89], v[88:89], v[172:173]
	v_pk_add_f32 v[86:87], v[86:87], v[168:169]
	v_pk_add_f32 v[84:85], v[84:85], v[138:139]
	v_pk_add_f32 v[82:83], v[82:83], v[134:135]
	v_pk_add_f32 v[80:81], v[80:81], v[130:131]
.LBB0_627:
	s_nop 10
	v_max3_f32 v128, v96, v97, v98
	v_max3_f32 v129, v80, v81, v82
	v_max3_f32 v128, v128, v99, v100
	v_max3_f32 v129, v129, v83, v84
	v_max3_f32 v128, v128, v101, v102
	v_max3_f32 v129, v129, v85, v86
	v_max3_f32 v128, v128, v103, v104
	v_max3_f32 v129, v129, v87, v88
	v_max3_f32 v128, v128, v105, v106
	v_max3_f32 v129, v129, v89, v90
	v_max3_f32 v128, v128, v107, v108
	v_max3_f32 v129, v129, v91, v92
	v_max3_f32 v128, v128, v109, v110
	v_max3_f32 v129, v129, v93, v94
	v_max3_f32 v128, v128, v129, v111
	v_max_f32_e32 v128, v128, v95
	v_mov_b32_e32 v129, v128
	s_nop 1
	v_permlane32_swap_b32_e32 v128, v129
	v_max_f32_e32 v128, v128, v129
	v_cmp_lt_f32_e32 vcc, s96, v128
	s_cbranch_vccz .LBB0_629
	v_max_f32_e32 v64, v128, v128
	v_max_f32_e32 v64, 0, v64
	v_exp_f32_e64 v66, -v64
	v_pk_add_f32 v[96:97], v[96:97], v[64:65] op_sel_hi:[1,0] neg_lo:[0,1] neg_hi:[0,1]
	v_pk_add_f32 v[98:99], v[98:99], v[64:65] op_sel_hi:[1,0] neg_lo:[0,1] neg_hi:[0,1]
	v_pk_add_f32 v[100:101], v[100:101], v[64:65] op_sel_hi:[1,0] neg_lo:[0,1] neg_hi:[0,1]
	v_pk_add_f32 v[102:103], v[102:103], v[64:65] op_sel_hi:[1,0] neg_lo:[0,1] neg_hi:[0,1]
	v_pk_add_f32 v[104:105], v[104:105], v[64:65] op_sel_hi:[1,0] neg_lo:[0,1] neg_hi:[0,1]
	v_pk_add_f32 v[106:107], v[106:107], v[64:65] op_sel_hi:[1,0] neg_lo:[0,1] neg_hi:[0,1]
	v_pk_add_f32 v[108:109], v[108:109], v[64:65] op_sel_hi:[1,0] neg_lo:[0,1] neg_hi:[0,1]
	v_pk_add_f32 v[110:111], v[110:111], v[64:65] op_sel_hi:[1,0] neg_lo:[0,1] neg_hi:[0,1]
	v_mov_b32_e32 v65, v66
	v_sub_f32_e32 v95, v95, v64
	v_sub_f32_e32 v94, v94, v64
	v_sub_f32_e32 v93, v93, v64
	v_sub_f32_e32 v92, v92, v64
	v_sub_f32_e32 v91, v91, v64
	v_sub_f32_e32 v90, v90, v64
	v_sub_f32_e32 v89, v89, v64
	v_sub_f32_e32 v88, v88, v64
	v_sub_f32_e32 v87, v87, v64
	v_sub_f32_e32 v86, v86, v64
	v_sub_f32_e32 v85, v85, v64
	v_sub_f32_e32 v84, v84, v64
	v_sub_f32_e32 v83, v83, v64
	v_sub_f32_e32 v82, v82, v64
	v_sub_f32_e32 v81, v81, v64
	v_sub_f32_e32 v80, v80, v64
	v_pk_mul_f32 v[62:63], v[62:63], v[66:67] op_sel_hi:[1,0]
	v_pk_mul_f32 v[60:61], v[60:61], v[66:67] op_sel_hi:[1,0]
	v_pk_mul_f32 v[58:59], v[58:59], v[66:67] op_sel_hi:[1,0]
	v_pk_mul_f32 v[56:57], v[56:57], v[66:67] op_sel_hi:[1,0]
	v_pk_mul_f32 v[54:55], v[54:55], v[66:67] op_sel_hi:[1,0]
	v_pk_mul_f32 v[52:53], v[52:53], v[66:67] op_sel_hi:[1,0]
	v_pk_mul_f32 v[50:51], v[50:51], v[66:67] op_sel_hi:[1,0]
	v_pk_mul_f32 v[48:49], v[48:49], v[66:67] op_sel_hi:[1,0]
	v_pk_mul_f32 v[14:15], v[14:15], v[66:67] op_sel_hi:[1,0]
	v_pk_mul_f32 v[12:13], v[12:13], v[66:67] op_sel_hi:[1,0]
	v_pk_mul_f32 v[10:11], v[10:11], v[66:67] op_sel_hi:[1,0]
	v_pk_mul_f32 v[8:9], v[8:9], v[66:67] op_sel_hi:[1,0]
	v_pk_mul_f32 v[6:7], v[6:7], v[66:67] op_sel_hi:[1,0]
	v_pk_mul_f32 v[4:5], v[4:5], v[66:67] op_sel_hi:[1,0]
	v_pk_mul_f32 v[2:3], v[2:3], v[66:67] op_sel_hi:[1,0]
	v_pk_mul_f32 v[0:1], v[0:1], v[66:67] op_sel_hi:[1,0]
	v_pk_mul_f32 v[46:47], v[46:47], v[66:67] op_sel_hi:[1,0]
	v_pk_mul_f32 v[44:45], v[44:45], v[66:67] op_sel_hi:[1,0]
	v_pk_mul_f32 v[42:43], v[42:43], v[66:67] op_sel_hi:[1,0]
	v_pk_mul_f32 v[40:41], v[40:41], v[66:67] op_sel_hi:[1,0]
	v_pk_mul_f32 v[38:39], v[38:39], v[66:67] op_sel_hi:[1,0]
	v_pk_mul_f32 v[36:37], v[36:37], v[66:67] op_sel_hi:[1,0]
	v_pk_mul_f32 v[34:35], v[34:35], v[66:67] op_sel_hi:[1,0]
	v_pk_mul_f32 v[32:33], v[32:33], v[66:67] op_sel_hi:[1,0]
	v_pk_mul_f32 v[30:31], v[30:31], v[66:67] op_sel_hi:[1,0]
	v_pk_mul_f32 v[28:29], v[28:29], v[66:67] op_sel_hi:[1,0]
	v_pk_mul_f32 v[26:27], v[26:27], v[66:67] op_sel_hi:[1,0]
	v_pk_mul_f32 v[24:25], v[24:25], v[66:67] op_sel_hi:[1,0]
	v_pk_mul_f32 v[22:23], v[22:23], v[66:67] op_sel_hi:[1,0]
	v_pk_mul_f32 v[20:21], v[20:21], v[66:67] op_sel_hi:[1,0]
	v_pk_mul_f32 v[18:19], v[18:19], v[66:67] op_sel_hi:[1,0]
	v_pk_mul_f32 v[16:17], v[16:17], v[66:67] op_sel_hi:[1,0]
	v_pk_add_f32 v[66:67], v[156:157], v[64:65]
	v_pk_mul_f32 v[64:65], v[156:157], v[64:65]
	s_nop 0
	v_mov_b32_e32 v67, v65
	v_sub_f32_e32 v64, v252, v66
	v_mov_b64_e32 v[156:157], v[66:67]
	v_mov_b32_e32 v65, v64
	v_mov_b32_e32 v66, v64
	v_mov_b32_e32 v67, v64
	v_mov_b32_e32 v68, v64
	v_mov_b32_e32 v69, v64
	v_mov_b32_e32 v70, v64
	v_mov_b32_e32 v71, v64
	v_mov_b32_e32 v72, v64
	v_mov_b32_e32 v73, v64
	v_mov_b32_e32 v74, v64
	v_mov_b32_e32 v75, v64
	v_mov_b32_e32 v76, v64
	v_mov_b32_e32 v77, v64
	v_mov_b32_e32 v78, v64
	v_mov_b32_e32 v79, v64

.LBB0_637:
	s_nop 10
	v_max_f32_e32 v32, v1, v1
	v_max_f32_e32 v33, v17, v17
	v_max_f32_e32 v32, v33, v32
	v_max_f32_e32 v33, v2, v2
	v_max_f32_e32 v34, v18, v18
	v_max_f32_e32 v33, v34, v33
	v_max_f32_e32 v34, v3, v3
	v_max_f32_e32 v35, v19, v19
	v_max3_f32 v32, v16, v0, v32
	v_max_f32_e32 v34, v35, v34
	v_max3_f32 v32, v32, v33, v34
	v_max_f32_e32 v33, v4, v4
	v_max_f32_e32 v34, v20, v20
	v_max_f32_e32 v33, v34, v33
	v_max_f32_e32 v34, v5, v5
	v_max_f32_e32 v35, v21, v21
	v_max_f32_e32 v34, v35, v34
	v_max3_f32 v32, v32, v33, v34
	v_max_f32_e32 v33, v6, v6
	v_max_f32_e32 v34, v22, v22
	v_max_f32_e32 v33, v34, v33
	v_max_f32_e32 v34, v7, v7
	v_max_f32_e32 v35, v23, v23
	v_max_f32_e32 v34, v35, v34
	v_max3_f32 v32, v32, v33, v34
	v_max_f32_e32 v33, v8, v8
	v_max_f32_e32 v34, v24, v24
	v_max_f32_e32 v33, v34, v33
	v_max_f32_e32 v34, v9, v9
	v_max_f32_e32 v35, v25, v25
	v_max_f32_e32 v34, v35, v34
	v_max3_f32 v32, v32, v33, v34
	v_max_f32_e32 v33, v10, v10
	v_max_f32_e32 v34, v26, v26
	v_max_f32_e32 v33, v34, v33
	v_max_f32_e32 v34, v11, v11
	v_max_f32_e32 v35, v27, v27
	v_max_f32_e32 v34, v35, v34
	v_max3_f32 v32, v32, v33, v34
	v_max_f32_e32 v33, v12, v12
	v_max_f32_e32 v34, v28, v28
	v_max_f32_e32 v33, v34, v33
	v_max_f32_e32 v34, v13, v13
	v_max_f32_e32 v35, v29, v29
	v_max_f32_e32 v34, v35, v34
	v_max3_f32 v32, v32, v33, v34
	v_max_f32_e32 v33, v14, v14
	v_max_f32_e32 v34, v30, v30
	v_max_f32_e32 v33, v34, v33
	v_max_f32_e32 v34, v15, v15
	v_max_f32_e32 v35, v31, v31
	v_max_f32_e32 v34, v35, v34
	v_max3_f32 v32, v32, v33, v34
	v_mov_b32_e32 v33, v32
	s_nop 1
	v_permlane32_swap_b32_e32 v32, v33
	v_max_f32_e32 v33, v33, v33
	v_max_f32_e32 v32, v32, v32
	v_max_f32_e32 v64, v32, v33
	v_sub_f32_e32 v32, v0, v64
	v_sub_f32_e32 v0, v16, v64
	v_sub_f32_e32 v33, v1, v64
	v_sub_f32_e32 v1, v17, v64
	v_exp_f32_e32 v0, v0
	v_sub_f32_e32 v34, v2, v64
	v_sub_f32_e32 v2, v18, v64
	v_exp_f32_e32 v1, v1
	v_sub_f32_e32 v35, v3, v64
	v_sub_f32_e32 v3, v19, v64
	v_exp_f32_e32 v2, v2
	v_sub_f32_e32 v36, v4, v64
	v_sub_f32_e32 v4, v20, v64
	v_exp_f32_e32 v3, v3
	v_sub_f32_e32 v37, v5, v64
	v_sub_f32_e32 v5, v21, v64
	v_add_f32_e32 v16, 0, v0
	v_exp_f32_e32 v4, v4
	v_sub_f32_e32 v38, v6, v64
	v_sub_f32_e32 v6, v22, v64
	v_add_f32_e32 v16, v1, v16
	v_exp_f32_e32 v5, v5
	v_sub_f32_e32 v39, v7, v64
	v_sub_f32_e32 v7, v23, v64
	v_add_f32_e32 v16, v2, v16
	v_exp_f32_e32 v6, v6
	v_sub_f32_e32 v65, v8, v64
	v_sub_f32_e32 v8, v24, v64
	v_add_f32_e32 v16, v3, v16
	v_exp_f32_e32 v7, v7
	v_sub_f32_e32 v66, v9, v64
	v_sub_f32_e32 v9, v25, v64
	v_add_f32_e32 v16, v4, v16
	v_exp_f32_e32 v8, v8
	v_sub_f32_e32 v100, v10, v64
	v_sub_f32_e32 v10, v26, v64
	v_add_f32_e32 v16, v5, v16
	v_exp_f32_e32 v9, v9
	v_sub_f32_e32 v101, v11, v64
	v_sub_f32_e32 v11, v27, v64
	v_add_f32_e32 v16, v6, v16
	v_exp_f32_e32 v10, v10
	v_sub_f32_e32 v102, v12, v64
	v_sub_f32_e32 v12, v28, v64
	v_add_f32_e32 v16, v7, v16
	v_exp_f32_e32 v11, v11
	v_sub_f32_e32 v103, v13, v64
	v_sub_f32_e32 v13, v29, v64
	v_add_f32_e32 v16, v8, v16
	v_exp_f32_e32 v12, v12
	v_sub_f32_e32 v104, v14, v64
	v_sub_f32_e32 v14, v30, v64
	v_add_f32_e32 v16, v9, v16
	v_exp_f32_e32 v13, v13
	v_sub_f32_e32 v105, v15, v64
	v_sub_f32_e32 v15, v31, v64
	v_add_f32_e32 v16, v10, v16
	v_exp_f32_e32 v14, v14
	v_add_f32_e32 v16, v11, v16
	v_exp_f32_e32 v15, v15
	v_add_f32_e32 v16, v12, v16
	v_add_f32_e32 v16, v13, v16
	v_mul_u32_u24_e32 v164, 0x90, v140
	v_and_b32_e32 v165, 32, v141
	v_add_f32_e32 v16, v14, v16
	v_add_f32_e32 v16, v15, v16
	s_waitcnt lgkmcnt(0)
	s_barrier
	v_add3_u32 v106, 0, v164, v165
	v_add_f32_e32 v67, 0, v16
	v_cvt_pk_bf16_f32 v16, v0, v1
	v_cvt_pk_bf16_f32 v17, v2, v3
	v_cvt_pk_bf16_f32 v18, v4, v5
	v_cvt_pk_bf16_f32 v19, v6, v7
	ds_read_b128 v[0:3], v106 offset:18432
	ds_read_b128 v[20:23], v106 offset:18448
	ds_read_b128 v[4:7], v106 offset:23040
	ds_read_b128 v[24:27], v106 offset:23056
	v_cvt_pk_bf16_f32 v68, v8, v9
	v_cvt_pk_bf16_f32 v69, v10, v11
	v_cvt_pk_bf16_f32 v70, v12, v13
	v_cvt_pk_bf16_f32 v71, v14, v15
	s_add_u32 s33, s21, 0xc0000
	s_addc_u32 s40, s84, 0
	s_add_u32 s41, s44, 0x100
	s_addc_u32 s42, s85, 0
	s_add_u32 s21, s21, 0xc0080
	s_addc_u32 s24, s84, 0
	s_and_b64 s[0:1], s[52:53], exec
	s_cselect_b32 s2, s42, s40
	s_cselect_b32 s4, s41, s33
	s_and_b64 s[0:1], s[48:49], exec
	s_cselect_b32 s4, s21, s4
	s_cselect_b32 s2, s24, s2
	s_and_b64 s[0:1], s[36:37], exec
	s_cselect_b32 s1, s40, s2
	s_cselect_b32 s0, s33, s4
	s_add_i32 m0, s26, 0x12000
	s_or_b32 s4, s3, 8
	s_cmp_lt_i32 s4, 9
	v_lshl_add_u64 v[8:9], s[0:1], 0, v[176:177]
	s_cselect_b64 s[0:1], -1, 0
	s_cmp_lt_u32 s4, 18
	s_cselect_b64 s[6:7], -1, 0
	s_cmp_lt_u32 s4, 36
	s_cselect_b64 s[12:13], -1, 0
	s_and_b64 s[8:9], s[12:13], exec
	s_cselect_b32 s2, s42, s40
	s_cselect_b32 s5, s41, s33
	s_and_b64 s[8:9], s[6:7], exec
	s_cselect_b32 s5, s21, s5
	s_cselect_b32 s2, s24, s2
	s_and_b64 s[8:9], s[0:1], exec
	s_cselect_b32 s9, s40, s2
	s_cselect_b32 s8, s33, s5
	s_lshl_b32 s2, s4, 10
	s_add_i32 s2, s2, 0
	global_load_lds_dwordx4 v[8:9], off
	s_add_i32 m0, s2, 0x12000
	s_or_b32 s5, s3, 16
	s_cmp_lt_u32 s5, 18
	s_cselect_b64 s[14:15], -1, 0
	s_cmp_lt_u32 s5, 36
	s_cselect_b64 s[22:23], -1, 0
	v_lshl_add_u64 v[8:9], s[8:9], 0, v[148:149]
	s_and_b64 s[8:9], s[22:23], exec
	s_cselect_b32 s25, s41, s33
	s_cselect_b32 s26, s42, s40
	s_and_b64 s[8:9], s[14:15], exec
	s_cselect_b32 s9, s24, s26
	s_cselect_b32 s8, s21, s25
	s_lshl_b32 s21, s5, 10
	global_load_lds_dwordx4 v[8:9], off
	v_lshl_add_u64 v[8:9], s[8:9], 0, v[150:151]
	s_add_i32 s8, s21, 0
	s_add_i32 m0, s8, 0x12000
	s_or_b32 s9, s3, 24
	s_cmp_lt_u32 s9, 36
	s_cselect_b64 s[24:25], -1, 0
	s_and_b64 s[26:27], s[24:25], exec
	s_cselect_b32 s27, s42, s40
	s_cselect_b32 s26, s41, s33
	s_lshl_b32 s8, s9, 10
	global_load_lds_dwordx4 v[8:9], off
	v_lshl_add_u64 v[8:9], s[26:27], 0, v[152:153]
	s_add_i32 s26, s8, 0
	s_add_i32 m0, s26, 0x12000
	s_or_b32 s27, s3, 32
	s_cmp_lt_u32 s27, 36
	s_cselect_b64 s[28:29], -1, 0
	s_and_b64 s[38:39], s[28:29], exec
	s_cselect_b32 s39, s42, s40
	s_cselect_b32 s38, s41, s33
	s_lshl_b32 s3, s27, 10
	s_add_i32 s8, s3, 0
	global_load_lds_dwordx4 v[8:9], off
	v_lshl_add_u64 v[8:9], s[38:39], 0, v[154:155]
	s_add_i32 m0, s8, 0x12000
	s_nop 0
	global_load_lds_dwordx4 v[8:9], off
	ds_read_b128 v[28:31], v106 offset:27648
	ds_read_b128 v[72:75], v106 offset:27664
	ds_read_b128 v[76:79], v106 offset:32256
	ds_read_b128 v[80:83], v106 offset:32272
	s_waitcnt lgkmcnt(0)
	v_mfma_f32_32x32x16_bf16 v[48:63], v[0:3], v[16:19], 0
	v_exp_f32_e32 v107, v32
	v_exp_f32_e32 v108, v33
	v_exp_f32_e32 v109, v34
	v_exp_f32_e32 v110, v35
	v_add_f32_e32 v32, 0, v107
	v_add_f32_e32 v32, v108, v32
	v_add_f32_e32 v32, v109, v32
	v_mfma_f32_32x32x16_bf16 v[0:15], v[4:7], v[16:19], 0
	v_add_f32_e32 v32, v110, v32
	v_mfma_f32_32x32x16_bf16 v[48:63], v[20:23], v[68:71], v[48:63]
	v_exp_f32_e32 v111, v36
	v_exp_f32_e32 v128, v37
	v_exp_f32_e32 v129, v38
	v_exp_f32_e32 v130, v39
	v_add_f32_e32 v20, v111, v32
	v_add_f32_e32 v20, v128, v20
	v_add_f32_e32 v20, v129, v20
	v_mfma_f32_32x32x16_bf16 v[0:15], v[24:27], v[68:71], v[0:15]
	v_add_f32_e32 v20, v130, v20
	ds_read_b128 v[84:87], v106 offset:18496
	ds_read_b128 v[88:91], v106 offset:18512
	ds_read_b128 v[92:95], v106 offset:23104
	ds_read_b128 v[96:99], v106 offset:23120
	v_exp_f32_e32 v131, v65
	v_exp_f32_e32 v132, v66
	v_exp_f32_e32 v100, v100
	v_exp_f32_e32 v101, v101
	v_add_f32_e32 v20, v131, v20
	v_add_f32_e32 v20, v132, v20
	v_add_f32_e32 v20, v100, v20
	v_mfma_f32_32x32x16_bf16 v[32:47], v[28:31], v[16:19], 0
	v_add_f32_e32 v65, v101, v20
	v_mfma_f32_32x32x16_bf16 v[16:31], v[76:79], v[16:19], 0
	v_mfma_f32_32x32x16_bf16 v[32:47], v[72:75], v[68:71], v[32:47]
	v_exp_f32_e32 v72, v102
	v_exp_f32_e32 v73, v103
	v_exp_f32_e32 v74, v104
	v_exp_f32_e32 v75, v105
	v_add_f32_e32 v65, v72, v65
	v_add_f32_e32 v65, v73, v65
	v_add_f32_e32 v65, v74, v65
	v_mfma_f32_32x32x16_bf16 v[16:31], v[80:83], v[68:71], v[16:31]
	v_add_f32_e32 v65, v75, v65
	v_mov_b32_e32 v66, v177
	v_add_f32_e64 v156, v64, v66
	v_add_f32_e64 v157, v65, v67
	v_cvt_pk_bf16_f32 v66, v107, v108
	v_sub_f32_e32 v64, v163, v156
	v_cvt_pk_bf16_f32 v67, v109, v110
	v_cvt_pk_bf16_f32 v68, v111, v128
	v_cvt_pk_bf16_f32 v69, v129, v130
	v_cvt_pk_bf16_f32 v70, v131, v132
	v_cvt_pk_bf16_f32 v71, v100, v101
	v_cvt_pk_bf16_f32 v72, v72, v73
	v_cvt_pk_bf16_f32 v73, v74, v75
	ds_read_b128 v[74:77], v106 offset:27712
	ds_read_b128 v[78:81], v106 offset:27728
	ds_read_b128 v[100:103], v106 offset:32320
	ds_read_b128 v[104:107], v106 offset:32336
	s_waitcnt lgkmcnt(0)
	v_mfma_f32_32x32x16_bf16 v[48:63], v[84:87], v[66:69], v[48:63]
	v_mfma_f32_32x32x16_bf16 v[0:15], v[92:95], v[66:69], v[0:15]
	v_mfma_f32_32x32x16_bf16 v[48:63], v[88:91], v[70:73], v[48:63]
	v_mfma_f32_32x32x16_bf16 v[0:15], v[96:99], v[70:73], v[0:15]
	v_mfma_f32_32x32x16_bf16 v[32:47], v[74:77], v[66:69], v[32:47]
	v_mfma_f32_32x32x16_bf16 v[16:31], v[100:103], v[66:69], v[16:31]
	v_mfma_f32_32x32x16_bf16 v[32:47], v[78:81], v[70:73], v[32:47]
	v_mfma_f32_32x32x16_bf16 v[16:31], v[104:107], v[70:73], v[16:31]
	s_cmp_lt_i32 s4, 36
	s_cselect_b64 s[38:39], -1, 0
	s_cmp_lt_i32 s5, 36
	s_cselect_b64 s[40:41], -1, 0
	s_or_b32 s8, s21, 0x12000
	s_cmp_lt_i32 s9, 36
	s_cselect_b64 s[42:43], -1, 0
	s_cmp_lt_i32 s27, 36
	s_cselect_b64 s[46:47], -1, 0
	s_add_i32 s4, s20, s88
	s_waitcnt vmcnt(5) lgkmcnt(0)
	s_barrier
	v_add_u32_e32 v65, s4, v140
	v_sub_u32_e32 v65, v146, v65
	s_or_b32 s9, s3, 0x12000
	v_add_u32_e32 v166, 64, v65
	s_mov_b32 s20, 0
	s_sub_i32 s27, 0, s4
	s_mov_b32 s33, 1
	s_mov_b32 s44, 0x9000
	s_mov_b32 s45, 0
	v_mov_b32_e32 v65, v64
	v_mov_b32_e32 v66, v64
	v_mov_b32_e32 v67, v64
	v_mov_b32_e32 v68, v64
	v_mov_b32_e32 v69, v64
	v_mov_b32_e32 v70, v64
	v_mov_b32_e32 v71, v64
	v_mov_b32_e32 v72, v64
	v_mov_b32_e32 v73, v64
	v_mov_b32_e32 v74, v64
	v_mov_b32_e32 v75, v64
	v_mov_b32_e32 v76, v64
	v_mov_b32_e32 v77, v64
	v_mov_b32_e32 v78, v64
	v_mov_b32_e32 v79, v64
	s_add_u32 s59, s10, 0xffffff80
	s_addc_u32 s62, s11, -1
	s_mov_b32 s63, 0x60000
	s_and_b64 s[56:57], s[52:53], exec
	s_cselect_b32 s61, s77, s62
	s_cselect_b32 s60, s76, s59
	s_cselect_b32 s64, 0x80, s63
	s_and_b64 s[56:57], s[48:49], exec
	s_cselect_b32 s61, s11, s61
	s_cselect_b32 s60, s10, s60
	s_cselect_b32 s64, s63, s64
	s_and_b64 s[56:57], s[36:37], exec
	s_cselect_b32 s57, s62, s61
	s_cselect_b32 s56, s59, s60
	s_cselect_b32 s64, s63, s64
	v_lshl_add_u64 v[240:241], s[56:57], 0, v[176:177]
	v_mov_b32_e32 v200, s64
	v_mov_b32_e32 v201, 0
	s_and_b64 s[56:57], s[12:13], exec
	s_cselect_b32 s61, s77, s62
	s_cselect_b32 s60, s76, s59
	s_cselect_b32 s64, 0x80, s63
	s_and_b64 s[56:57], s[6:7], exec
	s_cselect_b32 s61, s11, s61
	s_cselect_b32 s60, s10, s60
	s_cselect_b32 s64, s63, s64
	s_and_b64 s[56:57], s[0:1], exec
	s_cselect_b32 s57, s62, s61
	s_cselect_b32 s56, s59, s60
	s_cselect_b32 s64, s63, s64
	v_lshl_add_u64 v[242:243], s[56:57], 0, v[148:149]
	v_mov_b32_e32 v202, s64
	v_mov_b32_e32 v203, 0
	s_and_b64 s[56:57], s[22:23], exec
	s_cselect_b32 s61, s77, s62
	s_cselect_b32 s60, s76, s59
	s_cselect_b32 s64, 0x80, s63
	s_and_b64 s[56:57], s[14:15], exec
	s_cselect_b32 s57, s11, s61
	s_cselect_b32 s56, s10, s60
	s_cselect_b32 s64, s63, s64
	v_lshl_add_u64 v[244:245], s[56:57], 0, v[150:151]
	v_mov_b32_e32 v204, s64
	v_mov_b32_e32 v205, 0
	s_and_b64 s[56:57], s[24:25], exec
	s_cselect_b32 s57, s77, s62
	s_cselect_b32 s56, s76, s59
	s_cselect_b32 s64, 0x80, s63
	v_lshl_add_u64 v[246:247], s[56:57], 0, v[152:153]
	v_mov_b32_e32 v206, s64
	v_mov_b32_e32 v207, 0
	s_and_b64 s[56:57], s[28:29], exec
	s_cselect_b32 s57, s77, s62
	s_cselect_b32 s56, s76, s59
	s_cselect_b32 s64, 0x80, s63
	v_lshl_add_u64 v[248:249], s[56:57], 0, v[154:155]
	v_mov_b32_e32 v208, s64
	v_mov_b32_e32 v209, 0
	s_mov_b32 s32, 3
	s_branch .LBB0_639
.LBB0_638:
	v_add_f32_e32 v96, v97, v96
	v_add_f32_e32 v96, v98, v96
	v_add_f32_e32 v80, v81, v80
	v_add_f32_e32 v96, v99, v96
	v_add_f32_e32 v80, v82, v80
	v_add_f32_e32 v96, v100, v96
	v_add_f32_e32 v80, v83, v80
	v_add_f32_e32 v96, v101, v96
	v_add_f32_e32 v80, v84, v80
	v_add_f32_e32 v96, v102, v96
	v_add_f32_e32 v80, v85, v80
	v_add_f32_e32 v96, v103, v96
	v_add_f32_e32 v80, v86, v80
	v_add_f32_e32 v96, v104, v96
	v_add_f32_e32 v80, v87, v80
	s_add_i32 s4, s44, 0x9000
	v_add_f32_e32 v96, v105, v96
	v_add_f32_e32 v80, v88, v80
	s_cmp_lg_u32 s44, 0x12000
	v_add_f32_e32 v96, v106, v96
	v_add_f32_e32 v80, v89, v80
	s_cselect_b32 s44, s4, 0
	s_add_i32 s4, s45, 1
	v_add_f32_e32 v96, v107, v96
	v_add_f32_e32 v80, v90, v80
	s_cmp_lg_u32 s45, 2
	v_add_f32_e32 v96, v108, v96
	v_add_f32_e32 v80, v91, v80
	s_cselect_b32 s45, s4, 0
	s_add_i32 s33, s33, 1
	v_add_f32_e32 v96, v109, v96
	v_add_f32_e32 v80, v92, v80
	s_add_u32 s76, s76, 0x80
	v_add_f32_e32 v96, v110, v96
	v_add_f32_e32 v80, v93, v80
	s_addc_u32 s77, s77, 0
	v_add_f32_e32 v96, v111, v96
	v_add_f32_e32 v80, v94, v80
	s_add_u32 s10, s10, 0x60000
	v_add_f32_e32 v96, v157, v96
	v_add_f32_e32 v80, v95, v80
	s_addc_u32 s11, s11, 0
	s_add_i32 s20, s20, 64
	v_add_f32_e32 v157, v96, v80
	s_cmpk_eq_i32 s20, 0xfc0
	s_cbranch_scc1 .LBB0_649
.LBB0_639:
	s_add_i32 s50, s44, 0
	v_add3_u32 v84, s50, v162, v146
	ds_read_b128 v[80:83], v84
	ds_read_b128 v[128:131], v84 offset:32
	ds_read_b128 v[132:135], v84 offset:4608
	ds_read_b128 v[136:139], v84 offset:4640
	ds_read_b128 v[140:143], v84 offset:64
	ds_read_b128 v[168:171], v84 offset:96
	ds_read_b128 v[172:175], v84 offset:4672
	ds_read_b128 v[178:181], v84 offset:4704
	s_add_i32 s51, s27, s20
	s_add_i32 s4, s51, 64
	s_cmpk_lt_i32 s4, 0xff42
	s_cselect_b32 s5, 1, 0
	s_cmpk_gt_i32 s4, 0x9e
	s_cselect_b32 s4, 2, s5
	s_cmp_eq_u32 s4, s32
	s_cbranch_scc1 .Lattn_negm_keep_1
	s_mov_b32 s32, s4
	s_cmp_eq_u32 s4, 1
	s_cselect_b64 vcc, -1, 0
	s_cmp_eq_u32 s4, 2
	s_cselect_b64 s[4:5], -1, 0
	v_cndmask_b32_e64 v84, 0, v160, s[4:5]
	v_cndmask_b32_e32 v252, v84, v159, vcc
	v_sub_f32_e32 v84, v252, v156
	v_mov_b32_e32 v79, v84
	v_mov_b32_e32 v78, v84
	v_mov_b32_e32 v77, v84
	v_mov_b32_e32 v76, v84
	v_mov_b32_e32 v75, v84
	v_mov_b32_e32 v74, v84
	v_mov_b32_e32 v73, v84
	v_mov_b32_e32 v72, v84
	v_mov_b32_e32 v71, v84
	v_mov_b32_e32 v70, v84
	v_mov_b32_e32 v69, v84
	v_mov_b32_e32 v68, v84
	v_mov_b32_e32 v67, v84
	v_mov_b32_e32 v66, v84
	v_mov_b32_e32 v65, v84
	v_mov_b32_e32 v64, v84
.Lattn_negm_keep_1:
	s_addk_i32 s51, 0xffa1
	s_cmp_lt_u32 s51, 0xfffffea3
	s_waitcnt lgkmcnt(0)
	s_nop 0
	v_mfma_f32_32x32x16_bf16 v[96:111], v[80:83], v[112:115], v[64:79]
	v_mfma_f32_32x32x16_bf16 v[80:95], v[132:135], v[112:115], v[64:79]
	v_mfma_f32_32x32x16_bf16 v[96:111], v[128:131], v[116:119], v[96:111]
	v_mfma_f32_32x32x16_bf16 v[80:95], v[136:139], v[116:119], v[80:95]
	v_mfma_f32_32x32x16_bf16 v[96:111], v[140:143], v[120:123], v[96:111]
	v_mfma_f32_32x32x16_bf16 v[80:95], v[172:175], v[120:123], v[80:95]
	v_mfma_f32_32x32x16_bf16 v[96:111], v[168:171], v[124:127], v[96:111]
	v_mfma_f32_32x32x16_bf16 v[80:95], v[178:181], v[124:127], v[80:95]
	s_cbranch_scc1 .LBB0_641
	v_add_u32_e32 v178, s20, v166
	v_max_i32_e32 v130, 0xffffff7f, v178
	v_add_u32_e32 v130, 0x81, v130
	s_add_i32 s51, 0, 0x20000
	v_min_u32_e32 v130, 0x100, v130
	v_lshl_add_u32 v132, v130, 2, s51
	v_max_i32_e32 v130, 0xffffff7e, v178
	v_add_u32_e32 v130, 0x82, v130
	v_max_i32_e32 v138, 0xffffff7b, v178
	v_min_u32_e32 v130, 0x100, v130
	v_add_u32_e32 v138, 0x85, v138
	v_max_i32_e32 v128, 0xffffff80, v178
	v_max_i32_e32 v129, 0xffffff60, v178
	v_max_i32_e32 v131, 0xffffff5f, v178
	v_max_i32_e32 v133, 0xffffff5e, v178
	v_lshl_add_u32 v134, v130, 2, s51
	v_max_i32_e32 v130, 0xffffff7d, v178
	v_max_i32_e32 v135, 0xffffff5d, v178
	v_min_u32_e32 v138, 0x100, v138
	v_add_u32_e32 v128, 0x80, v128
	v_add_u32_e32 v129, 0xa0, v129
	v_add_u32_e32 v131, 0xa1, v131
	v_add_u32_e32 v133, 0xa2, v133
	v_add_u32_e32 v130, 0x83, v130
	v_add_u32_e32 v135, 0xa3, v135
	v_lshl_add_u32 v140, v138, 2, s51
	v_max_i32_e32 v138, 0xffffff7a, v178
	v_min_u32_e32 v128, 0x100, v128
	v_min_u32_e32 v129, 0x100, v129
	v_min_u32_e32 v131, 0x100, v131
	v_min_u32_e32 v133, 0x100, v133
	v_min_u32_e32 v130, 0x100, v130
	v_min_u32_e32 v135, 0x100, v135
	v_add_u32_e32 v138, 0x86, v138
	v_max_i32_e32 v170, 0xffffff77, v178
	v_lshl_add_u32 v128, v128, 2, s51
	v_lshl_add_u32 v129, v129, 2, s51
	v_lshl_add_u32 v131, v131, 2, s51
	v_lshl_add_u32 v133, v133, 2, s51
	v_lshl_add_u32 v136, v130, 2, s51
	v_lshl_add_u32 v135, v135, 2, s51
	v_min_u32_e32 v138, 0x100, v138
	v_add_u32_e32 v170, 0x89, v170
	ds_read_b32 v128, v128
	ds_read_b32 v130, v129
	ds_read_b32 v129, v132
	ds_read_b32 v131, v131
	ds_read_b32 v132, v134
	ds_read_b32 v134, v133
	ds_read_b32 v133, v136
	ds_read_b32 v135, v135
	v_max_i32_e32 v136, 0xffffff7c, v178
	v_max_i32_e32 v137, 0xffffff5c, v178
	v_max_i32_e32 v139, 0xffffff5b, v178
	v_max_i32_e32 v141, 0xffffff5a, v178
	v_lshl_add_u32 v142, v138, 2, s51
	v_max_i32_e32 v138, 0xffffff79, v178
	v_max_i32_e32 v143, 0xffffff59, v178
	v_min_u32_e32 v170, 0x100, v170
	v_add_u32_e32 v136, 0x84, v136
	v_add_u32_e32 v137, 0xa4, v137
	v_add_u32_e32 v139, 0xa5, v139
	v_add_u32_e32 v141, 0xa6, v141
	v_add_u32_e32 v138, 0x87, v138
	v_add_u32_e32 v143, 0xa7, v143
	v_lshl_add_u32 v172, v170, 2, s51
	v_max_i32_e32 v170, 0xffffff76, v178
	v_min_u32_e32 v136, 0x100, v136
	v_min_u32_e32 v137, 0x100, v137
	v_min_u32_e32 v139, 0x100, v139
	v_min_u32_e32 v141, 0x100, v141
	v_min_u32_e32 v138, 0x100, v138
	v_min_u32_e32 v143, 0x100, v143
	v_add_u32_e32 v170, 0x8a, v170
	v_lshl_add_u32 v136, v136, 2, s51
	v_lshl_add_u32 v137, v137, 2, s51
	v_lshl_add_u32 v139, v139, 2, s51
	v_lshl_add_u32 v141, v141, 2, s51
	v_lshl_add_u32 v168, v138, 2, s51
	v_lshl_add_u32 v143, v143, 2, s51
	v_min_u32_e32 v170, 0x100, v170
	ds_read_b32 v136, v136
	ds_read_b32 v138, v137
	ds_read_b32 v137, v140
	ds_read_b32 v139, v139
	ds_read_b32 v140, v142
	ds_read_b32 v142, v141
	ds_read_b32 v141, v168
	ds_read_b32 v143, v143
	v_max_i32_e32 v168, 0xffffff78, v178
	v_max_i32_e32 v169, 0xffffff58, v178
	v_max_i32_e32 v171, 0xffffff57, v178
	v_max_i32_e32 v173, 0xffffff56, v178
	v_lshl_add_u32 v174, v170, 2, s51
	v_max_i32_e32 v170, 0xffffff75, v178
	v_max_i32_e32 v175, 0xffffff55, v178
	v_add_u32_e32 v168, 0x88, v168
	v_add_u32_e32 v169, 0xa8, v169
	v_add_u32_e32 v171, 0xa9, v171
	v_add_u32_e32 v173, 0xaa, v173
	v_add_u32_e32 v170, 0x8b, v170
	v_add_u32_e32 v175, 0xab, v175
	v_max_i32_e32 v182, 0xffffff53, v178
	v_max_i32_e32 v183, 0xffffff52, v178
	v_min_u32_e32 v168, 0x100, v168
	v_min_u32_e32 v169, 0x100, v169
	v_min_u32_e32 v171, 0x100, v171
	v_min_u32_e32 v173, 0x100, v173
	v_min_u32_e32 v170, 0x100, v170
	v_min_u32_e32 v175, 0x100, v175
	v_add_u32_e32 v182, 0xad, v182
	v_add_u32_e32 v183, 0xae, v183
	v_lshl_add_u32 v168, v168, 2, s51
	v_lshl_add_u32 v169, v169, 2, s51
	v_lshl_add_u32 v171, v171, 2, s51
	v_lshl_add_u32 v173, v173, 2, s51
	v_lshl_add_u32 v179, v170, 2, s51
	v_lshl_add_u32 v175, v175, 2, s51
	v_min_u32_e32 v182, 0x100, v182
	v_min_u32_e32 v183, 0x100, v183
	ds_read_b32 v168, v168
	ds_read_b32 v170, v169
	ds_read_b32 v169, v172
	ds_read_b32 v171, v171
	ds_read_b32 v172, v174
	ds_read_b32 v174, v173
	ds_read_b32 v173, v179
	ds_read_b32 v175, v175
	v_max_i32_e32 v179, 0xffffff74, v178
	v_max_i32_e32 v180, 0xffffff54, v178
	v_max_i32_e32 v181, 0xffffff73, v178
	v_lshl_add_u32 v186, v182, 2, s51
	v_max_i32_e32 v182, 0xffffff72, v178
	v_lshl_add_u32 v184, v183, 2, s51
	v_max_i32_e32 v183, 0xffffff71, v178
	v_max_i32_e32 v178, 0xffffff51, v178
	v_add_u32_e32 v179, 0x8c, v179
	v_add_u32_e32 v180, 0xac, v180
	v_add_u32_e32 v181, 0x8d, v181
	v_add_u32_e32 v182, 0x8e, v182
	v_add_u32_e32 v183, 0x8f, v183
	v_add_u32_e32 v178, 0xaf, v178
	v_min_u32_e32 v179, 0x100, v179
	v_min_u32_e32 v180, 0x100, v180
	v_min_u32_e32 v181, 0x100, v181
	v_min_u32_e32 v182, 0x100, v182
	v_min_u32_e32 v183, 0x100, v183
	v_min_u32_e32 v178, 0x100, v178
	v_lshl_add_u32 v179, v179, 2, s51
	v_lshl_add_u32 v180, v180, 2, s51
	v_lshl_add_u32 v181, v181, 2, s51
	v_lshl_add_u32 v182, v182, 2, s51
	v_lshl_add_u32 v183, v183, 2, s51
	v_lshl_add_u32 v185, v178, 2, s51
	ds_read_b32 v178, v179
	ds_read_b32 v180, v180
	ds_read_b32 v182, v182
	ds_read_b32 v183, v183
	ds_read_b32 v179, v181
	ds_read_b32 v185, v185
	ds_read_b32 v184, v184
	ds_read_b32 v181, v186
	s_waitcnt lgkmcnt(0)
	v_pk_add_f32 v[110:111], v[110:111], v[182:183]
	v_pk_add_f32 v[108:109], v[108:109], v[178:179]
	v_pk_add_f32 v[106:107], v[106:107], v[172:173]
	v_pk_add_f32 v[104:105], v[104:105], v[168:169]
	v_pk_add_f32 v[102:103], v[102:103], v[140:141]
	v_pk_add_f32 v[100:101], v[100:101], v[136:137]
	v_pk_add_f32 v[98:99], v[98:99], v[132:133]
	v_pk_add_f32 v[96:97], v[96:97], v[128:129]
	v_pk_add_f32 v[94:95], v[94:95], v[184:185]
	v_pk_add_f32 v[92:93], v[92:93], v[180:181]
	v_pk_add_f32 v[90:91], v[90:91], v[174:175]
	v_pk_add_f32 v[88:89], v[88:89], v[170:171]
	v_pk_add_f32 v[86:87], v[86:87], v[142:143]
	v_pk_add_f32 v[84:85], v[84:85], v[138:139]
	v_pk_add_f32 v[82:83], v[82:83], v[134:135]
	v_pk_add_f32 v[80:81], v[80:81], v[130:131]

.LBB0_682:
	s_nop 10
	v_max_f32_e32 v32, v1, v1
	v_max_f32_e32 v33, v17, v17
	v_max_f32_e32 v32, v33, v32
	v_max_f32_e32 v33, v2, v2
	v_max_f32_e32 v34, v18, v18
	v_max_f32_e32 v33, v34, v33
	v_max_f32_e32 v34, v3, v3
	v_max_f32_e32 v35, v19, v19
	v_max3_f32 v32, v16, v0, v32
	v_max_f32_e32 v34, v35, v34
	v_max3_f32 v32, v32, v33, v34
	v_max_f32_e32 v33, v4, v4
	v_max_f32_e32 v34, v20, v20
	v_max_f32_e32 v33, v34, v33
	v_max_f32_e32 v34, v5, v5
	v_max_f32_e32 v35, v21, v21
	v_max_f32_e32 v34, v35, v34
	v_max3_f32 v32, v32, v33, v34
	v_max_f32_e32 v33, v6, v6
	v_max_f32_e32 v34, v22, v22
	v_max_f32_e32 v33, v34, v33
	v_max_f32_e32 v34, v7, v7
	v_max_f32_e32 v35, v23, v23
	v_max_f32_e32 v34, v35, v34
	v_max3_f32 v32, v32, v33, v34
	v_max_f32_e32 v33, v8, v8
	v_max_f32_e32 v34, v24, v24
	v_max_f32_e32 v33, v34, v33
	v_max_f32_e32 v34, v9, v9
	v_max_f32_e32 v35, v25, v25
	v_max_f32_e32 v34, v35, v34
	v_max3_f32 v32, v32, v33, v34
	v_max_f32_e32 v33, v10, v10
	v_max_f32_e32 v34, v26, v26
	v_max_f32_e32 v33, v34, v33
	v_max_f32_e32 v34, v11, v11
	v_max_f32_e32 v35, v27, v27
	v_max_f32_e32 v34, v35, v34
	v_max3_f32 v32, v32, v33, v34
	v_max_f32_e32 v33, v12, v12
	v_max_f32_e32 v34, v28, v28
	v_max_f32_e32 v33, v34, v33
	v_max_f32_e32 v34, v13, v13
	v_max_f32_e32 v35, v29, v29
	v_max_f32_e32 v34, v35, v34
	v_max3_f32 v32, v32, v33, v34
	v_max_f32_e32 v33, v14, v14
	v_max_f32_e32 v34, v30, v30
	v_max_f32_e32 v33, v34, v33
	v_max_f32_e32 v34, v15, v15
	v_max_f32_e32 v35, v31, v31
	v_max_f32_e32 v34, v35, v34
	v_max3_f32 v32, v32, v33, v34
	v_mov_b32_e32 v33, v32
	s_nop 1
	v_permlane32_swap_b32_e32 v32, v33
	v_max_f32_e32 v33, v33, v33
	v_max_f32_e32 v32, v32, v32
	v_max_f32_e32 v64, v32, v33
	v_sub_f32_e32 v32, v0, v64
	v_sub_f32_e32 v0, v16, v64
	v_sub_f32_e32 v33, v1, v64
	v_sub_f32_e32 v1, v17, v64
	v_exp_f32_e32 v0, v0
	v_sub_f32_e32 v34, v2, v64
	v_sub_f32_e32 v2, v18, v64
	v_exp_f32_e32 v1, v1
	v_sub_f32_e32 v35, v3, v64
	v_sub_f32_e32 v3, v19, v64
	v_exp_f32_e32 v2, v2
	v_sub_f32_e32 v36, v4, v64
	v_sub_f32_e32 v4, v20, v64
	v_exp_f32_e32 v3, v3
	v_sub_f32_e32 v37, v5, v64
	v_sub_f32_e32 v5, v21, v64
	v_add_f32_e32 v16, 0, v0
	v_exp_f32_e32 v4, v4
	v_sub_f32_e32 v38, v6, v64
	v_sub_f32_e32 v6, v22, v64
	v_add_f32_e32 v16, v1, v16
	v_exp_f32_e32 v5, v5
	v_sub_f32_e32 v39, v7, v64
	v_sub_f32_e32 v7, v23, v64
	v_add_f32_e32 v16, v2, v16
	v_exp_f32_e32 v6, v6
	v_sub_f32_e32 v65, v8, v64
	v_sub_f32_e32 v8, v24, v64
	v_add_f32_e32 v16, v3, v16
	v_exp_f32_e32 v7, v7
	v_sub_f32_e32 v98, v9, v64
	v_sub_f32_e32 v9, v25, v64
	v_add_f32_e32 v16, v4, v16
	v_exp_f32_e32 v8, v8
	v_sub_f32_e32 v99, v10, v64
	v_sub_f32_e32 v10, v26, v64
	v_add_f32_e32 v16, v5, v16
	v_exp_f32_e32 v9, v9
	v_sub_f32_e32 v100, v11, v64
	v_sub_f32_e32 v11, v27, v64
	v_add_f32_e32 v16, v6, v16
	v_exp_f32_e32 v10, v10
	v_sub_f32_e32 v101, v12, v64
	v_sub_f32_e32 v12, v28, v64
	v_add_f32_e32 v16, v7, v16
	v_exp_f32_e32 v11, v11
	v_sub_f32_e32 v102, v13, v64
	v_sub_f32_e32 v13, v29, v64
	v_add_f32_e32 v16, v8, v16
	v_exp_f32_e32 v12, v12
	v_sub_f32_e32 v103, v14, v64
	v_sub_f32_e32 v14, v30, v64
	v_add_f32_e32 v16, v9, v16
	v_exp_f32_e32 v13, v13
	v_sub_f32_e32 v104, v15, v64
	v_sub_f32_e32 v15, v31, v64
	v_add_f32_e32 v16, v10, v16
	v_exp_f32_e32 v14, v14
	v_add_f32_e32 v16, v11, v16
	v_exp_f32_e32 v15, v15
	v_add_f32_e32 v16, v12, v16
	v_add_f32_e32 v16, v13, v16
	v_mul_u32_u24_e32 v143, 0x90, v140
	v_and_b32_e32 v163, 32, v141
	v_add_f32_e32 v16, v14, v16
	v_add_f32_e32 v16, v15, v16
	s_waitcnt vmcnt(5) lgkmcnt(0)
	s_barrier
	v_add3_u32 v105, 0, v143, v163
	v_add_f32_e32 v107, 0, v16
	v_cvt_pk_bf16_f32 v16, v0, v1
	v_cvt_pk_bf16_f32 v17, v2, v3
	v_cvt_pk_bf16_f32 v18, v4, v5
	v_cvt_pk_bf16_f32 v19, v6, v7
	ds_read_b128 v[0:3], v105 offset:18432
	ds_read_b128 v[20:23], v105 offset:18448
	ds_read_b128 v[4:7], v105 offset:23040
	ds_read_b128 v[24:27], v105 offset:23056
	v_cvt_pk_bf16_f32 v66, v8, v9
	v_cvt_pk_bf16_f32 v67, v10, v11
	v_cvt_pk_bf16_f32 v68, v12, v13
	v_cvt_pk_bf16_f32 v69, v14, v15
	ds_read_b128 v[28:31], v105 offset:27648
	ds_read_b128 v[70:73], v105 offset:27664
	ds_read_b128 v[74:77], v105 offset:32256
	ds_read_b128 v[78:81], v105 offset:32272
	s_waitcnt lgkmcnt(0)
	v_mfma_f32_32x32x16_bf16 v[48:63], v[0:3], v[16:19], 0
	v_exp_f32_e32 v106, v32
	v_exp_f32_e32 v108, v33
	v_exp_f32_e32 v109, v34
	v_exp_f32_e32 v110, v35
	v_mfma_f32_32x32x16_bf16 v[0:15], v[4:7], v[16:19], 0
	v_mfma_f32_32x32x16_bf16 v[48:63], v[20:23], v[66:69], v[48:63]
	v_exp_f32_e32 v111, v36
	v_exp_f32_e32 v128, v37
	v_exp_f32_e32 v129, v38
	v_exp_f32_e32 v130, v39
	v_mfma_f32_32x32x16_bf16 v[0:15], v[24:27], v[66:69], v[0:15]
	ds_read_b128 v[82:85], v105 offset:18496
	ds_read_b128 v[86:89], v105 offset:18512
	ds_read_b128 v[90:93], v105 offset:23104
	ds_read_b128 v[94:97], v105 offset:23120
	v_mfma_f32_32x32x16_bf16 v[32:47], v[28:31], v[16:19], 0
	v_exp_f32_e32 v65, v65
	v_exp_f32_e32 v131, v98
	v_exp_f32_e32 v132, v99
	v_exp_f32_e32 v133, v100
	v_mfma_f32_32x32x16_bf16 v[16:31], v[74:77], v[16:19], 0
	v_mfma_f32_32x32x16_bf16 v[32:47], v[70:73], v[66:69], v[32:47]
	v_exp_f32_e32 v134, v101
	v_exp_f32_e32 v135, v102
	v_exp_f32_e32 v136, v103
	v_exp_f32_e32 v137, v104
	v_cvt_pk_bf16_f32 v70, v65, v131
	v_cvt_pk_bf16_f32 v71, v132, v133
	v_cvt_pk_bf16_f32 v72, v134, v135
	v_mfma_f32_32x32x16_bf16 v[16:31], v[78:81], v[66:69], v[16:31]
	v_cvt_pk_bf16_f32 v66, v106, v108
	v_cvt_pk_bf16_f32 v67, v109, v110
	v_cvt_pk_bf16_f32 v68, v111, v128
	v_cvt_pk_bf16_f32 v69, v129, v130
	v_cvt_pk_bf16_f32 v73, v136, v137
	ds_read_b128 v[74:77], v105 offset:27712
	ds_read_b128 v[78:81], v105 offset:27728
	ds_read_b128 v[98:101], v105 offset:32320
	ds_read_b128 v[102:105], v105 offset:32336
	s_waitcnt lgkmcnt(0)
	v_mfma_f32_32x32x16_bf16 v[48:63], v[82:85], v[66:69], v[48:63]
	v_mfma_f32_32x32x16_bf16 v[0:15], v[90:93], v[66:69], v[0:15]
	v_mfma_f32_32x32x16_bf16 v[48:63], v[86:89], v[70:73], v[48:63]
	v_mfma_f32_32x32x16_bf16 v[0:15], v[94:97], v[70:73], v[0:15]
	v_mfma_f32_32x32x16_bf16 v[32:47], v[74:77], v[66:69], v[32:47]
	v_mfma_f32_32x32x16_bf16 v[16:31], v[98:101], v[66:69], v[16:31]
	v_mfma_f32_32x32x16_bf16 v[32:47], v[78:81], v[70:73], v[32:47]
	v_mfma_f32_32x32x16_bf16 v[16:31], v[102:105], v[70:73], v[16:31]
	v_add_f32_e32 v66, 0, v106
	v_add_f32_e32 v66, v108, v66
	v_add_f32_e32 v66, v109, v66
	v_add_f32_e32 v66, v110, v66
	v_add_f32_e32 v66, v111, v66
	v_add_f32_e32 v66, v128, v66
	v_add_f32_e32 v66, v129, v66
	v_add_f32_e32 v66, v130, v66
	v_add_f32_e32 v65, v65, v66
	v_add_f32_e32 v65, v131, v65
	v_add_f32_e32 v65, v132, v65
	v_add_f32_e32 v65, v133, v65
	v_add_f32_e32 v65, v134, v65
	v_add_f32_e32 v65, v135, v65
	v_add_f32_e32 v65, v136, v65
	v_add_f32_e32 v65, v137, v65
	v_mov_b32_e32 v106, v177
	s_add_i32 s4, s20, s88
	s_waitcnt lgkmcnt(0)
	s_barrier
	v_pk_add_f32 v[156:157], v[64:65], v[106:107]
	v_add_u32_e32 v65, s4, v140
	v_sub_f32_e32 v64, v142, v156
	v_sub_u32_e32 v65, v146, v65
	v_add_u32_e32 v164, 64, v65
	s_mov_b32 s58, 0
	s_sub_i32 s91, 0, s4
	s_mov_b32 s8, 1
	s_mov_b32 s9, 0x9000
	s_mov_b64 s[10:11], s[46:47]
	s_mov_b64 s[76:77], s[40:41]
	s_mov_b32 s56, 0
	v_mov_b32_e32 v65, v64
	v_mov_b32_e32 v66, v64
	v_mov_b32_e32 v67, v64
	v_mov_b32_e32 v68, v64
	v_mov_b32_e32 v69, v64
	v_mov_b32_e32 v70, v64
	v_mov_b32_e32 v71, v64
	v_mov_b32_e32 v72, v64
	v_mov_b32_e32 v73, v64
	v_mov_b32_e32 v74, v64
	v_mov_b32_e32 v75, v64
	v_mov_b32_e32 v76, v64
	v_mov_b32_e32 v77, v64
	v_mov_b32_e32 v78, v64
	v_mov_b32_e32 v79, v64
	s_add_u32 s16, s10, 0xffffff80
	s_addc_u32 s17, s11, -1
	s_mov_b32 vcc_lo, 0x60000
	s_and_b64 s[4:5], s[52:53], exec
	s_cselect_b32 s80, s77, s17
	s_cselect_b32 s81, s76, s16
	s_cselect_b32 vcc_hi, 0x80, vcc_lo
	s_and_b64 s[4:5], s[48:49], exec
	s_cselect_b32 s80, s11, s80
	s_cselect_b32 s81, s10, s81
	s_cselect_b32 vcc_hi, vcc_lo, vcc_hi
	s_and_b64 s[4:5], s[36:37], exec
	s_cselect_b32 s5, s17, s80
	s_cselect_b32 s4, s16, s81
	s_cselect_b32 vcc_hi, vcc_lo, vcc_hi
	v_lshl_add_u64 v[240:241], s[4:5], 0, v[176:177]
	v_mov_b32_e32 v200, vcc_hi
	v_mov_b32_e32 v201, 0
	s_and_b64 s[4:5], s[28:29], exec
	s_cselect_b32 s80, s77, s17
	s_cselect_b32 s81, s76, s16
	s_cselect_b32 vcc_hi, 0x80, vcc_lo
	s_and_b64 s[4:5], s[66:67], exec
	s_cselect_b32 s80, s11, s80
	s_cselect_b32 s81, s10, s81
	s_cselect_b32 vcc_hi, vcc_lo, vcc_hi
	s_and_b64 s[4:5], s[50:51], exec
	s_cselect_b32 s5, s17, s80
	s_cselect_b32 s4, s16, s81
	s_cselect_b32 vcc_hi, vcc_lo, vcc_hi
	v_lshl_add_u64 v[242:243], s[4:5], 0, v[148:149]
	v_mov_b32_e32 v202, vcc_hi
	v_mov_b32_e32 v203, 0
	s_and_b64 s[4:5], s[60:61], exec
	s_cselect_b32 s80, s77, s17
	s_cselect_b32 s81, s76, s16
	s_cselect_b32 vcc_hi, 0x80, vcc_lo
	s_and_b64 s[4:5], s[38:39], exec
	s_cselect_b32 s80, s11, s80
	s_cselect_b32 s81, s10, s81
	s_cselect_b32 vcc_hi, vcc_lo, vcc_hi
	s_and_b64 s[4:5], s[62:63], exec
	s_cselect_b32 s5, s17, s80
	s_cselect_b32 s4, s16, s81
	s_cselect_b32 vcc_hi, vcc_lo, vcc_hi
	v_lshl_add_u64 v[244:245], s[4:5], 0, v[150:151]
	v_mov_b32_e32 v204, vcc_hi
	v_mov_b32_e32 v205, 0
	s_and_b64 s[4:5], s[6:7], exec
	s_cselect_b32 s80, s77, s17
	s_cselect_b32 s81, s76, s16
	s_cselect_b32 vcc_hi, 0x80, vcc_lo
	s_and_b64 s[4:5], s[12:13], exec
	s_cselect_b32 s80, s11, s80
	s_cselect_b32 s81, s10, s81
	s_cselect_b32 vcc_hi, vcc_lo, vcc_hi
	s_and_b64 s[4:5], s[22:23], exec
	s_cselect_b32 s5, s17, s80
	s_cselect_b32 s4, s16, s81
	s_cselect_b32 vcc_hi, vcc_lo, vcc_hi
	v_lshl_add_u64 v[246:247], s[4:5], 0, v[152:153]
	v_mov_b32_e32 v206, vcc_hi
	v_mov_b32_e32 v207, 0
	s_and_b64 s[4:5], s[14:15], exec
	s_cselect_b32 s80, s77, s17
	s_cselect_b32 s81, s76, s16
	s_cselect_b32 vcc_hi, 0x80, vcc_lo
	s_and_b64 s[4:5], s[0:1], exec
	s_cselect_b32 s80, s11, s80
	s_cselect_b32 s81, s10, s81
	s_cselect_b32 vcc_hi, vcc_lo, vcc_hi
	s_and_b64 s[4:5], s[68:69], exec
	s_cselect_b32 s5, s17, s80
	s_cselect_b32 s4, s16, s81
	s_cselect_b32 vcc_hi, vcc_lo, vcc_hi
	v_lshl_add_u64 v[248:249], s[4:5], 0, v[154:155]
	v_mov_b32_e32 v208, vcc_hi
	v_mov_b32_e32 v209, 0
	s_mov_b32 s32, 3
	s_branch .LBB0_684
.LBB0_683:
	v_exp_f32_e32 v96, v96
	v_exp_f32_e32 v97, v97
	v_exp_f32_e32 v98, v98
	v_exp_f32_e32 v99, v99
	v_exp_f32_e32 v100, v100
	v_add_f32_e32 v128, v97, v96
	v_exp_f32_e32 v101, v101
	v_add_f32_e32 v128, v98, v128
	v_exp_f32_e32 v102, v102
	v_add_f32_e32 v128, v99, v128
	v_exp_f32_e32 v103, v103
	v_add_f32_e32 v128, v100, v128
	v_exp_f32_e32 v104, v104
	v_add_f32_e32 v128, v101, v128
	v_exp_f32_e32 v105, v105
	v_add_f32_e32 v128, v102, v128
	v_exp_f32_e32 v106, v106
	v_add_f32_e32 v128, v103, v128
	v_exp_f32_e32 v107, v107
	v_add_f32_e32 v128, v104, v128
	v_exp_f32_e32 v108, v108
	v_add_f32_e32 v128, v105, v128
	v_exp_f32_e32 v109, v109
	v_add_f32_e32 v128, v106, v128
	v_exp_f32_e32 v110, v110
	v_add_f32_e32 v128, v107, v128
	v_exp_f32_e32 v111, v111
	v_add_f32_e32 v128, v108, v128
	v_add_f32_e32 v128, v109, v128
	v_add_f32_e32 v128, v110, v128
	v_add_f32_e32 v128, v111, v128
	v_add3_u32 v165, s57, v143, v163
	v_add_f32_e32 v157, v157, v128
	v_cvt_pk_bf16_f32 v96, v96, v97
	v_cvt_pk_bf16_f32 v97, v98, v99
	v_cvt_pk_bf16_f32 v98, v100, v101
	v_cvt_pk_bf16_f32 v99, v102, v103
	v_cvt_pk_bf16_f32 v100, v104, v105
	v_cvt_pk_bf16_f32 v101, v106, v107
	v_cvt_pk_bf16_f32 v102, v108, v109
	v_cvt_pk_bf16_f32 v103, v110, v111
	ds_read_b128 v[104:107], v165 offset:18432
	ds_read_b128 v[108:111], v165 offset:18448
	ds_read_b128 v[128:131], v165 offset:23040
	ds_read_b128 v[132:135], v165 offset:23056
	ds_read_b128 v[136:139], v165 offset:27648
	ds_read_b128 v[166:169], v165 offset:27664
	ds_read_b128 v[170:173], v165 offset:32256
	ds_read_b128 v[178:181], v165 offset:32272
	s_waitcnt lgkmcnt(0)
	v_mfma_f32_32x32x16_bf16 v[48:63], v[104:107], v[96:99], v[48:63]
	v_exp_f32_e32 v174, v80
	v_exp_f32_e32 v175, v81
	v_exp_f32_e32 v182, v82
	v_exp_f32_e32 v183, v83
	v_add_f32_e32 v80, v175, v174
	v_add_f32_e32 v80, v182, v80
	v_mfma_f32_32x32x16_bf16 v[0:15], v[128:131], v[96:99], v[0:15]
	v_add_f32_e32 v80, v183, v80
	v_mfma_f32_32x32x16_bf16 v[48:63], v[108:111], v[100:103], v[48:63]
	v_exp_f32_e32 v128, v84
	v_exp_f32_e32 v129, v85
	v_exp_f32_e32 v130, v86
	v_exp_f32_e32 v131, v87
	v_add_f32_e32 v80, v128, v80
	v_add_f32_e32 v80, v129, v80
	v_add_f32_e32 v80, v130, v80
	v_mfma_f32_32x32x16_bf16 v[0:15], v[132:135], v[100:103], v[0:15]
	v_add_f32_e32 v184, v131, v80
	ds_read_b128 v[80:83], v165 offset:18496
	ds_read_b128 v[84:87], v165 offset:18512
	ds_read_b128 v[104:107], v165 offset:23104
	ds_read_b128 v[108:111], v165 offset:23120
	v_mfma_f32_32x32x16_bf16 v[32:47], v[136:139], v[96:99], v[32:47]
	v_exp_f32_e32 v132, v88
	v_exp_f32_e32 v133, v89
	v_exp_f32_e32 v134, v90
	v_exp_f32_e32 v135, v91
	v_add_f32_e32 v88, v132, v184
	v_add_f32_e32 v88, v133, v88
	v_add_f32_e32 v88, v134, v88
	v_mfma_f32_32x32x16_bf16 v[16:31], v[170:173], v[96:99], v[16:31]
	v_add_f32_e32 v88, v135, v88
	v_exp_f32_e32 v96, v92
	v_mfma_f32_32x32x16_bf16 v[32:47], v[166:169], v[100:103], v[32:47]
	v_exp_f32_e32 v97, v93
	v_exp_f32_e32 v98, v94
	v_exp_f32_e32 v95, v95
	v_add_f32_e32 v88, v96, v88
	v_add_f32_e32 v88, v97, v88
	v_add_f32_e32 v88, v98, v88
	v_add_f32_e32 v88, v95, v88
	v_mfma_f32_32x32x16_bf16 v[16:31], v[178:181], v[100:103], v[16:31]
	v_add_f32_e32 v157, v157, v88
	v_cvt_pk_bf16_f32 v88, v174, v175
	v_cvt_pk_bf16_f32 v89, v182, v183
	v_cvt_pk_bf16_f32 v90, v128, v129
	v_cvt_pk_bf16_f32 v91, v130, v131
	v_cvt_pk_bf16_f32 v92, v132, v133
	v_cvt_pk_bf16_f32 v93, v134, v135
	v_cvt_pk_bf16_f32 v94, v96, v97
	v_cvt_pk_bf16_f32 v95, v98, v95
	ds_read_b128 v[96:99], v165 offset:27712
	ds_read_b128 v[100:103], v165 offset:27728
	ds_read_b128 v[128:131], v165 offset:32320
	ds_read_b128 v[132:135], v165 offset:32336
	s_waitcnt lgkmcnt(0)
	v_mfma_f32_32x32x16_bf16 v[48:63], v[80:83], v[88:91], v[48:63]
	v_mfma_f32_32x32x16_bf16 v[0:15], v[104:107], v[88:91], v[0:15]
	v_mfma_f32_32x32x16_bf16 v[48:63], v[84:87], v[92:95], v[48:63]
	v_mfma_f32_32x32x16_bf16 v[0:15], v[108:111], v[92:95], v[0:15]
	v_mfma_f32_32x32x16_bf16 v[32:47], v[96:99], v[88:91], v[32:47]
	v_mfma_f32_32x32x16_bf16 v[16:31], v[128:131], v[88:91], v[16:31]
	v_mfma_f32_32x32x16_bf16 v[32:47], v[100:103], v[92:95], v[32:47]
	v_mfma_f32_32x32x16_bf16 v[16:31], v[132:135], v[92:95], v[16:31]
	s_add_i32 s4, s9, 0x9000
	s_cmp_lg_u32 s9, 0x12000
	s_cselect_b32 s9, s4, 0
	s_add_i32 s4, s56, 1
	s_cmp_lg_u32 s56, 2
	s_cselect_b32 s56, s4, 0
	s_add_i32 s8, s8, 1
	s_add_u32 s76, s76, 0x80
	s_addc_u32 s77, s77, 0
	s_add_u32 s10, s10, 0x60000
	s_waitcnt lgkmcnt(0)
	s_barrier
	s_addc_u32 s11, s11, 0
	s_add_i32 s58, s58, 64
	s_cmpk_lg_i32 s58, 0x7c0
	s_cbranch_scc0 .LBB0_694

.LBB0_686:
	ds_read_b128 v[166:169], v84 offset:64
	ds_read_b128 v[170:173], v84 offset:96
	ds_read_b128 v[178:181], v84 offset:4672
	ds_read_b128 v[182:185], v84 offset:4704
	s_add_i32 s16, s91, s58
	s_add_i32 s4, s16, 64
	s_cmpk_lt_i32 s4, 0xff42
	s_cselect_b32 s5, 1, 0
	s_cmpk_gt_i32 s4, 0x9e
	s_cselect_b32 s4, 2, s5
	s_cmp_eq_u32 s4, s32
	s_cbranch_scc1 .Lattn_negm_keep_2
	s_mov_b32 s32, s4
	s_cmp_eq_u32 s4, 1
	s_cselect_b64 vcc, -1, 0
	s_cmp_eq_u32 s4, 2
	s_cselect_b64 s[4:5], -1, 0
	v_cndmask_b32_e64 v84, 0, v160, s[4:5]
	v_cndmask_b32_e32 v252, v84, v159, vcc
	v_sub_f32_e32 v84, v252, v156
	v_mov_b32_e32 v79, v84
	v_mov_b32_e32 v78, v84
	v_mov_b32_e32 v77, v84
	v_mov_b32_e32 v76, v84
	v_mov_b32_e32 v75, v84
	v_mov_b32_e32 v74, v84
	v_mov_b32_e32 v73, v84
	v_mov_b32_e32 v72, v84
	v_mov_b32_e32 v71, v84
	v_mov_b32_e32 v70, v84
	v_mov_b32_e32 v69, v84
	v_mov_b32_e32 v68, v84
	v_mov_b32_e32 v67, v84
	v_mov_b32_e32 v66, v84
	v_mov_b32_e32 v65, v84
	v_mov_b32_e32 v64, v84
.Lattn_negm_keep_2:
	s_addk_i32 s16, 0xffa1
	s_cmp_lt_u32 s16, 0xfffffea3
	s_waitcnt lgkmcnt(0)
	s_nop 0
	v_mfma_f32_32x32x16_bf16 v[96:111], v[80:83], v[112:115], v[64:79]
	v_mfma_f32_32x32x16_bf16 v[80:95], v[136:139], v[112:115], v[64:79]
	v_mfma_f32_32x32x16_bf16 v[96:111], v[128:131], v[116:119], v[96:111]
	v_mfma_f32_32x32x16_bf16 v[80:95], v[132:135], v[116:119], v[80:95]
	v_mfma_f32_32x32x16_bf16 v[96:111], v[166:169], v[120:123], v[96:111]
	v_mfma_f32_32x32x16_bf16 v[80:95], v[178:181], v[120:123], v[80:95]
	v_mfma_f32_32x32x16_bf16 v[96:111], v[170:173], v[124:127], v[96:111]
	v_mfma_f32_32x32x16_bf16 v[80:95], v[182:185], v[124:127], v[80:95]
	s_cbranch_scc1 .LBB0_688
	v_add_u32_e32 v180, s58, v164
	v_max_i32_e32 v130, 0xffffff7f, v180
	v_add_u32_e32 v130, 0x81, v130
	s_add_i32 s80, 0, 0x20000
	v_min_u32_e32 v130, 0x100, v130
	v_lshl_add_u32 v132, v130, 2, s80
	v_max_i32_e32 v130, 0xffffff7e, v180
	v_add_u32_e32 v130, 0x82, v130
	v_max_i32_e32 v138, 0xffffff7b, v180
	v_min_u32_e32 v130, 0x100, v130
	v_add_u32_e32 v138, 0x85, v138
	v_max_i32_e32 v128, 0xffffff80, v180
	v_max_i32_e32 v129, 0xffffff60, v180
	v_max_i32_e32 v131, 0xffffff5f, v180
	v_max_i32_e32 v133, 0xffffff5e, v180
	v_lshl_add_u32 v134, v130, 2, s80
	v_max_i32_e32 v130, 0xffffff7d, v180
	v_max_i32_e32 v135, 0xffffff5d, v180
	v_min_u32_e32 v138, 0x100, v138
	v_add_u32_e32 v128, 0x80, v128
	v_add_u32_e32 v129, 0xa0, v129
	v_add_u32_e32 v131, 0xa1, v131
	v_add_u32_e32 v133, 0xa2, v133
	v_add_u32_e32 v130, 0x83, v130
	v_add_u32_e32 v135, 0xa3, v135
	v_lshl_add_u32 v166, v138, 2, s80
	v_max_i32_e32 v138, 0xffffff7a, v180
	v_min_u32_e32 v128, 0x100, v128
	v_min_u32_e32 v129, 0x100, v129
	v_min_u32_e32 v131, 0x100, v131
	v_min_u32_e32 v133, 0x100, v133
	v_min_u32_e32 v130, 0x100, v130
	v_min_u32_e32 v135, 0x100, v135
	v_add_u32_e32 v138, 0x86, v138
	v_max_i32_e32 v172, 0xffffff77, v180
	v_lshl_add_u32 v128, v128, 2, s80
	v_lshl_add_u32 v129, v129, 2, s80
	v_lshl_add_u32 v131, v131, 2, s80
	v_lshl_add_u32 v133, v133, 2, s80
	v_lshl_add_u32 v136, v130, 2, s80
	v_lshl_add_u32 v135, v135, 2, s80
	v_min_u32_e32 v138, 0x100, v138
	v_add_u32_e32 v172, 0x89, v172
	ds_read_b32 v128, v128
	ds_read_b32 v130, v129
	ds_read_b32 v129, v132
	ds_read_b32 v131, v131
	ds_read_b32 v132, v134
	ds_read_b32 v134, v133
	ds_read_b32 v133, v136
	ds_read_b32 v135, v135
	v_max_i32_e32 v136, 0xffffff7c, v180
	v_max_i32_e32 v137, 0xffffff5c, v180
	v_max_i32_e32 v139, 0xffffff5b, v180
	v_max_i32_e32 v167, 0xffffff5a, v180
	v_lshl_add_u32 v168, v138, 2, s80
	v_max_i32_e32 v138, 0xffffff79, v180
	v_max_i32_e32 v169, 0xffffff59, v180
	v_min_u32_e32 v172, 0x100, v172
	v_add_u32_e32 v136, 0x84, v136
	v_add_u32_e32 v137, 0xa4, v137
	v_add_u32_e32 v139, 0xa5, v139
	v_add_u32_e32 v167, 0xa6, v167
	v_add_u32_e32 v138, 0x87, v138
	v_add_u32_e32 v169, 0xa7, v169
	v_lshl_add_u32 v174, v172, 2, s80
	v_max_i32_e32 v172, 0xffffff76, v180
	v_min_u32_e32 v136, 0x100, v136
	v_min_u32_e32 v137, 0x100, v137
	v_min_u32_e32 v139, 0x100, v139
	v_min_u32_e32 v167, 0x100, v167
	v_min_u32_e32 v138, 0x100, v138
	v_min_u32_e32 v169, 0x100, v169
	v_add_u32_e32 v172, 0x8a, v172
	v_lshl_add_u32 v136, v136, 2, s80
	v_lshl_add_u32 v137, v137, 2, s80
	v_lshl_add_u32 v139, v139, 2, s80
	v_lshl_add_u32 v167, v167, 2, s80
	v_lshl_add_u32 v170, v138, 2, s80
	v_lshl_add_u32 v169, v169, 2, s80
	v_min_u32_e32 v172, 0x100, v172
	ds_read_b32 v136, v136
	ds_read_b32 v138, v137
	ds_read_b32 v137, v166
	ds_read_b32 v139, v139
	ds_read_b32 v166, v168
	ds_read_b32 v168, v167
	ds_read_b32 v167, v170
	ds_read_b32 v169, v169
	v_max_i32_e32 v170, 0xffffff78, v180
	v_max_i32_e32 v171, 0xffffff58, v180
	v_max_i32_e32 v173, 0xffffff57, v180
	v_max_i32_e32 v175, 0xffffff56, v180
	v_lshl_add_u32 v178, v172, 2, s80
	v_max_i32_e32 v172, 0xffffff75, v180
	v_max_i32_e32 v179, 0xffffff55, v180
	v_add_u32_e32 v170, 0x88, v170
	v_add_u32_e32 v171, 0xa8, v171
	v_add_u32_e32 v173, 0xa9, v173
	v_add_u32_e32 v175, 0xaa, v175
	v_add_u32_e32 v172, 0x8b, v172
	v_add_u32_e32 v179, 0xab, v179
	v_max_i32_e32 v184, 0xffffff53, v180
	v_max_i32_e32 v185, 0xffffff52, v180
	v_min_u32_e32 v170, 0x100, v170
	v_min_u32_e32 v171, 0x100, v171
	v_min_u32_e32 v173, 0x100, v173
	v_min_u32_e32 v175, 0x100, v175
	v_min_u32_e32 v172, 0x100, v172
	v_min_u32_e32 v179, 0x100, v179
	v_add_u32_e32 v184, 0xad, v184
	v_add_u32_e32 v185, 0xae, v185
	v_lshl_add_u32 v170, v170, 2, s80
	v_lshl_add_u32 v171, v171, 2, s80
	v_lshl_add_u32 v173, v173, 2, s80
	v_lshl_add_u32 v175, v175, 2, s80
	v_lshl_add_u32 v181, v172, 2, s80
	v_lshl_add_u32 v179, v179, 2, s80
	v_min_u32_e32 v184, 0x100, v184
	v_min_u32_e32 v185, 0x100, v185
	ds_read_b32 v170, v170
	ds_read_b32 v172, v171
	ds_read_b32 v171, v174
	ds_read_b32 v173, v173
	ds_read_b32 v174, v178
	ds_read_b32 v178, v175
	ds_read_b32 v175, v181
	ds_read_b32 v179, v179
	v_max_i32_e32 v181, 0xffffff74, v180
	v_max_i32_e32 v182, 0xffffff54, v180
	v_max_i32_e32 v183, 0xffffff73, v180
	v_lshl_add_u32 v188, v184, 2, s80
	v_max_i32_e32 v184, 0xffffff72, v180
	v_lshl_add_u32 v186, v185, 2, s80
	v_max_i32_e32 v185, 0xffffff71, v180
	v_max_i32_e32 v180, 0xffffff51, v180
	v_add_u32_e32 v181, 0x8c, v181
	v_add_u32_e32 v182, 0xac, v182
	v_add_u32_e32 v183, 0x8d, v183
	v_add_u32_e32 v184, 0x8e, v184
	v_add_u32_e32 v185, 0x8f, v185
	v_add_u32_e32 v180, 0xaf, v180
	v_min_u32_e32 v181, 0x100, v181
	v_min_u32_e32 v182, 0x100, v182
	v_min_u32_e32 v183, 0x100, v183
	v_min_u32_e32 v184, 0x100, v184
	v_min_u32_e32 v185, 0x100, v185
	v_min_u32_e32 v180, 0x100, v180
	v_lshl_add_u32 v181, v181, 2, s80
	v_lshl_add_u32 v182, v182, 2, s80
	v_lshl_add_u32 v183, v183, 2, s80
	v_lshl_add_u32 v184, v184, 2, s80
	v_lshl_add_u32 v185, v185, 2, s80
	v_lshl_add_u32 v187, v180, 2, s80
	ds_read_b32 v180, v181
	ds_read_b32 v182, v182
	ds_read_b32 v184, v184
	ds_read_b32 v185, v185
	ds_read_b32 v181, v183
	ds_read_b32 v187, v187
	ds_read_b32 v186, v186
	ds_read_b32 v183, v188
	s_waitcnt lgkmcnt(0)
	v_pk_add_f32 v[110:111], v[110:111], v[184:185]
	v_pk_add_f32 v[108:109], v[108:109], v[180:181]
	v_pk_add_f32 v[106:107], v[106:107], v[174:175]
	v_pk_add_f32 v[104:105], v[104:105], v[170:171]
	v_pk_add_f32 v[102:103], v[102:103], v[166:167]
	v_pk_add_f32 v[100:101], v[100:101], v[136:137]
	v_pk_add_f32 v[98:99], v[98:99], v[132:133]
	v_pk_add_f32 v[96:97], v[96:97], v[128:129]
	v_pk_add_f32 v[94:95], v[94:95], v[186:187]
	v_pk_add_f32 v[92:93], v[92:93], v[182:183]
	v_pk_add_f32 v[90:91], v[90:91], v[178:179]
	v_pk_add_f32 v[88:89], v[88:89], v[172:173]
	v_pk_add_f32 v[86:87], v[86:87], v[168:169]
	v_pk_add_f32 v[84:85], v[84:85], v[138:139]
	v_pk_add_f32 v[82:83], v[82:83], v[134:135]
	v_pk_add_f32 v[80:81], v[80:81], v[130:131]

.LBB0_698:
	s_nop 10
	v_max_f32_e32 v32, v1, v1
	v_max_f32_e32 v33, v17, v17
	v_max_f32_e32 v32, v33, v32
	v_max_f32_e32 v33, v2, v2
	v_max_f32_e32 v34, v18, v18
	v_max_f32_e32 v33, v34, v33
	v_max_f32_e32 v34, v3, v3
	v_max_f32_e32 v35, v19, v19
	v_max3_f32 v32, v16, v0, v32
	v_max_f32_e32 v34, v35, v34
	v_max3_f32 v32, v32, v33, v34
	v_max_f32_e32 v33, v4, v4
	v_max_f32_e32 v34, v20, v20
	v_max_f32_e32 v33, v34, v33
	v_max_f32_e32 v34, v5, v5
	v_max_f32_e32 v35, v21, v21
	v_max_f32_e32 v34, v35, v34
	v_max3_f32 v32, v32, v33, v34
	v_max_f32_e32 v33, v6, v6
	v_max_f32_e32 v34, v22, v22
	v_max_f32_e32 v33, v34, v33
	v_max_f32_e32 v34, v7, v7
	v_max_f32_e32 v35, v23, v23
	v_max_f32_e32 v34, v35, v34
	v_max3_f32 v32, v32, v33, v34
	v_max_f32_e32 v33, v8, v8
	v_max_f32_e32 v34, v24, v24
	v_max_f32_e32 v33, v34, v33
	v_max_f32_e32 v34, v9, v9
	v_max_f32_e32 v35, v25, v25
	v_max_f32_e32 v34, v35, v34
	v_max3_f32 v32, v32, v33, v34
	v_max_f32_e32 v33, v10, v10
	v_max_f32_e32 v34, v26, v26
	v_max_f32_e32 v33, v34, v33
	v_max_f32_e32 v34, v11, v11
	v_max_f32_e32 v35, v27, v27
	v_max_f32_e32 v34, v35, v34
	v_max3_f32 v32, v32, v33, v34
	v_max_f32_e32 v33, v12, v12
	v_max_f32_e32 v34, v28, v28
	v_max_f32_e32 v33, v34, v33
	v_max_f32_e32 v34, v13, v13
	v_max_f32_e32 v35, v29, v29
	v_max_f32_e32 v34, v35, v34
	v_max3_f32 v32, v32, v33, v34
	v_max_f32_e32 v33, v14, v14
	v_max_f32_e32 v34, v30, v30
	v_max_f32_e32 v33, v34, v33
	v_max_f32_e32 v34, v15, v15
	v_max_f32_e32 v35, v31, v31
	v_max_f32_e32 v34, v35, v34
	v_max3_f32 v32, v32, v33, v34
	v_mov_b32_e32 v33, v32
	s_nop 1
	v_permlane32_swap_b32_e32 v32, v33
	v_max_f32_e32 v33, v33, v33
	v_max_f32_e32 v32, v32, v32
	v_max_f32_e32 v64, v32, v33
	v_sub_f32_e32 v32, v0, v64
	v_sub_f32_e32 v0, v16, v64
	v_sub_f32_e32 v33, v1, v64
	v_sub_f32_e32 v1, v17, v64
	v_exp_f32_e32 v0, v0
	v_sub_f32_e32 v34, v2, v64
	v_sub_f32_e32 v2, v18, v64
	v_exp_f32_e32 v1, v1
	v_sub_f32_e32 v35, v3, v64
	v_sub_f32_e32 v3, v19, v64
	v_exp_f32_e32 v2, v2
	v_sub_f32_e32 v36, v4, v64
	v_sub_f32_e32 v4, v20, v64
	v_exp_f32_e32 v3, v3
	v_sub_f32_e32 v37, v5, v64
	v_sub_f32_e32 v5, v21, v64
	v_add_f32_e32 v16, 0, v0
	v_exp_f32_e32 v4, v4
	v_sub_f32_e32 v38, v6, v64
	v_sub_f32_e32 v6, v22, v64
	v_add_f32_e32 v16, v1, v16
	v_exp_f32_e32 v5, v5
	v_sub_f32_e32 v39, v7, v64
	v_sub_f32_e32 v7, v23, v64
	v_add_f32_e32 v16, v2, v16
	v_exp_f32_e32 v6, v6
	v_sub_f32_e32 v65, v8, v64
	v_sub_f32_e32 v8, v24, v64
	v_add_f32_e32 v16, v3, v16
	v_exp_f32_e32 v7, v7
	v_sub_f32_e32 v66, v9, v64
	v_sub_f32_e32 v9, v25, v64
	v_add_f32_e32 v16, v4, v16
	v_exp_f32_e32 v8, v8
	v_sub_f32_e32 v100, v10, v64
	v_sub_f32_e32 v10, v26, v64
	v_add_f32_e32 v16, v5, v16
	v_exp_f32_e32 v9, v9
	v_sub_f32_e32 v101, v11, v64
	v_sub_f32_e32 v11, v27, v64
	v_add_f32_e32 v16, v6, v16
	v_exp_f32_e32 v10, v10
	v_sub_f32_e32 v102, v12, v64
	v_sub_f32_e32 v12, v28, v64
	v_add_f32_e32 v16, v7, v16
	v_exp_f32_e32 v11, v11
	v_sub_f32_e32 v103, v13, v64
	v_sub_f32_e32 v13, v29, v64
	v_add_f32_e32 v16, v8, v16
	v_exp_f32_e32 v12, v12
	v_sub_f32_e32 v104, v14, v64
	v_sub_f32_e32 v14, v30, v64
	v_add_f32_e32 v16, v9, v16
	v_exp_f32_e32 v13, v13
	v_sub_f32_e32 v105, v15, v64
	v_sub_f32_e32 v15, v31, v64
	v_add_f32_e32 v16, v10, v16
	v_exp_f32_e32 v14, v14
	v_add_f32_e32 v16, v11, v16
	v_exp_f32_e32 v15, v15
	v_add_f32_e32 v16, v12, v16
	v_add_f32_e32 v16, v13, v16
	v_mul_u32_u24_e32 v164, 0x90, v140
	v_and_b32_e32 v165, 32, v141
	v_add_f32_e32 v16, v14, v16
	v_add_f32_e32 v16, v15, v16
	s_waitcnt lgkmcnt(0)
	s_barrier
	v_add3_u32 v106, 0, v164, v165
	v_add_f32_e32 v67, 0, v16
	v_cvt_pk_bf16_f32 v16, v0, v1
	v_cvt_pk_bf16_f32 v17, v2, v3
	v_cvt_pk_bf16_f32 v18, v4, v5
	v_cvt_pk_bf16_f32 v19, v6, v7
	ds_read_b128 v[0:3], v106 offset:18432
	ds_read_b128 v[20:23], v106 offset:18448
	ds_read_b128 v[4:7], v106 offset:23040
	ds_read_b128 v[24:27], v106 offset:23056
	v_cvt_pk_bf16_f32 v68, v8, v9
	v_cvt_pk_bf16_f32 v69, v10, v11
	v_cvt_pk_bf16_f32 v70, v12, v13
	v_cvt_pk_bf16_f32 v71, v14, v15
	s_add_u32 s16, s21, 0xc0000
	s_addc_u32 s17, s84, 0
	s_add_u32 s33, s44, 0x100
	s_addc_u32 s38, s85, 0
	s_add_u32 s10, s21, 0xc0080
	s_addc_u32 s11, s84, 0
	s_and_b64 s[0:1], s[52:53], exec
	s_cselect_b32 s2, s38, s17
	s_cselect_b32 s4, s33, s16
	s_and_b64 s[0:1], s[48:49], exec
	s_cselect_b32 s4, s10, s4
	s_cselect_b32 s2, s11, s2
	s_and_b64 s[0:1], s[36:37], exec
	s_cselect_b32 s1, s17, s2
	s_cselect_b32 s0, s16, s4
	s_add_i32 m0, s26, 0x12000
	s_or_b32 s4, s3, 8
	s_cmp_lt_i32 s4, 9
	v_lshl_add_u64 v[8:9], s[0:1], 0, v[176:177]
	s_cselect_b64 s[0:1], -1, 0
	s_cmp_lt_u32 s4, 18
	s_cselect_b64 s[6:7], -1, 0
	s_cmp_lt_u32 s4, 36
	s_cselect_b64 s[12:13], -1, 0
	s_and_b64 s[8:9], s[12:13], exec
	s_cselect_b32 s2, s38, s17
	s_cselect_b32 s5, s33, s16
	s_and_b64 s[8:9], s[6:7], exec
	s_cselect_b32 s5, s10, s5
	s_cselect_b32 s2, s11, s2
	s_and_b64 s[8:9], s[0:1], exec
	s_cselect_b32 s9, s17, s2
	s_cselect_b32 s8, s16, s5
	s_lshl_b32 s2, s4, 10
	s_add_i32 s2, s2, 0
	global_load_lds_dwordx4 v[8:9], off
	s_add_i32 m0, s2, 0x12000
	s_or_b32 s5, s3, 16
	s_cmp_lt_u32 s5, 18
	s_cselect_b64 s[14:15], -1, 0
	s_cmp_lt_u32 s5, 36
	s_cselect_b64 s[22:23], -1, 0
	v_lshl_add_u64 v[8:9], s[8:9], 0, v[148:149]
	s_and_b64 s[8:9], s[22:23], exec
	s_cselect_b32 s21, s33, s16
	s_cselect_b32 s24, s38, s17
	s_and_b64 s[8:9], s[14:15], exec
	s_cselect_b32 s9, s11, s24
	s_cselect_b32 s8, s10, s21
	s_lshl_b32 s21, s5, 10
	global_load_lds_dwordx4 v[8:9], off
	v_lshl_add_u64 v[8:9], s[8:9], 0, v[150:151]
	s_add_i32 s8, s21, 0
	s_add_i32 m0, s8, 0x12000
	s_or_b32 s9, s3, 24
	s_cmp_lt_u32 s9, 36
	s_cselect_b64 s[24:25], -1, 0
	s_and_b64 s[10:11], s[24:25], exec
	s_cselect_b32 s11, s38, s17
	s_cselect_b32 s10, s33, s16
	s_lshl_b32 s8, s9, 10
	s_add_i32 s26, s8, 0
	global_load_lds_dwordx4 v[8:9], off
	s_add_i32 m0, s26, 0x12000
	s_or_b32 s27, s3, 32
	s_cmp_lt_u32 s27, 36
	s_cselect_b64 s[28:29], -1, 0
	v_lshl_add_u64 v[8:9], s[10:11], 0, v[152:153]
	s_and_b64 s[10:11], s[28:29], exec
	s_cselect_b32 s11, s38, s17
	s_cselect_b32 s10, s33, s16
	s_lshl_b32 s3, s27, 10
	s_add_i32 s8, s3, 0
	global_load_lds_dwordx4 v[8:9], off
	v_lshl_add_u64 v[8:9], s[10:11], 0, v[154:155]
	s_add_i32 m0, s8, 0x12000
	s_nop 0
	global_load_lds_dwordx4 v[8:9], off
	ds_read_b128 v[28:31], v106 offset:27648
	ds_read_b128 v[72:75], v106 offset:27664
	ds_read_b128 v[76:79], v106 offset:32256
	ds_read_b128 v[80:83], v106 offset:32272
	s_waitcnt lgkmcnt(0)
	v_mfma_f32_32x32x16_bf16 v[48:63], v[0:3], v[16:19], 0
	v_exp_f32_e32 v107, v32
	v_exp_f32_e32 v108, v33
	v_exp_f32_e32 v109, v34
	v_exp_f32_e32 v110, v35
	v_add_f32_e32 v32, 0, v107
	v_add_f32_e32 v32, v108, v32
	v_add_f32_e32 v32, v109, v32
	v_mfma_f32_32x32x16_bf16 v[0:15], v[4:7], v[16:19], 0
	v_add_f32_e32 v32, v110, v32
	v_mfma_f32_32x32x16_bf16 v[48:63], v[20:23], v[68:71], v[48:63]
	v_exp_f32_e32 v111, v36
	v_exp_f32_e32 v128, v37
	v_exp_f32_e32 v129, v38
	v_exp_f32_e32 v130, v39
	v_add_f32_e32 v20, v111, v32
	v_add_f32_e32 v20, v128, v20
	v_add_f32_e32 v20, v129, v20
	v_mfma_f32_32x32x16_bf16 v[0:15], v[24:27], v[68:71], v[0:15]
	v_add_f32_e32 v20, v130, v20
	ds_read_b128 v[84:87], v106 offset:18496
	ds_read_b128 v[88:91], v106 offset:18512
	ds_read_b128 v[92:95], v106 offset:23104
	ds_read_b128 v[96:99], v106 offset:23120
	v_exp_f32_e32 v131, v65
	v_exp_f32_e32 v132, v66
	v_exp_f32_e32 v100, v100
	v_exp_f32_e32 v101, v101
	v_add_f32_e32 v20, v131, v20
	v_add_f32_e32 v20, v132, v20
	v_add_f32_e32 v20, v100, v20
	v_mfma_f32_32x32x16_bf16 v[32:47], v[28:31], v[16:19], 0
	v_add_f32_e32 v65, v101, v20
	v_mfma_f32_32x32x16_bf16 v[16:31], v[76:79], v[16:19], 0
	v_mfma_f32_32x32x16_bf16 v[32:47], v[72:75], v[68:71], v[32:47]
	v_exp_f32_e32 v72, v102
	v_exp_f32_e32 v73, v103
	v_exp_f32_e32 v74, v104
	v_exp_f32_e32 v75, v105
	v_add_f32_e32 v65, v72, v65
	v_add_f32_e32 v65, v73, v65
	v_add_f32_e32 v65, v74, v65
	v_mfma_f32_32x32x16_bf16 v[16:31], v[80:83], v[68:71], v[16:31]
	v_add_f32_e32 v65, v75, v65
	v_mov_b32_e32 v66, v177
	v_add_f32_e64 v156, v64, v66
	v_add_f32_e64 v157, v65, v67
	v_cvt_pk_bf16_f32 v66, v107, v108
	v_sub_f32_e32 v64, v163, v156
	v_cvt_pk_bf16_f32 v67, v109, v110
	v_cvt_pk_bf16_f32 v68, v111, v128
	v_cvt_pk_bf16_f32 v69, v129, v130
	v_cvt_pk_bf16_f32 v70, v131, v132
	v_cvt_pk_bf16_f32 v71, v100, v101
	v_cvt_pk_bf16_f32 v72, v72, v73
	v_cvt_pk_bf16_f32 v73, v74, v75
	ds_read_b128 v[74:77], v106 offset:27712
	ds_read_b128 v[78:81], v106 offset:27728
	ds_read_b128 v[100:103], v106 offset:32320
	ds_read_b128 v[104:107], v106 offset:32336
	s_waitcnt lgkmcnt(0)
	v_mfma_f32_32x32x16_bf16 v[48:63], v[84:87], v[66:69], v[48:63]
	v_mfma_f32_32x32x16_bf16 v[0:15], v[92:95], v[66:69], v[0:15]
	v_mfma_f32_32x32x16_bf16 v[48:63], v[88:91], v[70:73], v[48:63]
	v_mfma_f32_32x32x16_bf16 v[0:15], v[96:99], v[70:73], v[0:15]
	v_mfma_f32_32x32x16_bf16 v[32:47], v[74:77], v[66:69], v[32:47]
	v_mfma_f32_32x32x16_bf16 v[16:31], v[100:103], v[66:69], v[16:31]
	v_mfma_f32_32x32x16_bf16 v[32:47], v[78:81], v[70:73], v[32:47]
	v_mfma_f32_32x32x16_bf16 v[16:31], v[104:107], v[70:73], v[16:31]
	s_cmp_lt_i32 s4, 36
	s_cselect_b64 s[10:11], -1, 0
	s_cmp_lt_i32 s5, 36
	s_cselect_b64 s[38:39], -1, 0
	s_or_b32 s8, s21, 0x12000
	s_cmp_lt_i32 s9, 36
	s_cselect_b64 s[42:43], -1, 0
	s_cmp_lt_i32 s27, 36
	s_cselect_b64 s[50:51], -1, 0
	s_add_i32 s4, s20, s88
	s_waitcnt vmcnt(5) lgkmcnt(0)
	s_barrier
	v_add_u32_e32 v65, s4, v140
	v_sub_u32_e32 v65, v146, v65
	s_or_b32 s9, s3, 0x12000
	v_add_u32_e32 v166, 64, v65
	s_mov_b32 s20, 0
	s_sub_i32 s27, 0, s4
	s_mov_b32 s33, 1
	s_mov_b32 s44, 0x9000
	s_mov_b32 s45, 0
	v_mov_b32_e32 v65, v64
	v_mov_b32_e32 v66, v64
	v_mov_b32_e32 v67, v64
	v_mov_b32_e32 v68, v64
	v_mov_b32_e32 v69, v64
	v_mov_b32_e32 v70, v64
	v_mov_b32_e32 v71, v64
	v_mov_b32_e32 v72, v64
	v_mov_b32_e32 v73, v64
	v_mov_b32_e32 v74, v64
	v_mov_b32_e32 v75, v64
	v_mov_b32_e32 v76, v64
	v_mov_b32_e32 v77, v64
	v_mov_b32_e32 v78, v64
	v_mov_b32_e32 v79, v64
	s_add_u32 s16, s46, 0xffffff80
	s_addc_u32 s17, s47, -1
	s_mov_b32 s62, 0x60000
	s_and_b64 s[56:57], s[52:53], exec
	s_cselect_b32 s59, s41, s17
	s_cselect_b32 s58, s40, s16
	s_cselect_b32 s63, 0x80, s62
	s_and_b64 s[56:57], s[48:49], exec
	s_cselect_b32 s59, s47, s59
	s_cselect_b32 s58, s46, s58
	s_cselect_b32 s63, s62, s63
	s_and_b64 s[56:57], s[36:37], exec
	s_cselect_b32 s57, s17, s59
	s_cselect_b32 s56, s16, s58
	s_cselect_b32 s63, s62, s63
	v_lshl_add_u64 v[240:241], s[56:57], 0, v[176:177]
	v_mov_b32_e32 v200, s63
	v_mov_b32_e32 v201, 0
	s_and_b64 s[56:57], s[12:13], exec
	s_cselect_b32 s59, s41, s17
	s_cselect_b32 s58, s40, s16
	s_cselect_b32 s63, 0x80, s62
	s_and_b64 s[56:57], s[6:7], exec
	s_cselect_b32 s59, s47, s59
	s_cselect_b32 s58, s46, s58
	s_cselect_b32 s63, s62, s63
	s_and_b64 s[56:57], s[0:1], exec
	s_cselect_b32 s57, s17, s59
	s_cselect_b32 s56, s16, s58
	s_cselect_b32 s63, s62, s63
	v_lshl_add_u64 v[242:243], s[56:57], 0, v[148:149]
	v_mov_b32_e32 v202, s63
	v_mov_b32_e32 v203, 0
	s_and_b64 s[56:57], s[22:23], exec
	s_cselect_b32 s59, s41, s17
	s_cselect_b32 s58, s40, s16
	s_cselect_b32 s63, 0x80, s62
	s_and_b64 s[56:57], s[14:15], exec
	s_cselect_b32 s57, s47, s59
	s_cselect_b32 s56, s46, s58
	s_cselect_b32 s63, s62, s63
	v_lshl_add_u64 v[244:245], s[56:57], 0, v[150:151]
	v_mov_b32_e32 v204, s63
	v_mov_b32_e32 v205, 0
	s_and_b64 s[56:57], s[24:25], exec
	s_cselect_b32 s57, s41, s17
	s_cselect_b32 s56, s40, s16
	s_cselect_b32 s63, 0x80, s62
	v_lshl_add_u64 v[246:247], s[56:57], 0, v[152:153]
	v_mov_b32_e32 v206, s63
	v_mov_b32_e32 v207, 0
	s_and_b64 s[56:57], s[28:29], exec
	s_cselect_b32 s57, s41, s17
	s_cselect_b32 s56, s40, s16
	s_cselect_b32 s63, 0x80, s62
	v_lshl_add_u64 v[248:249], s[56:57], 0, v[154:155]
	v_mov_b32_e32 v208, s63
	v_mov_b32_e32 v209, 0
	s_mov_b32 s32, 3
	s_branch .LBB0_700
.LBB0_699:
	v_add_f32_e32 v96, v97, v96
	v_add_f32_e32 v96, v98, v96
	v_add_f32_e32 v80, v81, v80
	v_add_f32_e32 v96, v99, v96
	v_add_f32_e32 v80, v82, v80
	v_add_f32_e32 v96, v100, v96
	v_add_f32_e32 v80, v83, v80
	v_add_f32_e32 v96, v101, v96
	v_add_f32_e32 v80, v84, v80
	v_add_f32_e32 v96, v102, v96
	v_add_f32_e32 v80, v85, v80
	v_add_f32_e32 v96, v103, v96
	v_add_f32_e32 v80, v86, v80
	v_add_f32_e32 v96, v104, v96
	v_add_f32_e32 v80, v87, v80
	s_add_i32 s4, s44, 0x9000
	v_add_f32_e32 v96, v105, v96
	v_add_f32_e32 v80, v88, v80
	s_cmp_lg_u32 s44, 0x12000
	v_add_f32_e32 v96, v106, v96
	v_add_f32_e32 v80, v89, v80
	s_cselect_b32 s44, s4, 0
	s_add_i32 s4, s45, 1
	v_add_f32_e32 v96, v107, v96
	v_add_f32_e32 v80, v90, v80
	s_cmp_lg_u32 s45, 2
	v_add_f32_e32 v96, v108, v96
	v_add_f32_e32 v80, v91, v80
	s_cselect_b32 s45, s4, 0
	s_add_i32 s33, s33, 1
	v_add_f32_e32 v96, v109, v96
	v_add_f32_e32 v80, v92, v80
	s_add_u32 s40, s40, 0x80
	v_add_f32_e32 v96, v110, v96
	v_add_f32_e32 v80, v93, v80
	s_addc_u32 s41, s41, 0
	v_add_f32_e32 v96, v111, v96
	v_add_f32_e32 v80, v94, v80
	s_add_u32 s46, s46, 0x60000
	v_add_f32_e32 v96, v157, v96
	v_add_f32_e32 v80, v95, v80
	s_addc_u32 s47, s47, 0
	s_add_i32 s20, s20, 64
	v_add_f32_e32 v157, v96, v80
	s_cmpk_eq_i32 s20, 0x7c0
	s_cbranch_scc1 .LBB0_710
.LBB0_700:
	s_add_i32 s56, s44, 0
	v_add3_u32 v84, s56, v162, v146
	ds_read_b128 v[80:83], v84
	ds_read_b128 v[128:131], v84 offset:32
	ds_read_b128 v[132:135], v84 offset:4608
	ds_read_b128 v[136:139], v84 offset:4640
	ds_read_b128 v[140:143], v84 offset:64
	ds_read_b128 v[168:171], v84 offset:96
	ds_read_b128 v[172:175], v84 offset:4672
	ds_read_b128 v[178:181], v84 offset:4704
	s_add_i32 s16, s27, s20
	s_add_i32 s4, s16, 64
	s_cmpk_lt_i32 s4, 0xff42
	s_cselect_b32 s5, 1, 0
	s_cmpk_gt_i32 s4, 0x9e
	s_cselect_b32 s4, 2, s5
	s_cmp_eq_u32 s4, s32
	s_cbranch_scc1 .Lattn_negm_keep_3
	s_mov_b32 s32, s4
	s_cmp_eq_u32 s4, 1
	s_cselect_b64 vcc, -1, 0
	s_cmp_eq_u32 s4, 2
	s_cselect_b64 s[4:5], -1, 0
	v_cndmask_b32_e64 v84, 0, v160, s[4:5]
	v_cndmask_b32_e32 v252, v84, v159, vcc
	v_sub_f32_e32 v84, v252, v156
	v_mov_b32_e32 v79, v84
	v_mov_b32_e32 v78, v84
	v_mov_b32_e32 v77, v84
	v_mov_b32_e32 v76, v84
	v_mov_b32_e32 v75, v84
	v_mov_b32_e32 v74, v84
	v_mov_b32_e32 v73, v84
	v_mov_b32_e32 v72, v84
	v_mov_b32_e32 v71, v84
	v_mov_b32_e32 v70, v84
	v_mov_b32_e32 v69, v84
	v_mov_b32_e32 v68, v84
	v_mov_b32_e32 v67, v84
	v_mov_b32_e32 v66, v84
	v_mov_b32_e32 v65, v84
	v_mov_b32_e32 v64, v84
.Lattn_negm_keep_3:
	s_addk_i32 s16, 0xffa1
	s_cmp_lt_u32 s16, 0xfffffea3
	s_waitcnt lgkmcnt(0)
	s_nop 0
	v_mfma_f32_32x32x16_bf16 v[96:111], v[80:83], v[112:115], v[64:79]
	v_mfma_f32_32x32x16_bf16 v[80:95], v[132:135], v[112:115], v[64:79]
	v_mfma_f32_32x32x16_bf16 v[96:111], v[128:131], v[116:119], v[96:111]
	v_mfma_f32_32x32x16_bf16 v[80:95], v[136:139], v[116:119], v[80:95]
	v_mfma_f32_32x32x16_bf16 v[96:111], v[140:143], v[120:123], v[96:111]
	v_mfma_f32_32x32x16_bf16 v[80:95], v[172:175], v[120:123], v[80:95]
	v_mfma_f32_32x32x16_bf16 v[96:111], v[168:171], v[124:127], v[96:111]
	v_mfma_f32_32x32x16_bf16 v[80:95], v[178:181], v[124:127], v[80:95]
	s_cbranch_scc1 .LBB0_702
	v_add_u32_e32 v178, s20, v166
	v_max_i32_e32 v130, 0xffffff7f, v178
	v_add_u32_e32 v130, 0x81, v130
	s_add_i32 s57, 0, 0x20000
	v_min_u32_e32 v130, 0x100, v130
	v_lshl_add_u32 v132, v130, 2, s57
	v_max_i32_e32 v130, 0xffffff7e, v178
	v_add_u32_e32 v130, 0x82, v130
	v_max_i32_e32 v138, 0xffffff7b, v178
	v_min_u32_e32 v130, 0x100, v130
	v_add_u32_e32 v138, 0x85, v138
	v_max_i32_e32 v128, 0xffffff80, v178
	v_max_i32_e32 v129, 0xffffff60, v178
	v_max_i32_e32 v131, 0xffffff5f, v178
	v_max_i32_e32 v133, 0xffffff5e, v178
	v_lshl_add_u32 v134, v130, 2, s57
	v_max_i32_e32 v130, 0xffffff7d, v178
	v_max_i32_e32 v135, 0xffffff5d, v178
	v_min_u32_e32 v138, 0x100, v138
	v_add_u32_e32 v128, 0x80, v128
	v_add_u32_e32 v129, 0xa0, v129
	v_add_u32_e32 v131, 0xa1, v131
	v_add_u32_e32 v133, 0xa2, v133
	v_add_u32_e32 v130, 0x83, v130
	v_add_u32_e32 v135, 0xa3, v135
	v_lshl_add_u32 v140, v138, 2, s57
	v_max_i32_e32 v138, 0xffffff7a, v178
	v_min_u32_e32 v128, 0x100, v128
	v_min_u32_e32 v129, 0x100, v129
	v_min_u32_e32 v131, 0x100, v131
	v_min_u32_e32 v133, 0x100, v133
	v_min_u32_e32 v130, 0x100, v130
	v_min_u32_e32 v135, 0x100, v135
	v_add_u32_e32 v138, 0x86, v138
	v_max_i32_e32 v170, 0xffffff77, v178
	v_lshl_add_u32 v128, v128, 2, s57
	v_lshl_add_u32 v129, v129, 2, s57
	v_lshl_add_u32 v131, v131, 2, s57
	v_lshl_add_u32 v133, v133, 2, s57
	v_lshl_add_u32 v136, v130, 2, s57
	v_lshl_add_u32 v135, v135, 2, s57
	v_min_u32_e32 v138, 0x100, v138
	v_add_u32_e32 v170, 0x89, v170
	ds_read_b32 v128, v128
	ds_read_b32 v130, v129
	ds_read_b32 v129, v132
	ds_read_b32 v131, v131
	ds_read_b32 v132, v134
	ds_read_b32 v134, v133
	ds_read_b32 v133, v136
	ds_read_b32 v135, v135
	v_max_i32_e32 v136, 0xffffff7c, v178
	v_max_i32_e32 v137, 0xffffff5c, v178
	v_max_i32_e32 v139, 0xffffff5b, v178
	v_max_i32_e32 v141, 0xffffff5a, v178
	v_lshl_add_u32 v142, v138, 2, s57
	v_max_i32_e32 v138, 0xffffff79, v178
	v_max_i32_e32 v143, 0xffffff59, v178
	v_min_u32_e32 v170, 0x100, v170
	v_add_u32_e32 v136, 0x84, v136
	v_add_u32_e32 v137, 0xa4, v137
	v_add_u32_e32 v139, 0xa5, v139
	v_add_u32_e32 v141, 0xa6, v141
	v_add_u32_e32 v138, 0x87, v138
	v_add_u32_e32 v143, 0xa7, v143
	v_lshl_add_u32 v172, v170, 2, s57
	v_max_i32_e32 v170, 0xffffff76, v178
	v_min_u32_e32 v136, 0x100, v136
	v_min_u32_e32 v137, 0x100, v137
	v_min_u32_e32 v139, 0x100, v139
	v_min_u32_e32 v141, 0x100, v141
	v_min_u32_e32 v138, 0x100, v138
	v_min_u32_e32 v143, 0x100, v143
	v_add_u32_e32 v170, 0x8a, v170
	v_lshl_add_u32 v136, v136, 2, s57
	v_lshl_add_u32 v137, v137, 2, s57
	v_lshl_add_u32 v139, v139, 2, s57
	v_lshl_add_u32 v141, v141, 2, s57
	v_lshl_add_u32 v168, v138, 2, s57
	v_lshl_add_u32 v143, v143, 2, s57
	v_min_u32_e32 v170, 0x100, v170
	ds_read_b32 v136, v136
	ds_read_b32 v138, v137
	ds_read_b32 v137, v140
	ds_read_b32 v139, v139
	ds_read_b32 v140, v142
	ds_read_b32 v142, v141
	ds_read_b32 v141, v168
	ds_read_b32 v143, v143
	v_max_i32_e32 v168, 0xffffff78, v178
	v_max_i32_e32 v169, 0xffffff58, v178
	v_max_i32_e32 v171, 0xffffff57, v178
	v_max_i32_e32 v173, 0xffffff56, v178
	v_lshl_add_u32 v174, v170, 2, s57
	v_max_i32_e32 v170, 0xffffff75, v178
	v_max_i32_e32 v175, 0xffffff55, v178
	v_add_u32_e32 v168, 0x88, v168
	v_add_u32_e32 v169, 0xa8, v169
	v_add_u32_e32 v171, 0xa9, v171
	v_add_u32_e32 v173, 0xaa, v173
	v_add_u32_e32 v170, 0x8b, v170
	v_add_u32_e32 v175, 0xab, v175
	v_max_i32_e32 v182, 0xffffff53, v178
	v_max_i32_e32 v183, 0xffffff52, v178
	v_min_u32_e32 v168, 0x100, v168
	v_min_u32_e32 v169, 0x100, v169
	v_min_u32_e32 v171, 0x100, v171
	v_min_u32_e32 v173, 0x100, v173
	v_min_u32_e32 v170, 0x100, v170
	v_min_u32_e32 v175, 0x100, v175
	v_add_u32_e32 v182, 0xad, v182
	v_add_u32_e32 v183, 0xae, v183
	v_lshl_add_u32 v168, v168, 2, s57
	v_lshl_add_u32 v169, v169, 2, s57
	v_lshl_add_u32 v171, v171, 2, s57
	v_lshl_add_u32 v173, v173, 2, s57
	v_lshl_add_u32 v179, v170, 2, s57
	v_lshl_add_u32 v175, v175, 2, s57
	v_min_u32_e32 v182, 0x100, v182
	v_min_u32_e32 v183, 0x100, v183
	ds_read_b32 v168, v168
	ds_read_b32 v170, v169
	ds_read_b32 v169, v172
	ds_read_b32 v171, v171
	ds_read_b32 v172, v174
	ds_read_b32 v174, v173
	ds_read_b32 v173, v179
	ds_read_b32 v175, v175
	v_max_i32_e32 v179, 0xffffff74, v178
	v_max_i32_e32 v180, 0xffffff54, v178
	v_max_i32_e32 v181, 0xffffff73, v178
	v_lshl_add_u32 v186, v182, 2, s57
	v_max_i32_e32 v182, 0xffffff72, v178
	v_lshl_add_u32 v184, v183, 2, s57
	v_max_i32_e32 v183, 0xffffff71, v178
	v_max_i32_e32 v178, 0xffffff51, v178
	v_add_u32_e32 v179, 0x8c, v179
	v_add_u32_e32 v180, 0xac, v180
	v_add_u32_e32 v181, 0x8d, v181
	v_add_u32_e32 v182, 0x8e, v182
	v_add_u32_e32 v183, 0x8f, v183
	v_add_u32_e32 v178, 0xaf, v178
	v_min_u32_e32 v179, 0x100, v179
	v_min_u32_e32 v180, 0x100, v180
	v_min_u32_e32 v181, 0x100, v181
	v_min_u32_e32 v182, 0x100, v182
	v_min_u32_e32 v183, 0x100, v183
	v_min_u32_e32 v178, 0x100, v178
	v_lshl_add_u32 v179, v179, 2, s57
	v_lshl_add_u32 v180, v180, 2, s57
	v_lshl_add_u32 v181, v181, 2, s57
	v_lshl_add_u32 v182, v182, 2, s57
	v_lshl_add_u32 v183, v183, 2, s57
	v_lshl_add_u32 v185, v178, 2, s57
	ds_read_b32 v178, v179
	ds_read_b32 v180, v180
	ds_read_b32 v182, v182
	ds_read_b32 v183, v183
	ds_read_b32 v179, v181
	ds_read_b32 v185, v185
	ds_read_b32 v184, v184
	ds_read_b32 v181, v186
	s_waitcnt lgkmcnt(0)
	v_pk_add_f32 v[110:111], v[110:111], v[182:183]
	v_pk_add_f32 v[108:109], v[108:109], v[178:179]
	v_pk_add_f32 v[106:107], v[106:107], v[172:173]
	v_pk_add_f32 v[104:105], v[104:105], v[168:169]
	v_pk_add_f32 v[102:103], v[102:103], v[140:141]
	v_pk_add_f32 v[100:101], v[100:101], v[136:137]
	v_pk_add_f32 v[98:99], v[98:99], v[132:133]
	v_pk_add_f32 v[96:97], v[96:97], v[128:129]
	v_pk_add_f32 v[94:95], v[94:95], v[184:185]
	v_pk_add_f32 v[92:93], v[92:93], v[180:181]
	v_pk_add_f32 v[90:91], v[90:91], v[174:175]
	v_pk_add_f32 v[88:89], v[88:89], v[170:171]
	v_pk_add_f32 v[86:87], v[86:87], v[142:143]
	v_pk_add_f32 v[84:85], v[84:85], v[138:139]
	v_pk_add_f32 v[82:83], v[82:83], v[134:135]
	v_pk_add_f32 v[80:81], v[80:81], v[130:131]

.LBB0_729:
	s_ashr_i32 s7, s6, 31
	s_lshl_b64 s[24:25], s[6:7], 22
	s_add_u32 s7, s26, s24
	s_addc_u32 s16, s27, s25
	s_and_b64 s[14:15], s[14:15], exec
	s_cselect_b32 s15, s16, s19
	s_cselect_b32 s14, s7, s18
	s_add_u32 s18, s18, 0x200080
	s_addc_u32 s19, s19, 0
	s_add_u32 s7, s22, 0x100
	s_addc_u32 s40, s23, 0
	s_mov_b32 s41, -2
	v_add_u32_e32 v253, 0x10000, v142
	s_add_u32 s16, s18, 0xffe00080
	s_addc_u32 s17, s19, -1
	s_add_i32 s42, 0, 0x10000
	s_cmpk_eq_i32 s41, 0x7c
	s_cselect_b32 s25, s15, s17
	s_cselect_b32 s24, s14, s16
	s_cselect_b32 s23, s13, s40
	s_cselect_b32 s22, s12, s7
	s_add_i32 s16, 0, 0x14000
	ds_read_b128 v[144:147], v253
	ds_read_b128 v[148:151], v253 offset:1024
	ds_read_b128 v[152:155], v253 offset:2048
	ds_read_b128 v[156:159], v253 offset:3072
	ds_read_b128 v[160:163], v253 offset:16384
	ds_read_b128 v[164:167], v253 offset:17408
	ds_read_b128 v[168:171], v253 offset:18432
	ds_read_b128 v[172:175], v253 offset:19456
	s_add_i32 m0, s31, 0xc000
	ds_read_b128 v[178:181], v143
	ds_read_b128 v[182:185], v143 offset:1024
	ds_read_b128 v[186:189], v143 offset:2048
	ds_read_b128 v[190:193], v143 offset:3072
	ds_read_b128 v[194:197], v143 offset:4096
	ds_read_b128 v[198:201], v143 offset:5120
	ds_read_b128 v[202:205], v143 offset:6144
	ds_read_b128 v[206:209], v143 offset:7168
	global_load_lds_dwordx4 v138, s[18:19]
	s_add_i32 m0, s31, 0xe000
	s_nop 0
	global_load_lds_dwordx4 v140, s[18:19]
	s_waitcnt vmcnt(8)
	s_waitcnt lgkmcnt(0)
	s_barrier
	s_setprio 1
	s_waitcnt lgkmcnt(0)
	v_mfma_f32_16x16x32_bf16 v[124:127], v[144:147], v[178:181], 0
	v_mfma_f32_16x16x32_bf16 v[120:123], v[152:155], v[178:181], 0
	v_mfma_f32_16x16x32_bf16 v[116:119], v[144:147], v[186:189], 0
	v_mfma_f32_16x16x32_bf16 v[112:115], v[152:155], v[186:189], 0
	v_mfma_f32_16x16x32_bf16 v[100:103], v[144:147], v[194:197], 0
	v_mfma_f32_16x16x32_bf16 v[96:99], v[152:155], v[194:197], 0
	v_mfma_f32_16x16x32_bf16 v[84:87], v[144:147], v[202:205], 0
	v_mfma_f32_16x16x32_bf16 v[80:83], v[152:155], v[202:205], 0
	v_mfma_f32_16x16x32_bf16 v[124:127], v[148:151], v[182:185], v[124:127]
	v_mfma_f32_16x16x32_bf16 v[120:123], v[156:159], v[182:185], v[120:123]
	v_mfma_f32_16x16x32_bf16 v[116:119], v[148:151], v[190:193], v[116:119]
	v_mfma_f32_16x16x32_bf16 v[112:115], v[156:159], v[190:193], v[112:115]
	v_mfma_f32_16x16x32_bf16 v[100:103], v[148:151], v[198:201], v[100:103]
	v_mfma_f32_16x16x32_bf16 v[96:99], v[156:159], v[198:201], v[96:99]
	v_mfma_f32_16x16x32_bf16 v[84:87], v[148:151], v[206:209], v[84:87]
	v_mfma_f32_16x16x32_bf16 v[80:83], v[156:159], v[206:209], v[80:83]
	s_setprio 0
	s_setprio 1
	v_mfma_f32_16x16x32_bf16 v[108:111], v[160:163], v[178:181], 0
	v_mfma_f32_16x16x32_bf16 v[104:107], v[168:171], v[178:181], 0
	v_mfma_f32_16x16x32_bf16 v[92:95], v[160:163], v[186:189], 0
	v_mfma_f32_16x16x32_bf16 v[88:91], v[168:171], v[186:189], 0
	v_mfma_f32_16x16x32_bf16 v[76:79], v[160:163], v[194:197], 0
	v_mfma_f32_16x16x32_bf16 v[72:75], v[168:171], v[194:197], 0
	v_mfma_f32_16x16x32_bf16 v[68:71], v[160:163], v[202:205], 0
	v_mfma_f32_16x16x32_bf16 v[64:67], v[168:171], v[202:205], 0
	v_mfma_f32_16x16x32_bf16 v[108:111], v[164:167], v[182:185], v[108:111]
	v_mfma_f32_16x16x32_bf16 v[104:107], v[172:175], v[182:185], v[104:107]
	v_mfma_f32_16x16x32_bf16 v[92:95], v[164:167], v[190:193], v[92:95]
	v_mfma_f32_16x16x32_bf16 v[88:91], v[172:175], v[190:193], v[88:91]
	v_mfma_f32_16x16x32_bf16 v[76:79], v[164:167], v[198:201], v[76:79]
	v_mfma_f32_16x16x32_bf16 v[72:75], v[172:175], v[198:201], v[72:75]
	v_mfma_f32_16x16x32_bf16 v[68:71], v[164:167], v[206:209], v[68:71]
	v_mfma_f32_16x16x32_bf16 v[64:67], v[172:175], v[206:209], v[64:67]
	s_setprio 0
	s_barrier
	s_add_i32 s17, s42, s28
	s_mov_b32 m0, s17
	ds_read_b128 v[178:181], v143 offset:16384
	ds_read_b128 v[182:185], v143 offset:17408
	ds_read_b128 v[186:189], v143 offset:18432
	ds_read_b128 v[190:193], v143 offset:19456
	ds_read_b128 v[194:197], v143 offset:20480
	ds_read_b128 v[198:201], v143 offset:21504
	ds_read_b128 v[202:205], v143 offset:22528
	ds_read_b128 v[206:209], v143 offset:23552
	global_load_lds_dwordx4 v132, s[22:23]
	s_add_i32 m0, s17, 0x2000
	s_add_u32 s42, s22, 0x400000
	s_addc_u32 s43, s23, 0
	s_add_i32 s16, s16, s28
	global_load_lds_dwordx4 v128, s[22:23]
	s_mov_b32 m0, s16
	s_nop 0
	global_load_lds_dwordx4 v132, s[42:43]
	s_add_i32 m0, s16, 0x2000
	s_nop 0
	global_load_lds_dwordx4 v128, s[42:43]
	s_mov_b32 m0, s31
	s_nop 0
	global_load_lds_dwordx4 v134, s[24:25]
	s_mov_b32 m0, s8
	s_nop 0
	global_load_lds_dwordx4 v130, s[24:25]
	s_waitcnt vmcnt(8)
	s_waitcnt lgkmcnt(0)
	s_barrier
	s_setprio 1
	s_waitcnt lgkmcnt(0)
	v_mfma_f32_16x16x32_bf16 v[60:63], v[144:147], v[178:181], 0
	v_mfma_f32_16x16x32_bf16 v[56:59], v[152:155], v[178:181], 0
	v_mfma_f32_16x16x32_bf16 v[52:55], v[144:147], v[186:189], 0
	v_mfma_f32_16x16x32_bf16 v[48:51], v[152:155], v[186:189], 0
	v_mfma_f32_16x16x32_bf16 v[36:39], v[144:147], v[194:197], 0
	v_mfma_f32_16x16x32_bf16 v[32:35], v[152:155], v[194:197], 0
	v_mfma_f32_16x16x32_bf16 v[20:23], v[144:147], v[202:205], 0
	v_mfma_f32_16x16x32_bf16 v[16:19], v[152:155], v[202:205], 0
	v_mfma_f32_16x16x32_bf16 v[60:63], v[148:151], v[182:185], v[60:63]
	v_mfma_f32_16x16x32_bf16 v[56:59], v[156:159], v[182:185], v[56:59]
	v_mfma_f32_16x16x32_bf16 v[52:55], v[148:151], v[190:193], v[52:55]
	v_mfma_f32_16x16x32_bf16 v[48:51], v[156:159], v[190:193], v[48:51]
	v_mfma_f32_16x16x32_bf16 v[36:39], v[148:151], v[198:201], v[36:39]
	v_mfma_f32_16x16x32_bf16 v[32:35], v[156:159], v[198:201], v[32:35]
	v_mfma_f32_16x16x32_bf16 v[20:23], v[148:151], v[206:209], v[20:23]
	v_mfma_f32_16x16x32_bf16 v[16:19], v[156:159], v[206:209], v[16:19]
	s_setprio 0
	s_setprio 1
	v_mfma_f32_16x16x32_bf16 v[44:47], v[160:163], v[178:181], 0
	v_mfma_f32_16x16x32_bf16 v[40:43], v[168:171], v[178:181], 0
	v_mfma_f32_16x16x32_bf16 v[28:31], v[160:163], v[186:189], 0
	v_mfma_f32_16x16x32_bf16 v[24:27], v[168:171], v[186:189], 0
	v_mfma_f32_16x16x32_bf16 v[12:15], v[160:163], v[194:197], 0
	v_mfma_f32_16x16x32_bf16 v[8:11], v[168:171], v[194:197], 0
	v_mfma_f32_16x16x32_bf16 v[4:7], v[160:163], v[202:205], 0
	v_mfma_f32_16x16x32_bf16 v[0:3], v[168:171], v[202:205], 0
	v_mfma_f32_16x16x32_bf16 v[44:47], v[164:167], v[182:185], v[44:47]
	v_mfma_f32_16x16x32_bf16 v[40:43], v[172:175], v[182:185], v[40:43]
	v_mfma_f32_16x16x32_bf16 v[28:31], v[164:167], v[190:193], v[28:31]
	v_mfma_f32_16x16x32_bf16 v[24:27], v[172:175], v[190:193], v[24:27]
	v_mfma_f32_16x16x32_bf16 v[12:15], v[164:167], v[198:201], v[12:15]
	v_mfma_f32_16x16x32_bf16 v[8:11], v[172:175], v[198:201], v[8:11]
	v_mfma_f32_16x16x32_bf16 v[4:7], v[164:167], v[206:209], v[4:7]
	v_mfma_f32_16x16x32_bf16 v[0:3], v[172:175], v[206:209], v[0:3]
	s_setprio 0
	s_barrier
	s_add_i32 s16, 0, 0x18000
	s_add_i32 s17, 0, 0x1c000
	ds_read_b128 v[144:147], v253 offset:32768
	ds_read_b128 v[148:151], v253 offset:33792
	ds_read_b128 v[152:155], v253 offset:34816
	ds_read_b128 v[156:159], v253 offset:35840
	ds_read_b128 v[160:163], v253 offset:49152
	ds_read_b128 v[164:167], v253 offset:50176
	ds_read_b128 v[168:171], v253 offset:51200
	ds_read_b128 v[172:175], v253 offset:52224
	s_add_u32 s24, s24, 0x200000
	s_addc_u32 s25, s25, 0
	s_mov_b32 m0, s9
	ds_read_b128 v[178:181], v143 offset:32768
	ds_read_b128 v[182:185], v143 offset:33792
	ds_read_b128 v[186:189], v143 offset:34816
	ds_read_b128 v[190:193], v143 offset:35840
	ds_read_b128 v[194:197], v143 offset:36864
	ds_read_b128 v[198:201], v143 offset:37888
	ds_read_b128 v[202:205], v143 offset:38912
	ds_read_b128 v[206:209], v143 offset:39936
	global_load_lds_dwordx4 v134, s[24:25]
	s_mov_b32 m0, s33
	s_nop 0
	global_load_lds_dwordx4 v130, s[24:25]
	s_waitcnt vmcnt(8)
	s_waitcnt lgkmcnt(0)
	s_barrier
	s_setprio 1
	s_waitcnt lgkmcnt(0)
	v_mfma_f32_16x16x32_bf16 v[124:127], v[144:147], v[178:181], v[124:127]
	v_mfma_f32_16x16x32_bf16 v[120:123], v[152:155], v[178:181], v[120:123]
	v_mfma_f32_16x16x32_bf16 v[116:119], v[144:147], v[186:189], v[116:119]
	v_mfma_f32_16x16x32_bf16 v[112:115], v[152:155], v[186:189], v[112:115]
	v_mfma_f32_16x16x32_bf16 v[100:103], v[144:147], v[194:197], v[100:103]
	v_mfma_f32_16x16x32_bf16 v[96:99], v[152:155], v[194:197], v[96:99]
	v_mfma_f32_16x16x32_bf16 v[84:87], v[144:147], v[202:205], v[84:87]
	v_mfma_f32_16x16x32_bf16 v[80:83], v[152:155], v[202:205], v[80:83]
	v_mfma_f32_16x16x32_bf16 v[124:127], v[148:151], v[182:185], v[124:127]
	v_mfma_f32_16x16x32_bf16 v[120:123], v[156:159], v[182:185], v[120:123]
	v_mfma_f32_16x16x32_bf16 v[116:119], v[148:151], v[190:193], v[116:119]
	v_mfma_f32_16x16x32_bf16 v[112:115], v[156:159], v[190:193], v[112:115]
	v_mfma_f32_16x16x32_bf16 v[100:103], v[148:151], v[198:201], v[100:103]
	v_mfma_f32_16x16x32_bf16 v[96:99], v[156:159], v[198:201], v[96:99]
	v_mfma_f32_16x16x32_bf16 v[84:87], v[148:151], v[206:209], v[84:87]
	v_mfma_f32_16x16x32_bf16 v[80:83], v[156:159], v[206:209], v[80:83]
	s_setprio 0
	s_setprio 1
	v_mfma_f32_16x16x32_bf16 v[108:111], v[160:163], v[178:181], v[108:111]
	v_mfma_f32_16x16x32_bf16 v[104:107], v[168:171], v[178:181], v[104:107]
	v_mfma_f32_16x16x32_bf16 v[92:95], v[160:163], v[186:189], v[92:95]
	v_mfma_f32_16x16x32_bf16 v[88:91], v[168:171], v[186:189], v[88:91]
	v_mfma_f32_16x16x32_bf16 v[76:79], v[160:163], v[194:197], v[76:79]
	v_mfma_f32_16x16x32_bf16 v[72:75], v[168:171], v[194:197], v[72:75]
	v_mfma_f32_16x16x32_bf16 v[68:71], v[160:163], v[202:205], v[68:71]
	v_mfma_f32_16x16x32_bf16 v[64:67], v[168:171], v[202:205], v[64:67]
	v_mfma_f32_16x16x32_bf16 v[108:111], v[164:167], v[182:185], v[108:111]
	v_mfma_f32_16x16x32_bf16 v[104:107], v[172:175], v[182:185], v[104:107]
	v_mfma_f32_16x16x32_bf16 v[92:95], v[164:167], v[190:193], v[92:95]
	v_mfma_f32_16x16x32_bf16 v[88:91], v[172:175], v[190:193], v[88:91]
	v_mfma_f32_16x16x32_bf16 v[76:79], v[164:167], v[198:201], v[76:79]
	v_mfma_f32_16x16x32_bf16 v[72:75], v[172:175], v[198:201], v[72:75]
	v_mfma_f32_16x16x32_bf16 v[68:71], v[164:167], v[206:209], v[68:71]
	v_mfma_f32_16x16x32_bf16 v[64:67], v[172:175], v[206:209], v[64:67]
	s_setprio 0
	s_barrier
	s_add_i32 s16, s16, s28
	s_mov_b32 m0, s16
	ds_read_b128 v[178:181], v143 offset:49152
	ds_read_b128 v[182:185], v143 offset:50176
	ds_read_b128 v[186:189], v143 offset:51200
	ds_read_b128 v[190:193], v143 offset:52224
	ds_read_b128 v[194:197], v143 offset:53248
	ds_read_b128 v[198:201], v143 offset:54272
	ds_read_b128 v[202:205], v143 offset:55296
	ds_read_b128 v[206:209], v143 offset:56320
	s_add_u32 s98, s22, 0x80
	s_addc_u32 s99, s23, 0
	global_load_lds_dwordx4 v132, s[98:99]
	s_add_i32 m0, s16, 0x2000
	s_add_u32 s22, s22, 0x400080
	s_addc_u32 s23, s23, 0
	s_add_i32 s16, s17, s28
	s_add_u32 s98, s42, 0xffc00080
	s_addc_u32 s99, s43, -1
	global_load_lds_dwordx4 v128, s[98:99]
	s_mov_b32 m0, s16
	s_nop 0
	global_load_lds_dwordx4 v132, s[22:23]
	s_add_i32 m0, s16, 0x2000
	s_nop 0
	global_load_lds_dwordx4 v128, s[22:23]
	s_mov_b32 m0, s34
	s_nop 0
	s_add_u32 s98, s24, 0xffe00080
	s_addc_u32 s99, s25, -1
	global_load_lds_dwordx4 v134, s[98:99]
	s_mov_b32 m0, s35
	s_nop 0
	s_add_u32 s98, s24, 0xffe00080
	s_addc_u32 s99, s25, -1
	global_load_lds_dwordx4 v130, s[98:99]
	s_waitcnt vmcnt(8)
	s_waitcnt lgkmcnt(0)
	s_barrier
	s_setprio 1
	s_waitcnt lgkmcnt(0)
	v_mfma_f32_16x16x32_bf16 v[60:63], v[144:147], v[178:181], v[60:63]
	v_mfma_f32_16x16x32_bf16 v[56:59], v[152:155], v[178:181], v[56:59]
	v_mfma_f32_16x16x32_bf16 v[52:55], v[144:147], v[186:189], v[52:55]
	v_mfma_f32_16x16x32_bf16 v[48:51], v[152:155], v[186:189], v[48:51]
	v_mfma_f32_16x16x32_bf16 v[36:39], v[144:147], v[194:197], v[36:39]
	v_mfma_f32_16x16x32_bf16 v[32:35], v[152:155], v[194:197], v[32:35]
	v_mfma_f32_16x16x32_bf16 v[20:23], v[144:147], v[202:205], v[20:23]
	v_mfma_f32_16x16x32_bf16 v[16:19], v[152:155], v[202:205], v[16:19]
	v_mfma_f32_16x16x32_bf16 v[60:63], v[148:151], v[182:185], v[60:63]
	v_mfma_f32_16x16x32_bf16 v[56:59], v[156:159], v[182:185], v[56:59]
	v_mfma_f32_16x16x32_bf16 v[52:55], v[148:151], v[190:193], v[52:55]
	v_mfma_f32_16x16x32_bf16 v[48:51], v[156:159], v[190:193], v[48:51]
	v_mfma_f32_16x16x32_bf16 v[36:39], v[148:151], v[198:201], v[36:39]
	v_mfma_f32_16x16x32_bf16 v[32:35], v[156:159], v[198:201], v[32:35]
	v_mfma_f32_16x16x32_bf16 v[20:23], v[148:151], v[206:209], v[20:23]
	v_mfma_f32_16x16x32_bf16 v[16:19], v[156:159], v[206:209], v[16:19]
	s_setprio 0
	s_setprio 1
	v_mfma_f32_16x16x32_bf16 v[44:47], v[160:163], v[178:181], v[44:47]
	v_mfma_f32_16x16x32_bf16 v[40:43], v[168:171], v[178:181], v[40:43]
	v_mfma_f32_16x16x32_bf16 v[28:31], v[160:163], v[186:189], v[28:31]
	v_mfma_f32_16x16x32_bf16 v[24:27], v[168:171], v[186:189], v[24:27]
	v_mfma_f32_16x16x32_bf16 v[12:15], v[160:163], v[194:197], v[12:15]
	v_mfma_f32_16x16x32_bf16 v[8:11], v[168:171], v[194:197], v[8:11]
	v_mfma_f32_16x16x32_bf16 v[4:7], v[160:163], v[202:205], v[4:7]
	v_mfma_f32_16x16x32_bf16 v[0:3], v[168:171], v[202:205], v[0:3]
	v_mfma_f32_16x16x32_bf16 v[44:47], v[164:167], v[182:185], v[44:47]
	v_mfma_f32_16x16x32_bf16 v[40:43], v[172:175], v[182:185], v[40:43]
	v_mfma_f32_16x16x32_bf16 v[28:31], v[164:167], v[190:193], v[28:31]
	v_mfma_f32_16x16x32_bf16 v[24:27], v[172:175], v[190:193], v[24:27]
	v_mfma_f32_16x16x32_bf16 v[12:15], v[164:167], v[198:201], v[12:15]
	v_mfma_f32_16x16x32_bf16 v[8:11], v[172:175], v[198:201], v[8:11]
	v_mfma_f32_16x16x32_bf16 v[4:7], v[164:167], v[206:209], v[4:7]
	v_mfma_f32_16x16x32_bf16 v[0:3], v[172:175], v[206:209], v[0:3]
	s_setprio 0
	s_barrier
	s_add_i32 s41, s41, 2
	s_add_u32 s18, s18, 0x100
	s_addc_u32 s19, s19, 0
	s_add_u32 s7, s7, 0x100
	s_addc_u32 s40, s40, 0
	s_cmpk_gt_u32 s41, 0x7d
.LBB0_730:
	s_add_u32 s16, s18, 0xffe00080
	s_addc_u32 s17, s19, -1
	s_add_i32 s42, 0, 0x10000
	s_cmpk_eq_i32 s41, 0x7c
	s_cselect_b32 s25, s15, s17
	s_cselect_b32 s24, s14, s16
	s_cselect_b32 s23, s13, s40
	s_cselect_b32 s22, s12, s7
	s_add_i32 s16, 0, 0x14000
	ds_read_b128 v[144:147], v253
	ds_read_b128 v[148:151], v253 offset:1024
	ds_read_b128 v[152:155], v253 offset:2048
	ds_read_b128 v[156:159], v253 offset:3072
	ds_read_b128 v[160:163], v253 offset:16384
	ds_read_b128 v[164:167], v253 offset:17408
	ds_read_b128 v[168:171], v253 offset:18432
	ds_read_b128 v[172:175], v253 offset:19456
	s_add_i32 m0, s31, 0xc000
	ds_read_b128 v[178:181], v143
	ds_read_b128 v[182:185], v143 offset:1024
	ds_read_b128 v[186:189], v143 offset:2048
	ds_read_b128 v[190:193], v143 offset:3072
	ds_read_b128 v[194:197], v143 offset:4096
	ds_read_b128 v[198:201], v143 offset:5120
	ds_read_b128 v[202:205], v143 offset:6144
	ds_read_b128 v[206:209], v143 offset:7168
	global_load_lds_dwordx4 v138, s[18:19]
	s_add_i32 m0, s31, 0xe000
	s_nop 0
	global_load_lds_dwordx4 v140, s[18:19]
	s_waitcnt vmcnt(8)
	s_waitcnt lgkmcnt(0)
	s_barrier
	s_setprio 1
	s_waitcnt lgkmcnt(0)
	v_mfma_f32_16x16x32_bf16 v[124:127], v[144:147], v[178:181], v[124:127]
	v_mfma_f32_16x16x32_bf16 v[120:123], v[152:155], v[178:181], v[120:123]
	v_mfma_f32_16x16x32_bf16 v[116:119], v[144:147], v[186:189], v[116:119]
	v_mfma_f32_16x16x32_bf16 v[112:115], v[152:155], v[186:189], v[112:115]
	v_mfma_f32_16x16x32_bf16 v[100:103], v[144:147], v[194:197], v[100:103]
	v_mfma_f32_16x16x32_bf16 v[96:99], v[152:155], v[194:197], v[96:99]
	v_mfma_f32_16x16x32_bf16 v[84:87], v[144:147], v[202:205], v[84:87]
	v_mfma_f32_16x16x32_bf16 v[80:83], v[152:155], v[202:205], v[80:83]
	v_mfma_f32_16x16x32_bf16 v[124:127], v[148:151], v[182:185], v[124:127]
	v_mfma_f32_16x16x32_bf16 v[120:123], v[156:159], v[182:185], v[120:123]
	v_mfma_f32_16x16x32_bf16 v[116:119], v[148:151], v[190:193], v[116:119]
	v_mfma_f32_16x16x32_bf16 v[112:115], v[156:159], v[190:193], v[112:115]
	v_mfma_f32_16x16x32_bf16 v[100:103], v[148:151], v[198:201], v[100:103]
	v_mfma_f32_16x16x32_bf16 v[96:99], v[156:159], v[198:201], v[96:99]
	v_mfma_f32_16x16x32_bf16 v[84:87], v[148:151], v[206:209], v[84:87]
	v_mfma_f32_16x16x32_bf16 v[80:83], v[156:159], v[206:209], v[80:83]
	s_setprio 0
	s_setprio 1
	v_mfma_f32_16x16x32_bf16 v[108:111], v[160:163], v[178:181], v[108:111]
	v_mfma_f32_16x16x32_bf16 v[104:107], v[168:171], v[178:181], v[104:107]
	v_mfma_f32_16x16x32_bf16 v[92:95], v[160:163], v[186:189], v[92:95]
	v_mfma_f32_16x16x32_bf16 v[88:91], v[168:171], v[186:189], v[88:91]
	v_mfma_f32_16x16x32_bf16 v[76:79], v[160:163], v[194:197], v[76:79]
	v_mfma_f32_16x16x32_bf16 v[72:75], v[168:171], v[194:197], v[72:75]
	v_mfma_f32_16x16x32_bf16 v[68:71], v[160:163], v[202:205], v[68:71]
	v_mfma_f32_16x16x32_bf16 v[64:67], v[168:171], v[202:205], v[64:67]
	v_mfma_f32_16x16x32_bf16 v[108:111], v[164:167], v[182:185], v[108:111]
	v_mfma_f32_16x16x32_bf16 v[104:107], v[172:175], v[182:185], v[104:107]
	v_mfma_f32_16x16x32_bf16 v[92:95], v[164:167], v[190:193], v[92:95]
	v_mfma_f32_16x16x32_bf16 v[88:91], v[172:175], v[190:193], v[88:91]
	v_mfma_f32_16x16x32_bf16 v[76:79], v[164:167], v[198:201], v[76:79]
	v_mfma_f32_16x16x32_bf16 v[72:75], v[172:175], v[198:201], v[72:75]
	v_mfma_f32_16x16x32_bf16 v[68:71], v[164:167], v[206:209], v[68:71]
	v_mfma_f32_16x16x32_bf16 v[64:67], v[172:175], v[206:209], v[64:67]
	s_setprio 0
	s_barrier
	s_add_i32 s17, s42, s28
	s_mov_b32 m0, s17
	ds_read_b128 v[178:181], v143 offset:16384
	ds_read_b128 v[182:185], v143 offset:17408
	ds_read_b128 v[186:189], v143 offset:18432
	ds_read_b128 v[190:193], v143 offset:19456
	ds_read_b128 v[194:197], v143 offset:20480
	ds_read_b128 v[198:201], v143 offset:21504
	ds_read_b128 v[202:205], v143 offset:22528
	ds_read_b128 v[206:209], v143 offset:23552
	global_load_lds_dwordx4 v132, s[22:23]
	s_add_i32 m0, s17, 0x2000
	s_add_u32 s42, s22, 0x400000
	s_addc_u32 s43, s23, 0
	s_add_i32 s16, s16, s28
	global_load_lds_dwordx4 v128, s[22:23]
	s_mov_b32 m0, s16
	s_nop 0
	global_load_lds_dwordx4 v132, s[42:43]
	s_add_i32 m0, s16, 0x2000
	s_nop 0
	global_load_lds_dwordx4 v128, s[42:43]
	s_mov_b32 m0, s31
	s_nop 0
	global_load_lds_dwordx4 v134, s[24:25]
	s_mov_b32 m0, s8
	s_nop 0
	global_load_lds_dwordx4 v130, s[24:25]
	s_waitcnt vmcnt(8)
	s_waitcnt lgkmcnt(0)
	s_barrier
	s_setprio 1
	s_waitcnt lgkmcnt(0)
	v_mfma_f32_16x16x32_bf16 v[60:63], v[144:147], v[178:181], v[60:63]
	v_mfma_f32_16x16x32_bf16 v[56:59], v[152:155], v[178:181], v[56:59]
	v_mfma_f32_16x16x32_bf16 v[52:55], v[144:147], v[186:189], v[52:55]
	v_mfma_f32_16x16x32_bf16 v[48:51], v[152:155], v[186:189], v[48:51]
	v_mfma_f32_16x16x32_bf16 v[36:39], v[144:147], v[194:197], v[36:39]
	v_mfma_f32_16x16x32_bf16 v[32:35], v[152:155], v[194:197], v[32:35]
	v_mfma_f32_16x16x32_bf16 v[20:23], v[144:147], v[202:205], v[20:23]
	v_mfma_f32_16x16x32_bf16 v[16:19], v[152:155], v[202:205], v[16:19]
	v_mfma_f32_16x16x32_bf16 v[60:63], v[148:151], v[182:185], v[60:63]
	v_mfma_f32_16x16x32_bf16 v[56:59], v[156:159], v[182:185], v[56:59]
	v_mfma_f32_16x16x32_bf16 v[52:55], v[148:151], v[190:193], v[52:55]
	v_mfma_f32_16x16x32_bf16 v[48:51], v[156:159], v[190:193], v[48:51]
	v_mfma_f32_16x16x32_bf16 v[36:39], v[148:151], v[198:201], v[36:39]
	v_mfma_f32_16x16x32_bf16 v[32:35], v[156:159], v[198:201], v[32:35]
	v_mfma_f32_16x16x32_bf16 v[20:23], v[148:151], v[206:209], v[20:23]
	v_mfma_f32_16x16x32_bf16 v[16:19], v[156:159], v[206:209], v[16:19]
	s_setprio 0
	s_setprio 1
	v_mfma_f32_16x16x32_bf16 v[44:47], v[160:163], v[178:181], v[44:47]
	v_mfma_f32_16x16x32_bf16 v[40:43], v[168:171], v[178:181], v[40:43]
	v_mfma_f32_16x16x32_bf16 v[28:31], v[160:163], v[186:189], v[28:31]
	v_mfma_f32_16x16x32_bf16 v[24:27], v[168:171], v[186:189], v[24:27]
	v_mfma_f32_16x16x32_bf16 v[12:15], v[160:163], v[194:197], v[12:15]
	v_mfma_f32_16x16x32_bf16 v[8:11], v[168:171], v[194:197], v[8:11]
	v_mfma_f32_16x16x32_bf16 v[4:7], v[160:163], v[202:205], v[4:7]
	v_mfma_f32_16x16x32_bf16 v[0:3], v[168:171], v[202:205], v[0:3]
	v_mfma_f32_16x16x32_bf16 v[44:47], v[164:167], v[182:185], v[44:47]
	v_mfma_f32_16x16x32_bf16 v[40:43], v[172:175], v[182:185], v[40:43]
	v_mfma_f32_16x16x32_bf16 v[28:31], v[164:167], v[190:193], v[28:31]
	v_mfma_f32_16x16x32_bf16 v[24:27], v[172:175], v[190:193], v[24:27]
	v_mfma_f32_16x16x32_bf16 v[12:15], v[164:167], v[198:201], v[12:15]
	v_mfma_f32_16x16x32_bf16 v[8:11], v[172:175], v[198:201], v[8:11]
	v_mfma_f32_16x16x32_bf16 v[4:7], v[164:167], v[206:209], v[4:7]
	v_mfma_f32_16x16x32_bf16 v[0:3], v[172:175], v[206:209], v[0:3]
	s_setprio 0
	s_barrier
	s_add_i32 s16, 0, 0x18000
	s_add_i32 s17, 0, 0x1c000
	ds_read_b128 v[144:147], v253 offset:32768
	ds_read_b128 v[148:151], v253 offset:33792
	ds_read_b128 v[152:155], v253 offset:34816
	ds_read_b128 v[156:159], v253 offset:35840
	ds_read_b128 v[160:163], v253 offset:49152
	ds_read_b128 v[164:167], v253 offset:50176
	ds_read_b128 v[168:171], v253 offset:51200
	ds_read_b128 v[172:175], v253 offset:52224
	s_add_u32 s24, s24, 0x200000
	s_addc_u32 s25, s25, 0
	s_mov_b32 m0, s9
	ds_read_b128 v[178:181], v143 offset:32768
	ds_read_b128 v[182:185], v143 offset:33792
	ds_read_b128 v[186:189], v143 offset:34816
	ds_read_b128 v[190:193], v143 offset:35840
	ds_read_b128 v[194:197], v143 offset:36864
	ds_read_b128 v[198:201], v143 offset:37888
	ds_read_b128 v[202:205], v143 offset:38912
	ds_read_b128 v[206:209], v143 offset:39936
	global_load_lds_dwordx4 v134, s[24:25]
	s_mov_b32 m0, s33
	s_nop 0
	global_load_lds_dwordx4 v130, s[24:25]
	s_waitcnt vmcnt(8)
	s_waitcnt lgkmcnt(0)
	s_barrier
	s_setprio 1
	s_waitcnt lgkmcnt(0)
	v_mfma_f32_16x16x32_bf16 v[124:127], v[144:147], v[178:181], v[124:127]
	v_mfma_f32_16x16x32_bf16 v[120:123], v[152:155], v[178:181], v[120:123]
	v_mfma_f32_16x16x32_bf16 v[116:119], v[144:147], v[186:189], v[116:119]
	v_mfma_f32_16x16x32_bf16 v[112:115], v[152:155], v[186:189], v[112:115]
	v_mfma_f32_16x16x32_bf16 v[100:103], v[144:147], v[194:197], v[100:103]
	v_mfma_f32_16x16x32_bf16 v[96:99], v[152:155], v[194:197], v[96:99]
	v_mfma_f32_16x16x32_bf16 v[84:87], v[144:147], v[202:205], v[84:87]
	v_mfma_f32_16x16x32_bf16 v[80:83], v[152:155], v[202:205], v[80:83]
	v_mfma_f32_16x16x32_bf16 v[124:127], v[148:151], v[182:185], v[124:127]
	v_mfma_f32_16x16x32_bf16 v[120:123], v[156:159], v[182:185], v[120:123]
	v_mfma_f32_16x16x32_bf16 v[116:119], v[148:151], v[190:193], v[116:119]
	v_mfma_f32_16x16x32_bf16 v[112:115], v[156:159], v[190:193], v[112:115]
	v_mfma_f32_16x16x32_bf16 v[100:103], v[148:151], v[198:201], v[100:103]
	v_mfma_f32_16x16x32_bf16 v[96:99], v[156:159], v[198:201], v[96:99]
	v_mfma_f32_16x16x32_bf16 v[84:87], v[148:151], v[206:209], v[84:87]
	v_mfma_f32_16x16x32_bf16 v[80:83], v[156:159], v[206:209], v[80:83]
	s_setprio 0
	s_setprio 1
	v_mfma_f32_16x16x32_bf16 v[108:111], v[160:163], v[178:181], v[108:111]
	v_mfma_f32_16x16x32_bf16 v[104:107], v[168:171], v[178:181], v[104:107]
	v_mfma_f32_16x16x32_bf16 v[92:95], v[160:163], v[186:189], v[92:95]
	v_mfma_f32_16x16x32_bf16 v[88:91], v[168:171], v[186:189], v[88:91]
	v_mfma_f32_16x16x32_bf16 v[76:79], v[160:163], v[194:197], v[76:79]
	v_mfma_f32_16x16x32_bf16 v[72:75], v[168:171], v[194:197], v[72:75]
	v_mfma_f32_16x16x32_bf16 v[68:71], v[160:163], v[202:205], v[68:71]
	v_mfma_f32_16x16x32_bf16 v[64:67], v[168:171], v[202:205], v[64:67]
	v_mfma_f32_16x16x32_bf16 v[108:111], v[164:167], v[182:185], v[108:111]
	v_mfma_f32_16x16x32_bf16 v[104:107], v[172:175], v[182:185], v[104:107]
	v_mfma_f32_16x16x32_bf16 v[92:95], v[164:167], v[190:193], v[92:95]
	v_mfma_f32_16x16x32_bf16 v[88:91], v[172:175], v[190:193], v[88:91]
	v_mfma_f32_16x16x32_bf16 v[76:79], v[164:167], v[198:201], v[76:79]
	v_mfma_f32_16x16x32_bf16 v[72:75], v[172:175], v[198:201], v[72:75]
	v_mfma_f32_16x16x32_bf16 v[68:71], v[164:167], v[206:209], v[68:71]
	v_mfma_f32_16x16x32_bf16 v[64:67], v[172:175], v[206:209], v[64:67]
	s_setprio 0
	s_barrier
	s_add_i32 s16, s16, s28
	s_mov_b32 m0, s16
	ds_read_b128 v[178:181], v143 offset:49152
	ds_read_b128 v[182:185], v143 offset:50176
	ds_read_b128 v[186:189], v143 offset:51200
	ds_read_b128 v[190:193], v143 offset:52224
	ds_read_b128 v[194:197], v143 offset:53248
	ds_read_b128 v[198:201], v143 offset:54272
	ds_read_b128 v[202:205], v143 offset:55296
	ds_read_b128 v[206:209], v143 offset:56320
	s_add_u32 s98, s22, 0x80
	s_addc_u32 s99, s23, 0
	global_load_lds_dwordx4 v132, s[98:99]
	s_add_i32 m0, s16, 0x2000
	s_add_u32 s22, s22, 0x400080
	s_addc_u32 s23, s23, 0
	s_add_i32 s16, s17, s28
	s_add_u32 s98, s42, 0xffc00080
	s_addc_u32 s99, s43, -1
	global_load_lds_dwordx4 v128, s[98:99]
	s_mov_b32 m0, s16
	s_nop 0
	global_load_lds_dwordx4 v132, s[22:23]
	s_add_i32 m0, s16, 0x2000
	s_nop 0
	global_load_lds_dwordx4 v128, s[22:23]
	s_mov_b32 m0, s34
	s_nop 0
	s_add_u32 s98, s24, 0xffe00080
	s_addc_u32 s99, s25, -1
	global_load_lds_dwordx4 v134, s[98:99]
	s_mov_b32 m0, s35
	s_nop 0
	s_add_u32 s98, s24, 0xffe00080
	s_addc_u32 s99, s25, -1
	global_load_lds_dwordx4 v130, s[98:99]
	s_waitcnt vmcnt(8)
	s_waitcnt lgkmcnt(0)
	s_barrier
	s_setprio 1
	s_waitcnt lgkmcnt(0)
	v_mfma_f32_16x16x32_bf16 v[60:63], v[144:147], v[178:181], v[60:63]
	v_mfma_f32_16x16x32_bf16 v[56:59], v[152:155], v[178:181], v[56:59]
	v_mfma_f32_16x16x32_bf16 v[52:55], v[144:147], v[186:189], v[52:55]
	v_mfma_f32_16x16x32_bf16 v[48:51], v[152:155], v[186:189], v[48:51]
	v_mfma_f32_16x16x32_bf16 v[36:39], v[144:147], v[194:197], v[36:39]
	v_mfma_f32_16x16x32_bf16 v[32:35], v[152:155], v[194:197], v[32:35]
	v_mfma_f32_16x16x32_bf16 v[20:23], v[144:147], v[202:205], v[20:23]
	v_mfma_f32_16x16x32_bf16 v[16:19], v[152:155], v[202:205], v[16:19]
	v_mfma_f32_16x16x32_bf16 v[60:63], v[148:151], v[182:185], v[60:63]
	v_mfma_f32_16x16x32_bf16 v[56:59], v[156:159], v[182:185], v[56:59]
	v_mfma_f32_16x16x32_bf16 v[52:55], v[148:151], v[190:193], v[52:55]
	v_mfma_f32_16x16x32_bf16 v[48:51], v[156:159], v[190:193], v[48:51]
	v_mfma_f32_16x16x32_bf16 v[36:39], v[148:151], v[198:201], v[36:39]
	v_mfma_f32_16x16x32_bf16 v[32:35], v[156:159], v[198:201], v[32:35]
	v_mfma_f32_16x16x32_bf16 v[20:23], v[148:151], v[206:209], v[20:23]
	v_mfma_f32_16x16x32_bf16 v[16:19], v[156:159], v[206:209], v[16:19]
	s_setprio 0
	s_setprio 1
	v_mfma_f32_16x16x32_bf16 v[44:47], v[160:163], v[178:181], v[44:47]
	v_mfma_f32_16x16x32_bf16 v[40:43], v[168:171], v[178:181], v[40:43]
	v_mfma_f32_16x16x32_bf16 v[28:31], v[160:163], v[186:189], v[28:31]
	v_mfma_f32_16x16x32_bf16 v[24:27], v[168:171], v[186:189], v[24:27]
	v_mfma_f32_16x16x32_bf16 v[12:15], v[160:163], v[194:197], v[12:15]
	v_mfma_f32_16x16x32_bf16 v[8:11], v[168:171], v[194:197], v[8:11]
	v_mfma_f32_16x16x32_bf16 v[4:7], v[160:163], v[202:205], v[4:7]
	v_mfma_f32_16x16x32_bf16 v[0:3], v[168:171], v[202:205], v[0:3]
	v_mfma_f32_16x16x32_bf16 v[44:47], v[164:167], v[182:185], v[44:47]
	v_mfma_f32_16x16x32_bf16 v[40:43], v[172:175], v[182:185], v[40:43]
	v_mfma_f32_16x16x32_bf16 v[28:31], v[164:167], v[190:193], v[28:31]
	v_mfma_f32_16x16x32_bf16 v[24:27], v[172:175], v[190:193], v[24:27]
	v_mfma_f32_16x16x32_bf16 v[12:15], v[164:167], v[198:201], v[12:15]
	v_mfma_f32_16x16x32_bf16 v[8:11], v[172:175], v[198:201], v[8:11]
	v_mfma_f32_16x16x32_bf16 v[4:7], v[164:167], v[206:209], v[4:7]
	v_mfma_f32_16x16x32_bf16 v[0:3], v[172:175], v[206:209], v[0:3]
	s_setprio 0
	s_barrier
	s_add_i32 s41, s41, 2
	s_add_u32 s18, s18, 0x100
	s_addc_u32 s19, s19, 0
	s_add_u32 s7, s7, 0x100
	s_addc_u32 s40, s40, 0
	s_cmpk_gt_u32 s41, 0x7d
	s_cbranch_scc0 .LBB0_730
	s_and_b64 vcc, exec, s[4:5]
	s_cbranch_vccz .LBB0_733
	s_barrier

.LBB0_747:
	s_ashr_i32 s7, s6, 31
	s_lshl_b64 s[22:23], s[6:7], 21
	s_add_u32 s7, s2, s22
	s_addc_u32 s22, s21, s23
	s_and_b64 s[14:15], s[14:15], exec
	s_cselect_b32 s15, s22, s17
	s_cselect_b32 s14, s7, s16
	s_add_u32 s16, s16, 0x100080
	s_addc_u32 s17, s17, 0
	s_add_u32 s7, s18, 0x100
	s_addc_u32 s36, s19, 0
	s_mov_b32 s37, -2
	v_add_u32_e32 v253, 0x10000, v142
	s_add_u32 s18, s16, 0xfff00080
	s_addc_u32 s19, s17, -1
	s_add_i32 s38, 0, 0x10000
	s_cmp_eq_u32 s37, 60
	s_cselect_b32 s23, s15, s19
	s_cselect_b32 s22, s14, s18
	s_cselect_b32 s19, s13, s36
	s_cselect_b32 s18, s12, s7
	s_add_i32 s40, 0, 0x14000
	ds_read_b128 v[144:147], v253
	ds_read_b128 v[148:151], v253 offset:1024
	ds_read_b128 v[152:155], v253 offset:2048
	ds_read_b128 v[156:159], v253 offset:3072
	ds_read_b128 v[160:163], v253 offset:16384
	ds_read_b128 v[164:167], v253 offset:17408
	ds_read_b128 v[168:171], v253 offset:18432
	ds_read_b128 v[172:175], v253 offset:19456
	s_add_i32 m0, s27, 0xc000
	ds_read_b128 v[178:181], v143
	ds_read_b128 v[182:185], v143 offset:1024
	ds_read_b128 v[186:189], v143 offset:2048
	ds_read_b128 v[190:193], v143 offset:3072
	ds_read_b128 v[194:197], v143 offset:4096
	ds_read_b128 v[198:201], v143 offset:5120
	ds_read_b128 v[202:205], v143 offset:6144
	ds_read_b128 v[206:209], v143 offset:7168
	global_load_lds_dwordx4 v138, s[16:17]
	s_add_i32 m0, s27, 0xe000
	s_nop 0
	global_load_lds_dwordx4 v140, s[16:17]
	s_waitcnt vmcnt(8)
	s_waitcnt lgkmcnt(0)
	s_barrier
	s_setprio 1
	s_waitcnt lgkmcnt(0)
	v_mfma_f32_16x16x32_bf16 v[124:127], v[144:147], v[178:181], 0
	v_mfma_f32_16x16x32_bf16 v[120:123], v[152:155], v[178:181], 0
	v_mfma_f32_16x16x32_bf16 v[116:119], v[144:147], v[186:189], 0
	v_mfma_f32_16x16x32_bf16 v[112:115], v[152:155], v[186:189], 0
	v_mfma_f32_16x16x32_bf16 v[100:103], v[144:147], v[194:197], 0
	v_mfma_f32_16x16x32_bf16 v[96:99], v[152:155], v[194:197], 0
	v_mfma_f32_16x16x32_bf16 v[84:87], v[144:147], v[202:205], 0
	v_mfma_f32_16x16x32_bf16 v[80:83], v[152:155], v[202:205], 0
	v_mfma_f32_16x16x32_bf16 v[124:127], v[148:151], v[182:185], v[124:127]
	v_mfma_f32_16x16x32_bf16 v[120:123], v[156:159], v[182:185], v[120:123]
	v_mfma_f32_16x16x32_bf16 v[116:119], v[148:151], v[190:193], v[116:119]
	v_mfma_f32_16x16x32_bf16 v[112:115], v[156:159], v[190:193], v[112:115]
	v_mfma_f32_16x16x32_bf16 v[100:103], v[148:151], v[198:201], v[100:103]
	v_mfma_f32_16x16x32_bf16 v[96:99], v[156:159], v[198:201], v[96:99]
	v_mfma_f32_16x16x32_bf16 v[84:87], v[148:151], v[206:209], v[84:87]
	v_mfma_f32_16x16x32_bf16 v[80:83], v[156:159], v[206:209], v[80:83]
	s_setprio 0
	s_setprio 1
	v_mfma_f32_16x16x32_bf16 v[108:111], v[160:163], v[178:181], 0
	v_mfma_f32_16x16x32_bf16 v[104:107], v[168:171], v[178:181], 0
	v_mfma_f32_16x16x32_bf16 v[92:95], v[160:163], v[186:189], 0
	v_mfma_f32_16x16x32_bf16 v[88:91], v[168:171], v[186:189], 0
	v_mfma_f32_16x16x32_bf16 v[76:79], v[160:163], v[194:197], 0
	v_mfma_f32_16x16x32_bf16 v[72:75], v[168:171], v[194:197], 0
	v_mfma_f32_16x16x32_bf16 v[68:71], v[160:163], v[202:205], 0
	v_mfma_f32_16x16x32_bf16 v[64:67], v[168:171], v[202:205], 0
	v_mfma_f32_16x16x32_bf16 v[108:111], v[164:167], v[182:185], v[108:111]
	v_mfma_f32_16x16x32_bf16 v[104:107], v[172:175], v[182:185], v[104:107]
	v_mfma_f32_16x16x32_bf16 v[92:95], v[164:167], v[190:193], v[92:95]
	v_mfma_f32_16x16x32_bf16 v[88:91], v[172:175], v[190:193], v[88:91]
	v_mfma_f32_16x16x32_bf16 v[76:79], v[164:167], v[198:201], v[76:79]
	v_mfma_f32_16x16x32_bf16 v[72:75], v[172:175], v[198:201], v[72:75]
	v_mfma_f32_16x16x32_bf16 v[68:71], v[164:167], v[206:209], v[68:71]
	v_mfma_f32_16x16x32_bf16 v[64:67], v[172:175], v[206:209], v[64:67]
	s_setprio 0
	s_barrier
	s_add_i32 s38, s38, s26
	s_mov_b32 m0, s38
	ds_read_b128 v[178:181], v143 offset:16384
	ds_read_b128 v[182:185], v143 offset:17408
	ds_read_b128 v[186:189], v143 offset:18432
	ds_read_b128 v[190:193], v143 offset:19456
	ds_read_b128 v[194:197], v143 offset:20480
	ds_read_b128 v[198:201], v143 offset:21504
	ds_read_b128 v[202:205], v143 offset:22528
	ds_read_b128 v[206:209], v143 offset:23552
	global_load_lds_dwordx4 v132, s[18:19]
	s_add_i32 m0, s38, 0x2000
	s_add_u32 s38, s18, 0x800000
	s_addc_u32 s39, s19, 0
	s_add_i32 s40, s40, s26
	global_load_lds_dwordx4 v128, s[18:19]
	s_mov_b32 m0, s40
	s_nop 0
	global_load_lds_dwordx4 v132, s[38:39]
	s_add_i32 m0, s40, 0x2000
	s_nop 0
	global_load_lds_dwordx4 v128, s[38:39]
	s_add_u32 s60, s22, 0x80
	s_addc_u32 s61, s23, 0
	s_mov_b32 m0, s27
	s_nop 0
	global_load_lds_dwordx4 v134, s[22:23]
	s_mov_b32 m0, s8
	s_nop 0
	global_load_lds_dwordx4 v130, s[22:23]
	s_waitcnt vmcnt(8)
	s_waitcnt lgkmcnt(0)
	s_barrier
	s_setprio 1
	s_waitcnt lgkmcnt(0)
	v_mfma_f32_16x16x32_bf16 v[60:63], v[144:147], v[178:181], 0
	v_mfma_f32_16x16x32_bf16 v[56:59], v[152:155], v[178:181], 0
	v_mfma_f32_16x16x32_bf16 v[52:55], v[144:147], v[186:189], 0
	v_mfma_f32_16x16x32_bf16 v[48:51], v[152:155], v[186:189], 0
	v_mfma_f32_16x16x32_bf16 v[36:39], v[144:147], v[194:197], 0
	v_mfma_f32_16x16x32_bf16 v[32:35], v[152:155], v[194:197], 0
	v_mfma_f32_16x16x32_bf16 v[20:23], v[144:147], v[202:205], 0
	v_mfma_f32_16x16x32_bf16 v[16:19], v[152:155], v[202:205], 0
	v_mfma_f32_16x16x32_bf16 v[60:63], v[148:151], v[182:185], v[60:63]
	v_mfma_f32_16x16x32_bf16 v[56:59], v[156:159], v[182:185], v[56:59]
	v_mfma_f32_16x16x32_bf16 v[52:55], v[148:151], v[190:193], v[52:55]
	v_mfma_f32_16x16x32_bf16 v[48:51], v[156:159], v[190:193], v[48:51]
	v_mfma_f32_16x16x32_bf16 v[36:39], v[148:151], v[198:201], v[36:39]
	v_mfma_f32_16x16x32_bf16 v[32:35], v[156:159], v[198:201], v[32:35]
	v_mfma_f32_16x16x32_bf16 v[20:23], v[148:151], v[206:209], v[20:23]
	v_mfma_f32_16x16x32_bf16 v[16:19], v[156:159], v[206:209], v[16:19]
	s_setprio 0
	s_setprio 1
	v_mfma_f32_16x16x32_bf16 v[44:47], v[160:163], v[178:181], 0
	v_mfma_f32_16x16x32_bf16 v[40:43], v[168:171], v[178:181], 0
	v_mfma_f32_16x16x32_bf16 v[28:31], v[160:163], v[186:189], 0
	v_mfma_f32_16x16x32_bf16 v[24:27], v[168:171], v[186:189], 0
	v_mfma_f32_16x16x32_bf16 v[12:15], v[160:163], v[194:197], 0
	v_mfma_f32_16x16x32_bf16 v[8:11], v[168:171], v[194:197], 0
	v_mfma_f32_16x16x32_bf16 v[4:7], v[160:163], v[202:205], 0
	v_mfma_f32_16x16x32_bf16 v[0:3], v[168:171], v[202:205], 0
	v_mfma_f32_16x16x32_bf16 v[44:47], v[164:167], v[182:185], v[44:47]
	v_mfma_f32_16x16x32_bf16 v[40:43], v[172:175], v[182:185], v[40:43]
	v_mfma_f32_16x16x32_bf16 v[28:31], v[164:167], v[190:193], v[28:31]
	v_mfma_f32_16x16x32_bf16 v[24:27], v[172:175], v[190:193], v[24:27]
	v_mfma_f32_16x16x32_bf16 v[12:15], v[164:167], v[198:201], v[12:15]
	v_mfma_f32_16x16x32_bf16 v[8:11], v[172:175], v[198:201], v[8:11]
	v_mfma_f32_16x16x32_bf16 v[4:7], v[164:167], v[206:209], v[4:7]
	v_mfma_f32_16x16x32_bf16 v[0:3], v[172:175], v[206:209], v[0:3]
	s_setprio 0
	s_barrier
	s_add_i32 s38, 0, 0x18000
	s_add_i32 s39, 0, 0x1c000
	ds_read_b128 v[144:147], v253 offset:32768
	ds_read_b128 v[148:151], v253 offset:33792
	ds_read_b128 v[152:155], v253 offset:34816
	ds_read_b128 v[156:159], v253 offset:35840
	ds_read_b128 v[160:163], v253 offset:49152
	ds_read_b128 v[164:167], v253 offset:50176
	ds_read_b128 v[168:171], v253 offset:51200
	ds_read_b128 v[172:175], v253 offset:52224
	s_add_u32 s22, s22, 0x100000
	s_addc_u32 s23, s23, 0
	s_mov_b32 m0, s9
	ds_read_b128 v[178:181], v143 offset:32768
	ds_read_b128 v[182:185], v143 offset:33792
	ds_read_b128 v[186:189], v143 offset:34816
	ds_read_b128 v[190:193], v143 offset:35840
	ds_read_b128 v[194:197], v143 offset:36864
	ds_read_b128 v[198:201], v143 offset:37888
	ds_read_b128 v[202:205], v143 offset:38912
	ds_read_b128 v[206:209], v143 offset:39936
	global_load_lds_dwordx4 v134, s[22:23]
	s_mov_b32 m0, s28
	s_nop 0
	global_load_lds_dwordx4 v130, s[22:23]
	s_waitcnt vmcnt(8)
	s_waitcnt lgkmcnt(0)
	s_barrier
	s_setprio 1
	s_waitcnt lgkmcnt(0)
	v_mfma_f32_16x16x32_bf16 v[124:127], v[144:147], v[178:181], v[124:127]
	v_mfma_f32_16x16x32_bf16 v[120:123], v[152:155], v[178:181], v[120:123]
	v_mfma_f32_16x16x32_bf16 v[116:119], v[144:147], v[186:189], v[116:119]
	v_mfma_f32_16x16x32_bf16 v[112:115], v[152:155], v[186:189], v[112:115]
	v_mfma_f32_16x16x32_bf16 v[100:103], v[144:147], v[194:197], v[100:103]
	v_mfma_f32_16x16x32_bf16 v[96:99], v[152:155], v[194:197], v[96:99]
	v_mfma_f32_16x16x32_bf16 v[84:87], v[144:147], v[202:205], v[84:87]
	v_mfma_f32_16x16x32_bf16 v[80:83], v[152:155], v[202:205], v[80:83]
	v_mfma_f32_16x16x32_bf16 v[124:127], v[148:151], v[182:185], v[124:127]
	v_mfma_f32_16x16x32_bf16 v[120:123], v[156:159], v[182:185], v[120:123]
	v_mfma_f32_16x16x32_bf16 v[116:119], v[148:151], v[190:193], v[116:119]
	v_mfma_f32_16x16x32_bf16 v[112:115], v[156:159], v[190:193], v[112:115]
	v_mfma_f32_16x16x32_bf16 v[100:103], v[148:151], v[198:201], v[100:103]
	v_mfma_f32_16x16x32_bf16 v[96:99], v[156:159], v[198:201], v[96:99]
	v_mfma_f32_16x16x32_bf16 v[84:87], v[148:151], v[206:209], v[84:87]
	v_mfma_f32_16x16x32_bf16 v[80:83], v[156:159], v[206:209], v[80:83]
	s_setprio 0
	s_setprio 1
	v_mfma_f32_16x16x32_bf16 v[108:111], v[160:163], v[178:181], v[108:111]
	v_mfma_f32_16x16x32_bf16 v[104:107], v[168:171], v[178:181], v[104:107]
	v_mfma_f32_16x16x32_bf16 v[92:95], v[160:163], v[186:189], v[92:95]
	v_mfma_f32_16x16x32_bf16 v[88:91], v[168:171], v[186:189], v[88:91]
	v_mfma_f32_16x16x32_bf16 v[76:79], v[160:163], v[194:197], v[76:79]
	v_mfma_f32_16x16x32_bf16 v[72:75], v[168:171], v[194:197], v[72:75]
	v_mfma_f32_16x16x32_bf16 v[68:71], v[160:163], v[202:205], v[68:71]
	v_mfma_f32_16x16x32_bf16 v[64:67], v[168:171], v[202:205], v[64:67]
	v_mfma_f32_16x16x32_bf16 v[108:111], v[164:167], v[182:185], v[108:111]
	v_mfma_f32_16x16x32_bf16 v[104:107], v[172:175], v[182:185], v[104:107]
	v_mfma_f32_16x16x32_bf16 v[92:95], v[164:167], v[190:193], v[92:95]
	v_mfma_f32_16x16x32_bf16 v[88:91], v[172:175], v[190:193], v[88:91]
	v_mfma_f32_16x16x32_bf16 v[76:79], v[164:167], v[198:201], v[76:79]
	v_mfma_f32_16x16x32_bf16 v[72:75], v[172:175], v[198:201], v[72:75]
	v_mfma_f32_16x16x32_bf16 v[68:71], v[164:167], v[206:209], v[68:71]
	v_mfma_f32_16x16x32_bf16 v[64:67], v[172:175], v[206:209], v[64:67]
	s_setprio 0
	s_barrier
	s_add_i32 s22, s38, s26
	s_mov_b32 m0, s22
	ds_read_b128 v[178:181], v143 offset:49152
	ds_read_b128 v[182:185], v143 offset:50176
	ds_read_b128 v[186:189], v143 offset:51200
	ds_read_b128 v[190:193], v143 offset:52224
	ds_read_b128 v[194:197], v143 offset:53248
	ds_read_b128 v[198:201], v143 offset:54272
	ds_read_b128 v[202:205], v143 offset:55296
	ds_read_b128 v[206:209], v143 offset:56320
	s_add_u32 s98, s18, 0x80
	s_addc_u32 s99, s19, 0
	global_load_lds_dwordx4 v132, s[98:99]
	s_add_i32 m0, s22, 0x2000
	s_add_u32 s18, s18, 0x800080
	s_addc_u32 s19, s19, 0
	s_add_i32 s22, s39, s26
	s_add_u32 s98, s18, 0xff800000
	s_addc_u32 s99, s19, -1
	global_load_lds_dwordx4 v128, s[98:99]
	s_mov_b32 m0, s22
	s_nop 0
	global_load_lds_dwordx4 v132, s[18:19]
	s_add_i32 m0, s22, 0x2000
	s_nop 0
	global_load_lds_dwordx4 v128, s[18:19]
	s_mov_b32 m0, s29
	s_nop 0
	global_load_lds_dwordx4 v134, s[60:61]
	s_mov_b32 m0, s30
	s_nop 0
	global_load_lds_dwordx4 v130, s[60:61]
	s_waitcnt vmcnt(8)
	s_waitcnt lgkmcnt(0)
	s_barrier
	s_setprio 1
	s_waitcnt lgkmcnt(0)
	v_mfma_f32_16x16x32_bf16 v[60:63], v[144:147], v[178:181], v[60:63]
	v_mfma_f32_16x16x32_bf16 v[56:59], v[152:155], v[178:181], v[56:59]
	v_mfma_f32_16x16x32_bf16 v[52:55], v[144:147], v[186:189], v[52:55]
	v_mfma_f32_16x16x32_bf16 v[48:51], v[152:155], v[186:189], v[48:51]
	v_mfma_f32_16x16x32_bf16 v[36:39], v[144:147], v[194:197], v[36:39]
	v_mfma_f32_16x16x32_bf16 v[32:35], v[152:155], v[194:197], v[32:35]
	v_mfma_f32_16x16x32_bf16 v[20:23], v[144:147], v[202:205], v[20:23]
	v_mfma_f32_16x16x32_bf16 v[16:19], v[152:155], v[202:205], v[16:19]
	v_mfma_f32_16x16x32_bf16 v[60:63], v[148:151], v[182:185], v[60:63]
	v_mfma_f32_16x16x32_bf16 v[56:59], v[156:159], v[182:185], v[56:59]
	v_mfma_f32_16x16x32_bf16 v[52:55], v[148:151], v[190:193], v[52:55]
	v_mfma_f32_16x16x32_bf16 v[48:51], v[156:159], v[190:193], v[48:51]
	v_mfma_f32_16x16x32_bf16 v[36:39], v[148:151], v[198:201], v[36:39]
	v_mfma_f32_16x16x32_bf16 v[32:35], v[156:159], v[198:201], v[32:35]
	v_mfma_f32_16x16x32_bf16 v[20:23], v[148:151], v[206:209], v[20:23]
	v_mfma_f32_16x16x32_bf16 v[16:19], v[156:159], v[206:209], v[16:19]
	s_setprio 0
	s_setprio 1
	v_mfma_f32_16x16x32_bf16 v[44:47], v[160:163], v[178:181], v[44:47]
	v_mfma_f32_16x16x32_bf16 v[40:43], v[168:171], v[178:181], v[40:43]
	v_mfma_f32_16x16x32_bf16 v[28:31], v[160:163], v[186:189], v[28:31]
	v_mfma_f32_16x16x32_bf16 v[24:27], v[168:171], v[186:189], v[24:27]
	v_mfma_f32_16x16x32_bf16 v[12:15], v[160:163], v[194:197], v[12:15]
	v_mfma_f32_16x16x32_bf16 v[8:11], v[168:171], v[194:197], v[8:11]
	v_mfma_f32_16x16x32_bf16 v[4:7], v[160:163], v[202:205], v[4:7]
	v_mfma_f32_16x16x32_bf16 v[0:3], v[168:171], v[202:205], v[0:3]
	v_mfma_f32_16x16x32_bf16 v[44:47], v[164:167], v[182:185], v[44:47]
	v_mfma_f32_16x16x32_bf16 v[40:43], v[172:175], v[182:185], v[40:43]
	v_mfma_f32_16x16x32_bf16 v[28:31], v[164:167], v[190:193], v[28:31]
	v_mfma_f32_16x16x32_bf16 v[24:27], v[172:175], v[190:193], v[24:27]
	v_mfma_f32_16x16x32_bf16 v[12:15], v[164:167], v[198:201], v[12:15]
	v_mfma_f32_16x16x32_bf16 v[8:11], v[172:175], v[198:201], v[8:11]
	v_mfma_f32_16x16x32_bf16 v[4:7], v[164:167], v[206:209], v[4:7]
	v_mfma_f32_16x16x32_bf16 v[0:3], v[172:175], v[206:209], v[0:3]
	s_setprio 0
	s_barrier
	s_add_i32 s37, s37, 2
	s_add_u32 s16, s16, 0x100
	s_addc_u32 s17, s17, 0
	s_add_u32 s7, s7, 0x100
	s_addc_u32 s36, s36, 0
	s_cmp_gt_u32 s37, 61
.LBB0_748:
	s_add_u32 s18, s16, 0xfff00080
	s_addc_u32 s19, s17, -1
	s_add_i32 s38, 0, 0x10000
	s_cmp_eq_u32 s37, 60
	s_cselect_b32 s23, s15, s19
	s_cselect_b32 s22, s14, s18
	s_cselect_b32 s19, s13, s36
	s_cselect_b32 s18, s12, s7
	s_add_i32 s40, 0, 0x14000
	ds_read_b128 v[144:147], v253
	ds_read_b128 v[148:151], v253 offset:1024
	ds_read_b128 v[152:155], v253 offset:2048
	ds_read_b128 v[156:159], v253 offset:3072
	ds_read_b128 v[160:163], v253 offset:16384
	ds_read_b128 v[164:167], v253 offset:17408
	ds_read_b128 v[168:171], v253 offset:18432
	ds_read_b128 v[172:175], v253 offset:19456
	s_add_i32 m0, s27, 0xc000
	ds_read_b128 v[178:181], v143
	ds_read_b128 v[182:185], v143 offset:1024
	ds_read_b128 v[186:189], v143 offset:2048
	ds_read_b128 v[190:193], v143 offset:3072
	ds_read_b128 v[194:197], v143 offset:4096
	ds_read_b128 v[198:201], v143 offset:5120
	ds_read_b128 v[202:205], v143 offset:6144
	ds_read_b128 v[206:209], v143 offset:7168
	global_load_lds_dwordx4 v138, s[16:17]
	s_add_i32 m0, s27, 0xe000
	s_nop 0
	global_load_lds_dwordx4 v140, s[16:17]
	s_waitcnt vmcnt(8)
	s_waitcnt lgkmcnt(0)
	s_barrier
	s_setprio 1
	s_waitcnt lgkmcnt(0)
	v_mfma_f32_16x16x32_bf16 v[124:127], v[144:147], v[178:181], v[124:127]
	v_mfma_f32_16x16x32_bf16 v[120:123], v[152:155], v[178:181], v[120:123]
	v_mfma_f32_16x16x32_bf16 v[116:119], v[144:147], v[186:189], v[116:119]
	v_mfma_f32_16x16x32_bf16 v[112:115], v[152:155], v[186:189], v[112:115]
	v_mfma_f32_16x16x32_bf16 v[100:103], v[144:147], v[194:197], v[100:103]
	v_mfma_f32_16x16x32_bf16 v[96:99], v[152:155], v[194:197], v[96:99]
	v_mfma_f32_16x16x32_bf16 v[84:87], v[144:147], v[202:205], v[84:87]
	v_mfma_f32_16x16x32_bf16 v[80:83], v[152:155], v[202:205], v[80:83]
	v_mfma_f32_16x16x32_bf16 v[124:127], v[148:151], v[182:185], v[124:127]
	v_mfma_f32_16x16x32_bf16 v[120:123], v[156:159], v[182:185], v[120:123]
	v_mfma_f32_16x16x32_bf16 v[116:119], v[148:151], v[190:193], v[116:119]
	v_mfma_f32_16x16x32_bf16 v[112:115], v[156:159], v[190:193], v[112:115]
	v_mfma_f32_16x16x32_bf16 v[100:103], v[148:151], v[198:201], v[100:103]
	v_mfma_f32_16x16x32_bf16 v[96:99], v[156:159], v[198:201], v[96:99]
	v_mfma_f32_16x16x32_bf16 v[84:87], v[148:151], v[206:209], v[84:87]
	v_mfma_f32_16x16x32_bf16 v[80:83], v[156:159], v[206:209], v[80:83]
	s_setprio 0
	s_setprio 1
	v_mfma_f32_16x16x32_bf16 v[108:111], v[160:163], v[178:181], v[108:111]
	v_mfma_f32_16x16x32_bf16 v[104:107], v[168:171], v[178:181], v[104:107]
	v_mfma_f32_16x16x32_bf16 v[92:95], v[160:163], v[186:189], v[92:95]
	v_mfma_f32_16x16x32_bf16 v[88:91], v[168:171], v[186:189], v[88:91]
	v_mfma_f32_16x16x32_bf16 v[76:79], v[160:163], v[194:197], v[76:79]
	v_mfma_f32_16x16x32_bf16 v[72:75], v[168:171], v[194:197], v[72:75]
	v_mfma_f32_16x16x32_bf16 v[68:71], v[160:163], v[202:205], v[68:71]
	v_mfma_f32_16x16x32_bf16 v[64:67], v[168:171], v[202:205], v[64:67]
	v_mfma_f32_16x16x32_bf16 v[108:111], v[164:167], v[182:185], v[108:111]
	v_mfma_f32_16x16x32_bf16 v[104:107], v[172:175], v[182:185], v[104:107]
	v_mfma_f32_16x16x32_bf16 v[92:95], v[164:167], v[190:193], v[92:95]
	v_mfma_f32_16x16x32_bf16 v[88:91], v[172:175], v[190:193], v[88:91]
	v_mfma_f32_16x16x32_bf16 v[76:79], v[164:167], v[198:201], v[76:79]
	v_mfma_f32_16x16x32_bf16 v[72:75], v[172:175], v[198:201], v[72:75]
	v_mfma_f32_16x16x32_bf16 v[68:71], v[164:167], v[206:209], v[68:71]
	v_mfma_f32_16x16x32_bf16 v[64:67], v[172:175], v[206:209], v[64:67]
	s_setprio 0
	s_barrier
	s_add_i32 s38, s38, s26
	s_mov_b32 m0, s38
	ds_read_b128 v[178:181], v143 offset:16384
	ds_read_b128 v[182:185], v143 offset:17408
	ds_read_b128 v[186:189], v143 offset:18432
	ds_read_b128 v[190:193], v143 offset:19456
	ds_read_b128 v[194:197], v143 offset:20480
	ds_read_b128 v[198:201], v143 offset:21504
	ds_read_b128 v[202:205], v143 offset:22528
	ds_read_b128 v[206:209], v143 offset:23552
	global_load_lds_dwordx4 v132, s[18:19]
	s_add_i32 m0, s38, 0x2000
	s_add_u32 s38, s18, 0x800000
	s_addc_u32 s39, s19, 0
	s_add_i32 s40, s40, s26
	global_load_lds_dwordx4 v128, s[18:19]
	s_mov_b32 m0, s40
	s_nop 0
	global_load_lds_dwordx4 v132, s[38:39]
	s_add_i32 m0, s40, 0x2000
	s_nop 0
	global_load_lds_dwordx4 v128, s[38:39]
	s_add_u32 s60, s22, 0x80
	s_addc_u32 s61, s23, 0
	s_mov_b32 m0, s27
	s_nop 0
	global_load_lds_dwordx4 v134, s[22:23]
	s_mov_b32 m0, s8
	s_nop 0
	global_load_lds_dwordx4 v130, s[22:23]
	s_waitcnt vmcnt(8)
	s_waitcnt lgkmcnt(0)
	s_barrier
	s_setprio 1
	s_waitcnt lgkmcnt(0)
	v_mfma_f32_16x16x32_bf16 v[60:63], v[144:147], v[178:181], v[60:63]
	v_mfma_f32_16x16x32_bf16 v[56:59], v[152:155], v[178:181], v[56:59]
	v_mfma_f32_16x16x32_bf16 v[52:55], v[144:147], v[186:189], v[52:55]
	v_mfma_f32_16x16x32_bf16 v[48:51], v[152:155], v[186:189], v[48:51]
	v_mfma_f32_16x16x32_bf16 v[36:39], v[144:147], v[194:197], v[36:39]
	v_mfma_f32_16x16x32_bf16 v[32:35], v[152:155], v[194:197], v[32:35]
	v_mfma_f32_16x16x32_bf16 v[20:23], v[144:147], v[202:205], v[20:23]
	v_mfma_f32_16x16x32_bf16 v[16:19], v[152:155], v[202:205], v[16:19]
	v_mfma_f32_16x16x32_bf16 v[60:63], v[148:151], v[182:185], v[60:63]
	v_mfma_f32_16x16x32_bf16 v[56:59], v[156:159], v[182:185], v[56:59]
	v_mfma_f32_16x16x32_bf16 v[52:55], v[148:151], v[190:193], v[52:55]
	v_mfma_f32_16x16x32_bf16 v[48:51], v[156:159], v[190:193], v[48:51]
	v_mfma_f32_16x16x32_bf16 v[36:39], v[148:151], v[198:201], v[36:39]
	v_mfma_f32_16x16x32_bf16 v[32:35], v[156:159], v[198:201], v[32:35]
	v_mfma_f32_16x16x32_bf16 v[20:23], v[148:151], v[206:209], v[20:23]
	v_mfma_f32_16x16x32_bf16 v[16:19], v[156:159], v[206:209], v[16:19]
	s_setprio 0
	s_setprio 1
	v_mfma_f32_16x16x32_bf16 v[44:47], v[160:163], v[178:181], v[44:47]
	v_mfma_f32_16x16x32_bf16 v[40:43], v[168:171], v[178:181], v[40:43]
	v_mfma_f32_16x16x32_bf16 v[28:31], v[160:163], v[186:189], v[28:31]
	v_mfma_f32_16x16x32_bf16 v[24:27], v[168:171], v[186:189], v[24:27]
	v_mfma_f32_16x16x32_bf16 v[12:15], v[160:163], v[194:197], v[12:15]
	v_mfma_f32_16x16x32_bf16 v[8:11], v[168:171], v[194:197], v[8:11]
	v_mfma_f32_16x16x32_bf16 v[4:7], v[160:163], v[202:205], v[4:7]
	v_mfma_f32_16x16x32_bf16 v[0:3], v[168:171], v[202:205], v[0:3]
	v_mfma_f32_16x16x32_bf16 v[44:47], v[164:167], v[182:185], v[44:47]
	v_mfma_f32_16x16x32_bf16 v[40:43], v[172:175], v[182:185], v[40:43]
	v_mfma_f32_16x16x32_bf16 v[28:31], v[164:167], v[190:193], v[28:31]
	v_mfma_f32_16x16x32_bf16 v[24:27], v[172:175], v[190:193], v[24:27]
	v_mfma_f32_16x16x32_bf16 v[12:15], v[164:167], v[198:201], v[12:15]
	v_mfma_f32_16x16x32_bf16 v[8:11], v[172:175], v[198:201], v[8:11]
	v_mfma_f32_16x16x32_bf16 v[4:7], v[164:167], v[206:209], v[4:7]
	v_mfma_f32_16x16x32_bf16 v[0:3], v[172:175], v[206:209], v[0:3]
	s_setprio 0
	s_barrier
	s_add_i32 s38, 0, 0x18000
	s_add_i32 s39, 0, 0x1c000
	ds_read_b128 v[144:147], v253 offset:32768
	ds_read_b128 v[148:151], v253 offset:33792
	ds_read_b128 v[152:155], v253 offset:34816
	ds_read_b128 v[156:159], v253 offset:35840
	ds_read_b128 v[160:163], v253 offset:49152
	ds_read_b128 v[164:167], v253 offset:50176
	ds_read_b128 v[168:171], v253 offset:51200
	ds_read_b128 v[172:175], v253 offset:52224
	s_add_u32 s22, s22, 0x100000
	s_addc_u32 s23, s23, 0
	s_mov_b32 m0, s9
	ds_read_b128 v[178:181], v143 offset:32768
	ds_read_b128 v[182:185], v143 offset:33792
	ds_read_b128 v[186:189], v143 offset:34816
	ds_read_b128 v[190:193], v143 offset:35840
	ds_read_b128 v[194:197], v143 offset:36864
	ds_read_b128 v[198:201], v143 offset:37888
	ds_read_b128 v[202:205], v143 offset:38912
	ds_read_b128 v[206:209], v143 offset:39936
	global_load_lds_dwordx4 v134, s[22:23]
	s_mov_b32 m0, s28
	s_nop 0
	global_load_lds_dwordx4 v130, s[22:23]
	s_waitcnt vmcnt(8)
	s_waitcnt lgkmcnt(0)
	s_barrier
	s_setprio 1
	s_waitcnt lgkmcnt(0)
	v_mfma_f32_16x16x32_bf16 v[124:127], v[144:147], v[178:181], v[124:127]
	v_mfma_f32_16x16x32_bf16 v[120:123], v[152:155], v[178:181], v[120:123]
	v_mfma_f32_16x16x32_bf16 v[116:119], v[144:147], v[186:189], v[116:119]
	v_mfma_f32_16x16x32_bf16 v[112:115], v[152:155], v[186:189], v[112:115]
	v_mfma_f32_16x16x32_bf16 v[100:103], v[144:147], v[194:197], v[100:103]
	v_mfma_f32_16x16x32_bf16 v[96:99], v[152:155], v[194:197], v[96:99]
	v_mfma_f32_16x16x32_bf16 v[84:87], v[144:147], v[202:205], v[84:87]
	v_mfma_f32_16x16x32_bf16 v[80:83], v[152:155], v[202:205], v[80:83]
	v_mfma_f32_16x16x32_bf16 v[124:127], v[148:151], v[182:185], v[124:127]
	v_mfma_f32_16x16x32_bf16 v[120:123], v[156:159], v[182:185], v[120:123]
	v_mfma_f32_16x16x32_bf16 v[116:119], v[148:151], v[190:193], v[116:119]
	v_mfma_f32_16x16x32_bf16 v[112:115], v[156:159], v[190:193], v[112:115]
	v_mfma_f32_16x16x32_bf16 v[100:103], v[148:151], v[198:201], v[100:103]
	v_mfma_f32_16x16x32_bf16 v[96:99], v[156:159], v[198:201], v[96:99]
	v_mfma_f32_16x16x32_bf16 v[84:87], v[148:151], v[206:209], v[84:87]
	v_mfma_f32_16x16x32_bf16 v[80:83], v[156:159], v[206:209], v[80:83]
	s_setprio 0
	s_setprio 1
	v_mfma_f32_16x16x32_bf16 v[108:111], v[160:163], v[178:181], v[108:111]
	v_mfma_f32_16x16x32_bf16 v[104:107], v[168:171], v[178:181], v[104:107]
	v_mfma_f32_16x16x32_bf16 v[92:95], v[160:163], v[186:189], v[92:95]
	v_mfma_f32_16x16x32_bf16 v[88:91], v[168:171], v[186:189], v[88:91]
	v_mfma_f32_16x16x32_bf16 v[76:79], v[160:163], v[194:197], v[76:79]
	v_mfma_f32_16x16x32_bf16 v[72:75], v[168:171], v[194:197], v[72:75]
	v_mfma_f32_16x16x32_bf16 v[68:71], v[160:163], v[202:205], v[68:71]
	v_mfma_f32_16x16x32_bf16 v[64:67], v[168:171], v[202:205], v[64:67]
	v_mfma_f32_16x16x32_bf16 v[108:111], v[164:167], v[182:185], v[108:111]
	v_mfma_f32_16x16x32_bf16 v[104:107], v[172:175], v[182:185], v[104:107]
	v_mfma_f32_16x16x32_bf16 v[92:95], v[164:167], v[190:193], v[92:95]
	v_mfma_f32_16x16x32_bf16 v[88:91], v[172:175], v[190:193], v[88:91]
	v_mfma_f32_16x16x32_bf16 v[76:79], v[164:167], v[198:201], v[76:79]
	v_mfma_f32_16x16x32_bf16 v[72:75], v[172:175], v[198:201], v[72:75]
	v_mfma_f32_16x16x32_bf16 v[68:71], v[164:167], v[206:209], v[68:71]
	v_mfma_f32_16x16x32_bf16 v[64:67], v[172:175], v[206:209], v[64:67]
	s_setprio 0
	s_barrier
	s_add_i32 s22, s38, s26
	s_mov_b32 m0, s22
	ds_read_b128 v[178:181], v143 offset:49152
	ds_read_b128 v[182:185], v143 offset:50176
	ds_read_b128 v[186:189], v143 offset:51200
	ds_read_b128 v[190:193], v143 offset:52224
	ds_read_b128 v[194:197], v143 offset:53248
	ds_read_b128 v[198:201], v143 offset:54272
	ds_read_b128 v[202:205], v143 offset:55296
	ds_read_b128 v[206:209], v143 offset:56320
	s_add_u32 s98, s18, 0x80
	s_addc_u32 s99, s19, 0
	global_load_lds_dwordx4 v132, s[98:99]
	s_add_i32 m0, s22, 0x2000
	s_add_u32 s18, s18, 0x800080
	s_addc_u32 s19, s19, 0
	s_add_i32 s22, s39, s26
	s_add_u32 s98, s18, 0xff800000
	s_addc_u32 s99, s19, -1
	global_load_lds_dwordx4 v128, s[98:99]
	s_mov_b32 m0, s22
	s_nop 0
	global_load_lds_dwordx4 v132, s[18:19]
	s_add_i32 m0, s22, 0x2000
	s_nop 0
	global_load_lds_dwordx4 v128, s[18:19]
	s_mov_b32 m0, s29
	s_nop 0
	global_load_lds_dwordx4 v134, s[60:61]
	s_mov_b32 m0, s30
	s_nop 0
	global_load_lds_dwordx4 v130, s[60:61]
	s_waitcnt vmcnt(8)
	s_waitcnt lgkmcnt(0)
	s_barrier
	s_setprio 1
	s_waitcnt lgkmcnt(0)
	v_mfma_f32_16x16x32_bf16 v[60:63], v[144:147], v[178:181], v[60:63]
	v_mfma_f32_16x16x32_bf16 v[56:59], v[152:155], v[178:181], v[56:59]
	v_mfma_f32_16x16x32_bf16 v[52:55], v[144:147], v[186:189], v[52:55]
	v_mfma_f32_16x16x32_bf16 v[48:51], v[152:155], v[186:189], v[48:51]
	v_mfma_f32_16x16x32_bf16 v[36:39], v[144:147], v[194:197], v[36:39]
	v_mfma_f32_16x16x32_bf16 v[32:35], v[152:155], v[194:197], v[32:35]
	v_mfma_f32_16x16x32_bf16 v[20:23], v[144:147], v[202:205], v[20:23]
	v_mfma_f32_16x16x32_bf16 v[16:19], v[152:155], v[202:205], v[16:19]
	v_mfma_f32_16x16x32_bf16 v[60:63], v[148:151], v[182:185], v[60:63]
	v_mfma_f32_16x16x32_bf16 v[56:59], v[156:159], v[182:185], v[56:59]
	v_mfma_f32_16x16x32_bf16 v[52:55], v[148:151], v[190:193], v[52:55]
	v_mfma_f32_16x16x32_bf16 v[48:51], v[156:159], v[190:193], v[48:51]
	v_mfma_f32_16x16x32_bf16 v[36:39], v[148:151], v[198:201], v[36:39]
	v_mfma_f32_16x16x32_bf16 v[32:35], v[156:159], v[198:201], v[32:35]
	v_mfma_f32_16x16x32_bf16 v[20:23], v[148:151], v[206:209], v[20:23]
	v_mfma_f32_16x16x32_bf16 v[16:19], v[156:159], v[206:209], v[16:19]
	s_setprio 0
	s_setprio 1
	v_mfma_f32_16x16x32_bf16 v[44:47], v[160:163], v[178:181], v[44:47]
	v_mfma_f32_16x16x32_bf16 v[40:43], v[168:171], v[178:181], v[40:43]
	v_mfma_f32_16x16x32_bf16 v[28:31], v[160:163], v[186:189], v[28:31]
	v_mfma_f32_16x16x32_bf16 v[24:27], v[168:171], v[186:189], v[24:27]
	v_mfma_f32_16x16x32_bf16 v[12:15], v[160:163], v[194:197], v[12:15]
	v_mfma_f32_16x16x32_bf16 v[8:11], v[168:171], v[194:197], v[8:11]
	v_mfma_f32_16x16x32_bf16 v[4:7], v[160:163], v[202:205], v[4:7]
	v_mfma_f32_16x16x32_bf16 v[0:3], v[168:171], v[202:205], v[0:3]
	v_mfma_f32_16x16x32_bf16 v[44:47], v[164:167], v[182:185], v[44:47]
	v_mfma_f32_16x16x32_bf16 v[40:43], v[172:175], v[182:185], v[40:43]
	v_mfma_f32_16x16x32_bf16 v[28:31], v[164:167], v[190:193], v[28:31]
	v_mfma_f32_16x16x32_bf16 v[24:27], v[172:175], v[190:193], v[24:27]
	v_mfma_f32_16x16x32_bf16 v[12:15], v[164:167], v[198:201], v[12:15]
	v_mfma_f32_16x16x32_bf16 v[8:11], v[172:175], v[198:201], v[8:11]
	v_mfma_f32_16x16x32_bf16 v[4:7], v[164:167], v[206:209], v[4:7]
	v_mfma_f32_16x16x32_bf16 v[0:3], v[172:175], v[206:209], v[0:3]
	s_setprio 0
	s_barrier
	s_add_i32 s37, s37, 2
	s_add_u32 s16, s16, 0x100
	s_addc_u32 s17, s17, 0
	s_add_u32 s7, s7, 0x100
	s_addc_u32 s36, s36, 0
	s_cmp_gt_u32 s37, 61
	s_cbranch_scc0 .LBB0_748
	s_and_b64 vcc, exec, s[4:5]
	s_cbranch_vccz .LBB0_751
	s_barrier

.LBB0_829:
	s_mov_b32 s59, s58
	s_add_i32 s58, s58, 1
	s_cmp_lt_u32 s59, 2
	s_cselect_b64 s[10:11], -1, 0
	s_lshl_b32 s1, s58, 5
	s_add_i32 s1, s90, s1
	s_and_b64 s[12:13], s[10:11], exec
	s_mov_b32 s2, s56
	s_cselect_b32 s56, s1, s56
	s_mov_b32 s0, s54
	s_cselect_b32 s54, s94, s54
	s_ashr_i32 s57, s56, 31
	s_lshl_b64 s[12:13], s[56:57], 20
	s_add_u32 s1, s22, s12
	s_addc_u32 s3, s23, s13
	s_mov_b64 s[6:7], s[30:31]
	s_and_b64 s[12:13], s[10:11], exec
	s_cselect_b32 s31, s3, s7
	s_cselect_b32 s30, s1, s6
	s_ashr_i32 s55, s54, 31
	s_lshl_b64 s[12:13], s[54:55], 20
	s_add_u32 s1, s24, s12
	s_addc_u32 s3, s25, s13
	s_mov_b64 s[8:9], s[18:19]
	s_and_b64 s[10:11], s[10:11], exec
	s_cselect_b32 s19, s3, s9
	s_cselect_b32 s18, s1, s8
	s_add_u32 s6, s6, 0x80080
	s_addc_u32 s7, s7, 0
	s_add_u32 s1, s8, 0x100
	s_addc_u32 s3, s9, 0
	s_mov_b32 s12, -2
	s_waitcnt lgkmcnt(0)
	v_add_u32_e32 v253, 0x10000, v209
	s_add_u32 s8, s6, 0xfff80080
	s_addc_u32 s9, s7, -1
	s_add_i32 s13, 0, 0x10000
	s_cmp_eq_u32 s12, 28
	s_cselect_b32 s11, s31, s9
	s_cselect_b32 s10, s30, s8
	s_cselect_b32 s9, s19, s3
	s_cselect_b32 s8, s18, s1
	s_add_i32 s20, 0, 0x14000
	ds_read_b128 v[104:107], v253
	ds_read_b128 v[116:119], v253 offset:1024
	ds_read_b128 v[120:123], v253 offset:2048
	ds_read_b128 v[124:127], v253 offset:3072
	ds_read_b128 v[136:139], v253 offset:16384
	ds_read_b128 v[140:143], v253 offset:17408
	ds_read_b128 v[152:155], v253 offset:18432
	ds_read_b128 v[156:159], v253 offset:19456
	s_add_i32 m0, s28, 0xc000
	ds_read_b128 v[160:163], v228
	ds_read_b128 v[164:167], v228 offset:1024
	ds_read_b128 v[168:171], v228 offset:2048
	ds_read_b128 v[172:175], v228 offset:3072
	ds_read_b128 v[230:233], v228 offset:4096
	ds_read_b128 v[234:237], v228 offset:5120
	ds_read_b128 v[238:241], v228 offset:6144
	ds_read_b128 v[242:245], v228 offset:7168
	global_load_lds_dwordx4 v202, s[6:7]
	s_add_i32 m0, s28, 0xe000
	s_nop 0
	global_load_lds_dwordx4 v204, s[6:7]
	s_waitcnt vmcnt(8)
	s_waitcnt lgkmcnt(0)
	s_barrier
	s_setprio 1
	s_waitcnt lgkmcnt(0)
	v_mfma_f32_16x16x32_bf16 v[148:151], v[104:107], v[160:163], 0
	v_mfma_f32_16x16x32_bf16 v[144:147], v[120:123], v[160:163], 0
	v_mfma_f32_16x16x32_bf16 v[112:115], v[104:107], v[168:171], 0
	v_mfma_f32_16x16x32_bf16 v[108:111], v[120:123], v[168:171], 0
	v_mfma_f32_16x16x32_bf16 v[92:95], v[104:107], v[230:233], 0
	v_mfma_f32_16x16x32_bf16 v[88:91], v[120:123], v[230:233], 0
	v_mfma_f32_16x16x32_bf16 v[76:79], v[104:107], v[238:241], 0
	v_mfma_f32_16x16x32_bf16 v[72:75], v[120:123], v[238:241], 0
	v_mfma_f32_16x16x32_bf16 v[148:151], v[116:119], v[164:167], v[148:151]
	v_mfma_f32_16x16x32_bf16 v[144:147], v[124:127], v[164:167], v[144:147]
	v_mfma_f32_16x16x32_bf16 v[112:115], v[116:119], v[172:175], v[112:115]
	v_mfma_f32_16x16x32_bf16 v[108:111], v[124:127], v[172:175], v[108:111]
	v_mfma_f32_16x16x32_bf16 v[92:95], v[116:119], v[234:237], v[92:95]
	v_mfma_f32_16x16x32_bf16 v[88:91], v[124:127], v[234:237], v[88:91]
	v_mfma_f32_16x16x32_bf16 v[76:79], v[116:119], v[242:245], v[76:79]
	v_mfma_f32_16x16x32_bf16 v[72:75], v[124:127], v[242:245], v[72:75]
	s_setprio 0
	s_setprio 1
	v_mfma_f32_16x16x32_bf16 v[132:135], v[136:139], v[160:163], 0
	v_mfma_f32_16x16x32_bf16 v[128:131], v[152:155], v[160:163], 0
	v_mfma_f32_16x16x32_bf16 v[100:103], v[136:139], v[168:171], 0
	v_mfma_f32_16x16x32_bf16 v[96:99], v[152:155], v[168:171], 0
	v_mfma_f32_16x16x32_bf16 v[84:87], v[136:139], v[230:233], 0
	v_mfma_f32_16x16x32_bf16 v[80:83], v[152:155], v[230:233], 0
	v_mfma_f32_16x16x32_bf16 v[68:71], v[136:139], v[238:241], 0
	v_mfma_f32_16x16x32_bf16 v[64:67], v[152:155], v[238:241], 0
	v_mfma_f32_16x16x32_bf16 v[132:135], v[140:143], v[164:167], v[132:135]
	v_mfma_f32_16x16x32_bf16 v[128:131], v[156:159], v[164:167], v[128:131]
	v_mfma_f32_16x16x32_bf16 v[100:103], v[140:143], v[172:175], v[100:103]
	v_mfma_f32_16x16x32_bf16 v[96:99], v[156:159], v[172:175], v[96:99]
	v_mfma_f32_16x16x32_bf16 v[84:87], v[140:143], v[234:237], v[84:87]
	v_mfma_f32_16x16x32_bf16 v[80:83], v[156:159], v[234:237], v[80:83]
	v_mfma_f32_16x16x32_bf16 v[68:71], v[140:143], v[242:245], v[68:71]
	v_mfma_f32_16x16x32_bf16 v[64:67], v[156:159], v[242:245], v[64:67]
	s_setprio 0
	s_barrier
	s_add_i32 s13, s13, s27
	s_mov_b32 m0, s13
	ds_read_b128 v[160:163], v228 offset:16384
	ds_read_b128 v[164:167], v228 offset:17408
	ds_read_b128 v[168:171], v228 offset:18432
	ds_read_b128 v[172:175], v228 offset:19456
	ds_read_b128 v[230:233], v228 offset:20480
	ds_read_b128 v[234:237], v228 offset:21504
	ds_read_b128 v[238:241], v228 offset:22528
	ds_read_b128 v[242:245], v228 offset:23552
	global_load_lds_dwordx4 v176, s[8:9]
	s_add_i32 m0, s13, 0x2000
	s_add_u32 s14, s8, 0x80000
	s_addc_u32 s15, s9, 0
	s_add_i32 s13, s20, s27
	global_load_lds_dwordx4 v182, s[8:9]
	s_mov_b32 m0, s13
	s_nop 0
	global_load_lds_dwordx4 v176, s[14:15]
	s_add_i32 m0, s13, 0x2000
	s_nop 0
	global_load_lds_dwordx4 v182, s[14:15]
	s_add_u32 s50, s10, 0x80
	s_addc_u32 s51, s11, 0
	s_mov_b32 m0, s28
	s_nop 0
	global_load_lds_dwordx4 v178, s[10:11]
	s_mov_b32 m0, s29
	s_nop 0
	global_load_lds_dwordx4 v180, s[10:11]
	s_waitcnt vmcnt(8)
	s_waitcnt lgkmcnt(0)
	s_barrier
	s_setprio 1
	s_waitcnt lgkmcnt(0)
	v_mfma_f32_16x16x32_bf16 v[60:63], v[104:107], v[160:163], 0
	v_mfma_f32_16x16x32_bf16 v[56:59], v[120:123], v[160:163], 0
	v_mfma_f32_16x16x32_bf16 v[44:47], v[104:107], v[168:171], 0
	v_mfma_f32_16x16x32_bf16 v[40:43], v[120:123], v[168:171], 0
	v_mfma_f32_16x16x32_bf16 v[28:31], v[104:107], v[230:233], 0
	v_mfma_f32_16x16x32_bf16 v[24:27], v[120:123], v[230:233], 0
	v_mfma_f32_16x16x32_bf16 v[12:15], v[104:107], v[238:241], 0
	v_mfma_f32_16x16x32_bf16 v[8:11], v[120:123], v[238:241], 0
	v_mfma_f32_16x16x32_bf16 v[60:63], v[116:119], v[164:167], v[60:63]
	v_mfma_f32_16x16x32_bf16 v[56:59], v[124:127], v[164:167], v[56:59]
	v_mfma_f32_16x16x32_bf16 v[44:47], v[116:119], v[172:175], v[44:47]
	v_mfma_f32_16x16x32_bf16 v[40:43], v[124:127], v[172:175], v[40:43]
	v_mfma_f32_16x16x32_bf16 v[28:31], v[116:119], v[234:237], v[28:31]
	v_mfma_f32_16x16x32_bf16 v[24:27], v[124:127], v[234:237], v[24:27]
	v_mfma_f32_16x16x32_bf16 v[12:15], v[116:119], v[242:245], v[12:15]
	v_mfma_f32_16x16x32_bf16 v[8:11], v[124:127], v[242:245], v[8:11]
	s_setprio 0
	s_setprio 1
	v_mfma_f32_16x16x32_bf16 v[52:55], v[136:139], v[160:163], 0
	v_mfma_f32_16x16x32_bf16 v[48:51], v[152:155], v[160:163], 0
	v_mfma_f32_16x16x32_bf16 v[36:39], v[136:139], v[168:171], 0
	v_mfma_f32_16x16x32_bf16 v[32:35], v[152:155], v[168:171], 0
	v_mfma_f32_16x16x32_bf16 v[20:23], v[136:139], v[230:233], 0
	v_mfma_f32_16x16x32_bf16 v[16:19], v[152:155], v[230:233], 0
	v_mfma_f32_16x16x32_bf16 v[4:7], v[136:139], v[238:241], 0
	v_mfma_f32_16x16x32_bf16 v[0:3], v[152:155], v[238:241], 0
	v_mfma_f32_16x16x32_bf16 v[52:55], v[140:143], v[164:167], v[52:55]
	v_mfma_f32_16x16x32_bf16 v[48:51], v[156:159], v[164:167], v[48:51]
	v_mfma_f32_16x16x32_bf16 v[36:39], v[140:143], v[172:175], v[36:39]
	v_mfma_f32_16x16x32_bf16 v[32:35], v[156:159], v[172:175], v[32:35]
	v_mfma_f32_16x16x32_bf16 v[20:23], v[140:143], v[234:237], v[20:23]
	v_mfma_f32_16x16x32_bf16 v[16:19], v[156:159], v[234:237], v[16:19]
	v_mfma_f32_16x16x32_bf16 v[4:7], v[140:143], v[242:245], v[4:7]
	v_mfma_f32_16x16x32_bf16 v[0:3], v[156:159], v[242:245], v[0:3]
	s_setprio 0
	s_barrier
	s_add_i32 s13, 0, 0x18000
	s_add_i32 s14, 0, 0x1c000
	ds_read_b128 v[104:107], v253 offset:32768
	ds_read_b128 v[116:119], v253 offset:33792
	ds_read_b128 v[120:123], v253 offset:34816
	ds_read_b128 v[124:127], v253 offset:35840
	ds_read_b128 v[136:139], v253 offset:49152
	ds_read_b128 v[140:143], v253 offset:50176
	ds_read_b128 v[152:155], v253 offset:51200
	ds_read_b128 v[156:159], v253 offset:52224
	s_add_u32 s10, s10, 0x80000
	s_addc_u32 s11, s11, 0
	s_mov_b32 m0, s38
	ds_read_b128 v[160:163], v228 offset:32768
	ds_read_b128 v[164:167], v228 offset:33792
	ds_read_b128 v[168:171], v228 offset:34816
	ds_read_b128 v[172:175], v228 offset:35840
	ds_read_b128 v[230:233], v228 offset:36864
	ds_read_b128 v[234:237], v228 offset:37888
	ds_read_b128 v[238:241], v228 offset:38912
	ds_read_b128 v[242:245], v228 offset:39936
	global_load_lds_dwordx4 v178, s[10:11]
	s_mov_b32 m0, s39
	s_nop 0
	global_load_lds_dwordx4 v180, s[10:11]
	s_waitcnt vmcnt(8)
	s_waitcnt lgkmcnt(0)
	s_barrier
	s_setprio 1
	s_waitcnt lgkmcnt(0)
	v_mfma_f32_16x16x32_bf16 v[148:151], v[104:107], v[160:163], v[148:151]
	v_mfma_f32_16x16x32_bf16 v[144:147], v[120:123], v[160:163], v[144:147]
	v_mfma_f32_16x16x32_bf16 v[112:115], v[104:107], v[168:171], v[112:115]
	v_mfma_f32_16x16x32_bf16 v[108:111], v[120:123], v[168:171], v[108:111]
	v_mfma_f32_16x16x32_bf16 v[92:95], v[104:107], v[230:233], v[92:95]
	v_mfma_f32_16x16x32_bf16 v[88:91], v[120:123], v[230:233], v[88:91]
	v_mfma_f32_16x16x32_bf16 v[76:79], v[104:107], v[238:241], v[76:79]
	v_mfma_f32_16x16x32_bf16 v[72:75], v[120:123], v[238:241], v[72:75]
	v_mfma_f32_16x16x32_bf16 v[148:151], v[116:119], v[164:167], v[148:151]
	v_mfma_f32_16x16x32_bf16 v[144:147], v[124:127], v[164:167], v[144:147]
	v_mfma_f32_16x16x32_bf16 v[112:115], v[116:119], v[172:175], v[112:115]
	v_mfma_f32_16x16x32_bf16 v[108:111], v[124:127], v[172:175], v[108:111]
	v_mfma_f32_16x16x32_bf16 v[92:95], v[116:119], v[234:237], v[92:95]
	v_mfma_f32_16x16x32_bf16 v[88:91], v[124:127], v[234:237], v[88:91]
	v_mfma_f32_16x16x32_bf16 v[76:79], v[116:119], v[242:245], v[76:79]
	v_mfma_f32_16x16x32_bf16 v[72:75], v[124:127], v[242:245], v[72:75]
	s_setprio 0
	s_setprio 1
	v_mfma_f32_16x16x32_bf16 v[132:135], v[136:139], v[160:163], v[132:135]
	v_mfma_f32_16x16x32_bf16 v[128:131], v[152:155], v[160:163], v[128:131]
	v_mfma_f32_16x16x32_bf16 v[100:103], v[136:139], v[168:171], v[100:103]
	v_mfma_f32_16x16x32_bf16 v[96:99], v[152:155], v[168:171], v[96:99]
	v_mfma_f32_16x16x32_bf16 v[84:87], v[136:139], v[230:233], v[84:87]
	v_mfma_f32_16x16x32_bf16 v[80:83], v[152:155], v[230:233], v[80:83]
	v_mfma_f32_16x16x32_bf16 v[68:71], v[136:139], v[238:241], v[68:71]
	v_mfma_f32_16x16x32_bf16 v[64:67], v[152:155], v[238:241], v[64:67]
	v_mfma_f32_16x16x32_bf16 v[132:135], v[140:143], v[164:167], v[132:135]
	v_mfma_f32_16x16x32_bf16 v[128:131], v[156:159], v[164:167], v[128:131]
	v_mfma_f32_16x16x32_bf16 v[100:103], v[140:143], v[172:175], v[100:103]
	v_mfma_f32_16x16x32_bf16 v[96:99], v[156:159], v[172:175], v[96:99]
	v_mfma_f32_16x16x32_bf16 v[84:87], v[140:143], v[234:237], v[84:87]
	v_mfma_f32_16x16x32_bf16 v[80:83], v[156:159], v[234:237], v[80:83]
	v_mfma_f32_16x16x32_bf16 v[68:71], v[140:143], v[242:245], v[68:71]
	v_mfma_f32_16x16x32_bf16 v[64:67], v[156:159], v[242:245], v[64:67]
	s_setprio 0
	s_barrier
	s_add_i32 s10, s13, s27
	s_mov_b32 m0, s10
	ds_read_b128 v[160:163], v228 offset:49152
	ds_read_b128 v[164:167], v228 offset:50176
	ds_read_b128 v[168:171], v228 offset:51200
	ds_read_b128 v[172:175], v228 offset:52224
	ds_read_b128 v[230:233], v228 offset:53248
	ds_read_b128 v[234:237], v228 offset:54272
	ds_read_b128 v[238:241], v228 offset:55296
	ds_read_b128 v[242:245], v228 offset:56320
	s_add_u32 s98, s8, 0x80
	s_addc_u32 s99, s9, 0
	global_load_lds_dwordx4 v176, s[98:99]
	s_add_i32 m0, s10, 0x2000
	s_add_u32 s8, s8, 0x80080
	s_addc_u32 s9, s9, 0
	s_add_i32 s10, s14, s27
	s_add_u32 s98, s8, 0xfff80000
	s_addc_u32 s99, s9, -1
	global_load_lds_dwordx4 v182, s[98:99]
	s_mov_b32 m0, s10
	s_nop 0
	global_load_lds_dwordx4 v176, s[8:9]
	s_add_i32 m0, s10, 0x2000
	s_nop 0
	global_load_lds_dwordx4 v182, s[8:9]
	s_mov_b32 m0, s44
	s_nop 0
	global_load_lds_dwordx4 v178, s[50:51]
	s_mov_b32 m0, s45
	s_nop 0
	global_load_lds_dwordx4 v180, s[50:51]
	s_waitcnt vmcnt(8)
	s_waitcnt lgkmcnt(0)
	s_barrier
	s_setprio 1
	s_waitcnt lgkmcnt(0)
	v_mfma_f32_16x16x32_bf16 v[60:63], v[104:107], v[160:163], v[60:63]
	v_mfma_f32_16x16x32_bf16 v[56:59], v[120:123], v[160:163], v[56:59]
	v_mfma_f32_16x16x32_bf16 v[44:47], v[104:107], v[168:171], v[44:47]
	v_mfma_f32_16x16x32_bf16 v[40:43], v[120:123], v[168:171], v[40:43]
	v_mfma_f32_16x16x32_bf16 v[28:31], v[104:107], v[230:233], v[28:31]
	v_mfma_f32_16x16x32_bf16 v[24:27], v[120:123], v[230:233], v[24:27]
	v_mfma_f32_16x16x32_bf16 v[12:15], v[104:107], v[238:241], v[12:15]
	v_mfma_f32_16x16x32_bf16 v[8:11], v[120:123], v[238:241], v[8:11]
	v_mfma_f32_16x16x32_bf16 v[60:63], v[116:119], v[164:167], v[60:63]
	v_mfma_f32_16x16x32_bf16 v[56:59], v[124:127], v[164:167], v[56:59]
	v_mfma_f32_16x16x32_bf16 v[44:47], v[116:119], v[172:175], v[44:47]
	v_mfma_f32_16x16x32_bf16 v[40:43], v[124:127], v[172:175], v[40:43]
	v_mfma_f32_16x16x32_bf16 v[28:31], v[116:119], v[234:237], v[28:31]
	v_mfma_f32_16x16x32_bf16 v[24:27], v[124:127], v[234:237], v[24:27]
	v_mfma_f32_16x16x32_bf16 v[12:15], v[116:119], v[242:245], v[12:15]
	v_mfma_f32_16x16x32_bf16 v[8:11], v[124:127], v[242:245], v[8:11]
	s_setprio 0
	s_setprio 1
	v_mfma_f32_16x16x32_bf16 v[52:55], v[136:139], v[160:163], v[52:55]
	v_mfma_f32_16x16x32_bf16 v[48:51], v[152:155], v[160:163], v[48:51]
	v_mfma_f32_16x16x32_bf16 v[36:39], v[136:139], v[168:171], v[36:39]
	v_mfma_f32_16x16x32_bf16 v[32:35], v[152:155], v[168:171], v[32:35]
	v_mfma_f32_16x16x32_bf16 v[20:23], v[136:139], v[230:233], v[20:23]
	v_mfma_f32_16x16x32_bf16 v[16:19], v[152:155], v[230:233], v[16:19]
	v_mfma_f32_16x16x32_bf16 v[4:7], v[136:139], v[238:241], v[4:7]
	v_mfma_f32_16x16x32_bf16 v[0:3], v[152:155], v[238:241], v[0:3]
	v_mfma_f32_16x16x32_bf16 v[52:55], v[140:143], v[164:167], v[52:55]
	v_mfma_f32_16x16x32_bf16 v[48:51], v[156:159], v[164:167], v[48:51]
	v_mfma_f32_16x16x32_bf16 v[36:39], v[140:143], v[172:175], v[36:39]
	v_mfma_f32_16x16x32_bf16 v[32:35], v[156:159], v[172:175], v[32:35]
	v_mfma_f32_16x16x32_bf16 v[20:23], v[140:143], v[234:237], v[20:23]
	v_mfma_f32_16x16x32_bf16 v[16:19], v[156:159], v[234:237], v[16:19]
	v_mfma_f32_16x16x32_bf16 v[4:7], v[140:143], v[242:245], v[4:7]
	v_mfma_f32_16x16x32_bf16 v[0:3], v[156:159], v[242:245], v[0:3]
	s_setprio 0
	s_barrier
	s_add_i32 s12, s12, 2
	s_add_u32 s6, s6, 0x100
	s_addc_u32 s7, s7, 0
	s_add_u32 s1, s1, 0x100
	s_addc_u32 s3, s3, 0
	s_cmp_gt_u32 s12, 29
.LBB0_830:
	s_add_u32 s8, s6, 0xfff80080
	s_addc_u32 s9, s7, -1
	s_add_i32 s13, 0, 0x10000
	s_cmp_eq_u32 s12, 28
	s_cselect_b32 s11, s31, s9
	s_cselect_b32 s10, s30, s8
	s_cselect_b32 s9, s19, s3
	s_cselect_b32 s8, s18, s1
	s_add_i32 s20, 0, 0x14000
	ds_read_b128 v[104:107], v253
	ds_read_b128 v[116:119], v253 offset:1024
	ds_read_b128 v[120:123], v253 offset:2048
	ds_read_b128 v[124:127], v253 offset:3072
	ds_read_b128 v[136:139], v253 offset:16384
	ds_read_b128 v[140:143], v253 offset:17408
	ds_read_b128 v[152:155], v253 offset:18432
	ds_read_b128 v[156:159], v253 offset:19456
	s_add_i32 m0, s28, 0xc000
	ds_read_b128 v[160:163], v228
	ds_read_b128 v[164:167], v228 offset:1024
	ds_read_b128 v[168:171], v228 offset:2048
	ds_read_b128 v[172:175], v228 offset:3072
	ds_read_b128 v[230:233], v228 offset:4096
	ds_read_b128 v[234:237], v228 offset:5120
	ds_read_b128 v[238:241], v228 offset:6144
	ds_read_b128 v[242:245], v228 offset:7168
	global_load_lds_dwordx4 v202, s[6:7]
	s_add_i32 m0, s28, 0xe000
	s_nop 0
	global_load_lds_dwordx4 v204, s[6:7]
	s_waitcnt vmcnt(8)
	s_waitcnt lgkmcnt(0)
	s_barrier
	s_setprio 1
	s_waitcnt lgkmcnt(0)
	v_mfma_f32_16x16x32_bf16 v[148:151], v[104:107], v[160:163], v[148:151]
	v_mfma_f32_16x16x32_bf16 v[144:147], v[120:123], v[160:163], v[144:147]
	v_mfma_f32_16x16x32_bf16 v[112:115], v[104:107], v[168:171], v[112:115]
	v_mfma_f32_16x16x32_bf16 v[108:111], v[120:123], v[168:171], v[108:111]
	v_mfma_f32_16x16x32_bf16 v[92:95], v[104:107], v[230:233], v[92:95]
	v_mfma_f32_16x16x32_bf16 v[88:91], v[120:123], v[230:233], v[88:91]
	v_mfma_f32_16x16x32_bf16 v[76:79], v[104:107], v[238:241], v[76:79]
	v_mfma_f32_16x16x32_bf16 v[72:75], v[120:123], v[238:241], v[72:75]
	v_mfma_f32_16x16x32_bf16 v[148:151], v[116:119], v[164:167], v[148:151]
	v_mfma_f32_16x16x32_bf16 v[144:147], v[124:127], v[164:167], v[144:147]
	v_mfma_f32_16x16x32_bf16 v[112:115], v[116:119], v[172:175], v[112:115]
	v_mfma_f32_16x16x32_bf16 v[108:111], v[124:127], v[172:175], v[108:111]
	v_mfma_f32_16x16x32_bf16 v[92:95], v[116:119], v[234:237], v[92:95]
	v_mfma_f32_16x16x32_bf16 v[88:91], v[124:127], v[234:237], v[88:91]
	v_mfma_f32_16x16x32_bf16 v[76:79], v[116:119], v[242:245], v[76:79]
	v_mfma_f32_16x16x32_bf16 v[72:75], v[124:127], v[242:245], v[72:75]
	s_setprio 0
	s_setprio 1
	v_mfma_f32_16x16x32_bf16 v[132:135], v[136:139], v[160:163], v[132:135]
	v_mfma_f32_16x16x32_bf16 v[128:131], v[152:155], v[160:163], v[128:131]
	v_mfma_f32_16x16x32_bf16 v[100:103], v[136:139], v[168:171], v[100:103]
	v_mfma_f32_16x16x32_bf16 v[96:99], v[152:155], v[168:171], v[96:99]
	v_mfma_f32_16x16x32_bf16 v[84:87], v[136:139], v[230:233], v[84:87]
	v_mfma_f32_16x16x32_bf16 v[80:83], v[152:155], v[230:233], v[80:83]
	v_mfma_f32_16x16x32_bf16 v[68:71], v[136:139], v[238:241], v[68:71]
	v_mfma_f32_16x16x32_bf16 v[64:67], v[152:155], v[238:241], v[64:67]
	v_mfma_f32_16x16x32_bf16 v[132:135], v[140:143], v[164:167], v[132:135]
	v_mfma_f32_16x16x32_bf16 v[128:131], v[156:159], v[164:167], v[128:131]
	v_mfma_f32_16x16x32_bf16 v[100:103], v[140:143], v[172:175], v[100:103]
	v_mfma_f32_16x16x32_bf16 v[96:99], v[156:159], v[172:175], v[96:99]
	v_mfma_f32_16x16x32_bf16 v[84:87], v[140:143], v[234:237], v[84:87]
	v_mfma_f32_16x16x32_bf16 v[80:83], v[156:159], v[234:237], v[80:83]
	v_mfma_f32_16x16x32_bf16 v[68:71], v[140:143], v[242:245], v[68:71]
	v_mfma_f32_16x16x32_bf16 v[64:67], v[156:159], v[242:245], v[64:67]
	s_setprio 0
	s_barrier
	s_add_i32 s13, s13, s27
	s_mov_b32 m0, s13
	ds_read_b128 v[160:163], v228 offset:16384
	ds_read_b128 v[164:167], v228 offset:17408
	ds_read_b128 v[168:171], v228 offset:18432
	ds_read_b128 v[172:175], v228 offset:19456
	ds_read_b128 v[230:233], v228 offset:20480
	ds_read_b128 v[234:237], v228 offset:21504
	ds_read_b128 v[238:241], v228 offset:22528
	ds_read_b128 v[242:245], v228 offset:23552
	global_load_lds_dwordx4 v176, s[8:9]
	s_add_i32 m0, s13, 0x2000
	s_add_u32 s14, s8, 0x80000
	s_addc_u32 s15, s9, 0
	s_add_i32 s13, s20, s27
	global_load_lds_dwordx4 v182, s[8:9]
	s_mov_b32 m0, s13
	s_nop 0
	global_load_lds_dwordx4 v176, s[14:15]
	s_add_i32 m0, s13, 0x2000
	s_nop 0
	global_load_lds_dwordx4 v182, s[14:15]
	s_add_u32 s50, s10, 0x80
	s_addc_u32 s51, s11, 0
	s_mov_b32 m0, s28
	s_nop 0
	global_load_lds_dwordx4 v178, s[10:11]
	s_mov_b32 m0, s29
	s_nop 0
	global_load_lds_dwordx4 v180, s[10:11]
	s_waitcnt vmcnt(8)
	s_waitcnt lgkmcnt(0)
	s_barrier
	s_setprio 1
	s_waitcnt lgkmcnt(0)
	v_mfma_f32_16x16x32_bf16 v[60:63], v[104:107], v[160:163], v[60:63]
	v_mfma_f32_16x16x32_bf16 v[56:59], v[120:123], v[160:163], v[56:59]
	v_mfma_f32_16x16x32_bf16 v[44:47], v[104:107], v[168:171], v[44:47]
	v_mfma_f32_16x16x32_bf16 v[40:43], v[120:123], v[168:171], v[40:43]
	v_mfma_f32_16x16x32_bf16 v[28:31], v[104:107], v[230:233], v[28:31]
	v_mfma_f32_16x16x32_bf16 v[24:27], v[120:123], v[230:233], v[24:27]
	v_mfma_f32_16x16x32_bf16 v[12:15], v[104:107], v[238:241], v[12:15]
	v_mfma_f32_16x16x32_bf16 v[8:11], v[120:123], v[238:241], v[8:11]
	v_mfma_f32_16x16x32_bf16 v[60:63], v[116:119], v[164:167], v[60:63]
	v_mfma_f32_16x16x32_bf16 v[56:59], v[124:127], v[164:167], v[56:59]
	v_mfma_f32_16x16x32_bf16 v[44:47], v[116:119], v[172:175], v[44:47]
	v_mfma_f32_16x16x32_bf16 v[40:43], v[124:127], v[172:175], v[40:43]
	v_mfma_f32_16x16x32_bf16 v[28:31], v[116:119], v[234:237], v[28:31]
	v_mfma_f32_16x16x32_bf16 v[24:27], v[124:127], v[234:237], v[24:27]
	v_mfma_f32_16x16x32_bf16 v[12:15], v[116:119], v[242:245], v[12:15]
	v_mfma_f32_16x16x32_bf16 v[8:11], v[124:127], v[242:245], v[8:11]
	s_setprio 0
	s_setprio 1
	v_mfma_f32_16x16x32_bf16 v[52:55], v[136:139], v[160:163], v[52:55]
	v_mfma_f32_16x16x32_bf16 v[48:51], v[152:155], v[160:163], v[48:51]
	v_mfma_f32_16x16x32_bf16 v[36:39], v[136:139], v[168:171], v[36:39]
	v_mfma_f32_16x16x32_bf16 v[32:35], v[152:155], v[168:171], v[32:35]
	v_mfma_f32_16x16x32_bf16 v[20:23], v[136:139], v[230:233], v[20:23]
	v_mfma_f32_16x16x32_bf16 v[16:19], v[152:155], v[230:233], v[16:19]
	v_mfma_f32_16x16x32_bf16 v[4:7], v[136:139], v[238:241], v[4:7]
	v_mfma_f32_16x16x32_bf16 v[0:3], v[152:155], v[238:241], v[0:3]
	v_mfma_f32_16x16x32_bf16 v[52:55], v[140:143], v[164:167], v[52:55]
	v_mfma_f32_16x16x32_bf16 v[48:51], v[156:159], v[164:167], v[48:51]
	v_mfma_f32_16x16x32_bf16 v[36:39], v[140:143], v[172:175], v[36:39]
	v_mfma_f32_16x16x32_bf16 v[32:35], v[156:159], v[172:175], v[32:35]
	v_mfma_f32_16x16x32_bf16 v[20:23], v[140:143], v[234:237], v[20:23]
	v_mfma_f32_16x16x32_bf16 v[16:19], v[156:159], v[234:237], v[16:19]
	v_mfma_f32_16x16x32_bf16 v[4:7], v[140:143], v[242:245], v[4:7]
	v_mfma_f32_16x16x32_bf16 v[0:3], v[156:159], v[242:245], v[0:3]
	s_setprio 0
	s_barrier
	s_add_i32 s13, 0, 0x18000
	s_add_i32 s14, 0, 0x1c000
	ds_read_b128 v[104:107], v253 offset:32768
	ds_read_b128 v[116:119], v253 offset:33792
	ds_read_b128 v[120:123], v253 offset:34816
	ds_read_b128 v[124:127], v253 offset:35840
	ds_read_b128 v[136:139], v253 offset:49152
	ds_read_b128 v[140:143], v253 offset:50176
	ds_read_b128 v[152:155], v253 offset:51200
	ds_read_b128 v[156:159], v253 offset:52224
	s_add_u32 s10, s10, 0x80000
	s_addc_u32 s11, s11, 0
	s_mov_b32 m0, s38
	ds_read_b128 v[160:163], v228 offset:32768
	ds_read_b128 v[164:167], v228 offset:33792
	ds_read_b128 v[168:171], v228 offset:34816
	ds_read_b128 v[172:175], v228 offset:35840
	ds_read_b128 v[230:233], v228 offset:36864
	ds_read_b128 v[234:237], v228 offset:37888
	ds_read_b128 v[238:241], v228 offset:38912
	ds_read_b128 v[242:245], v228 offset:39936
	global_load_lds_dwordx4 v178, s[10:11]
	s_mov_b32 m0, s39
	s_nop 0
	global_load_lds_dwordx4 v180, s[10:11]
	s_waitcnt vmcnt(8)
	s_waitcnt lgkmcnt(0)
	s_barrier
	s_setprio 1
	s_waitcnt lgkmcnt(0)
	v_mfma_f32_16x16x32_bf16 v[148:151], v[104:107], v[160:163], v[148:151]
	v_mfma_f32_16x16x32_bf16 v[144:147], v[120:123], v[160:163], v[144:147]
	v_mfma_f32_16x16x32_bf16 v[112:115], v[104:107], v[168:171], v[112:115]
	v_mfma_f32_16x16x32_bf16 v[108:111], v[120:123], v[168:171], v[108:111]
	v_mfma_f32_16x16x32_bf16 v[92:95], v[104:107], v[230:233], v[92:95]
	v_mfma_f32_16x16x32_bf16 v[88:91], v[120:123], v[230:233], v[88:91]
	v_mfma_f32_16x16x32_bf16 v[76:79], v[104:107], v[238:241], v[76:79]
	v_mfma_f32_16x16x32_bf16 v[72:75], v[120:123], v[238:241], v[72:75]
	v_mfma_f32_16x16x32_bf16 v[148:151], v[116:119], v[164:167], v[148:151]
	v_mfma_f32_16x16x32_bf16 v[144:147], v[124:127], v[164:167], v[144:147]
	v_mfma_f32_16x16x32_bf16 v[112:115], v[116:119], v[172:175], v[112:115]
	v_mfma_f32_16x16x32_bf16 v[108:111], v[124:127], v[172:175], v[108:111]
	v_mfma_f32_16x16x32_bf16 v[92:95], v[116:119], v[234:237], v[92:95]
	v_mfma_f32_16x16x32_bf16 v[88:91], v[124:127], v[234:237], v[88:91]
	v_mfma_f32_16x16x32_bf16 v[76:79], v[116:119], v[242:245], v[76:79]
	v_mfma_f32_16x16x32_bf16 v[72:75], v[124:127], v[242:245], v[72:75]
	s_setprio 0
	s_setprio 1
	v_mfma_f32_16x16x32_bf16 v[132:135], v[136:139], v[160:163], v[132:135]
	v_mfma_f32_16x16x32_bf16 v[128:131], v[152:155], v[160:163], v[128:131]
	v_mfma_f32_16x16x32_bf16 v[100:103], v[136:139], v[168:171], v[100:103]
	v_mfma_f32_16x16x32_bf16 v[96:99], v[152:155], v[168:171], v[96:99]
	v_mfma_f32_16x16x32_bf16 v[84:87], v[136:139], v[230:233], v[84:87]
	v_mfma_f32_16x16x32_bf16 v[80:83], v[152:155], v[230:233], v[80:83]
	v_mfma_f32_16x16x32_bf16 v[68:71], v[136:139], v[238:241], v[68:71]
	v_mfma_f32_16x16x32_bf16 v[64:67], v[152:155], v[238:241], v[64:67]
	v_mfma_f32_16x16x32_bf16 v[132:135], v[140:143], v[164:167], v[132:135]
	v_mfma_f32_16x16x32_bf16 v[128:131], v[156:159], v[164:167], v[128:131]
	v_mfma_f32_16x16x32_bf16 v[100:103], v[140:143], v[172:175], v[100:103]
	v_mfma_f32_16x16x32_bf16 v[96:99], v[156:159], v[172:175], v[96:99]
	v_mfma_f32_16x16x32_bf16 v[84:87], v[140:143], v[234:237], v[84:87]
	v_mfma_f32_16x16x32_bf16 v[80:83], v[156:159], v[234:237], v[80:83]
	v_mfma_f32_16x16x32_bf16 v[68:71], v[140:143], v[242:245], v[68:71]
	v_mfma_f32_16x16x32_bf16 v[64:67], v[156:159], v[242:245], v[64:67]
	s_setprio 0
	s_barrier
	s_add_i32 s10, s13, s27
	s_mov_b32 m0, s10
	ds_read_b128 v[160:163], v228 offset:49152
	ds_read_b128 v[164:167], v228 offset:50176
	ds_read_b128 v[168:171], v228 offset:51200
	ds_read_b128 v[172:175], v228 offset:52224
	ds_read_b128 v[230:233], v228 offset:53248
	ds_read_b128 v[234:237], v228 offset:54272
	ds_read_b128 v[238:241], v228 offset:55296
	ds_read_b128 v[242:245], v228 offset:56320
	s_add_u32 s98, s8, 0x80
	s_addc_u32 s99, s9, 0
	global_load_lds_dwordx4 v176, s[98:99]
	s_add_i32 m0, s10, 0x2000
	s_add_u32 s8, s8, 0x80080
	s_addc_u32 s9, s9, 0
	s_add_i32 s10, s14, s27
	s_add_u32 s98, s8, 0xfff80000
	s_addc_u32 s99, s9, -1
	global_load_lds_dwordx4 v182, s[98:99]
	s_mov_b32 m0, s10
	s_nop 0
	global_load_lds_dwordx4 v176, s[8:9]
	s_add_i32 m0, s10, 0x2000
	s_nop 0
	global_load_lds_dwordx4 v182, s[8:9]
	s_mov_b32 m0, s44
	s_nop 0
	global_load_lds_dwordx4 v178, s[50:51]
	s_mov_b32 m0, s45
	s_nop 0
	global_load_lds_dwordx4 v180, s[50:51]
	s_waitcnt vmcnt(8)
	s_waitcnt lgkmcnt(0)
	s_barrier
	s_setprio 1
	s_waitcnt lgkmcnt(0)
	v_mfma_f32_16x16x32_bf16 v[60:63], v[104:107], v[160:163], v[60:63]
	v_mfma_f32_16x16x32_bf16 v[56:59], v[120:123], v[160:163], v[56:59]
	v_mfma_f32_16x16x32_bf16 v[44:47], v[104:107], v[168:171], v[44:47]
	v_mfma_f32_16x16x32_bf16 v[40:43], v[120:123], v[168:171], v[40:43]
	v_mfma_f32_16x16x32_bf16 v[28:31], v[104:107], v[230:233], v[28:31]
	v_mfma_f32_16x16x32_bf16 v[24:27], v[120:123], v[230:233], v[24:27]
	v_mfma_f32_16x16x32_bf16 v[12:15], v[104:107], v[238:241], v[12:15]
	v_mfma_f32_16x16x32_bf16 v[8:11], v[120:123], v[238:241], v[8:11]
	v_mfma_f32_16x16x32_bf16 v[60:63], v[116:119], v[164:167], v[60:63]
	v_mfma_f32_16x16x32_bf16 v[56:59], v[124:127], v[164:167], v[56:59]
	v_mfma_f32_16x16x32_bf16 v[44:47], v[116:119], v[172:175], v[44:47]
	v_mfma_f32_16x16x32_bf16 v[40:43], v[124:127], v[172:175], v[40:43]
	v_mfma_f32_16x16x32_bf16 v[28:31], v[116:119], v[234:237], v[28:31]
	v_mfma_f32_16x16x32_bf16 v[24:27], v[124:127], v[234:237], v[24:27]
	v_mfma_f32_16x16x32_bf16 v[12:15], v[116:119], v[242:245], v[12:15]
	v_mfma_f32_16x16x32_bf16 v[8:11], v[124:127], v[242:245], v[8:11]
	s_setprio 0
	s_setprio 1
	v_mfma_f32_16x16x32_bf16 v[52:55], v[136:139], v[160:163], v[52:55]
	v_mfma_f32_16x16x32_bf16 v[48:51], v[152:155], v[160:163], v[48:51]
	v_mfma_f32_16x16x32_bf16 v[36:39], v[136:139], v[168:171], v[36:39]
	v_mfma_f32_16x16x32_bf16 v[32:35], v[152:155], v[168:171], v[32:35]
	v_mfma_f32_16x16x32_bf16 v[20:23], v[136:139], v[230:233], v[20:23]
	v_mfma_f32_16x16x32_bf16 v[16:19], v[152:155], v[230:233], v[16:19]
	v_mfma_f32_16x16x32_bf16 v[4:7], v[136:139], v[238:241], v[4:7]
	v_mfma_f32_16x16x32_bf16 v[0:3], v[152:155], v[238:241], v[0:3]
	v_mfma_f32_16x16x32_bf16 v[52:55], v[140:143], v[164:167], v[52:55]
	v_mfma_f32_16x16x32_bf16 v[48:51], v[156:159], v[164:167], v[48:51]
	v_mfma_f32_16x16x32_bf16 v[36:39], v[140:143], v[172:175], v[36:39]
	v_mfma_f32_16x16x32_bf16 v[32:35], v[156:159], v[172:175], v[32:35]
	v_mfma_f32_16x16x32_bf16 v[20:23], v[140:143], v[234:237], v[20:23]
	v_mfma_f32_16x16x32_bf16 v[16:19], v[156:159], v[234:237], v[16:19]
	v_mfma_f32_16x16x32_bf16 v[4:7], v[140:143], v[242:245], v[4:7]
	v_mfma_f32_16x16x32_bf16 v[0:3], v[156:159], v[242:245], v[0:3]
	s_setprio 0
	s_barrier
	s_add_i32 s12, s12, 2
	s_add_u32 s6, s6, 0x100
	s_addc_u32 s7, s7, 0
	s_add_u32 s1, s1, 0x100
	s_addc_u32 s3, s3, 0
	s_cmp_gt_u32 s12, 29
	s_cbranch_scc0 .LBB0_830
	s_and_b64 vcc, exec, s[52:53]
	s_cbranch_vccz .LBB0_833
	s_barrier

.Lf1g_rss_skip:
	v_add_u32_e32 v253, 0x10000, v143
	s_add_u32 s30, s4, 0xfff80080
	s_addc_u32 s31, s5, -1
	s_add_i32 s53, 0, 0x10000
	s_cmp_eq_u32 s52, 28
	s_cselect_b32 s35, s17, s31
	s_cselect_b32 s34, s25, s30
	s_cselect_b32 s31, s15, s51
	s_cselect_b32 s30, s36, s37
	s_add_i32 s56, 0, 0x14000
	ds_read_b128 v[148:151], v253
	ds_read_b128 v[152:155], v253 offset:1024
	ds_read_b128 v[156:159], v253 offset:2048
	ds_read_b128 v[160:163], v253 offset:3072
	ds_read_b128 v[164:167], v253 offset:16384
	ds_read_b128 v[168:171], v253 offset:17408
	ds_read_b128 v[172:175], v253 offset:18432
	ds_read_b128 v[178:181], v253 offset:19456
	s_add_i32 m0, s19, 0xc000
	ds_read_b128 v[182:185], v147
	ds_read_b128 v[186:189], v147 offset:1024
	ds_read_b128 v[190:193], v147 offset:2048
	ds_read_b128 v[194:197], v147 offset:3072
	ds_read_b128 v[198:201], v147 offset:4096
	ds_read_b128 v[202:205], v147 offset:5120
	ds_read_b128 v[206:209], v147 offset:6144
	ds_read_b128 v[220:223], v147 offset:7168
	global_load_lds_dwordx4 v138, s[4:5]
	s_add_i32 m0, s19, 0xe000
	s_nop 0
	global_load_lds_dwordx4 v140, s[4:5]
	s_waitcnt vmcnt(8)
	s_waitcnt lgkmcnt(0)
	s_barrier
	s_setprio 1
	s_waitcnt lgkmcnt(0)
	v_mfma_f32_16x16x32_bf16 v[124:127], v[148:151], v[182:185], 0
	v_mfma_f32_16x16x32_bf16 v[120:123], v[156:159], v[182:185], 0
	v_mfma_f32_16x16x32_bf16 v[108:111], v[148:151], v[190:193], 0
	v_mfma_f32_16x16x32_bf16 v[104:107], v[156:159], v[190:193], 0
	v_mfma_f32_16x16x32_bf16 v[92:95], v[148:151], v[198:201], 0
	v_mfma_f32_16x16x32_bf16 v[88:91], v[156:159], v[198:201], 0
	v_mfma_f32_16x16x32_bf16 v[76:79], v[148:151], v[206:209], 0
	v_mfma_f32_16x16x32_bf16 v[72:75], v[156:159], v[206:209], 0
	v_mfma_f32_16x16x32_bf16 v[124:127], v[152:155], v[186:189], v[124:127]
	v_mfma_f32_16x16x32_bf16 v[120:123], v[160:163], v[186:189], v[120:123]
	v_mfma_f32_16x16x32_bf16 v[108:111], v[152:155], v[194:197], v[108:111]
	v_mfma_f32_16x16x32_bf16 v[104:107], v[160:163], v[194:197], v[104:107]
	v_mfma_f32_16x16x32_bf16 v[92:95], v[152:155], v[202:205], v[92:95]
	v_mfma_f32_16x16x32_bf16 v[88:91], v[160:163], v[202:205], v[88:91]
	v_mfma_f32_16x16x32_bf16 v[76:79], v[152:155], v[220:223], v[76:79]
	v_mfma_f32_16x16x32_bf16 v[72:75], v[160:163], v[220:223], v[72:75]
	s_setprio 0
	s_setprio 1
	v_mfma_f32_16x16x32_bf16 v[116:119], v[164:167], v[182:185], 0
	v_mfma_f32_16x16x32_bf16 v[112:115], v[172:175], v[182:185], 0
	v_mfma_f32_16x16x32_bf16 v[100:103], v[164:167], v[190:193], 0
	v_mfma_f32_16x16x32_bf16 v[96:99], v[172:175], v[190:193], 0
	v_mfma_f32_16x16x32_bf16 v[84:87], v[164:167], v[198:201], 0
	v_mfma_f32_16x16x32_bf16 v[80:83], v[172:175], v[198:201], 0
	v_mfma_f32_16x16x32_bf16 v[68:71], v[164:167], v[206:209], 0
	v_mfma_f32_16x16x32_bf16 v[64:67], v[172:175], v[206:209], 0
	v_mfma_f32_16x16x32_bf16 v[116:119], v[168:171], v[186:189], v[116:119]
	v_mfma_f32_16x16x32_bf16 v[112:115], v[178:181], v[186:189], v[112:115]
	v_mfma_f32_16x16x32_bf16 v[100:103], v[168:171], v[194:197], v[100:103]
	v_mfma_f32_16x16x32_bf16 v[96:99], v[178:181], v[194:197], v[96:99]
	v_mfma_f32_16x16x32_bf16 v[84:87], v[168:171], v[202:205], v[84:87]
	v_mfma_f32_16x16x32_bf16 v[80:83], v[178:181], v[202:205], v[80:83]
	v_mfma_f32_16x16x32_bf16 v[68:71], v[168:171], v[220:223], v[68:71]
	v_mfma_f32_16x16x32_bf16 v[64:67], v[178:181], v[220:223], v[64:67]
	s_setprio 0
	s_barrier
	s_add_i32 s53, s53, s26
	s_mov_b32 m0, s53
	ds_read_b128 v[182:185], v147 offset:16384
	ds_read_b128 v[186:189], v147 offset:17408
	ds_read_b128 v[190:193], v147 offset:18432
	ds_read_b128 v[194:197], v147 offset:19456
	ds_read_b128 v[198:201], v147 offset:20480
	ds_read_b128 v[202:205], v147 offset:21504
	ds_read_b128 v[206:209], v147 offset:22528
	ds_read_b128 v[220:223], v147 offset:23552
	global_load_lds_dwordx4 v130, s[30:31]
	s_add_i32 m0, s53, 0x2000
	s_add_u32 s54, s30, 0x80000
	s_addc_u32 s55, s31, 0
	s_add_i32 s53, s56, s26
	global_load_lds_dwordx4 v134, s[30:31]
	s_mov_b32 m0, s53
	s_nop 0
	global_load_lds_dwordx4 v130, s[54:55]
	s_add_i32 m0, s53, 0x2000
	s_nop 0
	global_load_lds_dwordx4 v134, s[54:55]
	s_add_u32 s60, s34, 0x80
	s_addc_u32 s61, s35, 0
	s_mov_b32 m0, s19
	s_nop 0
	global_load_lds_dwordx4 v128, s[34:35]
	s_mov_b32 m0, s38
	s_nop 0
	global_load_lds_dwordx4 v132, s[34:35]
	s_waitcnt vmcnt(8)
	s_waitcnt lgkmcnt(0)
	s_barrier
	s_setprio 1
	s_waitcnt lgkmcnt(0)
	v_mfma_f32_16x16x32_bf16 v[60:63], v[148:151], v[182:185], 0
	v_mfma_f32_16x16x32_bf16 v[56:59], v[156:159], v[182:185], 0
	v_mfma_f32_16x16x32_bf16 v[44:47], v[148:151], v[190:193], 0
	v_mfma_f32_16x16x32_bf16 v[40:43], v[156:159], v[190:193], 0
	v_mfma_f32_16x16x32_bf16 v[28:31], v[148:151], v[198:201], 0
	v_mfma_f32_16x16x32_bf16 v[24:27], v[156:159], v[198:201], 0
	v_mfma_f32_16x16x32_bf16 v[12:15], v[148:151], v[206:209], 0
	v_mfma_f32_16x16x32_bf16 v[8:11], v[156:159], v[206:209], 0
	v_mfma_f32_16x16x32_bf16 v[60:63], v[152:155], v[186:189], v[60:63]
	v_mfma_f32_16x16x32_bf16 v[56:59], v[160:163], v[186:189], v[56:59]
	v_mfma_f32_16x16x32_bf16 v[44:47], v[152:155], v[194:197], v[44:47]
	v_mfma_f32_16x16x32_bf16 v[40:43], v[160:163], v[194:197], v[40:43]
	v_mfma_f32_16x16x32_bf16 v[28:31], v[152:155], v[202:205], v[28:31]
	v_mfma_f32_16x16x32_bf16 v[24:27], v[160:163], v[202:205], v[24:27]
	v_mfma_f32_16x16x32_bf16 v[12:15], v[152:155], v[220:223], v[12:15]
	v_mfma_f32_16x16x32_bf16 v[8:11], v[160:163], v[220:223], v[8:11]
	s_setprio 0
	s_setprio 1
	v_mfma_f32_16x16x32_bf16 v[52:55], v[164:167], v[182:185], 0
	v_mfma_f32_16x16x32_bf16 v[48:51], v[172:175], v[182:185], 0
	v_mfma_f32_16x16x32_bf16 v[36:39], v[164:167], v[190:193], 0
	v_mfma_f32_16x16x32_bf16 v[32:35], v[172:175], v[190:193], 0
	v_mfma_f32_16x16x32_bf16 v[20:23], v[164:167], v[198:201], 0
	v_mfma_f32_16x16x32_bf16 v[16:19], v[172:175], v[198:201], 0
	v_mfma_f32_16x16x32_bf16 v[4:7], v[164:167], v[206:209], 0
	v_mfma_f32_16x16x32_bf16 v[0:3], v[172:175], v[206:209], 0
	v_mfma_f32_16x16x32_bf16 v[52:55], v[168:171], v[186:189], v[52:55]
	v_mfma_f32_16x16x32_bf16 v[48:51], v[178:181], v[186:189], v[48:51]
	v_mfma_f32_16x16x32_bf16 v[36:39], v[168:171], v[194:197], v[36:39]
	v_mfma_f32_16x16x32_bf16 v[32:35], v[178:181], v[194:197], v[32:35]
	v_mfma_f32_16x16x32_bf16 v[20:23], v[168:171], v[202:205], v[20:23]
	v_mfma_f32_16x16x32_bf16 v[16:19], v[178:181], v[202:205], v[16:19]
	v_mfma_f32_16x16x32_bf16 v[4:7], v[168:171], v[220:223], v[4:7]
	v_mfma_f32_16x16x32_bf16 v[0:3], v[178:181], v[220:223], v[0:3]
	s_setprio 0
	s_barrier
	s_add_i32 s53, 0, 0x18000
	s_add_i32 s54, 0, 0x1c000
	ds_read_b128 v[148:151], v253 offset:32768
	ds_read_b128 v[152:155], v253 offset:33792
	ds_read_b128 v[156:159], v253 offset:34816
	ds_read_b128 v[160:163], v253 offset:35840
	ds_read_b128 v[164:167], v253 offset:49152
	ds_read_b128 v[168:171], v253 offset:50176
	ds_read_b128 v[172:175], v253 offset:51200
	ds_read_b128 v[178:181], v253 offset:52224
	s_add_u32 s34, s34, 0x80000
	s_addc_u32 s35, s35, 0
	s_mov_b32 m0, s39
	ds_read_b128 v[182:185], v147 offset:32768
	ds_read_b128 v[186:189], v147 offset:33792
	ds_read_b128 v[190:193], v147 offset:34816
	ds_read_b128 v[194:197], v147 offset:35840
	ds_read_b128 v[198:201], v147 offset:36864
	ds_read_b128 v[202:205], v147 offset:37888
	ds_read_b128 v[206:209], v147 offset:38912
	ds_read_b128 v[220:223], v147 offset:39936
	global_load_lds_dwordx4 v128, s[34:35]
	s_mov_b32 m0, s40
	s_nop 0
	global_load_lds_dwordx4 v132, s[34:35]
	s_waitcnt vmcnt(8)
	s_waitcnt lgkmcnt(0)
	s_barrier
	s_setprio 1
	s_waitcnt lgkmcnt(0)
	v_mfma_f32_16x16x32_bf16 v[124:127], v[148:151], v[182:185], v[124:127]
	v_mfma_f32_16x16x32_bf16 v[120:123], v[156:159], v[182:185], v[120:123]
	v_mfma_f32_16x16x32_bf16 v[108:111], v[148:151], v[190:193], v[108:111]
	v_mfma_f32_16x16x32_bf16 v[104:107], v[156:159], v[190:193], v[104:107]
	v_mfma_f32_16x16x32_bf16 v[92:95], v[148:151], v[198:201], v[92:95]
	v_mfma_f32_16x16x32_bf16 v[88:91], v[156:159], v[198:201], v[88:91]
	v_mfma_f32_16x16x32_bf16 v[76:79], v[148:151], v[206:209], v[76:79]
	v_mfma_f32_16x16x32_bf16 v[72:75], v[156:159], v[206:209], v[72:75]
	v_mfma_f32_16x16x32_bf16 v[124:127], v[152:155], v[186:189], v[124:127]
	v_mfma_f32_16x16x32_bf16 v[120:123], v[160:163], v[186:189], v[120:123]
	v_mfma_f32_16x16x32_bf16 v[108:111], v[152:155], v[194:197], v[108:111]
	v_mfma_f32_16x16x32_bf16 v[104:107], v[160:163], v[194:197], v[104:107]
	v_mfma_f32_16x16x32_bf16 v[92:95], v[152:155], v[202:205], v[92:95]
	v_mfma_f32_16x16x32_bf16 v[88:91], v[160:163], v[202:205], v[88:91]
	v_mfma_f32_16x16x32_bf16 v[76:79], v[152:155], v[220:223], v[76:79]
	v_mfma_f32_16x16x32_bf16 v[72:75], v[160:163], v[220:223], v[72:75]
	s_setprio 0
	s_setprio 1
	v_mfma_f32_16x16x32_bf16 v[116:119], v[164:167], v[182:185], v[116:119]
	v_mfma_f32_16x16x32_bf16 v[112:115], v[172:175], v[182:185], v[112:115]
	v_mfma_f32_16x16x32_bf16 v[100:103], v[164:167], v[190:193], v[100:103]
	v_mfma_f32_16x16x32_bf16 v[96:99], v[172:175], v[190:193], v[96:99]
	v_mfma_f32_16x16x32_bf16 v[84:87], v[164:167], v[198:201], v[84:87]
	v_mfma_f32_16x16x32_bf16 v[80:83], v[172:175], v[198:201], v[80:83]
	v_mfma_f32_16x16x32_bf16 v[68:71], v[164:167], v[206:209], v[68:71]
	v_mfma_f32_16x16x32_bf16 v[64:67], v[172:175], v[206:209], v[64:67]
	v_mfma_f32_16x16x32_bf16 v[116:119], v[168:171], v[186:189], v[116:119]
	v_mfma_f32_16x16x32_bf16 v[112:115], v[178:181], v[186:189], v[112:115]
	v_mfma_f32_16x16x32_bf16 v[100:103], v[168:171], v[194:197], v[100:103]
	v_mfma_f32_16x16x32_bf16 v[96:99], v[178:181], v[194:197], v[96:99]
	v_mfma_f32_16x16x32_bf16 v[84:87], v[168:171], v[202:205], v[84:87]
	v_mfma_f32_16x16x32_bf16 v[80:83], v[178:181], v[202:205], v[80:83]
	v_mfma_f32_16x16x32_bf16 v[68:71], v[168:171], v[220:223], v[68:71]
	v_mfma_f32_16x16x32_bf16 v[64:67], v[178:181], v[220:223], v[64:67]
	s_setprio 0
	s_barrier
	s_add_i32 s34, s53, s26
	s_mov_b32 m0, s34
	ds_read_b128 v[182:185], v147 offset:49152
	ds_read_b128 v[186:189], v147 offset:50176
	ds_read_b128 v[190:193], v147 offset:51200
	ds_read_b128 v[194:197], v147 offset:52224
	ds_read_b128 v[198:201], v147 offset:53248
	ds_read_b128 v[202:205], v147 offset:54272
	ds_read_b128 v[206:209], v147 offset:55296
	ds_read_b128 v[220:223], v147 offset:56320
	s_add_u32 s98, s30, 0x80
	s_addc_u32 s99, s31, 0
	global_load_lds_dwordx4 v130, s[98:99]
	s_add_i32 m0, s34, 0x2000
	s_add_u32 s30, s30, 0x80080
	s_addc_u32 s31, s31, 0
	s_add_i32 s34, s54, s26
	s_add_u32 s98, s30, 0xfff80000
	s_addc_u32 s99, s31, -1
	global_load_lds_dwordx4 v134, s[98:99]
	s_mov_b32 m0, s34
	s_nop 0
	global_load_lds_dwordx4 v130, s[30:31]
	s_add_i32 m0, s34, 0x2000
	s_nop 0
	global_load_lds_dwordx4 v134, s[30:31]
	s_mov_b32 m0, s47
	s_nop 0
	global_load_lds_dwordx4 v128, s[60:61]
	s_mov_b32 m0, s48
	s_nop 0
	global_load_lds_dwordx4 v132, s[60:61]
	s_waitcnt vmcnt(8)
	s_waitcnt lgkmcnt(0)
	s_barrier
	s_setprio 1
	s_waitcnt lgkmcnt(0)
	v_mfma_f32_16x16x32_bf16 v[60:63], v[148:151], v[182:185], v[60:63]
	v_mfma_f32_16x16x32_bf16 v[56:59], v[156:159], v[182:185], v[56:59]
	v_mfma_f32_16x16x32_bf16 v[44:47], v[148:151], v[190:193], v[44:47]
	v_mfma_f32_16x16x32_bf16 v[40:43], v[156:159], v[190:193], v[40:43]
	v_mfma_f32_16x16x32_bf16 v[28:31], v[148:151], v[198:201], v[28:31]
	v_mfma_f32_16x16x32_bf16 v[24:27], v[156:159], v[198:201], v[24:27]
	v_mfma_f32_16x16x32_bf16 v[12:15], v[148:151], v[206:209], v[12:15]
	v_mfma_f32_16x16x32_bf16 v[8:11], v[156:159], v[206:209], v[8:11]
	v_mfma_f32_16x16x32_bf16 v[60:63], v[152:155], v[186:189], v[60:63]
	v_mfma_f32_16x16x32_bf16 v[56:59], v[160:163], v[186:189], v[56:59]
	v_mfma_f32_16x16x32_bf16 v[44:47], v[152:155], v[194:197], v[44:47]
	v_mfma_f32_16x16x32_bf16 v[40:43], v[160:163], v[194:197], v[40:43]
	v_mfma_f32_16x16x32_bf16 v[28:31], v[152:155], v[202:205], v[28:31]
	v_mfma_f32_16x16x32_bf16 v[24:27], v[160:163], v[202:205], v[24:27]
	v_mfma_f32_16x16x32_bf16 v[12:15], v[152:155], v[220:223], v[12:15]
	v_mfma_f32_16x16x32_bf16 v[8:11], v[160:163], v[220:223], v[8:11]
	s_setprio 0
	s_setprio 1
	v_mfma_f32_16x16x32_bf16 v[52:55], v[164:167], v[182:185], v[52:55]
	v_mfma_f32_16x16x32_bf16 v[48:51], v[172:175], v[182:185], v[48:51]
	v_mfma_f32_16x16x32_bf16 v[36:39], v[164:167], v[190:193], v[36:39]
	v_mfma_f32_16x16x32_bf16 v[32:35], v[172:175], v[190:193], v[32:35]
	v_mfma_f32_16x16x32_bf16 v[20:23], v[164:167], v[198:201], v[20:23]
	v_mfma_f32_16x16x32_bf16 v[16:19], v[172:175], v[198:201], v[16:19]
	v_mfma_f32_16x16x32_bf16 v[4:7], v[164:167], v[206:209], v[4:7]
	v_mfma_f32_16x16x32_bf16 v[0:3], v[172:175], v[206:209], v[0:3]
	v_mfma_f32_16x16x32_bf16 v[52:55], v[168:171], v[186:189], v[52:55]
	v_mfma_f32_16x16x32_bf16 v[48:51], v[178:181], v[186:189], v[48:51]
	v_mfma_f32_16x16x32_bf16 v[36:39], v[168:171], v[194:197], v[36:39]
	v_mfma_f32_16x16x32_bf16 v[32:35], v[178:181], v[194:197], v[32:35]
	v_mfma_f32_16x16x32_bf16 v[20:23], v[168:171], v[202:205], v[20:23]
	v_mfma_f32_16x16x32_bf16 v[16:19], v[178:181], v[202:205], v[16:19]
	v_mfma_f32_16x16x32_bf16 v[4:7], v[168:171], v[220:223], v[4:7]
	v_mfma_f32_16x16x32_bf16 v[0:3], v[178:181], v[220:223], v[0:3]
	s_setprio 0
	s_barrier
	s_add_i32 s52, s52, 2
	s_add_u32 s4, s4, 0x100
	s_addc_u32 s5, s5, 0
	s_add_u32 s37, s37, 0x100
	s_addc_u32 s51, s51, 0
	s_cmp_gt_u32 s52, 29
.LBB0_966:
	s_add_u32 s30, s4, 0xfff80080
	s_addc_u32 s31, s5, -1
	s_add_i32 s53, 0, 0x10000
	s_cmp_eq_u32 s52, 28
	s_cselect_b32 s35, s17, s31
	s_cselect_b32 s34, s25, s30
	s_cselect_b32 s31, s15, s51
	s_cselect_b32 s30, s36, s37
	s_add_i32 s56, 0, 0x14000
	ds_read_b128 v[148:151], v253
	ds_read_b128 v[152:155], v253 offset:1024
	ds_read_b128 v[156:159], v253 offset:2048
	ds_read_b128 v[160:163], v253 offset:3072
	ds_read_b128 v[164:167], v253 offset:16384
	ds_read_b128 v[168:171], v253 offset:17408
	ds_read_b128 v[172:175], v253 offset:18432
	ds_read_b128 v[178:181], v253 offset:19456
	s_add_i32 m0, s19, 0xc000
	ds_read_b128 v[182:185], v147
	ds_read_b128 v[186:189], v147 offset:1024
	ds_read_b128 v[190:193], v147 offset:2048
	ds_read_b128 v[194:197], v147 offset:3072
	ds_read_b128 v[198:201], v147 offset:4096
	ds_read_b128 v[202:205], v147 offset:5120
	ds_read_b128 v[206:209], v147 offset:6144
	ds_read_b128 v[220:223], v147 offset:7168
	global_load_lds_dwordx4 v138, s[4:5]
	s_add_i32 m0, s19, 0xe000
	s_nop 0
	global_load_lds_dwordx4 v140, s[4:5]
	s_waitcnt vmcnt(8)
	s_waitcnt lgkmcnt(0)
	s_barrier
	s_setprio 1
	s_waitcnt lgkmcnt(0)
	v_mfma_f32_16x16x32_bf16 v[124:127], v[148:151], v[182:185], v[124:127]
	v_mfma_f32_16x16x32_bf16 v[120:123], v[156:159], v[182:185], v[120:123]
	v_mfma_f32_16x16x32_bf16 v[108:111], v[148:151], v[190:193], v[108:111]
	v_mfma_f32_16x16x32_bf16 v[104:107], v[156:159], v[190:193], v[104:107]
	v_mfma_f32_16x16x32_bf16 v[92:95], v[148:151], v[198:201], v[92:95]
	v_mfma_f32_16x16x32_bf16 v[88:91], v[156:159], v[198:201], v[88:91]
	v_mfma_f32_16x16x32_bf16 v[76:79], v[148:151], v[206:209], v[76:79]
	v_mfma_f32_16x16x32_bf16 v[72:75], v[156:159], v[206:209], v[72:75]
	v_mfma_f32_16x16x32_bf16 v[124:127], v[152:155], v[186:189], v[124:127]
	v_mfma_f32_16x16x32_bf16 v[120:123], v[160:163], v[186:189], v[120:123]
	v_mfma_f32_16x16x32_bf16 v[108:111], v[152:155], v[194:197], v[108:111]
	v_mfma_f32_16x16x32_bf16 v[104:107], v[160:163], v[194:197], v[104:107]
	v_mfma_f32_16x16x32_bf16 v[92:95], v[152:155], v[202:205], v[92:95]
	v_mfma_f32_16x16x32_bf16 v[88:91], v[160:163], v[202:205], v[88:91]
	v_mfma_f32_16x16x32_bf16 v[76:79], v[152:155], v[220:223], v[76:79]
	v_mfma_f32_16x16x32_bf16 v[72:75], v[160:163], v[220:223], v[72:75]
	s_setprio 0
	s_setprio 1
	v_mfma_f32_16x16x32_bf16 v[116:119], v[164:167], v[182:185], v[116:119]
	v_mfma_f32_16x16x32_bf16 v[112:115], v[172:175], v[182:185], v[112:115]
	v_mfma_f32_16x16x32_bf16 v[100:103], v[164:167], v[190:193], v[100:103]
	v_mfma_f32_16x16x32_bf16 v[96:99], v[172:175], v[190:193], v[96:99]
	v_mfma_f32_16x16x32_bf16 v[84:87], v[164:167], v[198:201], v[84:87]
	v_mfma_f32_16x16x32_bf16 v[80:83], v[172:175], v[198:201], v[80:83]
	v_mfma_f32_16x16x32_bf16 v[68:71], v[164:167], v[206:209], v[68:71]
	v_mfma_f32_16x16x32_bf16 v[64:67], v[172:175], v[206:209], v[64:67]
	v_mfma_f32_16x16x32_bf16 v[116:119], v[168:171], v[186:189], v[116:119]
	v_mfma_f32_16x16x32_bf16 v[112:115], v[178:181], v[186:189], v[112:115]
	v_mfma_f32_16x16x32_bf16 v[100:103], v[168:171], v[194:197], v[100:103]
	v_mfma_f32_16x16x32_bf16 v[96:99], v[178:181], v[194:197], v[96:99]
	v_mfma_f32_16x16x32_bf16 v[84:87], v[168:171], v[202:205], v[84:87]
	v_mfma_f32_16x16x32_bf16 v[80:83], v[178:181], v[202:205], v[80:83]
	v_mfma_f32_16x16x32_bf16 v[68:71], v[168:171], v[220:223], v[68:71]
	v_mfma_f32_16x16x32_bf16 v[64:67], v[178:181], v[220:223], v[64:67]
	s_setprio 0
	s_barrier
	s_add_i32 s53, s53, s26
	s_mov_b32 m0, s53
	ds_read_b128 v[182:185], v147 offset:16384
	ds_read_b128 v[186:189], v147 offset:17408
	ds_read_b128 v[190:193], v147 offset:18432
	ds_read_b128 v[194:197], v147 offset:19456
	ds_read_b128 v[198:201], v147 offset:20480
	ds_read_b128 v[202:205], v147 offset:21504
	ds_read_b128 v[206:209], v147 offset:22528
	ds_read_b128 v[220:223], v147 offset:23552
	global_load_lds_dwordx4 v130, s[30:31]
	s_add_i32 m0, s53, 0x2000
	s_add_u32 s54, s30, 0x80000
	s_addc_u32 s55, s31, 0
	s_add_i32 s53, s56, s26
	global_load_lds_dwordx4 v134, s[30:31]
	s_mov_b32 m0, s53
	s_nop 0
	global_load_lds_dwordx4 v130, s[54:55]
	s_add_i32 m0, s53, 0x2000
	s_nop 0
	global_load_lds_dwordx4 v134, s[54:55]
	s_add_u32 s60, s34, 0x80
	s_addc_u32 s61, s35, 0
	s_mov_b32 m0, s19
	s_nop 0
	global_load_lds_dwordx4 v128, s[34:35]
	s_mov_b32 m0, s38
	s_nop 0
	global_load_lds_dwordx4 v132, s[34:35]
	s_waitcnt vmcnt(8)
	s_waitcnt lgkmcnt(0)
	s_barrier
	s_setprio 1
	s_waitcnt lgkmcnt(0)
	v_mfma_f32_16x16x32_bf16 v[60:63], v[148:151], v[182:185], v[60:63]
	v_mfma_f32_16x16x32_bf16 v[56:59], v[156:159], v[182:185], v[56:59]
	v_mfma_f32_16x16x32_bf16 v[44:47], v[148:151], v[190:193], v[44:47]
	v_mfma_f32_16x16x32_bf16 v[40:43], v[156:159], v[190:193], v[40:43]
	v_mfma_f32_16x16x32_bf16 v[28:31], v[148:151], v[198:201], v[28:31]
	v_mfma_f32_16x16x32_bf16 v[24:27], v[156:159], v[198:201], v[24:27]
	v_mfma_f32_16x16x32_bf16 v[12:15], v[148:151], v[206:209], v[12:15]
	v_mfma_f32_16x16x32_bf16 v[8:11], v[156:159], v[206:209], v[8:11]
	v_mfma_f32_16x16x32_bf16 v[60:63], v[152:155], v[186:189], v[60:63]
	v_mfma_f32_16x16x32_bf16 v[56:59], v[160:163], v[186:189], v[56:59]
	v_mfma_f32_16x16x32_bf16 v[44:47], v[152:155], v[194:197], v[44:47]
	v_mfma_f32_16x16x32_bf16 v[40:43], v[160:163], v[194:197], v[40:43]
	v_mfma_f32_16x16x32_bf16 v[28:31], v[152:155], v[202:205], v[28:31]
	v_mfma_f32_16x16x32_bf16 v[24:27], v[160:163], v[202:205], v[24:27]
	v_mfma_f32_16x16x32_bf16 v[12:15], v[152:155], v[220:223], v[12:15]
	v_mfma_f32_16x16x32_bf16 v[8:11], v[160:163], v[220:223], v[8:11]
	s_setprio 0
	s_setprio 1
	v_mfma_f32_16x16x32_bf16 v[52:55], v[164:167], v[182:185], v[52:55]
	v_mfma_f32_16x16x32_bf16 v[48:51], v[172:175], v[182:185], v[48:51]
	v_mfma_f32_16x16x32_bf16 v[36:39], v[164:167], v[190:193], v[36:39]
	v_mfma_f32_16x16x32_bf16 v[32:35], v[172:175], v[190:193], v[32:35]
	v_mfma_f32_16x16x32_bf16 v[20:23], v[164:167], v[198:201], v[20:23]
	v_mfma_f32_16x16x32_bf16 v[16:19], v[172:175], v[198:201], v[16:19]
	v_mfma_f32_16x16x32_bf16 v[4:7], v[164:167], v[206:209], v[4:7]
	v_mfma_f32_16x16x32_bf16 v[0:3], v[172:175], v[206:209], v[0:3]
	v_mfma_f32_16x16x32_bf16 v[52:55], v[168:171], v[186:189], v[52:55]
	v_mfma_f32_16x16x32_bf16 v[48:51], v[178:181], v[186:189], v[48:51]
	v_mfma_f32_16x16x32_bf16 v[36:39], v[168:171], v[194:197], v[36:39]
	v_mfma_f32_16x16x32_bf16 v[32:35], v[178:181], v[194:197], v[32:35]
	v_mfma_f32_16x16x32_bf16 v[20:23], v[168:171], v[202:205], v[20:23]
	v_mfma_f32_16x16x32_bf16 v[16:19], v[178:181], v[202:205], v[16:19]
	v_mfma_f32_16x16x32_bf16 v[4:7], v[168:171], v[220:223], v[4:7]
	v_mfma_f32_16x16x32_bf16 v[0:3], v[178:181], v[220:223], v[0:3]
	s_setprio 0
	s_barrier
	s_add_i32 s53, 0, 0x18000
	s_add_i32 s54, 0, 0x1c000
	ds_read_b128 v[148:151], v253 offset:32768
	ds_read_b128 v[152:155], v253 offset:33792
	ds_read_b128 v[156:159], v253 offset:34816
	ds_read_b128 v[160:163], v253 offset:35840
	ds_read_b128 v[164:167], v253 offset:49152
	ds_read_b128 v[168:171], v253 offset:50176
	ds_read_b128 v[172:175], v253 offset:51200
	ds_read_b128 v[178:181], v253 offset:52224
	s_add_u32 s34, s34, 0x80000
	s_addc_u32 s35, s35, 0
	s_mov_b32 m0, s39
	ds_read_b128 v[182:185], v147 offset:32768
	ds_read_b128 v[186:189], v147 offset:33792
	ds_read_b128 v[190:193], v147 offset:34816
	ds_read_b128 v[194:197], v147 offset:35840
	ds_read_b128 v[198:201], v147 offset:36864
	ds_read_b128 v[202:205], v147 offset:37888
	ds_read_b128 v[206:209], v147 offset:38912
	ds_read_b128 v[220:223], v147 offset:39936
	global_load_lds_dwordx4 v128, s[34:35]
	s_mov_b32 m0, s40
	s_nop 0
	global_load_lds_dwordx4 v132, s[34:35]
	s_waitcnt vmcnt(8)
	s_waitcnt lgkmcnt(0)
	s_barrier
	s_setprio 1
	s_waitcnt lgkmcnt(0)
	v_mfma_f32_16x16x32_bf16 v[124:127], v[148:151], v[182:185], v[124:127]
	v_mfma_f32_16x16x32_bf16 v[120:123], v[156:159], v[182:185], v[120:123]
	v_mfma_f32_16x16x32_bf16 v[108:111], v[148:151], v[190:193], v[108:111]
	v_mfma_f32_16x16x32_bf16 v[104:107], v[156:159], v[190:193], v[104:107]
	v_mfma_f32_16x16x32_bf16 v[92:95], v[148:151], v[198:201], v[92:95]
	v_mfma_f32_16x16x32_bf16 v[88:91], v[156:159], v[198:201], v[88:91]
	v_mfma_f32_16x16x32_bf16 v[76:79], v[148:151], v[206:209], v[76:79]
	v_mfma_f32_16x16x32_bf16 v[72:75], v[156:159], v[206:209], v[72:75]
	v_mfma_f32_16x16x32_bf16 v[124:127], v[152:155], v[186:189], v[124:127]
	v_mfma_f32_16x16x32_bf16 v[120:123], v[160:163], v[186:189], v[120:123]
	v_mfma_f32_16x16x32_bf16 v[108:111], v[152:155], v[194:197], v[108:111]
	v_mfma_f32_16x16x32_bf16 v[104:107], v[160:163], v[194:197], v[104:107]
	v_mfma_f32_16x16x32_bf16 v[92:95], v[152:155], v[202:205], v[92:95]
	v_mfma_f32_16x16x32_bf16 v[88:91], v[160:163], v[202:205], v[88:91]
	v_mfma_f32_16x16x32_bf16 v[76:79], v[152:155], v[220:223], v[76:79]
	v_mfma_f32_16x16x32_bf16 v[72:75], v[160:163], v[220:223], v[72:75]
	s_setprio 0
	s_setprio 1
	v_mfma_f32_16x16x32_bf16 v[116:119], v[164:167], v[182:185], v[116:119]
	v_mfma_f32_16x16x32_bf16 v[112:115], v[172:175], v[182:185], v[112:115]
	v_mfma_f32_16x16x32_bf16 v[100:103], v[164:167], v[190:193], v[100:103]
	v_mfma_f32_16x16x32_bf16 v[96:99], v[172:175], v[190:193], v[96:99]
	v_mfma_f32_16x16x32_bf16 v[84:87], v[164:167], v[198:201], v[84:87]
	v_mfma_f32_16x16x32_bf16 v[80:83], v[172:175], v[198:201], v[80:83]
	v_mfma_f32_16x16x32_bf16 v[68:71], v[164:167], v[206:209], v[68:71]
	v_mfma_f32_16x16x32_bf16 v[64:67], v[172:175], v[206:209], v[64:67]
	v_mfma_f32_16x16x32_bf16 v[116:119], v[168:171], v[186:189], v[116:119]
	v_mfma_f32_16x16x32_bf16 v[112:115], v[178:181], v[186:189], v[112:115]
	v_mfma_f32_16x16x32_bf16 v[100:103], v[168:171], v[194:197], v[100:103]
	v_mfma_f32_16x16x32_bf16 v[96:99], v[178:181], v[194:197], v[96:99]
	v_mfma_f32_16x16x32_bf16 v[84:87], v[168:171], v[202:205], v[84:87]
	v_mfma_f32_16x16x32_bf16 v[80:83], v[178:181], v[202:205], v[80:83]
	v_mfma_f32_16x16x32_bf16 v[68:71], v[168:171], v[220:223], v[68:71]
	v_mfma_f32_16x16x32_bf16 v[64:67], v[178:181], v[220:223], v[64:67]
	s_setprio 0
	s_barrier
	s_add_i32 s34, s53, s26
	s_mov_b32 m0, s34
	ds_read_b128 v[182:185], v147 offset:49152
	ds_read_b128 v[186:189], v147 offset:50176
	ds_read_b128 v[190:193], v147 offset:51200
	ds_read_b128 v[194:197], v147 offset:52224
	ds_read_b128 v[198:201], v147 offset:53248
	ds_read_b128 v[202:205], v147 offset:54272
	ds_read_b128 v[206:209], v147 offset:55296
	ds_read_b128 v[220:223], v147 offset:56320
	s_add_u32 s98, s30, 0x80
	s_addc_u32 s99, s31, 0
	global_load_lds_dwordx4 v130, s[98:99]
	s_add_i32 m0, s34, 0x2000
	s_add_u32 s30, s30, 0x80080
	s_addc_u32 s31, s31, 0
	s_add_i32 s34, s54, s26
	s_add_u32 s98, s30, 0xfff80000
	s_addc_u32 s99, s31, -1
	global_load_lds_dwordx4 v134, s[98:99]
	s_mov_b32 m0, s34
	s_nop 0
	global_load_lds_dwordx4 v130, s[30:31]
	s_add_i32 m0, s34, 0x2000
	s_nop 0
	global_load_lds_dwordx4 v134, s[30:31]
	s_mov_b32 m0, s47
	s_nop 0
	global_load_lds_dwordx4 v128, s[60:61]
	s_mov_b32 m0, s48
	s_nop 0
	global_load_lds_dwordx4 v132, s[60:61]
	s_waitcnt vmcnt(8)
	s_waitcnt lgkmcnt(0)
	s_barrier
	s_setprio 1
	s_waitcnt lgkmcnt(0)
	v_mfma_f32_16x16x32_bf16 v[60:63], v[148:151], v[182:185], v[60:63]
	v_mfma_f32_16x16x32_bf16 v[56:59], v[156:159], v[182:185], v[56:59]
	v_mfma_f32_16x16x32_bf16 v[44:47], v[148:151], v[190:193], v[44:47]
	v_mfma_f32_16x16x32_bf16 v[40:43], v[156:159], v[190:193], v[40:43]
	v_mfma_f32_16x16x32_bf16 v[28:31], v[148:151], v[198:201], v[28:31]
	v_mfma_f32_16x16x32_bf16 v[24:27], v[156:159], v[198:201], v[24:27]
	v_mfma_f32_16x16x32_bf16 v[12:15], v[148:151], v[206:209], v[12:15]
	v_mfma_f32_16x16x32_bf16 v[8:11], v[156:159], v[206:209], v[8:11]
	v_mfma_f32_16x16x32_bf16 v[60:63], v[152:155], v[186:189], v[60:63]
	v_mfma_f32_16x16x32_bf16 v[56:59], v[160:163], v[186:189], v[56:59]
	v_mfma_f32_16x16x32_bf16 v[44:47], v[152:155], v[194:197], v[44:47]
	v_mfma_f32_16x16x32_bf16 v[40:43], v[160:163], v[194:197], v[40:43]
	v_mfma_f32_16x16x32_bf16 v[28:31], v[152:155], v[202:205], v[28:31]
	v_mfma_f32_16x16x32_bf16 v[24:27], v[160:163], v[202:205], v[24:27]
	v_mfma_f32_16x16x32_bf16 v[12:15], v[152:155], v[220:223], v[12:15]
	v_mfma_f32_16x16x32_bf16 v[8:11], v[160:163], v[220:223], v[8:11]
	s_setprio 0
	s_setprio 1
	v_mfma_f32_16x16x32_bf16 v[52:55], v[164:167], v[182:185], v[52:55]
	v_mfma_f32_16x16x32_bf16 v[48:51], v[172:175], v[182:185], v[48:51]
	v_mfma_f32_16x16x32_bf16 v[36:39], v[164:167], v[190:193], v[36:39]
	v_mfma_f32_16x16x32_bf16 v[32:35], v[172:175], v[190:193], v[32:35]
	v_mfma_f32_16x16x32_bf16 v[20:23], v[164:167], v[198:201], v[20:23]
	v_mfma_f32_16x16x32_bf16 v[16:19], v[172:175], v[198:201], v[16:19]
	v_mfma_f32_16x16x32_bf16 v[4:7], v[164:167], v[206:209], v[4:7]
	v_mfma_f32_16x16x32_bf16 v[0:3], v[172:175], v[206:209], v[0:3]
	v_mfma_f32_16x16x32_bf16 v[52:55], v[168:171], v[186:189], v[52:55]
	v_mfma_f32_16x16x32_bf16 v[48:51], v[178:181], v[186:189], v[48:51]
	v_mfma_f32_16x16x32_bf16 v[36:39], v[168:171], v[194:197], v[36:39]
	v_mfma_f32_16x16x32_bf16 v[32:35], v[178:181], v[194:197], v[32:35]
	v_mfma_f32_16x16x32_bf16 v[20:23], v[168:171], v[202:205], v[20:23]
	v_mfma_f32_16x16x32_bf16 v[16:19], v[178:181], v[202:205], v[16:19]
	v_mfma_f32_16x16x32_bf16 v[4:7], v[168:171], v[220:223], v[4:7]
	v_mfma_f32_16x16x32_bf16 v[0:3], v[178:181], v[220:223], v[0:3]
	s_setprio 0
	s_barrier
	s_add_i32 s52, s52, 2
	s_add_u32 s4, s4, 0x100
	s_addc_u32 s5, s5, 0
	s_add_u32 s37, s37, 0x100
	s_addc_u32 s51, s51, 0
	s_cmp_gt_u32 s52, 29
	s_cbranch_scc0 .LBB0_966
	s_and_b64 vcc, exec, s[8:9]
	s_cbranch_vccz .LBB0_969
	s_barrier

.LBB0_1056:
	s_ashr_i32 s53, s52, 31
	s_lshl_b64 s[14:15], s[52:53], 20
	s_add_u32 s70, s25, s14
	s_addc_u32 s71, s28, s15
	s_and_b64 s[14:15], s[68:69], exec
	s_cselect_b32 s20, s71, s1
	s_cselect_b32 s21, s70, s0
	s_ashr_i32 s55, s54, 31
	s_lshl_b64 s[14:15], s[54:55], 20
	s_add_u32 s56, s29, s14
	s_addc_u32 s57, s38, s15
	s_and_b64 s[14:15], s[68:69], exec
	s_cselect_b32 s22, s57, s13
	s_cselect_b32 s23, s56, s12
	s_add_u32 s0, s0, 0x80080
	s_addc_u32 s1, s1, 0
	s_add_u32 s26, s12, 0x100
	s_addc_u32 s27, s13, 0
	s_mov_b32 s33, -2
	v_add_u32_e32 v253, 0x10000, v222
	s_add_u32 s12, s0, 0xfff80080
	s_addc_u32 s13, s1, -1
	s_add_i32 s50, 0, 0x10000
	s_cmp_eq_u32 s33, 28
	s_cselect_b32 s15, s20, s13
	s_cselect_b32 s14, s21, s12
	s_cselect_b32 s13, s22, s27
	s_cselect_b32 s12, s23, s26
	s_add_i32 s53, 0, 0x14000
	ds_read_b128 v[88:91], v253
	ds_read_b128 v[92:95], v253 offset:1024
	ds_read_b128 v[96:99], v253 offset:2048
	ds_read_b128 v[100:103], v253 offset:3072
	ds_read_b128 v[108:111], v253 offset:16384
	ds_read_b128 v[112:115], v253 offset:17408
	ds_read_b128 v[116:119], v253 offset:18432
	ds_read_b128 v[120:123], v253 offset:19456
	s_add_i32 m0, s42, 0xc000
	ds_read_b128 v[152:155], v224
	ds_read_b128 v[164:167], v224 offset:1024
	ds_read_b128 v[168:171], v224 offset:2048
	ds_read_b128 v[172:175], v224 offset:3072
	ds_read_b128 v[188:191], v224 offset:4096
	ds_read_b128 v[192:195], v224 offset:5120
	ds_read_b128 v[196:199], v224 offset:6144
	ds_read_b128 v[200:203], v224 offset:7168
	global_load_lds_dwordx4 v184, s[0:1]
	s_add_i32 m0, s42, 0xe000
	s_nop 0
	global_load_lds_dwordx4 v186, s[0:1]
	s_waitcnt vmcnt(8)
	s_waitcnt lgkmcnt(0)
	s_barrier
	s_setprio 1
	s_waitcnt lgkmcnt(0)
	v_mfma_f32_16x16x32_bf16 v[160:163], v[88:91], v[152:155], 0
	v_mfma_f32_16x16x32_bf16 v[156:159], v[96:99], v[152:155], 0
	v_mfma_f32_16x16x32_bf16 v[148:151], v[88:91], v[168:171], 0
	v_mfma_f32_16x16x32_bf16 v[144:147], v[96:99], v[168:171], 0
	v_mfma_f32_16x16x32_bf16 v[140:143], v[88:91], v[188:191], 0
	v_mfma_f32_16x16x32_bf16 v[136:139], v[96:99], v[188:191], 0
	v_mfma_f32_16x16x32_bf16 v[132:135], v[88:91], v[196:199], 0
	v_mfma_f32_16x16x32_bf16 v[128:131], v[96:99], v[196:199], 0
	v_mfma_f32_16x16x32_bf16 v[160:163], v[92:95], v[164:167], v[160:163]
	v_mfma_f32_16x16x32_bf16 v[156:159], v[100:103], v[164:167], v[156:159]
	v_mfma_f32_16x16x32_bf16 v[148:151], v[92:95], v[172:175], v[148:151]
	v_mfma_f32_16x16x32_bf16 v[144:147], v[100:103], v[172:175], v[144:147]
	v_mfma_f32_16x16x32_bf16 v[140:143], v[92:95], v[192:195], v[140:143]
	v_mfma_f32_16x16x32_bf16 v[136:139], v[100:103], v[192:195], v[136:139]
	v_mfma_f32_16x16x32_bf16 v[132:135], v[92:95], v[200:203], v[132:135]
	v_mfma_f32_16x16x32_bf16 v[128:131], v[100:103], v[200:203], v[128:131]
	s_setprio 0
	s_setprio 1
	v_mfma_f32_16x16x32_bf16 v[60:63], v[108:111], v[152:155], 0
	v_mfma_f32_16x16x32_bf16 v[56:59], v[116:119], v[152:155], 0
	v_mfma_f32_16x16x32_bf16 v[52:55], v[108:111], v[168:171], 0
	v_mfma_f32_16x16x32_bf16 v[48:51], v[116:119], v[168:171], 0
	v_mfma_f32_16x16x32_bf16 v[44:47], v[108:111], v[188:191], 0
	v_mfma_f32_16x16x32_bf16 v[40:43], v[116:119], v[188:191], 0
	v_mfma_f32_16x16x32_bf16 v[36:39], v[108:111], v[196:199], 0
	v_mfma_f32_16x16x32_bf16 v[32:35], v[116:119], v[196:199], 0
	v_mfma_f32_16x16x32_bf16 v[60:63], v[112:115], v[164:167], v[60:63]
	v_mfma_f32_16x16x32_bf16 v[56:59], v[120:123], v[164:167], v[56:59]
	v_mfma_f32_16x16x32_bf16 v[52:55], v[112:115], v[172:175], v[52:55]
	v_mfma_f32_16x16x32_bf16 v[48:51], v[120:123], v[172:175], v[48:51]
	v_mfma_f32_16x16x32_bf16 v[44:47], v[112:115], v[192:195], v[44:47]
	v_mfma_f32_16x16x32_bf16 v[40:43], v[120:123], v[192:195], v[40:43]
	v_mfma_f32_16x16x32_bf16 v[36:39], v[112:115], v[200:203], v[36:39]
	v_mfma_f32_16x16x32_bf16 v[32:35], v[120:123], v[200:203], v[32:35]
	s_setprio 0
	s_barrier
	s_add_i32 s50, s50, s39
	s_mov_b32 m0, s50
	ds_read_b128 v[152:155], v224 offset:16384
	ds_read_b128 v[164:167], v224 offset:17408
	ds_read_b128 v[168:171], v224 offset:18432
	ds_read_b128 v[172:175], v224 offset:19456
	ds_read_b128 v[188:191], v224 offset:20480
	ds_read_b128 v[192:195], v224 offset:21504
	ds_read_b128 v[196:199], v224 offset:22528
	ds_read_b128 v[200:203], v224 offset:23552
	global_load_lds_dwordx4 v176, s[12:13]
	s_add_i32 m0, s50, 0x2000
	s_add_u32 s50, s12, 0x80000
	s_addc_u32 s51, s13, 0
	s_add_i32 s53, s53, s39
	global_load_lds_dwordx4 v178, s[12:13]
	s_mov_b32 m0, s53
	s_nop 0
	global_load_lds_dwordx4 v176, s[50:51]
	s_add_i32 m0, s53, 0x2000
	s_nop 0
	global_load_lds_dwordx4 v178, s[50:51]
	s_add_u32 s62, s14, 0x80
	s_addc_u32 s63, s15, 0
	s_mov_b32 m0, s42
	s_nop 0
	global_load_lds_dwordx4 v182, s[14:15]
	s_mov_b32 m0, s43
	s_nop 0
	global_load_lds_dwordx4 v180, s[14:15]
	s_waitcnt vmcnt(8)
	s_waitcnt lgkmcnt(0)
	s_barrier
	s_setprio 1
	s_waitcnt lgkmcnt(0)
	v_mfma_f32_16x16x32_bf16 v[124:127], v[88:91], v[152:155], 0
	v_mfma_f32_16x16x32_bf16 v[104:107], v[96:99], v[152:155], 0
	v_mfma_f32_16x16x32_bf16 v[84:87], v[88:91], v[168:171], 0
	v_mfma_f32_16x16x32_bf16 v[80:83], v[96:99], v[168:171], 0
	v_mfma_f32_16x16x32_bf16 v[76:79], v[88:91], v[188:191], 0
	v_mfma_f32_16x16x32_bf16 v[72:75], v[96:99], v[188:191], 0
	v_mfma_f32_16x16x32_bf16 v[68:71], v[88:91], v[196:199], 0
	v_mfma_f32_16x16x32_bf16 v[64:67], v[96:99], v[196:199], 0
	v_mfma_f32_16x16x32_bf16 v[124:127], v[92:95], v[164:167], v[124:127]
	v_mfma_f32_16x16x32_bf16 v[104:107], v[100:103], v[164:167], v[104:107]
	v_mfma_f32_16x16x32_bf16 v[84:87], v[92:95], v[172:175], v[84:87]
	v_mfma_f32_16x16x32_bf16 v[80:83], v[100:103], v[172:175], v[80:83]
	v_mfma_f32_16x16x32_bf16 v[76:79], v[92:95], v[192:195], v[76:79]
	v_mfma_f32_16x16x32_bf16 v[72:75], v[100:103], v[192:195], v[72:75]
	v_mfma_f32_16x16x32_bf16 v[68:71], v[92:95], v[200:203], v[68:71]
	v_mfma_f32_16x16x32_bf16 v[64:67], v[100:103], v[200:203], v[64:67]
	s_setprio 0
	s_setprio 1
	v_mfma_f32_16x16x32_bf16 v[28:31], v[108:111], v[152:155], 0
	v_mfma_f32_16x16x32_bf16 v[24:27], v[116:119], v[152:155], 0
	v_mfma_f32_16x16x32_bf16 v[20:23], v[108:111], v[168:171], 0
	v_mfma_f32_16x16x32_bf16 v[16:19], v[116:119], v[168:171], 0
	v_mfma_f32_16x16x32_bf16 v[12:15], v[108:111], v[188:191], 0
	v_mfma_f32_16x16x32_bf16 v[8:11], v[116:119], v[188:191], 0
	v_mfma_f32_16x16x32_bf16 v[4:7], v[108:111], v[196:199], 0
	v_mfma_f32_16x16x32_bf16 v[0:3], v[116:119], v[196:199], 0
	v_mfma_f32_16x16x32_bf16 v[28:31], v[112:115], v[164:167], v[28:31]
	v_mfma_f32_16x16x32_bf16 v[24:27], v[120:123], v[164:167], v[24:27]
	v_mfma_f32_16x16x32_bf16 v[20:23], v[112:115], v[172:175], v[20:23]
	v_mfma_f32_16x16x32_bf16 v[16:19], v[120:123], v[172:175], v[16:19]
	v_mfma_f32_16x16x32_bf16 v[12:15], v[112:115], v[192:195], v[12:15]
	v_mfma_f32_16x16x32_bf16 v[8:11], v[120:123], v[192:195], v[8:11]
	v_mfma_f32_16x16x32_bf16 v[4:7], v[112:115], v[200:203], v[4:7]
	v_mfma_f32_16x16x32_bf16 v[0:3], v[120:123], v[200:203], v[0:3]
	s_setprio 0
	s_barrier
	s_add_i32 s50, 0, 0x18000
	s_add_i32 s51, 0, 0x1c000
	ds_read_b128 v[88:91], v253 offset:32768
	ds_read_b128 v[92:95], v253 offset:33792
	ds_read_b128 v[96:99], v253 offset:34816
	ds_read_b128 v[100:103], v253 offset:35840
	ds_read_b128 v[108:111], v253 offset:49152
	ds_read_b128 v[112:115], v253 offset:50176
	ds_read_b128 v[116:119], v253 offset:51200
	ds_read_b128 v[120:123], v253 offset:52224
	s_add_u32 s14, s14, 0x80000
	s_addc_u32 s15, s15, 0
	s_mov_b32 m0, s44
	ds_read_b128 v[152:155], v224 offset:32768
	ds_read_b128 v[164:167], v224 offset:33792
	ds_read_b128 v[168:171], v224 offset:34816
	ds_read_b128 v[172:175], v224 offset:35840
	ds_read_b128 v[188:191], v224 offset:36864
	ds_read_b128 v[192:195], v224 offset:37888
	ds_read_b128 v[196:199], v224 offset:38912
	ds_read_b128 v[200:203], v224 offset:39936
	global_load_lds_dwordx4 v182, s[14:15]
	s_mov_b32 m0, s45
	s_nop 0
	global_load_lds_dwordx4 v180, s[14:15]
	s_waitcnt vmcnt(8)
	s_waitcnt lgkmcnt(0)
	s_barrier
	s_setprio 1
	s_waitcnt lgkmcnt(0)
	v_mfma_f32_16x16x32_bf16 v[160:163], v[88:91], v[152:155], v[160:163]
	v_mfma_f32_16x16x32_bf16 v[156:159], v[96:99], v[152:155], v[156:159]
	v_mfma_f32_16x16x32_bf16 v[148:151], v[88:91], v[168:171], v[148:151]
	v_mfma_f32_16x16x32_bf16 v[144:147], v[96:99], v[168:171], v[144:147]
	v_mfma_f32_16x16x32_bf16 v[140:143], v[88:91], v[188:191], v[140:143]
	v_mfma_f32_16x16x32_bf16 v[136:139], v[96:99], v[188:191], v[136:139]
	v_mfma_f32_16x16x32_bf16 v[132:135], v[88:91], v[196:199], v[132:135]
	v_mfma_f32_16x16x32_bf16 v[128:131], v[96:99], v[196:199], v[128:131]
	v_mfma_f32_16x16x32_bf16 v[160:163], v[92:95], v[164:167], v[160:163]
	v_mfma_f32_16x16x32_bf16 v[156:159], v[100:103], v[164:167], v[156:159]
	v_mfma_f32_16x16x32_bf16 v[148:151], v[92:95], v[172:175], v[148:151]
	v_mfma_f32_16x16x32_bf16 v[144:147], v[100:103], v[172:175], v[144:147]
	v_mfma_f32_16x16x32_bf16 v[140:143], v[92:95], v[192:195], v[140:143]
	v_mfma_f32_16x16x32_bf16 v[136:139], v[100:103], v[192:195], v[136:139]
	v_mfma_f32_16x16x32_bf16 v[132:135], v[92:95], v[200:203], v[132:135]
	v_mfma_f32_16x16x32_bf16 v[128:131], v[100:103], v[200:203], v[128:131]
	s_setprio 0
	s_setprio 1
	v_mfma_f32_16x16x32_bf16 v[60:63], v[108:111], v[152:155], v[60:63]
	v_mfma_f32_16x16x32_bf16 v[56:59], v[116:119], v[152:155], v[56:59]
	v_mfma_f32_16x16x32_bf16 v[52:55], v[108:111], v[168:171], v[52:55]
	v_mfma_f32_16x16x32_bf16 v[48:51], v[116:119], v[168:171], v[48:51]
	v_mfma_f32_16x16x32_bf16 v[44:47], v[108:111], v[188:191], v[44:47]
	v_mfma_f32_16x16x32_bf16 v[40:43], v[116:119], v[188:191], v[40:43]
	v_mfma_f32_16x16x32_bf16 v[36:39], v[108:111], v[196:199], v[36:39]
	v_mfma_f32_16x16x32_bf16 v[32:35], v[116:119], v[196:199], v[32:35]
	v_mfma_f32_16x16x32_bf16 v[60:63], v[112:115], v[164:167], v[60:63]
	v_mfma_f32_16x16x32_bf16 v[56:59], v[120:123], v[164:167], v[56:59]
	v_mfma_f32_16x16x32_bf16 v[52:55], v[112:115], v[172:175], v[52:55]
	v_mfma_f32_16x16x32_bf16 v[48:51], v[120:123], v[172:175], v[48:51]
	v_mfma_f32_16x16x32_bf16 v[44:47], v[112:115], v[192:195], v[44:47]
	v_mfma_f32_16x16x32_bf16 v[40:43], v[120:123], v[192:195], v[40:43]
	v_mfma_f32_16x16x32_bf16 v[36:39], v[112:115], v[200:203], v[36:39]
	v_mfma_f32_16x16x32_bf16 v[32:35], v[120:123], v[200:203], v[32:35]
	s_setprio 0
	s_barrier
	s_add_i32 s14, s50, s39
	s_mov_b32 m0, s14
	ds_read_b128 v[152:155], v224 offset:49152
	ds_read_b128 v[164:167], v224 offset:50176
	ds_read_b128 v[168:171], v224 offset:51200
	ds_read_b128 v[172:175], v224 offset:52224
	ds_read_b128 v[188:191], v224 offset:53248
	ds_read_b128 v[192:195], v224 offset:54272
	ds_read_b128 v[196:199], v224 offset:55296
	ds_read_b128 v[200:203], v224 offset:56320
	s_add_u32 s98, s12, 0x80
	s_addc_u32 s99, s13, 0
	global_load_lds_dwordx4 v176, s[98:99]
	s_add_i32 m0, s14, 0x2000
	s_add_u32 s12, s12, 0x80080
	s_addc_u32 s13, s13, 0
	s_add_i32 s14, s51, s39
	s_add_u32 s98, s12, 0xfff80000
	s_addc_u32 s99, s13, -1
	global_load_lds_dwordx4 v178, s[98:99]
	s_mov_b32 m0, s14
	s_nop 0
	global_load_lds_dwordx4 v176, s[12:13]
	s_add_i32 m0, s14, 0x2000
	s_nop 0
	global_load_lds_dwordx4 v178, s[12:13]
	s_mov_b32 m0, s61
	s_nop 0
	global_load_lds_dwordx4 v182, s[62:63]
	s_mov_b32 m0, s64
	s_nop 0
	global_load_lds_dwordx4 v180, s[62:63]
	s_waitcnt vmcnt(8)
	s_waitcnt lgkmcnt(0)
	s_barrier
	s_setprio 1
	s_waitcnt lgkmcnt(0)
	v_mfma_f32_16x16x32_bf16 v[124:127], v[88:91], v[152:155], v[124:127]
	v_mfma_f32_16x16x32_bf16 v[104:107], v[96:99], v[152:155], v[104:107]
	v_mfma_f32_16x16x32_bf16 v[84:87], v[88:91], v[168:171], v[84:87]
	v_mfma_f32_16x16x32_bf16 v[80:83], v[96:99], v[168:171], v[80:83]
	v_mfma_f32_16x16x32_bf16 v[76:79], v[88:91], v[188:191], v[76:79]
	v_mfma_f32_16x16x32_bf16 v[72:75], v[96:99], v[188:191], v[72:75]
	v_mfma_f32_16x16x32_bf16 v[68:71], v[88:91], v[196:199], v[68:71]
	v_mfma_f32_16x16x32_bf16 v[64:67], v[96:99], v[196:199], v[64:67]
	v_mfma_f32_16x16x32_bf16 v[124:127], v[92:95], v[164:167], v[124:127]
	v_mfma_f32_16x16x32_bf16 v[104:107], v[100:103], v[164:167], v[104:107]
	v_mfma_f32_16x16x32_bf16 v[84:87], v[92:95], v[172:175], v[84:87]
	v_mfma_f32_16x16x32_bf16 v[80:83], v[100:103], v[172:175], v[80:83]
	v_mfma_f32_16x16x32_bf16 v[76:79], v[92:95], v[192:195], v[76:79]
	v_mfma_f32_16x16x32_bf16 v[72:75], v[100:103], v[192:195], v[72:75]
	v_mfma_f32_16x16x32_bf16 v[68:71], v[92:95], v[200:203], v[68:71]
	v_mfma_f32_16x16x32_bf16 v[64:67], v[100:103], v[200:203], v[64:67]
	s_setprio 0
	s_setprio 1
	v_mfma_f32_16x16x32_bf16 v[28:31], v[108:111], v[152:155], v[28:31]
	v_mfma_f32_16x16x32_bf16 v[24:27], v[116:119], v[152:155], v[24:27]
	v_mfma_f32_16x16x32_bf16 v[20:23], v[108:111], v[168:171], v[20:23]
	v_mfma_f32_16x16x32_bf16 v[16:19], v[116:119], v[168:171], v[16:19]
	v_mfma_f32_16x16x32_bf16 v[12:15], v[108:111], v[188:191], v[12:15]
	v_mfma_f32_16x16x32_bf16 v[8:11], v[116:119], v[188:191], v[8:11]
	v_mfma_f32_16x16x32_bf16 v[4:7], v[108:111], v[196:199], v[4:7]
	v_mfma_f32_16x16x32_bf16 v[0:3], v[116:119], v[196:199], v[0:3]
	v_mfma_f32_16x16x32_bf16 v[28:31], v[112:115], v[164:167], v[28:31]
	v_mfma_f32_16x16x32_bf16 v[24:27], v[120:123], v[164:167], v[24:27]
	v_mfma_f32_16x16x32_bf16 v[20:23], v[112:115], v[172:175], v[20:23]
	v_mfma_f32_16x16x32_bf16 v[16:19], v[120:123], v[172:175], v[16:19]
	v_mfma_f32_16x16x32_bf16 v[12:15], v[112:115], v[192:195], v[12:15]
	v_mfma_f32_16x16x32_bf16 v[8:11], v[120:123], v[192:195], v[8:11]
	v_mfma_f32_16x16x32_bf16 v[4:7], v[112:115], v[200:203], v[4:7]
	v_mfma_f32_16x16x32_bf16 v[0:3], v[120:123], v[200:203], v[0:3]
	s_setprio 0
	s_barrier
	s_add_i32 s33, s33, 2
	s_add_u32 s0, s0, 0x100
	s_addc_u32 s1, s1, 0
	s_add_u32 s26, s26, 0x100
	s_addc_u32 s27, s27, 0
	s_cmp_gt_u32 s33, 29
.LBB0_1057:
	s_add_u32 s12, s0, 0xfff80080
	s_addc_u32 s13, s1, -1
	s_add_i32 s50, 0, 0x10000
	s_cmp_eq_u32 s33, 28
	s_cselect_b32 s15, s20, s13
	s_cselect_b32 s14, s21, s12
	s_cselect_b32 s13, s22, s27
	s_cselect_b32 s12, s23, s26
	s_add_i32 s53, 0, 0x14000
	ds_read_b128 v[88:91], v253
	ds_read_b128 v[92:95], v253 offset:1024
	ds_read_b128 v[96:99], v253 offset:2048
	ds_read_b128 v[100:103], v253 offset:3072
	ds_read_b128 v[108:111], v253 offset:16384
	ds_read_b128 v[112:115], v253 offset:17408
	ds_read_b128 v[116:119], v253 offset:18432
	ds_read_b128 v[120:123], v253 offset:19456
	s_add_i32 m0, s42, 0xc000
	ds_read_b128 v[152:155], v224
	ds_read_b128 v[164:167], v224 offset:1024
	ds_read_b128 v[168:171], v224 offset:2048
	ds_read_b128 v[172:175], v224 offset:3072
	ds_read_b128 v[188:191], v224 offset:4096
	ds_read_b128 v[192:195], v224 offset:5120
	ds_read_b128 v[196:199], v224 offset:6144
	ds_read_b128 v[200:203], v224 offset:7168
	global_load_lds_dwordx4 v184, s[0:1]
	s_add_i32 m0, s42, 0xe000
	s_nop 0
	global_load_lds_dwordx4 v186, s[0:1]
	s_waitcnt vmcnt(8)
	s_waitcnt lgkmcnt(0)
	s_barrier
	s_setprio 1
	s_waitcnt lgkmcnt(0)
	v_mfma_f32_16x16x32_bf16 v[160:163], v[88:91], v[152:155], v[160:163]
	v_mfma_f32_16x16x32_bf16 v[156:159], v[96:99], v[152:155], v[156:159]
	v_mfma_f32_16x16x32_bf16 v[148:151], v[88:91], v[168:171], v[148:151]
	v_mfma_f32_16x16x32_bf16 v[144:147], v[96:99], v[168:171], v[144:147]
	v_mfma_f32_16x16x32_bf16 v[140:143], v[88:91], v[188:191], v[140:143]
	v_mfma_f32_16x16x32_bf16 v[136:139], v[96:99], v[188:191], v[136:139]
	v_mfma_f32_16x16x32_bf16 v[132:135], v[88:91], v[196:199], v[132:135]
	v_mfma_f32_16x16x32_bf16 v[128:131], v[96:99], v[196:199], v[128:131]
	v_mfma_f32_16x16x32_bf16 v[160:163], v[92:95], v[164:167], v[160:163]
	v_mfma_f32_16x16x32_bf16 v[156:159], v[100:103], v[164:167], v[156:159]
	v_mfma_f32_16x16x32_bf16 v[148:151], v[92:95], v[172:175], v[148:151]
	v_mfma_f32_16x16x32_bf16 v[144:147], v[100:103], v[172:175], v[144:147]
	v_mfma_f32_16x16x32_bf16 v[140:143], v[92:95], v[192:195], v[140:143]
	v_mfma_f32_16x16x32_bf16 v[136:139], v[100:103], v[192:195], v[136:139]
	v_mfma_f32_16x16x32_bf16 v[132:135], v[92:95], v[200:203], v[132:135]
	v_mfma_f32_16x16x32_bf16 v[128:131], v[100:103], v[200:203], v[128:131]
	s_setprio 0
	s_setprio 1
	v_mfma_f32_16x16x32_bf16 v[60:63], v[108:111], v[152:155], v[60:63]
	v_mfma_f32_16x16x32_bf16 v[56:59], v[116:119], v[152:155], v[56:59]
	v_mfma_f32_16x16x32_bf16 v[52:55], v[108:111], v[168:171], v[52:55]
	v_mfma_f32_16x16x32_bf16 v[48:51], v[116:119], v[168:171], v[48:51]
	v_mfma_f32_16x16x32_bf16 v[44:47], v[108:111], v[188:191], v[44:47]
	v_mfma_f32_16x16x32_bf16 v[40:43], v[116:119], v[188:191], v[40:43]
	v_mfma_f32_16x16x32_bf16 v[36:39], v[108:111], v[196:199], v[36:39]
	v_mfma_f32_16x16x32_bf16 v[32:35], v[116:119], v[196:199], v[32:35]
	v_mfma_f32_16x16x32_bf16 v[60:63], v[112:115], v[164:167], v[60:63]
	v_mfma_f32_16x16x32_bf16 v[56:59], v[120:123], v[164:167], v[56:59]
	v_mfma_f32_16x16x32_bf16 v[52:55], v[112:115], v[172:175], v[52:55]
	v_mfma_f32_16x16x32_bf16 v[48:51], v[120:123], v[172:175], v[48:51]
	v_mfma_f32_16x16x32_bf16 v[44:47], v[112:115], v[192:195], v[44:47]
	v_mfma_f32_16x16x32_bf16 v[40:43], v[120:123], v[192:195], v[40:43]
	v_mfma_f32_16x16x32_bf16 v[36:39], v[112:115], v[200:203], v[36:39]
	v_mfma_f32_16x16x32_bf16 v[32:35], v[120:123], v[200:203], v[32:35]
	s_setprio 0
	s_barrier
	s_add_i32 s50, s50, s39
	s_mov_b32 m0, s50
	ds_read_b128 v[152:155], v224 offset:16384
	ds_read_b128 v[164:167], v224 offset:17408
	ds_read_b128 v[168:171], v224 offset:18432
	ds_read_b128 v[172:175], v224 offset:19456
	ds_read_b128 v[188:191], v224 offset:20480
	ds_read_b128 v[192:195], v224 offset:21504
	ds_read_b128 v[196:199], v224 offset:22528
	ds_read_b128 v[200:203], v224 offset:23552
	global_load_lds_dwordx4 v176, s[12:13]
	s_add_i32 m0, s50, 0x2000
	s_add_u32 s50, s12, 0x80000
	s_addc_u32 s51, s13, 0
	s_add_i32 s53, s53, s39
	global_load_lds_dwordx4 v178, s[12:13]
	s_mov_b32 m0, s53
	s_nop 0
	global_load_lds_dwordx4 v176, s[50:51]
	s_add_i32 m0, s53, 0x2000
	s_nop 0
	global_load_lds_dwordx4 v178, s[50:51]
	s_add_u32 s62, s14, 0x80
	s_addc_u32 s63, s15, 0
	s_mov_b32 m0, s42
	s_nop 0
	global_load_lds_dwordx4 v182, s[14:15]
	s_mov_b32 m0, s43
	s_nop 0
	global_load_lds_dwordx4 v180, s[14:15]
	s_waitcnt vmcnt(8)
	s_waitcnt lgkmcnt(0)
	s_barrier
	s_setprio 1
	s_waitcnt lgkmcnt(0)
	v_mfma_f32_16x16x32_bf16 v[124:127], v[88:91], v[152:155], v[124:127]
	v_mfma_f32_16x16x32_bf16 v[104:107], v[96:99], v[152:155], v[104:107]
	v_mfma_f32_16x16x32_bf16 v[84:87], v[88:91], v[168:171], v[84:87]
	v_mfma_f32_16x16x32_bf16 v[80:83], v[96:99], v[168:171], v[80:83]
	v_mfma_f32_16x16x32_bf16 v[76:79], v[88:91], v[188:191], v[76:79]
	v_mfma_f32_16x16x32_bf16 v[72:75], v[96:99], v[188:191], v[72:75]
	v_mfma_f32_16x16x32_bf16 v[68:71], v[88:91], v[196:199], v[68:71]
	v_mfma_f32_16x16x32_bf16 v[64:67], v[96:99], v[196:199], v[64:67]
	v_mfma_f32_16x16x32_bf16 v[124:127], v[92:95], v[164:167], v[124:127]
	v_mfma_f32_16x16x32_bf16 v[104:107], v[100:103], v[164:167], v[104:107]
	v_mfma_f32_16x16x32_bf16 v[84:87], v[92:95], v[172:175], v[84:87]
	v_mfma_f32_16x16x32_bf16 v[80:83], v[100:103], v[172:175], v[80:83]
	v_mfma_f32_16x16x32_bf16 v[76:79], v[92:95], v[192:195], v[76:79]
	v_mfma_f32_16x16x32_bf16 v[72:75], v[100:103], v[192:195], v[72:75]
	v_mfma_f32_16x16x32_bf16 v[68:71], v[92:95], v[200:203], v[68:71]
	v_mfma_f32_16x16x32_bf16 v[64:67], v[100:103], v[200:203], v[64:67]
	s_setprio 0
	s_setprio 1
	v_mfma_f32_16x16x32_bf16 v[28:31], v[108:111], v[152:155], v[28:31]
	v_mfma_f32_16x16x32_bf16 v[24:27], v[116:119], v[152:155], v[24:27]
	v_mfma_f32_16x16x32_bf16 v[20:23], v[108:111], v[168:171], v[20:23]
	v_mfma_f32_16x16x32_bf16 v[16:19], v[116:119], v[168:171], v[16:19]
	v_mfma_f32_16x16x32_bf16 v[12:15], v[108:111], v[188:191], v[12:15]
	v_mfma_f32_16x16x32_bf16 v[8:11], v[116:119], v[188:191], v[8:11]
	v_mfma_f32_16x16x32_bf16 v[4:7], v[108:111], v[196:199], v[4:7]
	v_mfma_f32_16x16x32_bf16 v[0:3], v[116:119], v[196:199], v[0:3]
	v_mfma_f32_16x16x32_bf16 v[28:31], v[112:115], v[164:167], v[28:31]
	v_mfma_f32_16x16x32_bf16 v[24:27], v[120:123], v[164:167], v[24:27]
	v_mfma_f32_16x16x32_bf16 v[20:23], v[112:115], v[172:175], v[20:23]
	v_mfma_f32_16x16x32_bf16 v[16:19], v[120:123], v[172:175], v[16:19]
	v_mfma_f32_16x16x32_bf16 v[12:15], v[112:115], v[192:195], v[12:15]
	v_mfma_f32_16x16x32_bf16 v[8:11], v[120:123], v[192:195], v[8:11]
	v_mfma_f32_16x16x32_bf16 v[4:7], v[112:115], v[200:203], v[4:7]
	v_mfma_f32_16x16x32_bf16 v[0:3], v[120:123], v[200:203], v[0:3]
	s_setprio 0
	s_barrier
	s_add_i32 s50, 0, 0x18000
	s_add_i32 s51, 0, 0x1c000
	ds_read_b128 v[88:91], v253 offset:32768
	ds_read_b128 v[92:95], v253 offset:33792
	ds_read_b128 v[96:99], v253 offset:34816
	ds_read_b128 v[100:103], v253 offset:35840
	ds_read_b128 v[108:111], v253 offset:49152
	ds_read_b128 v[112:115], v253 offset:50176
	ds_read_b128 v[116:119], v253 offset:51200
	ds_read_b128 v[120:123], v253 offset:52224
	s_add_u32 s14, s14, 0x80000
	s_addc_u32 s15, s15, 0
	s_mov_b32 m0, s44
	ds_read_b128 v[152:155], v224 offset:32768
	ds_read_b128 v[164:167], v224 offset:33792
	ds_read_b128 v[168:171], v224 offset:34816
	ds_read_b128 v[172:175], v224 offset:35840
	ds_read_b128 v[188:191], v224 offset:36864
	ds_read_b128 v[192:195], v224 offset:37888
	ds_read_b128 v[196:199], v224 offset:38912
	ds_read_b128 v[200:203], v224 offset:39936
	global_load_lds_dwordx4 v182, s[14:15]
	s_mov_b32 m0, s45
	s_nop 0
	global_load_lds_dwordx4 v180, s[14:15]
	s_waitcnt vmcnt(8)
	s_waitcnt lgkmcnt(0)
	s_barrier
	s_setprio 1
	s_waitcnt lgkmcnt(0)
	v_mfma_f32_16x16x32_bf16 v[160:163], v[88:91], v[152:155], v[160:163]
	v_mfma_f32_16x16x32_bf16 v[156:159], v[96:99], v[152:155], v[156:159]
	v_mfma_f32_16x16x32_bf16 v[148:151], v[88:91], v[168:171], v[148:151]
	v_mfma_f32_16x16x32_bf16 v[144:147], v[96:99], v[168:171], v[144:147]
	v_mfma_f32_16x16x32_bf16 v[140:143], v[88:91], v[188:191], v[140:143]
	v_mfma_f32_16x16x32_bf16 v[136:139], v[96:99], v[188:191], v[136:139]
	v_mfma_f32_16x16x32_bf16 v[132:135], v[88:91], v[196:199], v[132:135]
	v_mfma_f32_16x16x32_bf16 v[128:131], v[96:99], v[196:199], v[128:131]
	v_mfma_f32_16x16x32_bf16 v[160:163], v[92:95], v[164:167], v[160:163]
	v_mfma_f32_16x16x32_bf16 v[156:159], v[100:103], v[164:167], v[156:159]
	v_mfma_f32_16x16x32_bf16 v[148:151], v[92:95], v[172:175], v[148:151]
	v_mfma_f32_16x16x32_bf16 v[144:147], v[100:103], v[172:175], v[144:147]
	v_mfma_f32_16x16x32_bf16 v[140:143], v[92:95], v[192:195], v[140:143]
	v_mfma_f32_16x16x32_bf16 v[136:139], v[100:103], v[192:195], v[136:139]
	v_mfma_f32_16x16x32_bf16 v[132:135], v[92:95], v[200:203], v[132:135]
	v_mfma_f32_16x16x32_bf16 v[128:131], v[100:103], v[200:203], v[128:131]
	s_setprio 0
	s_setprio 1
	v_mfma_f32_16x16x32_bf16 v[60:63], v[108:111], v[152:155], v[60:63]
	v_mfma_f32_16x16x32_bf16 v[56:59], v[116:119], v[152:155], v[56:59]
	v_mfma_f32_16x16x32_bf16 v[52:55], v[108:111], v[168:171], v[52:55]
	v_mfma_f32_16x16x32_bf16 v[48:51], v[116:119], v[168:171], v[48:51]
	v_mfma_f32_16x16x32_bf16 v[44:47], v[108:111], v[188:191], v[44:47]
	v_mfma_f32_16x16x32_bf16 v[40:43], v[116:119], v[188:191], v[40:43]
	v_mfma_f32_16x16x32_bf16 v[36:39], v[108:111], v[196:199], v[36:39]
	v_mfma_f32_16x16x32_bf16 v[32:35], v[116:119], v[196:199], v[32:35]
	v_mfma_f32_16x16x32_bf16 v[60:63], v[112:115], v[164:167], v[60:63]
	v_mfma_f32_16x16x32_bf16 v[56:59], v[120:123], v[164:167], v[56:59]
	v_mfma_f32_16x16x32_bf16 v[52:55], v[112:115], v[172:175], v[52:55]
	v_mfma_f32_16x16x32_bf16 v[48:51], v[120:123], v[172:175], v[48:51]
	v_mfma_f32_16x16x32_bf16 v[44:47], v[112:115], v[192:195], v[44:47]
	v_mfma_f32_16x16x32_bf16 v[40:43], v[120:123], v[192:195], v[40:43]
	v_mfma_f32_16x16x32_bf16 v[36:39], v[112:115], v[200:203], v[36:39]
	v_mfma_f32_16x16x32_bf16 v[32:35], v[120:123], v[200:203], v[32:35]
	s_setprio 0
	s_barrier
	s_add_i32 s14, s50, s39
	s_mov_b32 m0, s14
	ds_read_b128 v[152:155], v224 offset:49152
	ds_read_b128 v[164:167], v224 offset:50176
	ds_read_b128 v[168:171], v224 offset:51200
	ds_read_b128 v[172:175], v224 offset:52224
	ds_read_b128 v[188:191], v224 offset:53248
	ds_read_b128 v[192:195], v224 offset:54272
	ds_read_b128 v[196:199], v224 offset:55296
	ds_read_b128 v[200:203], v224 offset:56320
	s_add_u32 s98, s12, 0x80
	s_addc_u32 s99, s13, 0
	global_load_lds_dwordx4 v176, s[98:99]
	s_add_i32 m0, s14, 0x2000
	s_add_u32 s12, s12, 0x80080
	s_addc_u32 s13, s13, 0
	s_add_i32 s14, s51, s39
	s_add_u32 s98, s12, 0xfff80000
	s_addc_u32 s99, s13, -1
	global_load_lds_dwordx4 v178, s[98:99]
	s_mov_b32 m0, s14
	s_nop 0
	global_load_lds_dwordx4 v176, s[12:13]
	s_add_i32 m0, s14, 0x2000
	s_nop 0
	global_load_lds_dwordx4 v178, s[12:13]
	s_mov_b32 m0, s61
	s_nop 0
	global_load_lds_dwordx4 v182, s[62:63]
	s_mov_b32 m0, s64
	s_nop 0
	global_load_lds_dwordx4 v180, s[62:63]
	s_waitcnt vmcnt(8)
	s_waitcnt lgkmcnt(0)
	s_barrier
	s_setprio 1
	s_waitcnt lgkmcnt(0)
	v_mfma_f32_16x16x32_bf16 v[124:127], v[88:91], v[152:155], v[124:127]
	v_mfma_f32_16x16x32_bf16 v[104:107], v[96:99], v[152:155], v[104:107]
	v_mfma_f32_16x16x32_bf16 v[84:87], v[88:91], v[168:171], v[84:87]
	v_mfma_f32_16x16x32_bf16 v[80:83], v[96:99], v[168:171], v[80:83]
	v_mfma_f32_16x16x32_bf16 v[76:79], v[88:91], v[188:191], v[76:79]
	v_mfma_f32_16x16x32_bf16 v[72:75], v[96:99], v[188:191], v[72:75]
	v_mfma_f32_16x16x32_bf16 v[68:71], v[88:91], v[196:199], v[68:71]
	v_mfma_f32_16x16x32_bf16 v[64:67], v[96:99], v[196:199], v[64:67]
	v_mfma_f32_16x16x32_bf16 v[124:127], v[92:95], v[164:167], v[124:127]
	v_mfma_f32_16x16x32_bf16 v[104:107], v[100:103], v[164:167], v[104:107]
	v_mfma_f32_16x16x32_bf16 v[84:87], v[92:95], v[172:175], v[84:87]
	v_mfma_f32_16x16x32_bf16 v[80:83], v[100:103], v[172:175], v[80:83]
	v_mfma_f32_16x16x32_bf16 v[76:79], v[92:95], v[192:195], v[76:79]
	v_mfma_f32_16x16x32_bf16 v[72:75], v[100:103], v[192:195], v[72:75]
	v_mfma_f32_16x16x32_bf16 v[68:71], v[92:95], v[200:203], v[68:71]
	v_mfma_f32_16x16x32_bf16 v[64:67], v[100:103], v[200:203], v[64:67]
	s_setprio 0
	s_setprio 1
	v_mfma_f32_16x16x32_bf16 v[28:31], v[108:111], v[152:155], v[28:31]
	v_mfma_f32_16x16x32_bf16 v[24:27], v[116:119], v[152:155], v[24:27]
	v_mfma_f32_16x16x32_bf16 v[20:23], v[108:111], v[168:171], v[20:23]
	v_mfma_f32_16x16x32_bf16 v[16:19], v[116:119], v[168:171], v[16:19]
	v_mfma_f32_16x16x32_bf16 v[12:15], v[108:111], v[188:191], v[12:15]
	v_mfma_f32_16x16x32_bf16 v[8:11], v[116:119], v[188:191], v[8:11]
	v_mfma_f32_16x16x32_bf16 v[4:7], v[108:111], v[196:199], v[4:7]
	v_mfma_f32_16x16x32_bf16 v[0:3], v[116:119], v[196:199], v[0:3]
	v_mfma_f32_16x16x32_bf16 v[28:31], v[112:115], v[164:167], v[28:31]
	v_mfma_f32_16x16x32_bf16 v[24:27], v[120:123], v[164:167], v[24:27]
	v_mfma_f32_16x16x32_bf16 v[20:23], v[112:115], v[172:175], v[20:23]
	v_mfma_f32_16x16x32_bf16 v[16:19], v[120:123], v[172:175], v[16:19]
	v_mfma_f32_16x16x32_bf16 v[12:15], v[112:115], v[192:195], v[12:15]
	v_mfma_f32_16x16x32_bf16 v[8:11], v[120:123], v[192:195], v[8:11]
	v_mfma_f32_16x16x32_bf16 v[4:7], v[112:115], v[200:203], v[4:7]
	v_mfma_f32_16x16x32_bf16 v[0:3], v[120:123], v[200:203], v[0:3]
	s_setprio 0
	s_barrier
	s_add_i32 s33, s33, 2
	s_add_u32 s0, s0, 0x100
	s_addc_u32 s1, s1, 0
	s_add_u32 s26, s26, 0x100
	s_addc_u32 s27, s27, 0
	s_cmp_gt_u32 s33, 29
	s_cbranch_scc0 .LBB0_1057
	s_and_b64 vcc, exec, s[40:41]
	s_cbranch_vccz .LBB0_1060
	s_barrier

.LBB0_1159:
	s_add_u32 s2, s30, 0x100
	s_addc_u32 s3, s31, 0
	s_mov_b32 s14, -2
	s_waitcnt lgkmcnt(0)
	v_add_u32_e32 v253, 0x10000, v204
	s_add_u32 s6, s0, 0x100
	s_addc_u32 s7, s1, 0
	s_add_i32 s15, 0, 0x10000
	s_cmpk_eq_i32 s14, 0x54
	s_cselect_b32 s13, s69, s7
	s_cselect_b32 s12, s68, s6
	s_cselect_b32 s9, s31, s3
	s_cselect_b32 s8, s30, s2
	s_add_i32 s20, 0, 0x14000
	ds_read_b128 v[100:103], v253
	ds_read_b128 v[108:111], v253 offset:1024
	ds_read_b128 v[112:115], v253 offset:2048
	ds_read_b128 v[116:119], v253 offset:3072
	ds_read_b128 v[136:139], v253 offset:16384
	ds_read_b128 v[148:151], v253 offset:17408
	ds_read_b128 v[152:155], v253 offset:18432
	ds_read_b128 v[156:159], v253 offset:19456
	s_add_i32 m0, s28, 0xc000
	ds_read_b128 v[160:163], v223
	ds_read_b128 v[164:167], v223 offset:1024
	ds_read_b128 v[168:171], v223 offset:2048
	ds_read_b128 v[172:175], v223 offset:3072
	ds_read_b128 v[200:203], v223 offset:4096
	ds_read_b128 v[226:229], v223 offset:5120
	ds_read_b128 v[230:233], v223 offset:6144
	ds_read_b128 v[234:237], v223 offset:7168
	global_load_lds_dwordx4 v196, s[0:1]
	s_add_i32 m0, s28, 0xe000
	s_nop 0
	global_load_lds_dwordx4 v198, s[0:1]
	s_waitcnt vmcnt(8)
	s_waitcnt lgkmcnt(0)
	s_barrier
	s_setprio 1
	s_waitcnt lgkmcnt(0)
	v_mfma_f32_16x16x32_bf16 v[144:147], v[100:103], v[160:163], 0
	v_mfma_f32_16x16x32_bf16 v[140:143], v[112:115], v[160:163], 0
	v_mfma_f32_16x16x32_bf16 v[124:127], v[100:103], v[168:171], 0
	v_mfma_f32_16x16x32_bf16 v[120:123], v[112:115], v[168:171], 0
	v_mfma_f32_16x16x32_bf16 v[92:95], v[100:103], v[200:203], 0
	v_mfma_f32_16x16x32_bf16 v[88:91], v[112:115], v[200:203], 0
	v_mfma_f32_16x16x32_bf16 v[76:79], v[100:103], v[230:233], 0
	v_mfma_f32_16x16x32_bf16 v[72:75], v[112:115], v[230:233], 0
	v_mfma_f32_16x16x32_bf16 v[144:147], v[108:111], v[164:167], v[144:147]
	v_mfma_f32_16x16x32_bf16 v[140:143], v[116:119], v[164:167], v[140:143]
	v_mfma_f32_16x16x32_bf16 v[124:127], v[108:111], v[172:175], v[124:127]
	v_mfma_f32_16x16x32_bf16 v[120:123], v[116:119], v[172:175], v[120:123]
	v_mfma_f32_16x16x32_bf16 v[92:95], v[108:111], v[226:229], v[92:95]
	v_mfma_f32_16x16x32_bf16 v[88:91], v[116:119], v[226:229], v[88:91]
	v_mfma_f32_16x16x32_bf16 v[76:79], v[108:111], v[234:237], v[76:79]
	v_mfma_f32_16x16x32_bf16 v[72:75], v[116:119], v[234:237], v[72:75]
	s_setprio 0
	s_setprio 1
	v_mfma_f32_16x16x32_bf16 v[132:135], v[136:139], v[160:163], 0
	v_mfma_f32_16x16x32_bf16 v[128:131], v[152:155], v[160:163], 0
	v_mfma_f32_16x16x32_bf16 v[104:107], v[136:139], v[168:171], 0
	v_mfma_f32_16x16x32_bf16 v[96:99], v[152:155], v[168:171], 0
	v_mfma_f32_16x16x32_bf16 v[84:87], v[136:139], v[200:203], 0
	v_mfma_f32_16x16x32_bf16 v[80:83], v[152:155], v[200:203], 0
	v_mfma_f32_16x16x32_bf16 v[68:71], v[136:139], v[230:233], 0
	v_mfma_f32_16x16x32_bf16 v[64:67], v[152:155], v[230:233], 0
	v_mfma_f32_16x16x32_bf16 v[132:135], v[148:151], v[164:167], v[132:135]
	v_mfma_f32_16x16x32_bf16 v[128:131], v[156:159], v[164:167], v[128:131]
	v_mfma_f32_16x16x32_bf16 v[104:107], v[148:151], v[172:175], v[104:107]
	v_mfma_f32_16x16x32_bf16 v[96:99], v[156:159], v[172:175], v[96:99]
	v_mfma_f32_16x16x32_bf16 v[84:87], v[148:151], v[226:229], v[84:87]
	v_mfma_f32_16x16x32_bf16 v[80:83], v[156:159], v[226:229], v[80:83]
	v_mfma_f32_16x16x32_bf16 v[68:71], v[148:151], v[234:237], v[68:71]
	v_mfma_f32_16x16x32_bf16 v[64:67], v[156:159], v[234:237], v[64:67]
	s_setprio 0
	s_barrier
	s_add_i32 s0, s15, s27
	s_mov_b32 m0, s0
	ds_read_b128 v[160:163], v223 offset:16384
	ds_read_b128 v[164:167], v223 offset:17408
	ds_read_b128 v[168:171], v223 offset:18432
	ds_read_b128 v[172:175], v223 offset:19456
	ds_read_b128 v[200:203], v223 offset:20480
	ds_read_b128 v[226:229], v223 offset:21504
	ds_read_b128 v[230:233], v223 offset:22528
	ds_read_b128 v[234:237], v223 offset:23552
	global_load_lds_dwordx4 v176, s[8:9]
	s_add_i32 m0, s0, 0x2000
	s_add_u32 s0, s8, 0x160000
	s_addc_u32 s1, s9, 0
	s_add_i32 s15, s20, s27
	global_load_lds_dwordx4 v182, s[8:9]
	s_mov_b32 m0, s15
	s_nop 0
	global_load_lds_dwordx4 v176, s[0:1]
	s_add_i32 m0, s15, 0x2000
	s_nop 0
	global_load_lds_dwordx4 v182, s[0:1]
	s_mov_b32 m0, s28
	s_nop 0
	global_load_lds_dwordx4 v178, s[12:13]
	s_mov_b32 m0, s29
	s_nop 0
	global_load_lds_dwordx4 v180, s[12:13]
	s_waitcnt vmcnt(8)
	s_waitcnt lgkmcnt(0)
	s_barrier
	s_setprio 1
	s_waitcnt lgkmcnt(0)
	v_mfma_f32_16x16x32_bf16 v[60:63], v[100:103], v[160:163], 0
	v_mfma_f32_16x16x32_bf16 v[56:59], v[112:115], v[160:163], 0
	v_mfma_f32_16x16x32_bf16 v[44:47], v[100:103], v[168:171], 0
	v_mfma_f32_16x16x32_bf16 v[40:43], v[112:115], v[168:171], 0
	v_mfma_f32_16x16x32_bf16 v[28:31], v[100:103], v[200:203], 0
	v_mfma_f32_16x16x32_bf16 v[24:27], v[112:115], v[200:203], 0
	v_mfma_f32_16x16x32_bf16 v[12:15], v[100:103], v[230:233], 0
	v_mfma_f32_16x16x32_bf16 v[8:11], v[112:115], v[230:233], 0
	v_mfma_f32_16x16x32_bf16 v[60:63], v[108:111], v[164:167], v[60:63]
	v_mfma_f32_16x16x32_bf16 v[56:59], v[116:119], v[164:167], v[56:59]
	v_mfma_f32_16x16x32_bf16 v[44:47], v[108:111], v[172:175], v[44:47]
	v_mfma_f32_16x16x32_bf16 v[40:43], v[116:119], v[172:175], v[40:43]
	v_mfma_f32_16x16x32_bf16 v[28:31], v[108:111], v[226:229], v[28:31]
	v_mfma_f32_16x16x32_bf16 v[24:27], v[116:119], v[226:229], v[24:27]
	v_mfma_f32_16x16x32_bf16 v[12:15], v[108:111], v[234:237], v[12:15]
	v_mfma_f32_16x16x32_bf16 v[8:11], v[116:119], v[234:237], v[8:11]
	s_setprio 0
	s_setprio 1
	v_mfma_f32_16x16x32_bf16 v[52:55], v[136:139], v[160:163], 0
	v_mfma_f32_16x16x32_bf16 v[48:51], v[152:155], v[160:163], 0
	v_mfma_f32_16x16x32_bf16 v[36:39], v[136:139], v[168:171], 0
	v_mfma_f32_16x16x32_bf16 v[32:35], v[152:155], v[168:171], 0
	v_mfma_f32_16x16x32_bf16 v[20:23], v[136:139], v[200:203], 0
	v_mfma_f32_16x16x32_bf16 v[16:19], v[152:155], v[200:203], 0
	v_mfma_f32_16x16x32_bf16 v[4:7], v[136:139], v[230:233], 0
	v_mfma_f32_16x16x32_bf16 v[0:3], v[152:155], v[230:233], 0
	v_mfma_f32_16x16x32_bf16 v[52:55], v[148:151], v[164:167], v[52:55]
	v_mfma_f32_16x16x32_bf16 v[48:51], v[156:159], v[164:167], v[48:51]
	v_mfma_f32_16x16x32_bf16 v[36:39], v[148:151], v[172:175], v[36:39]
	v_mfma_f32_16x16x32_bf16 v[32:35], v[156:159], v[172:175], v[32:35]
	v_mfma_f32_16x16x32_bf16 v[20:23], v[148:151], v[226:229], v[20:23]
	v_mfma_f32_16x16x32_bf16 v[16:19], v[156:159], v[226:229], v[16:19]
	v_mfma_f32_16x16x32_bf16 v[4:7], v[148:151], v[234:237], v[4:7]
	v_mfma_f32_16x16x32_bf16 v[0:3], v[156:159], v[234:237], v[0:3]
	s_setprio 0
	s_barrier
	s_add_i32 s15, 0, 0x18000
	s_add_i32 s20, 0, 0x1c000
	ds_read_b128 v[100:103], v253 offset:32768
	ds_read_b128 v[108:111], v253 offset:33792
	ds_read_b128 v[112:115], v253 offset:34816
	ds_read_b128 v[116:119], v253 offset:35840
	ds_read_b128 v[136:139], v253 offset:49152
	ds_read_b128 v[148:151], v253 offset:50176
	ds_read_b128 v[152:155], v253 offset:51200
	ds_read_b128 v[156:159], v253 offset:52224
	s_add_u32 s0, s12, 0x160000
	s_addc_u32 s1, s13, 0
	s_mov_b32 m0, s38
	ds_read_b128 v[160:163], v223 offset:32768
	ds_read_b128 v[164:167], v223 offset:33792
	ds_read_b128 v[168:171], v223 offset:34816
	ds_read_b128 v[172:175], v223 offset:35840
	ds_read_b128 v[200:203], v223 offset:36864
	ds_read_b128 v[226:229], v223 offset:37888
	ds_read_b128 v[230:233], v223 offset:38912
	ds_read_b128 v[234:237], v223 offset:39936
	global_load_lds_dwordx4 v178, s[0:1]
	s_mov_b32 m0, s39
	s_nop 0
	global_load_lds_dwordx4 v180, s[0:1]
	s_waitcnt vmcnt(8)
	s_waitcnt lgkmcnt(0)
	s_barrier
	s_setprio 1
	s_waitcnt lgkmcnt(0)
	v_mfma_f32_16x16x32_bf16 v[144:147], v[100:103], v[160:163], v[144:147]
	v_mfma_f32_16x16x32_bf16 v[140:143], v[112:115], v[160:163], v[140:143]
	v_mfma_f32_16x16x32_bf16 v[124:127], v[100:103], v[168:171], v[124:127]
	v_mfma_f32_16x16x32_bf16 v[120:123], v[112:115], v[168:171], v[120:123]
	v_mfma_f32_16x16x32_bf16 v[92:95], v[100:103], v[200:203], v[92:95]
	v_mfma_f32_16x16x32_bf16 v[88:91], v[112:115], v[200:203], v[88:91]
	v_mfma_f32_16x16x32_bf16 v[76:79], v[100:103], v[230:233], v[76:79]
	v_mfma_f32_16x16x32_bf16 v[72:75], v[112:115], v[230:233], v[72:75]
	v_mfma_f32_16x16x32_bf16 v[144:147], v[108:111], v[164:167], v[144:147]
	v_mfma_f32_16x16x32_bf16 v[140:143], v[116:119], v[164:167], v[140:143]
	v_mfma_f32_16x16x32_bf16 v[124:127], v[108:111], v[172:175], v[124:127]
	v_mfma_f32_16x16x32_bf16 v[120:123], v[116:119], v[172:175], v[120:123]
	v_mfma_f32_16x16x32_bf16 v[92:95], v[108:111], v[226:229], v[92:95]
	v_mfma_f32_16x16x32_bf16 v[88:91], v[116:119], v[226:229], v[88:91]
	v_mfma_f32_16x16x32_bf16 v[76:79], v[108:111], v[234:237], v[76:79]
	v_mfma_f32_16x16x32_bf16 v[72:75], v[116:119], v[234:237], v[72:75]
	s_setprio 0
	s_setprio 1
	v_mfma_f32_16x16x32_bf16 v[132:135], v[136:139], v[160:163], v[132:135]
	v_mfma_f32_16x16x32_bf16 v[128:131], v[152:155], v[160:163], v[128:131]
	v_mfma_f32_16x16x32_bf16 v[104:107], v[136:139], v[168:171], v[104:107]
	v_mfma_f32_16x16x32_bf16 v[96:99], v[152:155], v[168:171], v[96:99]
	v_mfma_f32_16x16x32_bf16 v[84:87], v[136:139], v[200:203], v[84:87]
	v_mfma_f32_16x16x32_bf16 v[80:83], v[152:155], v[200:203], v[80:83]
	v_mfma_f32_16x16x32_bf16 v[68:71], v[136:139], v[230:233], v[68:71]
	v_mfma_f32_16x16x32_bf16 v[64:67], v[152:155], v[230:233], v[64:67]
	v_mfma_f32_16x16x32_bf16 v[132:135], v[148:151], v[164:167], v[132:135]
	v_mfma_f32_16x16x32_bf16 v[128:131], v[156:159], v[164:167], v[128:131]
	v_mfma_f32_16x16x32_bf16 v[104:107], v[148:151], v[172:175], v[104:107]
	v_mfma_f32_16x16x32_bf16 v[96:99], v[156:159], v[172:175], v[96:99]
	v_mfma_f32_16x16x32_bf16 v[84:87], v[148:151], v[226:229], v[84:87]
	v_mfma_f32_16x16x32_bf16 v[80:83], v[156:159], v[226:229], v[80:83]
	v_mfma_f32_16x16x32_bf16 v[68:71], v[148:151], v[234:237], v[68:71]
	v_mfma_f32_16x16x32_bf16 v[64:67], v[156:159], v[234:237], v[64:67]
	s_setprio 0
	s_barrier
	s_add_i32 s0, s15, s27
	s_mov_b32 m0, s0
	ds_read_b128 v[160:163], v223 offset:49152
	ds_read_b128 v[164:167], v223 offset:50176
	ds_read_b128 v[168:171], v223 offset:51200
	ds_read_b128 v[172:175], v223 offset:52224
	ds_read_b128 v[200:203], v223 offset:53248
	ds_read_b128 v[226:229], v223 offset:54272
	ds_read_b128 v[230:233], v223 offset:55296
	ds_read_b128 v[234:237], v223 offset:56320
	s_add_u32 s98, s8, 0x80
	s_addc_u32 s99, s9, 0
	global_load_lds_dwordx4 v176, s[98:99]
	s_add_i32 m0, s0, 0x2000
	s_add_u32 s0, s8, 0x160080
	s_addc_u32 s1, s9, 0
	s_add_i32 s8, s20, s27
	s_add_u32 s98, s0, 0xffea0000
	s_addc_u32 s99, s1, -1
	global_load_lds_dwordx4 v182, s[98:99]
	s_mov_b32 m0, s8
	s_nop 0
	global_load_lds_dwordx4 v176, s[0:1]
	s_add_i32 m0, s8, 0x2000
	s_nop 0
	global_load_lds_dwordx4 v182, s[0:1]
	s_mov_b32 m0, s44
	s_nop 0
	s_add_u32 s98, s12, 0x80
	s_addc_u32 s99, s13, 0
	global_load_lds_dwordx4 v178, s[98:99]
	s_mov_b32 m0, s45
	s_nop 0
	s_add_u32 s98, s12, 0x80
	s_addc_u32 s99, s13, 0
	global_load_lds_dwordx4 v180, s[98:99]
	s_waitcnt vmcnt(8)
	s_waitcnt lgkmcnt(0)
	s_barrier
	s_setprio 1
	s_waitcnt lgkmcnt(0)
	v_mfma_f32_16x16x32_bf16 v[60:63], v[100:103], v[160:163], v[60:63]
	v_mfma_f32_16x16x32_bf16 v[56:59], v[112:115], v[160:163], v[56:59]
	v_mfma_f32_16x16x32_bf16 v[44:47], v[100:103], v[168:171], v[44:47]
	v_mfma_f32_16x16x32_bf16 v[40:43], v[112:115], v[168:171], v[40:43]
	v_mfma_f32_16x16x32_bf16 v[28:31], v[100:103], v[200:203], v[28:31]
	v_mfma_f32_16x16x32_bf16 v[24:27], v[112:115], v[200:203], v[24:27]
	v_mfma_f32_16x16x32_bf16 v[12:15], v[100:103], v[230:233], v[12:15]
	v_mfma_f32_16x16x32_bf16 v[8:11], v[112:115], v[230:233], v[8:11]
	v_mfma_f32_16x16x32_bf16 v[60:63], v[108:111], v[164:167], v[60:63]
	v_mfma_f32_16x16x32_bf16 v[56:59], v[116:119], v[164:167], v[56:59]
	v_mfma_f32_16x16x32_bf16 v[44:47], v[108:111], v[172:175], v[44:47]
	v_mfma_f32_16x16x32_bf16 v[40:43], v[116:119], v[172:175], v[40:43]
	v_mfma_f32_16x16x32_bf16 v[28:31], v[108:111], v[226:229], v[28:31]
	v_mfma_f32_16x16x32_bf16 v[24:27], v[116:119], v[226:229], v[24:27]
	v_mfma_f32_16x16x32_bf16 v[12:15], v[108:111], v[234:237], v[12:15]
	v_mfma_f32_16x16x32_bf16 v[8:11], v[116:119], v[234:237], v[8:11]
	s_setprio 0
	s_setprio 1
	v_mfma_f32_16x16x32_bf16 v[52:55], v[136:139], v[160:163], v[52:55]
	v_mfma_f32_16x16x32_bf16 v[48:51], v[152:155], v[160:163], v[48:51]
	v_mfma_f32_16x16x32_bf16 v[36:39], v[136:139], v[168:171], v[36:39]
	v_mfma_f32_16x16x32_bf16 v[32:35], v[152:155], v[168:171], v[32:35]
	v_mfma_f32_16x16x32_bf16 v[20:23], v[136:139], v[200:203], v[20:23]
	v_mfma_f32_16x16x32_bf16 v[16:19], v[152:155], v[200:203], v[16:19]
	v_mfma_f32_16x16x32_bf16 v[4:7], v[136:139], v[230:233], v[4:7]
	v_mfma_f32_16x16x32_bf16 v[0:3], v[152:155], v[230:233], v[0:3]
	v_mfma_f32_16x16x32_bf16 v[52:55], v[148:151], v[164:167], v[52:55]
	v_mfma_f32_16x16x32_bf16 v[48:51], v[156:159], v[164:167], v[48:51]
	v_mfma_f32_16x16x32_bf16 v[36:39], v[148:151], v[172:175], v[36:39]
	v_mfma_f32_16x16x32_bf16 v[32:35], v[156:159], v[172:175], v[32:35]
	v_mfma_f32_16x16x32_bf16 v[20:23], v[148:151], v[226:229], v[20:23]
	v_mfma_f32_16x16x32_bf16 v[16:19], v[156:159], v[226:229], v[16:19]
	v_mfma_f32_16x16x32_bf16 v[4:7], v[148:151], v[234:237], v[4:7]
	v_mfma_f32_16x16x32_bf16 v[0:3], v[156:159], v[234:237], v[0:3]
	s_setprio 0
	s_barrier
	s_add_i32 s14, s14, 2
	s_add_u32 s2, s2, 0x100
	s_addc_u32 s3, s3, 0
	s_cmpk_gt_u32 s14, 0x55
	s_mov_b64 s[0:1], s[6:7]
.LBB0_1160:
	s_add_u32 s6, s0, 0x100
	s_addc_u32 s7, s1, 0
	s_add_i32 s15, 0, 0x10000
	s_cmpk_eq_i32 s14, 0x54
	s_cselect_b32 s13, s69, s7
	s_cselect_b32 s12, s68, s6
	s_cselect_b32 s9, s31, s3
	s_cselect_b32 s8, s30, s2
	s_add_i32 s20, 0, 0x14000
	ds_read_b128 v[100:103], v253
	ds_read_b128 v[108:111], v253 offset:1024
	ds_read_b128 v[112:115], v253 offset:2048
	ds_read_b128 v[116:119], v253 offset:3072
	ds_read_b128 v[136:139], v253 offset:16384
	ds_read_b128 v[148:151], v253 offset:17408
	ds_read_b128 v[152:155], v253 offset:18432
	ds_read_b128 v[156:159], v253 offset:19456
	s_add_i32 m0, s28, 0xc000
	ds_read_b128 v[160:163], v223
	ds_read_b128 v[164:167], v223 offset:1024
	ds_read_b128 v[168:171], v223 offset:2048
	ds_read_b128 v[172:175], v223 offset:3072
	ds_read_b128 v[200:203], v223 offset:4096
	ds_read_b128 v[226:229], v223 offset:5120
	ds_read_b128 v[230:233], v223 offset:6144
	ds_read_b128 v[234:237], v223 offset:7168
	global_load_lds_dwordx4 v196, s[0:1]
	s_add_i32 m0, s28, 0xe000
	s_nop 0
	global_load_lds_dwordx4 v198, s[0:1]
	s_waitcnt vmcnt(8)
	s_waitcnt lgkmcnt(0)
	s_barrier
	s_setprio 1
	s_waitcnt lgkmcnt(0)
	v_mfma_f32_16x16x32_bf16 v[144:147], v[100:103], v[160:163], v[144:147]
	v_mfma_f32_16x16x32_bf16 v[140:143], v[112:115], v[160:163], v[140:143]
	v_mfma_f32_16x16x32_bf16 v[124:127], v[100:103], v[168:171], v[124:127]
	v_mfma_f32_16x16x32_bf16 v[120:123], v[112:115], v[168:171], v[120:123]
	v_mfma_f32_16x16x32_bf16 v[92:95], v[100:103], v[200:203], v[92:95]
	v_mfma_f32_16x16x32_bf16 v[88:91], v[112:115], v[200:203], v[88:91]
	v_mfma_f32_16x16x32_bf16 v[76:79], v[100:103], v[230:233], v[76:79]
	v_mfma_f32_16x16x32_bf16 v[72:75], v[112:115], v[230:233], v[72:75]
	v_mfma_f32_16x16x32_bf16 v[144:147], v[108:111], v[164:167], v[144:147]
	v_mfma_f32_16x16x32_bf16 v[140:143], v[116:119], v[164:167], v[140:143]
	v_mfma_f32_16x16x32_bf16 v[124:127], v[108:111], v[172:175], v[124:127]
	v_mfma_f32_16x16x32_bf16 v[120:123], v[116:119], v[172:175], v[120:123]
	v_mfma_f32_16x16x32_bf16 v[92:95], v[108:111], v[226:229], v[92:95]
	v_mfma_f32_16x16x32_bf16 v[88:91], v[116:119], v[226:229], v[88:91]
	v_mfma_f32_16x16x32_bf16 v[76:79], v[108:111], v[234:237], v[76:79]
	v_mfma_f32_16x16x32_bf16 v[72:75], v[116:119], v[234:237], v[72:75]
	s_setprio 0
	s_setprio 1
	v_mfma_f32_16x16x32_bf16 v[132:135], v[136:139], v[160:163], v[132:135]
	v_mfma_f32_16x16x32_bf16 v[128:131], v[152:155], v[160:163], v[128:131]
	v_mfma_f32_16x16x32_bf16 v[104:107], v[136:139], v[168:171], v[104:107]
	v_mfma_f32_16x16x32_bf16 v[96:99], v[152:155], v[168:171], v[96:99]
	v_mfma_f32_16x16x32_bf16 v[84:87], v[136:139], v[200:203], v[84:87]
	v_mfma_f32_16x16x32_bf16 v[80:83], v[152:155], v[200:203], v[80:83]
	v_mfma_f32_16x16x32_bf16 v[68:71], v[136:139], v[230:233], v[68:71]
	v_mfma_f32_16x16x32_bf16 v[64:67], v[152:155], v[230:233], v[64:67]
	v_mfma_f32_16x16x32_bf16 v[132:135], v[148:151], v[164:167], v[132:135]
	v_mfma_f32_16x16x32_bf16 v[128:131], v[156:159], v[164:167], v[128:131]
	v_mfma_f32_16x16x32_bf16 v[104:107], v[148:151], v[172:175], v[104:107]
	v_mfma_f32_16x16x32_bf16 v[96:99], v[156:159], v[172:175], v[96:99]
	v_mfma_f32_16x16x32_bf16 v[84:87], v[148:151], v[226:229], v[84:87]
	v_mfma_f32_16x16x32_bf16 v[80:83], v[156:159], v[226:229], v[80:83]
	v_mfma_f32_16x16x32_bf16 v[68:71], v[148:151], v[234:237], v[68:71]
	v_mfma_f32_16x16x32_bf16 v[64:67], v[156:159], v[234:237], v[64:67]
	s_setprio 0
	s_barrier
	s_add_i32 s0, s15, s27
	s_mov_b32 m0, s0
	ds_read_b128 v[160:163], v223 offset:16384
	ds_read_b128 v[164:167], v223 offset:17408
	ds_read_b128 v[168:171], v223 offset:18432
	ds_read_b128 v[172:175], v223 offset:19456
	ds_read_b128 v[200:203], v223 offset:20480
	ds_read_b128 v[226:229], v223 offset:21504
	ds_read_b128 v[230:233], v223 offset:22528
	ds_read_b128 v[234:237], v223 offset:23552
	global_load_lds_dwordx4 v176, s[8:9]
	s_add_i32 m0, s0, 0x2000
	s_add_u32 s0, s8, 0x160000
	s_addc_u32 s1, s9, 0
	s_add_i32 s15, s20, s27
	global_load_lds_dwordx4 v182, s[8:9]
	s_mov_b32 m0, s15
	s_nop 0
	global_load_lds_dwordx4 v176, s[0:1]
	s_add_i32 m0, s15, 0x2000
	s_nop 0
	global_load_lds_dwordx4 v182, s[0:1]
	s_mov_b32 m0, s28
	s_nop 0
	global_load_lds_dwordx4 v178, s[12:13]
	s_mov_b32 m0, s29
	s_nop 0
	global_load_lds_dwordx4 v180, s[12:13]
	s_waitcnt vmcnt(8)
	s_waitcnt lgkmcnt(0)
	s_barrier
	s_setprio 1
	s_waitcnt lgkmcnt(0)
	v_mfma_f32_16x16x32_bf16 v[60:63], v[100:103], v[160:163], v[60:63]
	v_mfma_f32_16x16x32_bf16 v[56:59], v[112:115], v[160:163], v[56:59]
	v_mfma_f32_16x16x32_bf16 v[44:47], v[100:103], v[168:171], v[44:47]
	v_mfma_f32_16x16x32_bf16 v[40:43], v[112:115], v[168:171], v[40:43]
	v_mfma_f32_16x16x32_bf16 v[28:31], v[100:103], v[200:203], v[28:31]
	v_mfma_f32_16x16x32_bf16 v[24:27], v[112:115], v[200:203], v[24:27]
	v_mfma_f32_16x16x32_bf16 v[12:15], v[100:103], v[230:233], v[12:15]
	v_mfma_f32_16x16x32_bf16 v[8:11], v[112:115], v[230:233], v[8:11]
	v_mfma_f32_16x16x32_bf16 v[60:63], v[108:111], v[164:167], v[60:63]
	v_mfma_f32_16x16x32_bf16 v[56:59], v[116:119], v[164:167], v[56:59]
	v_mfma_f32_16x16x32_bf16 v[44:47], v[108:111], v[172:175], v[44:47]
	v_mfma_f32_16x16x32_bf16 v[40:43], v[116:119], v[172:175], v[40:43]
	v_mfma_f32_16x16x32_bf16 v[28:31], v[108:111], v[226:229], v[28:31]
	v_mfma_f32_16x16x32_bf16 v[24:27], v[116:119], v[226:229], v[24:27]
	v_mfma_f32_16x16x32_bf16 v[12:15], v[108:111], v[234:237], v[12:15]
	v_mfma_f32_16x16x32_bf16 v[8:11], v[116:119], v[234:237], v[8:11]
	s_setprio 0
	s_setprio 1
	v_mfma_f32_16x16x32_bf16 v[52:55], v[136:139], v[160:163], v[52:55]
	v_mfma_f32_16x16x32_bf16 v[48:51], v[152:155], v[160:163], v[48:51]
	v_mfma_f32_16x16x32_bf16 v[36:39], v[136:139], v[168:171], v[36:39]
	v_mfma_f32_16x16x32_bf16 v[32:35], v[152:155], v[168:171], v[32:35]
	v_mfma_f32_16x16x32_bf16 v[20:23], v[136:139], v[200:203], v[20:23]
	v_mfma_f32_16x16x32_bf16 v[16:19], v[152:155], v[200:203], v[16:19]
	v_mfma_f32_16x16x32_bf16 v[4:7], v[136:139], v[230:233], v[4:7]
	v_mfma_f32_16x16x32_bf16 v[0:3], v[152:155], v[230:233], v[0:3]
	v_mfma_f32_16x16x32_bf16 v[52:55], v[148:151], v[164:167], v[52:55]
	v_mfma_f32_16x16x32_bf16 v[48:51], v[156:159], v[164:167], v[48:51]
	v_mfma_f32_16x16x32_bf16 v[36:39], v[148:151], v[172:175], v[36:39]
	v_mfma_f32_16x16x32_bf16 v[32:35], v[156:159], v[172:175], v[32:35]
	v_mfma_f32_16x16x32_bf16 v[20:23], v[148:151], v[226:229], v[20:23]
	v_mfma_f32_16x16x32_bf16 v[16:19], v[156:159], v[226:229], v[16:19]
	v_mfma_f32_16x16x32_bf16 v[4:7], v[148:151], v[234:237], v[4:7]
	v_mfma_f32_16x16x32_bf16 v[0:3], v[156:159], v[234:237], v[0:3]
	s_setprio 0
	s_barrier
	s_add_i32 s15, 0, 0x18000
	s_add_i32 s20, 0, 0x1c000
	ds_read_b128 v[100:103], v253 offset:32768
	ds_read_b128 v[108:111], v253 offset:33792
	ds_read_b128 v[112:115], v253 offset:34816
	ds_read_b128 v[116:119], v253 offset:35840
	ds_read_b128 v[136:139], v253 offset:49152
	ds_read_b128 v[148:151], v253 offset:50176
	ds_read_b128 v[152:155], v253 offset:51200
	ds_read_b128 v[156:159], v253 offset:52224
	s_add_u32 s0, s12, 0x160000
	s_addc_u32 s1, s13, 0
	s_mov_b32 m0, s38
	ds_read_b128 v[160:163], v223 offset:32768
	ds_read_b128 v[164:167], v223 offset:33792
	ds_read_b128 v[168:171], v223 offset:34816
	ds_read_b128 v[172:175], v223 offset:35840
	ds_read_b128 v[200:203], v223 offset:36864
	ds_read_b128 v[226:229], v223 offset:37888
	ds_read_b128 v[230:233], v223 offset:38912
	ds_read_b128 v[234:237], v223 offset:39936
	global_load_lds_dwordx4 v178, s[0:1]
	s_mov_b32 m0, s39
	s_nop 0
	global_load_lds_dwordx4 v180, s[0:1]
	s_waitcnt vmcnt(8)
	s_waitcnt lgkmcnt(0)
	s_barrier
	s_setprio 1
	s_waitcnt lgkmcnt(0)
	v_mfma_f32_16x16x32_bf16 v[144:147], v[100:103], v[160:163], v[144:147]
	v_mfma_f32_16x16x32_bf16 v[140:143], v[112:115], v[160:163], v[140:143]
	v_mfma_f32_16x16x32_bf16 v[124:127], v[100:103], v[168:171], v[124:127]
	v_mfma_f32_16x16x32_bf16 v[120:123], v[112:115], v[168:171], v[120:123]
	v_mfma_f32_16x16x32_bf16 v[92:95], v[100:103], v[200:203], v[92:95]
	v_mfma_f32_16x16x32_bf16 v[88:91], v[112:115], v[200:203], v[88:91]
	v_mfma_f32_16x16x32_bf16 v[76:79], v[100:103], v[230:233], v[76:79]
	v_mfma_f32_16x16x32_bf16 v[72:75], v[112:115], v[230:233], v[72:75]
	v_mfma_f32_16x16x32_bf16 v[144:147], v[108:111], v[164:167], v[144:147]
	v_mfma_f32_16x16x32_bf16 v[140:143], v[116:119], v[164:167], v[140:143]
	v_mfma_f32_16x16x32_bf16 v[124:127], v[108:111], v[172:175], v[124:127]
	v_mfma_f32_16x16x32_bf16 v[120:123], v[116:119], v[172:175], v[120:123]
	v_mfma_f32_16x16x32_bf16 v[92:95], v[108:111], v[226:229], v[92:95]
	v_mfma_f32_16x16x32_bf16 v[88:91], v[116:119], v[226:229], v[88:91]
	v_mfma_f32_16x16x32_bf16 v[76:79], v[108:111], v[234:237], v[76:79]
	v_mfma_f32_16x16x32_bf16 v[72:75], v[116:119], v[234:237], v[72:75]
	s_setprio 0
	s_setprio 1
	v_mfma_f32_16x16x32_bf16 v[132:135], v[136:139], v[160:163], v[132:135]
	v_mfma_f32_16x16x32_bf16 v[128:131], v[152:155], v[160:163], v[128:131]
	v_mfma_f32_16x16x32_bf16 v[104:107], v[136:139], v[168:171], v[104:107]
	v_mfma_f32_16x16x32_bf16 v[96:99], v[152:155], v[168:171], v[96:99]
	v_mfma_f32_16x16x32_bf16 v[84:87], v[136:139], v[200:203], v[84:87]
	v_mfma_f32_16x16x32_bf16 v[80:83], v[152:155], v[200:203], v[80:83]
	v_mfma_f32_16x16x32_bf16 v[68:71], v[136:139], v[230:233], v[68:71]
	v_mfma_f32_16x16x32_bf16 v[64:67], v[152:155], v[230:233], v[64:67]
	v_mfma_f32_16x16x32_bf16 v[132:135], v[148:151], v[164:167], v[132:135]
	v_mfma_f32_16x16x32_bf16 v[128:131], v[156:159], v[164:167], v[128:131]
	v_mfma_f32_16x16x32_bf16 v[104:107], v[148:151], v[172:175], v[104:107]
	v_mfma_f32_16x16x32_bf16 v[96:99], v[156:159], v[172:175], v[96:99]
	v_mfma_f32_16x16x32_bf16 v[84:87], v[148:151], v[226:229], v[84:87]
	v_mfma_f32_16x16x32_bf16 v[80:83], v[156:159], v[226:229], v[80:83]
	v_mfma_f32_16x16x32_bf16 v[68:71], v[148:151], v[234:237], v[68:71]
	v_mfma_f32_16x16x32_bf16 v[64:67], v[156:159], v[234:237], v[64:67]
	s_setprio 0
	s_barrier
	s_add_i32 s0, s15, s27
	s_mov_b32 m0, s0
	ds_read_b128 v[160:163], v223 offset:49152
	ds_read_b128 v[164:167], v223 offset:50176
	ds_read_b128 v[168:171], v223 offset:51200
	ds_read_b128 v[172:175], v223 offset:52224
	ds_read_b128 v[200:203], v223 offset:53248
	ds_read_b128 v[226:229], v223 offset:54272
	ds_read_b128 v[230:233], v223 offset:55296
	ds_read_b128 v[234:237], v223 offset:56320
	s_add_u32 s98, s8, 0x80
	s_addc_u32 s99, s9, 0
	global_load_lds_dwordx4 v176, s[98:99]
	s_add_i32 m0, s0, 0x2000
	s_add_u32 s0, s8, 0x160080
	s_addc_u32 s1, s9, 0
	s_add_i32 s8, s20, s27
	s_add_u32 s98, s0, 0xffea0000
	s_addc_u32 s99, s1, -1
	global_load_lds_dwordx4 v182, s[98:99]
	s_mov_b32 m0, s8
	s_nop 0
	global_load_lds_dwordx4 v176, s[0:1]
	s_add_i32 m0, s8, 0x2000
	s_nop 0
	global_load_lds_dwordx4 v182, s[0:1]
	s_mov_b32 m0, s44
	s_nop 0
	s_add_u32 s98, s12, 0x80
	s_addc_u32 s99, s13, 0
	global_load_lds_dwordx4 v178, s[98:99]
	s_mov_b32 m0, s45
	s_nop 0
	s_add_u32 s98, s12, 0x80
	s_addc_u32 s99, s13, 0
	global_load_lds_dwordx4 v180, s[98:99]
	s_waitcnt vmcnt(8)
	s_waitcnt lgkmcnt(0)
	s_barrier
	s_setprio 1
	s_waitcnt lgkmcnt(0)
	v_mfma_f32_16x16x32_bf16 v[60:63], v[100:103], v[160:163], v[60:63]
	v_mfma_f32_16x16x32_bf16 v[56:59], v[112:115], v[160:163], v[56:59]
	v_mfma_f32_16x16x32_bf16 v[44:47], v[100:103], v[168:171], v[44:47]
	v_mfma_f32_16x16x32_bf16 v[40:43], v[112:115], v[168:171], v[40:43]
	v_mfma_f32_16x16x32_bf16 v[28:31], v[100:103], v[200:203], v[28:31]
	v_mfma_f32_16x16x32_bf16 v[24:27], v[112:115], v[200:203], v[24:27]
	v_mfma_f32_16x16x32_bf16 v[12:15], v[100:103], v[230:233], v[12:15]
	v_mfma_f32_16x16x32_bf16 v[8:11], v[112:115], v[230:233], v[8:11]
	v_mfma_f32_16x16x32_bf16 v[60:63], v[108:111], v[164:167], v[60:63]
	v_mfma_f32_16x16x32_bf16 v[56:59], v[116:119], v[164:167], v[56:59]
	v_mfma_f32_16x16x32_bf16 v[44:47], v[108:111], v[172:175], v[44:47]
	v_mfma_f32_16x16x32_bf16 v[40:43], v[116:119], v[172:175], v[40:43]
	v_mfma_f32_16x16x32_bf16 v[28:31], v[108:111], v[226:229], v[28:31]
	v_mfma_f32_16x16x32_bf16 v[24:27], v[116:119], v[226:229], v[24:27]
	v_mfma_f32_16x16x32_bf16 v[12:15], v[108:111], v[234:237], v[12:15]
	v_mfma_f32_16x16x32_bf16 v[8:11], v[116:119], v[234:237], v[8:11]
	s_setprio 0
	s_setprio 1
	v_mfma_f32_16x16x32_bf16 v[52:55], v[136:139], v[160:163], v[52:55]
	v_mfma_f32_16x16x32_bf16 v[48:51], v[152:155], v[160:163], v[48:51]
	v_mfma_f32_16x16x32_bf16 v[36:39], v[136:139], v[168:171], v[36:39]
	v_mfma_f32_16x16x32_bf16 v[32:35], v[152:155], v[168:171], v[32:35]
	v_mfma_f32_16x16x32_bf16 v[20:23], v[136:139], v[200:203], v[20:23]
	v_mfma_f32_16x16x32_bf16 v[16:19], v[152:155], v[200:203], v[16:19]
	v_mfma_f32_16x16x32_bf16 v[4:7], v[136:139], v[230:233], v[4:7]
	v_mfma_f32_16x16x32_bf16 v[0:3], v[152:155], v[230:233], v[0:3]
	v_mfma_f32_16x16x32_bf16 v[52:55], v[148:151], v[164:167], v[52:55]
	v_mfma_f32_16x16x32_bf16 v[48:51], v[156:159], v[164:167], v[48:51]
	v_mfma_f32_16x16x32_bf16 v[36:39], v[148:151], v[172:175], v[36:39]
	v_mfma_f32_16x16x32_bf16 v[32:35], v[156:159], v[172:175], v[32:35]
	v_mfma_f32_16x16x32_bf16 v[20:23], v[148:151], v[226:229], v[20:23]
	v_mfma_f32_16x16x32_bf16 v[16:19], v[156:159], v[226:229], v[16:19]
	v_mfma_f32_16x16x32_bf16 v[4:7], v[148:151], v[234:237], v[4:7]
	v_mfma_f32_16x16x32_bf16 v[0:3], v[156:159], v[234:237], v[0:3]
	s_setprio 0
	s_barrier
	s_add_i32 s14, s14, 2
	s_add_u32 s2, s2, 0x100
	s_addc_u32 s3, s3, 0
	s_cmpk_gt_u32 s14, 0x55
	s_mov_b64 s[0:1], s[6:7]
	s_cbranch_scc0 .LBB0_1160
	s_and_b64 vcc, exec, s[52:53]
	s_cbranch_vccz .LBB0_1163
	s_barrier
